# PEER expert U/V batch loops (both layers): all 32 gather loads issued up front with immediate lane indices, waits re-derived
# speedup vs baseline: 1.0274x; 1.0125x over previous
.LBB0_2100:
	v_cmp_gt_u32_e64 s[12:13], 64, v127
	s_nop 1
	v_cndmask_b32_e64 v70, v118, v117, s[12:13]
	v_readfirstlane_b32 s92, v127
	s_nop 1
	s_and_b32 s92, s92, 32
	s_cbranch_scc1 .Lh3_u10_hi
	v_readlane_b32 s84, v70, 0
	v_readlane_b32 s86, v70, 1
	v_readlane_b32 s88, v70, 2
	v_readlane_b32 s90, v70, 3
	s_ashr_i32 s85, s84, 31
	s_ashr_i32 s87, s86, 31
	s_ashr_i32 s89, s88, 31
	s_ashr_i32 s91, s90, 31
	s_lshl_b64 s[84:85], s[84:85], 9
	s_lshl_b64 s[86:87], s[86:87], 9
	s_lshl_b64 s[88:89], s[88:89], 9
	s_lshl_b64 s[90:91], s[90:91], 9
	v_lshl_add_u64 v[72:73], v[38:39], 0, s[84:85]
	v_lshl_add_u64 v[74:75], v[38:39], 0, s[86:87]
	v_lshl_add_u64 v[76:77], v[38:39], 0, s[88:89]
	v_lshl_add_u64 v[78:79], v[38:39], 0, s[90:91]
	global_load_dwordx2 v[72:73], v[72:73], off
	global_load_dwordx2 v[74:75], v[74:75], off
	global_load_dwordx2 v[76:77], v[76:77], off
	global_load_dwordx2 v[78:79], v[78:79], off
	v_readlane_b32 s84, v70, 4
	v_readlane_b32 s86, v70, 5
	v_readlane_b32 s88, v70, 6
	v_readlane_b32 s90, v70, 7
	s_ashr_i32 s85, s84, 31
	s_ashr_i32 s87, s86, 31
	s_ashr_i32 s89, s88, 31
	s_ashr_i32 s91, s90, 31
	s_lshl_b64 s[84:85], s[84:85], 9
	s_lshl_b64 s[86:87], s[86:87], 9
	s_lshl_b64 s[88:89], s[88:89], 9
	s_lshl_b64 s[90:91], s[90:91], 9
	v_lshl_add_u64 v[80:81], v[38:39], 0, s[84:85]
	v_lshl_add_u64 v[82:83], v[38:39], 0, s[86:87]
	v_lshl_add_u64 v[84:85], v[38:39], 0, s[88:89]
	v_lshl_add_u64 v[86:87], v[38:39], 0, s[90:91]
	global_load_dwordx2 v[80:81], v[80:81], off
	global_load_dwordx2 v[82:83], v[82:83], off
	global_load_dwordx2 v[84:85], v[84:85], off
	global_load_dwordx2 v[86:87], v[86:87], off
	v_readlane_b32 s84, v70, 8
	v_readlane_b32 s86, v70, 9
	v_readlane_b32 s88, v70, 10
	v_readlane_b32 s90, v70, 11
	s_ashr_i32 s85, s84, 31
	s_ashr_i32 s87, s86, 31
	s_ashr_i32 s89, s88, 31
	s_ashr_i32 s91, s90, 31
	s_lshl_b64 s[84:85], s[84:85], 9
	s_lshl_b64 s[86:87], s[86:87], 9
	s_lshl_b64 s[88:89], s[88:89], 9
	s_lshl_b64 s[90:91], s[90:91], 9
	v_lshl_add_u64 v[88:89], v[38:39], 0, s[84:85]
	v_lshl_add_u64 v[90:91], v[38:39], 0, s[86:87]
	v_lshl_add_u64 v[92:93], v[38:39], 0, s[88:89]
	v_lshl_add_u64 v[94:95], v[38:39], 0, s[90:91]
	global_load_dwordx2 v[88:89], v[88:89], off
	global_load_dwordx2 v[90:91], v[90:91], off
	global_load_dwordx2 v[92:93], v[92:93], off
	global_load_dwordx2 v[94:95], v[94:95], off
	v_readlane_b32 s84, v70, 12
	v_readlane_b32 s86, v70, 13
	v_readlane_b32 s88, v70, 14
	v_readlane_b32 s90, v70, 15
	s_ashr_i32 s85, s84, 31
	s_ashr_i32 s87, s86, 31
	s_ashr_i32 s89, s88, 31
	s_ashr_i32 s91, s90, 31
	s_lshl_b64 s[84:85], s[84:85], 9
	s_lshl_b64 s[86:87], s[86:87], 9
	s_lshl_b64 s[88:89], s[88:89], 9
	s_lshl_b64 s[90:91], s[90:91], 9
	v_lshl_add_u64 v[96:97], v[38:39], 0, s[84:85]
	v_lshl_add_u64 v[98:99], v[38:39], 0, s[86:87]
	v_lshl_add_u64 v[100:101], v[38:39], 0, s[88:89]
	v_lshl_add_u64 v[102:103], v[38:39], 0, s[90:91]
	global_load_dwordx2 v[96:97], v[96:97], off
	global_load_dwordx2 v[98:99], v[98:99], off
	global_load_dwordx2 v[100:101], v[100:101], off
	global_load_dwordx2 v[102:103], v[102:103], off
	v_readlane_b32 s84, v70, 16
	v_readlane_b32 s86, v70, 17
	v_readlane_b32 s88, v70, 18
	v_readlane_b32 s90, v70, 19
	s_ashr_i32 s85, s84, 31
	s_ashr_i32 s87, s86, 31
	s_ashr_i32 s89, s88, 31
	s_ashr_i32 s91, s90, 31
	s_lshl_b64 s[84:85], s[84:85], 9
	s_lshl_b64 s[86:87], s[86:87], 9
	s_lshl_b64 s[88:89], s[88:89], 9
	s_lshl_b64 s[90:91], s[90:91], 9
	v_lshl_add_u64 v[20:21], v[38:39], 0, s[84:85]
	v_lshl_add_u64 v[22:23], v[38:39], 0, s[86:87]
	v_lshl_add_u64 v[24:25], v[38:39], 0, s[88:89]
	v_lshl_add_u64 v[26:27], v[38:39], 0, s[90:91]
	global_load_dwordx2 v[20:21], v[20:21], off
	global_load_dwordx2 v[22:23], v[22:23], off
	global_load_dwordx2 v[24:25], v[24:25], off
	global_load_dwordx2 v[26:27], v[26:27], off
	v_readlane_b32 s84, v70, 20
	v_readlane_b32 s86, v70, 21
	v_readlane_b32 s88, v70, 22
	v_readlane_b32 s90, v70, 23
	s_ashr_i32 s85, s84, 31
	s_ashr_i32 s87, s86, 31
	s_ashr_i32 s89, s88, 31
	s_ashr_i32 s91, s90, 31
	s_lshl_b64 s[84:85], s[84:85], 9
	s_lshl_b64 s[86:87], s[86:87], 9
	s_lshl_b64 s[88:89], s[88:89], 9
	s_lshl_b64 s[90:91], s[90:91], 9
	v_lshl_add_u64 v[28:29], v[38:39], 0, s[84:85]
	v_lshl_add_u64 v[30:31], v[38:39], 0, s[86:87]
	v_lshl_add_u64 v[32:33], v[38:39], 0, s[88:89]
	v_lshl_add_u64 v[34:35], v[38:39], 0, s[90:91]
	global_load_dwordx2 v[28:29], v[28:29], off
	global_load_dwordx2 v[30:31], v[30:31], off
	global_load_dwordx2 v[32:33], v[32:33], off
	global_load_dwordx2 v[34:35], v[34:35], off
	v_readlane_b32 s84, v70, 24
	v_readlane_b32 s86, v70, 25
	v_readlane_b32 s88, v70, 26
	v_readlane_b32 s90, v70, 27
	s_ashr_i32 s85, s84, 31
	s_ashr_i32 s87, s86, 31
	s_ashr_i32 s89, s88, 31
	s_ashr_i32 s91, s90, 31
	s_lshl_b64 s[84:85], s[84:85], 9
	s_lshl_b64 s[86:87], s[86:87], 9
	s_lshl_b64 s[88:89], s[88:89], 9
	s_lshl_b64 s[90:91], s[90:91], 9
	v_lshl_add_u64 v[56:57], v[38:39], 0, s[84:85]
	v_lshl_add_u64 v[58:59], v[38:39], 0, s[86:87]
	v_lshl_add_u64 v[60:61], v[38:39], 0, s[88:89]
	v_lshl_add_u64 v[62:63], v[38:39], 0, s[90:91]
	global_load_dwordx2 v[56:57], v[56:57], off
	global_load_dwordx2 v[58:59], v[58:59], off
	global_load_dwordx2 v[60:61], v[60:61], off
	global_load_dwordx2 v[62:63], v[62:63], off
	v_readlane_b32 s84, v70, 28
	v_readlane_b32 s86, v70, 29
	v_readlane_b32 s88, v70, 30
	v_readlane_b32 s90, v70, 31
	s_ashr_i32 s85, s84, 31
	s_ashr_i32 s87, s86, 31
	s_ashr_i32 s89, s88, 31
	s_ashr_i32 s91, s90, 31
	s_lshl_b64 s[84:85], s[84:85], 9
	s_lshl_b64 s[86:87], s[86:87], 9
	s_lshl_b64 s[88:89], s[88:89], 9
	s_lshl_b64 s[90:91], s[90:91], 9
	v_lshl_add_u64 v[64:65], v[38:39], 0, s[84:85]
	v_lshl_add_u64 v[66:67], v[38:39], 0, s[86:87]
	v_lshl_add_u64 v[68:69], v[38:39], 0, s[88:89]
	v_lshl_add_u64 v[70:71], v[38:39], 0, s[90:91]
	global_load_dwordx2 v[64:65], v[64:65], off
	global_load_dwordx2 v[66:67], v[66:67], off
	global_load_dwordx2 v[68:69], v[68:69], off
	global_load_dwordx2 v[70:71], v[70:71], off
	s_waitcnt vmcnt(31)
	v_cvt_scalef32_pk_f32_fp4 v[132:133], v72, 1.0 op_sel:[1,0,0]
	s_nop 0
	v_cvt_scalef32_pk_f32_fp4 v[130:131], v72, 1.0
	v_pk_mul_f32 v[132:133], v[132:133], v[6:7]
	s_nop 0
	v_pk_fma_f32 v[130:131], v[130:131], v[4:5], v[132:133]
	v_cvt_scalef32_pk_f32_fp4 v[132:133], v72, 1.0 op_sel:[0,1,0]
	v_pk_fma_f32 v[130:131], v[132:133], v[8:9], v[130:131]
	v_cvt_scalef32_pk_f32_fp4 v[132:133], v72, 1.0 op_sel:[1,1,0]
	v_pk_fma_f32 v[130:131], v[132:133], v[10:11], v[130:131]
	v_cvt_scalef32_pk_f32_fp4 v[132:133], v73, 1.0
	v_pk_fma_f32 v[130:131], v[132:133], v[12:13], v[130:131]
	v_cvt_scalef32_pk_f32_fp4 v[132:133], v73, 1.0 op_sel:[1,0,0]
	v_pk_fma_f32 v[130:131], v[132:133], v[14:15], v[130:131]
	v_cvt_scalef32_pk_f32_fp4 v[132:133], v73, 1.0 op_sel:[0,1,0]
	v_pk_fma_f32 v[130:131], v[132:133], v[16:17], v[130:131]
	v_cvt_scalef32_pk_f32_fp4 v[72:73], v73, 1.0 op_sel:[1,1,0]
	v_pk_fma_f32 v[72:73], v[72:73], v[18:19], v[130:131]
	s_waitcnt vmcnt(30)
	v_cvt_scalef32_pk_f32_fp4 v[130:131], v74, 1.0 op_sel:[1,0,0]
	v_add_f32_e32 v132, v72, v73
	v_cvt_scalef32_pk_f32_fp4 v[72:73], v74, 1.0
	v_pk_mul_f32 v[130:131], v[130:131], v[6:7]
	s_nop 0
	v_pk_fma_f32 v[72:73], v[72:73], v[4:5], v[130:131]
	v_cvt_scalef32_pk_f32_fp4 v[130:131], v74, 1.0 op_sel:[0,1,0]
	v_pk_fma_f32 v[72:73], v[130:131], v[8:9], v[72:73]
	v_cvt_scalef32_pk_f32_fp4 v[130:131], v74, 1.0 op_sel:[1,1,0]
	v_pk_fma_f32 v[72:73], v[130:131], v[10:11], v[72:73]
	v_cvt_scalef32_pk_f32_fp4 v[130:131], v75, 1.0
	v_pk_fma_f32 v[72:73], v[130:131], v[12:13], v[72:73]
	v_cvt_scalef32_pk_f32_fp4 v[130:131], v75, 1.0 op_sel:[1,0,0]
	v_pk_fma_f32 v[72:73], v[130:131], v[14:15], v[72:73]
	v_cvt_scalef32_pk_f32_fp4 v[130:131], v75, 1.0 op_sel:[0,1,0]
	v_pk_fma_f32 v[72:73], v[130:131], v[16:17], v[72:73]
	v_cvt_scalef32_pk_f32_fp4 v[74:75], v75, 1.0 op_sel:[1,1,0]
	v_pk_fma_f32 v[72:73], v[74:75], v[18:19], v[72:73]
	s_waitcnt vmcnt(29)
	v_cvt_scalef32_pk_f32_fp4 v[74:75], v76, 1.0 op_sel:[1,0,0]
	v_add_f32_e32 v130, v72, v73
	v_cvt_scalef32_pk_f32_fp4 v[72:73], v76, 1.0
	v_pk_mul_f32 v[74:75], v[74:75], v[6:7]
	s_nop 0
	v_pk_fma_f32 v[72:73], v[72:73], v[4:5], v[74:75]
	v_cvt_scalef32_pk_f32_fp4 v[74:75], v76, 1.0 op_sel:[0,1,0]
	v_pk_fma_f32 v[72:73], v[74:75], v[8:9], v[72:73]
	v_cvt_scalef32_pk_f32_fp4 v[74:75], v76, 1.0 op_sel:[1,1,0]
	v_pk_fma_f32 v[72:73], v[74:75], v[10:11], v[72:73]
	v_cvt_scalef32_pk_f32_fp4 v[74:75], v77, 1.0
	v_pk_fma_f32 v[72:73], v[74:75], v[12:13], v[72:73]
	v_cvt_scalef32_pk_f32_fp4 v[74:75], v77, 1.0 op_sel:[1,0,0]
	v_pk_fma_f32 v[72:73], v[74:75], v[14:15], v[72:73]
	v_cvt_scalef32_pk_f32_fp4 v[74:75], v77, 1.0 op_sel:[0,1,0]
	v_pk_fma_f32 v[72:73], v[74:75], v[16:17], v[72:73]
	v_cvt_scalef32_pk_f32_fp4 v[74:75], v77, 1.0 op_sel:[1,1,0]
	v_pk_fma_f32 v[72:73], v[74:75], v[18:19], v[72:73]
	s_waitcnt vmcnt(28)
	v_cvt_scalef32_pk_f32_fp4 v[74:75], v78, 1.0 op_sel:[1,0,0]
	v_add_f32_e32 v76, v72, v73
	v_cvt_scalef32_pk_f32_fp4 v[72:73], v78, 1.0
	v_pk_mul_f32 v[74:75], v[74:75], v[6:7]
	s_nop 0
	v_pk_fma_f32 v[72:73], v[72:73], v[4:5], v[74:75]
	v_cvt_scalef32_pk_f32_fp4 v[74:75], v78, 1.0 op_sel:[0,1,0]
	v_pk_fma_f32 v[72:73], v[74:75], v[8:9], v[72:73]
	v_cvt_scalef32_pk_f32_fp4 v[74:75], v78, 1.0 op_sel:[1,1,0]
	v_pk_fma_f32 v[72:73], v[74:75], v[10:11], v[72:73]
	v_cvt_scalef32_pk_f32_fp4 v[74:75], v79, 1.0
	v_pk_fma_f32 v[72:73], v[74:75], v[12:13], v[72:73]
	v_cvt_scalef32_pk_f32_fp4 v[74:75], v79, 1.0 op_sel:[1,0,0]
	v_pk_fma_f32 v[72:73], v[74:75], v[14:15], v[72:73]
	v_cvt_scalef32_pk_f32_fp4 v[74:75], v79, 1.0 op_sel:[0,1,0]
	v_pk_fma_f32 v[72:73], v[74:75], v[16:17], v[72:73]
	v_cvt_scalef32_pk_f32_fp4 v[74:75], v79, 1.0 op_sel:[1,1,0]
	v_pk_fma_f32 v[72:73], v[74:75], v[18:19], v[72:73]
	s_waitcnt vmcnt(27)
	v_cvt_scalef32_pk_f32_fp4 v[74:75], v80, 1.0 op_sel:[1,0,0]
	v_add_f32_e32 v77, v72, v73
	v_cvt_scalef32_pk_f32_fp4 v[72:73], v80, 1.0
	v_pk_mul_f32 v[74:75], v[74:75], v[6:7]
	s_nop 0
	v_pk_fma_f32 v[72:73], v[72:73], v[4:5], v[74:75]
	v_cvt_scalef32_pk_f32_fp4 v[74:75], v80, 1.0 op_sel:[0,1,0]
	v_pk_fma_f32 v[72:73], v[74:75], v[8:9], v[72:73]
	v_cvt_scalef32_pk_f32_fp4 v[74:75], v80, 1.0 op_sel:[1,1,0]
	v_pk_fma_f32 v[72:73], v[74:75], v[10:11], v[72:73]
	v_cvt_scalef32_pk_f32_fp4 v[74:75], v81, 1.0
	v_pk_fma_f32 v[72:73], v[74:75], v[12:13], v[72:73]
	v_cvt_scalef32_pk_f32_fp4 v[74:75], v81, 1.0 op_sel:[1,0,0]
	v_pk_fma_f32 v[72:73], v[74:75], v[14:15], v[72:73]
	v_cvt_scalef32_pk_f32_fp4 v[74:75], v81, 1.0 op_sel:[0,1,0]
	v_pk_fma_f32 v[72:73], v[74:75], v[16:17], v[72:73]
	v_cvt_scalef32_pk_f32_fp4 v[74:75], v81, 1.0 op_sel:[1,1,0]
	v_pk_fma_f32 v[72:73], v[74:75], v[18:19], v[72:73]
	s_waitcnt vmcnt(26)
	v_cvt_scalef32_pk_f32_fp4 v[74:75], v82, 1.0 op_sel:[1,0,0]
	v_add_f32_e32 v78, v72, v73
	v_cvt_scalef32_pk_f32_fp4 v[72:73], v82, 1.0
	v_pk_mul_f32 v[74:75], v[74:75], v[6:7]
	s_nop 0
	v_pk_fma_f32 v[72:73], v[72:73], v[4:5], v[74:75]
	v_cvt_scalef32_pk_f32_fp4 v[74:75], v82, 1.0 op_sel:[0,1,0]
	v_pk_fma_f32 v[72:73], v[74:75], v[8:9], v[72:73]
	v_cvt_scalef32_pk_f32_fp4 v[74:75], v82, 1.0 op_sel:[1,1,0]
	v_pk_fma_f32 v[72:73], v[74:75], v[10:11], v[72:73]
	v_cvt_scalef32_pk_f32_fp4 v[74:75], v83, 1.0
	v_pk_fma_f32 v[72:73], v[74:75], v[12:13], v[72:73]
	v_cvt_scalef32_pk_f32_fp4 v[74:75], v83, 1.0 op_sel:[1,0,0]
	v_pk_fma_f32 v[72:73], v[74:75], v[14:15], v[72:73]
	v_cvt_scalef32_pk_f32_fp4 v[74:75], v83, 1.0 op_sel:[0,1,0]
	v_pk_fma_f32 v[72:73], v[74:75], v[16:17], v[72:73]
	v_cvt_scalef32_pk_f32_fp4 v[74:75], v83, 1.0 op_sel:[1,1,0]
	v_pk_fma_f32 v[72:73], v[74:75], v[18:19], v[72:73]
	s_waitcnt vmcnt(25)
	v_cvt_scalef32_pk_f32_fp4 v[74:75], v84, 1.0 op_sel:[1,0,0]
	v_add_f32_e32 v79, v72, v73
	v_cvt_scalef32_pk_f32_fp4 v[72:73], v84, 1.0
	v_pk_mul_f32 v[74:75], v[74:75], v[6:7]
	s_nop 0
	v_pk_fma_f32 v[72:73], v[72:73], v[4:5], v[74:75]
	v_cvt_scalef32_pk_f32_fp4 v[74:75], v84, 1.0 op_sel:[0,1,0]
	v_pk_fma_f32 v[72:73], v[74:75], v[8:9], v[72:73]
	v_cvt_scalef32_pk_f32_fp4 v[74:75], v84, 1.0 op_sel:[1,1,0]
	v_pk_fma_f32 v[72:73], v[74:75], v[10:11], v[72:73]
	v_cvt_scalef32_pk_f32_fp4 v[74:75], v85, 1.0
	v_pk_fma_f32 v[72:73], v[74:75], v[12:13], v[72:73]
	v_cvt_scalef32_pk_f32_fp4 v[74:75], v85, 1.0 op_sel:[1,0,0]
	v_pk_fma_f32 v[72:73], v[74:75], v[14:15], v[72:73]
	v_cvt_scalef32_pk_f32_fp4 v[74:75], v85, 1.0 op_sel:[0,1,0]
	v_pk_fma_f32 v[72:73], v[74:75], v[16:17], v[72:73]
	v_cvt_scalef32_pk_f32_fp4 v[74:75], v85, 1.0 op_sel:[1,1,0]
	v_pk_fma_f32 v[72:73], v[74:75], v[18:19], v[72:73]
	s_waitcnt vmcnt(24)
	v_cvt_scalef32_pk_f32_fp4 v[74:75], v86, 1.0 op_sel:[1,0,0]
	v_add_f32_e32 v80, v72, v73
	v_cvt_scalef32_pk_f32_fp4 v[72:73], v86, 1.0
	v_pk_mul_f32 v[74:75], v[74:75], v[6:7]
	s_nop 0
	v_pk_fma_f32 v[72:73], v[72:73], v[4:5], v[74:75]
	v_cvt_scalef32_pk_f32_fp4 v[74:75], v86, 1.0 op_sel:[0,1,0]
	v_pk_fma_f32 v[72:73], v[74:75], v[8:9], v[72:73]
	v_cvt_scalef32_pk_f32_fp4 v[74:75], v86, 1.0 op_sel:[1,1,0]
	v_pk_fma_f32 v[72:73], v[74:75], v[10:11], v[72:73]
	v_cvt_scalef32_pk_f32_fp4 v[74:75], v87, 1.0
	v_pk_fma_f32 v[72:73], v[74:75], v[12:13], v[72:73]
	v_cvt_scalef32_pk_f32_fp4 v[74:75], v87, 1.0 op_sel:[1,0,0]
	v_pk_fma_f32 v[72:73], v[74:75], v[14:15], v[72:73]
	v_cvt_scalef32_pk_f32_fp4 v[74:75], v87, 1.0 op_sel:[0,1,0]
	v_pk_fma_f32 v[72:73], v[74:75], v[16:17], v[72:73]
	v_cvt_scalef32_pk_f32_fp4 v[74:75], v87, 1.0 op_sel:[1,1,0]
	v_pk_fma_f32 v[72:73], v[74:75], v[18:19], v[72:73]
	s_waitcnt vmcnt(23)
	v_cvt_scalef32_pk_f32_fp4 v[74:75], v88, 1.0 op_sel:[1,0,0]
	v_add_f32_e32 v81, v72, v73
	v_cvt_scalef32_pk_f32_fp4 v[72:73], v88, 1.0
	v_pk_mul_f32 v[74:75], v[74:75], v[6:7]
	s_nop 0
	v_pk_fma_f32 v[72:73], v[72:73], v[4:5], v[74:75]
	v_cvt_scalef32_pk_f32_fp4 v[74:75], v88, 1.0 op_sel:[0,1,0]
	v_pk_fma_f32 v[72:73], v[74:75], v[8:9], v[72:73]
	v_cvt_scalef32_pk_f32_fp4 v[74:75], v88, 1.0 op_sel:[1,1,0]
	v_pk_fma_f32 v[72:73], v[74:75], v[10:11], v[72:73]
	v_cvt_scalef32_pk_f32_fp4 v[74:75], v89, 1.0
	v_pk_fma_f32 v[72:73], v[74:75], v[12:13], v[72:73]
	v_cvt_scalef32_pk_f32_fp4 v[74:75], v89, 1.0 op_sel:[1,0,0]
	v_pk_fma_f32 v[72:73], v[74:75], v[14:15], v[72:73]
	v_cvt_scalef32_pk_f32_fp4 v[74:75], v89, 1.0 op_sel:[0,1,0]
	v_pk_fma_f32 v[72:73], v[74:75], v[16:17], v[72:73]
	v_cvt_scalef32_pk_f32_fp4 v[74:75], v89, 1.0 op_sel:[1,1,0]
	v_pk_fma_f32 v[72:73], v[74:75], v[18:19], v[72:73]
	s_waitcnt vmcnt(22)
	v_cvt_scalef32_pk_f32_fp4 v[74:75], v90, 1.0 op_sel:[1,0,0]
	v_add_f32_e32 v82, v72, v73
	v_cvt_scalef32_pk_f32_fp4 v[72:73], v90, 1.0
	v_pk_mul_f32 v[74:75], v[74:75], v[6:7]
	s_nop 0
	v_pk_fma_f32 v[72:73], v[72:73], v[4:5], v[74:75]
	v_cvt_scalef32_pk_f32_fp4 v[74:75], v90, 1.0 op_sel:[0,1,0]
	v_pk_fma_f32 v[72:73], v[74:75], v[8:9], v[72:73]
	v_cvt_scalef32_pk_f32_fp4 v[74:75], v90, 1.0 op_sel:[1,1,0]
	v_pk_fma_f32 v[72:73], v[74:75], v[10:11], v[72:73]
	v_cvt_scalef32_pk_f32_fp4 v[74:75], v91, 1.0
	v_pk_fma_f32 v[72:73], v[74:75], v[12:13], v[72:73]
	v_cvt_scalef32_pk_f32_fp4 v[74:75], v91, 1.0 op_sel:[1,0,0]
	v_pk_fma_f32 v[72:73], v[74:75], v[14:15], v[72:73]
	v_cvt_scalef32_pk_f32_fp4 v[74:75], v91, 1.0 op_sel:[0,1,0]
	v_pk_fma_f32 v[72:73], v[74:75], v[16:17], v[72:73]
	v_cvt_scalef32_pk_f32_fp4 v[74:75], v91, 1.0 op_sel:[1,1,0]
	v_pk_fma_f32 v[72:73], v[74:75], v[18:19], v[72:73]
	s_waitcnt vmcnt(21)
	v_cvt_scalef32_pk_f32_fp4 v[74:75], v92, 1.0 op_sel:[1,0,0]
	v_add_f32_e32 v83, v72, v73
	v_cvt_scalef32_pk_f32_fp4 v[72:73], v92, 1.0
	v_pk_mul_f32 v[74:75], v[74:75], v[6:7]
	s_nop 0
	v_pk_fma_f32 v[72:73], v[72:73], v[4:5], v[74:75]
	v_cvt_scalef32_pk_f32_fp4 v[74:75], v92, 1.0 op_sel:[0,1,0]
	v_pk_fma_f32 v[72:73], v[74:75], v[8:9], v[72:73]
	v_cvt_scalef32_pk_f32_fp4 v[74:75], v92, 1.0 op_sel:[1,1,0]
	v_pk_fma_f32 v[72:73], v[74:75], v[10:11], v[72:73]
	v_cvt_scalef32_pk_f32_fp4 v[74:75], v93, 1.0
	v_pk_fma_f32 v[72:73], v[74:75], v[12:13], v[72:73]
	v_cvt_scalef32_pk_f32_fp4 v[74:75], v93, 1.0 op_sel:[1,0,0]
	v_pk_fma_f32 v[72:73], v[74:75], v[14:15], v[72:73]
	v_cvt_scalef32_pk_f32_fp4 v[74:75], v93, 1.0 op_sel:[0,1,0]
	v_pk_fma_f32 v[72:73], v[74:75], v[16:17], v[72:73]
	v_cvt_scalef32_pk_f32_fp4 v[74:75], v93, 1.0 op_sel:[1,1,0]
	v_pk_fma_f32 v[72:73], v[74:75], v[18:19], v[72:73]
	s_waitcnt vmcnt(20)
	v_cvt_scalef32_pk_f32_fp4 v[74:75], v94, 1.0 op_sel:[1,0,0]
	v_add_f32_e32 v84, v72, v73
	v_cvt_scalef32_pk_f32_fp4 v[72:73], v94, 1.0
	v_pk_mul_f32 v[74:75], v[74:75], v[6:7]
	s_nop 0
	v_pk_fma_f32 v[72:73], v[72:73], v[4:5], v[74:75]
	v_cvt_scalef32_pk_f32_fp4 v[74:75], v94, 1.0 op_sel:[0,1,0]
	v_pk_fma_f32 v[72:73], v[74:75], v[8:9], v[72:73]
	v_cvt_scalef32_pk_f32_fp4 v[74:75], v94, 1.0 op_sel:[1,1,0]
	v_pk_fma_f32 v[72:73], v[74:75], v[10:11], v[72:73]
	v_cvt_scalef32_pk_f32_fp4 v[74:75], v95, 1.0
	v_pk_fma_f32 v[72:73], v[74:75], v[12:13], v[72:73]
	v_cvt_scalef32_pk_f32_fp4 v[74:75], v95, 1.0 op_sel:[1,0,0]
	v_pk_fma_f32 v[72:73], v[74:75], v[14:15], v[72:73]
	v_cvt_scalef32_pk_f32_fp4 v[74:75], v95, 1.0 op_sel:[0,1,0]
	v_pk_fma_f32 v[72:73], v[74:75], v[16:17], v[72:73]
	v_cvt_scalef32_pk_f32_fp4 v[74:75], v95, 1.0 op_sel:[1,1,0]
	v_pk_fma_f32 v[72:73], v[74:75], v[18:19], v[72:73]
	s_waitcnt vmcnt(19)
	v_cvt_scalef32_pk_f32_fp4 v[74:75], v96, 1.0 op_sel:[1,0,0]
	v_add_f32_e32 v85, v72, v73
	v_cvt_scalef32_pk_f32_fp4 v[72:73], v96, 1.0
	v_pk_mul_f32 v[74:75], v[74:75], v[6:7]
	s_nop 0
	v_pk_fma_f32 v[72:73], v[72:73], v[4:5], v[74:75]
	v_cvt_scalef32_pk_f32_fp4 v[74:75], v96, 1.0 op_sel:[0,1,0]
	v_pk_fma_f32 v[72:73], v[74:75], v[8:9], v[72:73]
	v_cvt_scalef32_pk_f32_fp4 v[74:75], v96, 1.0 op_sel:[1,1,0]
	v_pk_fma_f32 v[72:73], v[74:75], v[10:11], v[72:73]
	v_cvt_scalef32_pk_f32_fp4 v[74:75], v97, 1.0
	v_pk_fma_f32 v[72:73], v[74:75], v[12:13], v[72:73]
	v_cvt_scalef32_pk_f32_fp4 v[74:75], v97, 1.0 op_sel:[1,0,0]
	v_pk_fma_f32 v[72:73], v[74:75], v[14:15], v[72:73]
	v_cvt_scalef32_pk_f32_fp4 v[74:75], v97, 1.0 op_sel:[0,1,0]
	v_pk_fma_f32 v[72:73], v[74:75], v[16:17], v[72:73]
	v_cvt_scalef32_pk_f32_fp4 v[74:75], v97, 1.0 op_sel:[1,1,0]
	v_pk_fma_f32 v[72:73], v[74:75], v[18:19], v[72:73]
	s_waitcnt vmcnt(18)
	v_cvt_scalef32_pk_f32_fp4 v[74:75], v98, 1.0 op_sel:[1,0,0]
	v_add_f32_e32 v86, v72, v73
	v_cvt_scalef32_pk_f32_fp4 v[72:73], v98, 1.0
	v_pk_mul_f32 v[74:75], v[74:75], v[6:7]
	s_nop 0
	v_pk_fma_f32 v[72:73], v[72:73], v[4:5], v[74:75]
	v_cvt_scalef32_pk_f32_fp4 v[74:75], v98, 1.0 op_sel:[0,1,0]
	v_pk_fma_f32 v[72:73], v[74:75], v[8:9], v[72:73]
	v_cvt_scalef32_pk_f32_fp4 v[74:75], v98, 1.0 op_sel:[1,1,0]
	v_pk_fma_f32 v[72:73], v[74:75], v[10:11], v[72:73]
	v_cvt_scalef32_pk_f32_fp4 v[74:75], v99, 1.0
	v_pk_fma_f32 v[72:73], v[74:75], v[12:13], v[72:73]
	v_cvt_scalef32_pk_f32_fp4 v[74:75], v99, 1.0 op_sel:[1,0,0]
	v_pk_fma_f32 v[72:73], v[74:75], v[14:15], v[72:73]
	v_cvt_scalef32_pk_f32_fp4 v[74:75], v99, 1.0 op_sel:[0,1,0]
	v_pk_fma_f32 v[72:73], v[74:75], v[16:17], v[72:73]
	v_cvt_scalef32_pk_f32_fp4 v[74:75], v99, 1.0 op_sel:[1,1,0]
	v_pk_fma_f32 v[72:73], v[74:75], v[18:19], v[72:73]
	s_waitcnt vmcnt(17)
	v_cvt_scalef32_pk_f32_fp4 v[74:75], v100, 1.0 op_sel:[1,0,0]
	v_add_f32_e32 v87, v72, v73
	v_cvt_scalef32_pk_f32_fp4 v[72:73], v100, 1.0
	v_pk_mul_f32 v[74:75], v[74:75], v[6:7]
	s_nop 0
	v_pk_fma_f32 v[72:73], v[72:73], v[4:5], v[74:75]
	v_cvt_scalef32_pk_f32_fp4 v[74:75], v100, 1.0 op_sel:[0,1,0]
	v_pk_fma_f32 v[72:73], v[74:75], v[8:9], v[72:73]
	v_cvt_scalef32_pk_f32_fp4 v[74:75], v100, 1.0 op_sel:[1,1,0]
	v_pk_fma_f32 v[72:73], v[74:75], v[10:11], v[72:73]
	v_cvt_scalef32_pk_f32_fp4 v[74:75], v101, 1.0
	v_pk_fma_f32 v[72:73], v[74:75], v[12:13], v[72:73]
	v_cvt_scalef32_pk_f32_fp4 v[74:75], v101, 1.0 op_sel:[1,0,0]
	v_pk_fma_f32 v[72:73], v[74:75], v[14:15], v[72:73]
	v_cvt_scalef32_pk_f32_fp4 v[74:75], v101, 1.0 op_sel:[0,1,0]
	v_pk_fma_f32 v[72:73], v[74:75], v[16:17], v[72:73]
	v_cvt_scalef32_pk_f32_fp4 v[74:75], v101, 1.0 op_sel:[1,1,0]
	v_pk_fma_f32 v[72:73], v[74:75], v[18:19], v[72:73]
	s_waitcnt vmcnt(16)
	v_cvt_scalef32_pk_f32_fp4 v[74:75], v102, 1.0 op_sel:[1,0,0]
	v_add_f32_e32 v88, v72, v73
	v_cvt_scalef32_pk_f32_fp4 v[72:73], v102, 1.0
	v_pk_mul_f32 v[74:75], v[74:75], v[6:7]
	s_nop 0
	v_pk_fma_f32 v[72:73], v[72:73], v[4:5], v[74:75]
	v_cvt_scalef32_pk_f32_fp4 v[74:75], v102, 1.0 op_sel:[0,1,0]
	v_pk_fma_f32 v[72:73], v[74:75], v[8:9], v[72:73]
	v_cvt_scalef32_pk_f32_fp4 v[74:75], v102, 1.0 op_sel:[1,1,0]
	v_pk_fma_f32 v[72:73], v[74:75], v[10:11], v[72:73]
	v_cvt_scalef32_pk_f32_fp4 v[74:75], v103, 1.0
	v_pk_fma_f32 v[72:73], v[74:75], v[12:13], v[72:73]
	v_cvt_scalef32_pk_f32_fp4 v[74:75], v103, 1.0 op_sel:[1,0,0]
	v_pk_fma_f32 v[72:73], v[74:75], v[14:15], v[72:73]
	v_cvt_scalef32_pk_f32_fp4 v[74:75], v103, 1.0 op_sel:[0,1,0]
	v_pk_fma_f32 v[72:73], v[74:75], v[16:17], v[72:73]
	v_cvt_scalef32_pk_f32_fp4 v[74:75], v103, 1.0 op_sel:[1,1,0]
	v_pk_fma_f32 v[72:73], v[74:75], v[18:19], v[72:73]
	v_cndmask_b32_e64 v74, v132, v82, s[0:1]
	v_add_f32_e32 v72, v72, v73
	v_cndmask_b32_e64 v73, v82, v132, s[0:1]
	v_cndmask_b32_e64 v75, v130, v83, s[0:1]
	s_nop 0
	v_add_f32_dpp v73, v74, v73 quad_perm:[1,0,3,2] row_mask:0xf bank_mask:0xf bound_ctrl:1
	v_cndmask_b32_e64 v74, v83, v130, s[0:1]
	v_add_u32_e32 v127, 32, v127
	s_nop 0
	v_add_f32_dpp v74, v75, v74 quad_perm:[1,0,3,2] row_mask:0xf bank_mask:0xf bound_ctrl:1
	v_cndmask_b32_e64 v75, v84, v76, s[0:1]
	v_cndmask_b32_e64 v76, v76, v84, s[0:1]
	s_nop 1
	v_add_f32_dpp v75, v76, v75 quad_perm:[1,0,3,2] row_mask:0xf bank_mask:0xf bound_ctrl:1
	v_cndmask_b32_e64 v76, v85, v77, s[0:1]
	v_cndmask_b32_e64 v77, v77, v85, s[0:1]
	s_nop 1
	v_add_f32_dpp v76, v77, v76 quad_perm:[1,0,3,2] row_mask:0xf bank_mask:0xf bound_ctrl:1
	v_cndmask_b32_e64 v77, v86, v78, s[0:1]
	v_cndmask_b32_e64 v78, v78, v86, s[0:1]
	s_nop 1
	v_add_f32_dpp v77, v78, v77 quad_perm:[1,0,3,2] row_mask:0xf bank_mask:0xf bound_ctrl:1
	v_cndmask_b32_e64 v78, v87, v79, s[0:1]
	v_cndmask_b32_e64 v79, v79, v87, s[0:1]
	s_nop 0
	s_nop 0
	v_add_f32_dpp v78, v79, v78 quad_perm:[1,0,3,2] row_mask:0xf bank_mask:0xf bound_ctrl:1
	v_cndmask_b32_e64 v79, v88, v80, s[0:1]
	v_cndmask_b32_e64 v80, v80, v88, s[0:1]
	s_nop 1
	v_add_f32_dpp v79, v80, v79 quad_perm:[1,0,3,2] row_mask:0xf bank_mask:0xf bound_ctrl:1
	v_cndmask_b32_e64 v80, v72, v81, s[0:1]
	v_cndmask_b32_e64 v72, v81, v72, s[0:1]
	s_nop 1
	v_add_f32_dpp v72, v72, v80 quad_perm:[1,0,3,2] row_mask:0xf bank_mask:0xf bound_ctrl:1
	v_cndmask_b32_e64 v80, v77, v73, s[4:5]
	v_cndmask_b32_e64 v73, v73, v77, s[4:5]
	v_cndmask_b32_e64 v77, v78, v74, s[4:5]
	v_cndmask_b32_e64 v74, v74, v78, s[4:5]
	v_add_f32_dpp v73, v73, v80 quad_perm:[2,3,0,1] row_mask:0xf bank_mask:0xf bound_ctrl:1
	s_nop 0
	v_add_f32_dpp v74, v74, v77 quad_perm:[2,3,0,1] row_mask:0xf bank_mask:0xf bound_ctrl:1
	v_cndmask_b32_e64 v77, v79, v75, s[4:5]
	v_cndmask_b32_e64 v75, v75, v79, s[4:5]
	s_nop 0
	s_nop 0
	v_add_f32_dpp v75, v75, v77 quad_perm:[2,3,0,1] row_mask:0xf bank_mask:0xf bound_ctrl:1
	v_cndmask_b32_e64 v77, v72, v76, s[4:5]
	v_cndmask_b32_e64 v72, v76, v72, s[4:5]
	v_cndmask_b32_e64 v76, v75, v73, s[6:7]
	v_cndmask_b32_e64 v73, v73, v75, s[6:7]
	v_add_f32_dpp v72, v72, v77 quad_perm:[2,3,0,1] row_mask:0xf bank_mask:0xf bound_ctrl:1
	v_cndmask_b32_e64 v75, v72, v74, s[6:7]
	v_cndmask_b32_e64 v72, v74, v72, s[6:7]
	v_mov_b32_dpp v73, v73 row_half_mirror row_mask:0xf bank_mask:0xf bound_ctrl:1
	s_nop 0
	v_mov_b32_dpp v72, v72 row_half_mirror row_mask:0xf bank_mask:0xf bound_ctrl:1
	v_add_f32_dpp v73, v73, v76 quad_perm:[3,2,1,0] row_mask:0xf bank_mask:0xf bound_ctrl:1
	s_nop 0
	v_add_f32_dpp v72, v72, v75 quad_perm:[3,2,1,0] row_mask:0xf bank_mask:0xf bound_ctrl:1
	v_cndmask_b32_e64 v74, v72, v73, s[8:9]
	v_cndmask_b32_e64 v72, v73, v72, s[8:9]
	s_nop 1
	v_mov_b32_dpp v72, v72 row_mirror row_mask:0xf bank_mask:0xf bound_ctrl:1
	v_and_b32_e32 v76, 2, v124
	s_nop 0
	v_add_f32_dpp v72, v72, v74 row_half_mirror row_mask:0xf bank_mask:0xf bound_ctrl:1
	ds_bpermute_b32 v73, v125, v72
	v_cmp_eq_u32_e64 s[14:15], v106, v76
	s_waitcnt lgkmcnt(0)
	v_add_f32_e32 v72, v72, v73
	ds_bpermute_b32 v73, v126, v72
	s_waitcnt vmcnt(15)
	v_cvt_scalef32_pk_f32_fp4 v[74:75], v20, 1.0 op_sel:[1,0,0]
	v_pk_mul_f32 v[74:75], v[74:75], v[6:7]
	s_waitcnt lgkmcnt(0)
	v_add_f32_e32 v72, v72, v73
	v_cndmask_b32_e64 v73, v72, v128, s[12:13]
	v_cndmask_b32_e64 v77, v128, v73, s[14:15]
	s_and_b64 s[14:15], s[14:15], s[12:13]
	v_cndmask_b32_e64 v78, v129, v72, s[14:15]
	v_cvt_scalef32_pk_f32_fp4 v[72:73], v20, 1.0
	v_pk_fma_f32 v[72:73], v[72:73], v[4:5], v[74:75]
	v_cvt_scalef32_pk_f32_fp4 v[74:75], v20, 1.0 op_sel:[0,1,0]
	v_pk_fma_f32 v[72:73], v[74:75], v[8:9], v[72:73]
	v_cvt_scalef32_pk_f32_fp4 v[74:75], v20, 1.0 op_sel:[1,1,0]
	v_pk_fma_f32 v[72:73], v[74:75], v[10:11], v[72:73]
	v_cvt_scalef32_pk_f32_fp4 v[74:75], v21, 1.0
	v_pk_fma_f32 v[72:73], v[74:75], v[12:13], v[72:73]
	v_cvt_scalef32_pk_f32_fp4 v[74:75], v21, 1.0 op_sel:[1,0,0]
	v_pk_fma_f32 v[72:73], v[74:75], v[14:15], v[72:73]
	v_cvt_scalef32_pk_f32_fp4 v[74:75], v21, 1.0 op_sel:[0,1,0]
	v_pk_fma_f32 v[72:73], v[74:75], v[16:17], v[72:73]
	v_cvt_scalef32_pk_f32_fp4 v[20:21], v21, 1.0 op_sel:[1,1,0]
	v_pk_fma_f32 v[20:21], v[20:21], v[18:19], v[72:73]
	s_waitcnt vmcnt(14)
	v_cvt_scalef32_pk_f32_fp4 v[72:73], v22, 1.0 op_sel:[1,0,0]
	v_add_f32_e32 v74, v20, v21
	v_cvt_scalef32_pk_f32_fp4 v[20:21], v22, 1.0
	v_pk_mul_f32 v[72:73], v[72:73], v[6:7]
	s_nop 0
	v_pk_fma_f32 v[20:21], v[20:21], v[4:5], v[72:73]
	v_cvt_scalef32_pk_f32_fp4 v[72:73], v22, 1.0 op_sel:[0,1,0]
	v_pk_fma_f32 v[20:21], v[72:73], v[8:9], v[20:21]
	v_cvt_scalef32_pk_f32_fp4 v[72:73], v22, 1.0 op_sel:[1,1,0]
	v_pk_fma_f32 v[20:21], v[72:73], v[10:11], v[20:21]
	v_cvt_scalef32_pk_f32_fp4 v[72:73], v23, 1.0
	v_pk_fma_f32 v[20:21], v[72:73], v[12:13], v[20:21]
	v_cvt_scalef32_pk_f32_fp4 v[72:73], v23, 1.0 op_sel:[1,0,0]
	v_pk_fma_f32 v[20:21], v[72:73], v[14:15], v[20:21]
	v_cvt_scalef32_pk_f32_fp4 v[72:73], v23, 1.0 op_sel:[0,1,0]
	v_pk_fma_f32 v[20:21], v[72:73], v[16:17], v[20:21]
	v_cvt_scalef32_pk_f32_fp4 v[22:23], v23, 1.0 op_sel:[1,1,0]
	v_pk_fma_f32 v[20:21], v[22:23], v[18:19], v[20:21]
	s_waitcnt vmcnt(13)
	v_cvt_scalef32_pk_f32_fp4 v[22:23], v24, 1.0 op_sel:[1,0,0]
	v_add_f32_e32 v72, v20, v21
	v_cvt_scalef32_pk_f32_fp4 v[20:21], v24, 1.0
	v_pk_mul_f32 v[22:23], v[22:23], v[6:7]
	s_nop 0
	v_pk_fma_f32 v[20:21], v[20:21], v[4:5], v[22:23]
	v_cvt_scalef32_pk_f32_fp4 v[22:23], v24, 1.0 op_sel:[0,1,0]
	v_pk_fma_f32 v[20:21], v[22:23], v[8:9], v[20:21]
	v_cvt_scalef32_pk_f32_fp4 v[22:23], v24, 1.0 op_sel:[1,1,0]
	v_pk_fma_f32 v[20:21], v[22:23], v[10:11], v[20:21]
	v_cvt_scalef32_pk_f32_fp4 v[22:23], v25, 1.0
	v_pk_fma_f32 v[20:21], v[22:23], v[12:13], v[20:21]
	v_cvt_scalef32_pk_f32_fp4 v[22:23], v25, 1.0 op_sel:[1,0,0]
	v_pk_fma_f32 v[20:21], v[22:23], v[14:15], v[20:21]
	v_cvt_scalef32_pk_f32_fp4 v[22:23], v25, 1.0 op_sel:[0,1,0]
	v_pk_fma_f32 v[20:21], v[22:23], v[16:17], v[20:21]
	v_cvt_scalef32_pk_f32_fp4 v[22:23], v25, 1.0 op_sel:[1,1,0]
	v_pk_fma_f32 v[20:21], v[22:23], v[18:19], v[20:21]
	s_waitcnt vmcnt(12)
	v_cvt_scalef32_pk_f32_fp4 v[22:23], v26, 1.0 op_sel:[1,0,0]
	v_add_f32_e32 v24, v20, v21
	v_cvt_scalef32_pk_f32_fp4 v[20:21], v26, 1.0
	v_pk_mul_f32 v[22:23], v[22:23], v[6:7]
	s_nop 0
	v_pk_fma_f32 v[20:21], v[20:21], v[4:5], v[22:23]
	v_cvt_scalef32_pk_f32_fp4 v[22:23], v26, 1.0 op_sel:[0,1,0]
	v_pk_fma_f32 v[20:21], v[22:23], v[8:9], v[20:21]
	v_cvt_scalef32_pk_f32_fp4 v[22:23], v26, 1.0 op_sel:[1,1,0]
	v_pk_fma_f32 v[20:21], v[22:23], v[10:11], v[20:21]
	v_cvt_scalef32_pk_f32_fp4 v[22:23], v27, 1.0
	v_pk_fma_f32 v[20:21], v[22:23], v[12:13], v[20:21]
	v_cvt_scalef32_pk_f32_fp4 v[22:23], v27, 1.0 op_sel:[1,0,0]
	v_pk_fma_f32 v[20:21], v[22:23], v[14:15], v[20:21]
	v_cvt_scalef32_pk_f32_fp4 v[22:23], v27, 1.0 op_sel:[0,1,0]
	v_pk_fma_f32 v[20:21], v[22:23], v[16:17], v[20:21]
	v_cvt_scalef32_pk_f32_fp4 v[22:23], v27, 1.0 op_sel:[1,1,0]
	v_pk_fma_f32 v[20:21], v[22:23], v[18:19], v[20:21]
	s_waitcnt vmcnt(11)
	v_cvt_scalef32_pk_f32_fp4 v[22:23], v28, 1.0 op_sel:[1,0,0]
	v_add_f32_e32 v25, v20, v21
	v_cvt_scalef32_pk_f32_fp4 v[20:21], v28, 1.0
	v_pk_mul_f32 v[22:23], v[22:23], v[6:7]
	s_nop 0
	v_pk_fma_f32 v[20:21], v[20:21], v[4:5], v[22:23]
	v_cvt_scalef32_pk_f32_fp4 v[22:23], v28, 1.0 op_sel:[0,1,0]
	v_pk_fma_f32 v[20:21], v[22:23], v[8:9], v[20:21]
	v_cvt_scalef32_pk_f32_fp4 v[22:23], v28, 1.0 op_sel:[1,1,0]
	v_pk_fma_f32 v[20:21], v[22:23], v[10:11], v[20:21]
	v_cvt_scalef32_pk_f32_fp4 v[22:23], v29, 1.0
	v_pk_fma_f32 v[20:21], v[22:23], v[12:13], v[20:21]
	v_cvt_scalef32_pk_f32_fp4 v[22:23], v29, 1.0 op_sel:[1,0,0]
	v_pk_fma_f32 v[20:21], v[22:23], v[14:15], v[20:21]
	v_cvt_scalef32_pk_f32_fp4 v[22:23], v29, 1.0 op_sel:[0,1,0]
	v_pk_fma_f32 v[20:21], v[22:23], v[16:17], v[20:21]
	v_cvt_scalef32_pk_f32_fp4 v[22:23], v29, 1.0 op_sel:[1,1,0]
	v_pk_fma_f32 v[20:21], v[22:23], v[18:19], v[20:21]
	s_waitcnt vmcnt(10)
	v_cvt_scalef32_pk_f32_fp4 v[22:23], v30, 1.0 op_sel:[1,0,0]
	v_add_f32_e32 v26, v20, v21
	v_cvt_scalef32_pk_f32_fp4 v[20:21], v30, 1.0
	v_pk_mul_f32 v[22:23], v[22:23], v[6:7]
	v_add_u32_e32 v124, 2, v124
	v_pk_fma_f32 v[20:21], v[20:21], v[4:5], v[22:23]
	v_cvt_scalef32_pk_f32_fp4 v[22:23], v30, 1.0 op_sel:[0,1,0]
	v_pk_fma_f32 v[20:21], v[22:23], v[8:9], v[20:21]
	v_cvt_scalef32_pk_f32_fp4 v[22:23], v30, 1.0 op_sel:[1,1,0]
	v_pk_fma_f32 v[20:21], v[22:23], v[10:11], v[20:21]
	v_cvt_scalef32_pk_f32_fp4 v[22:23], v31, 1.0
	v_pk_fma_f32 v[20:21], v[22:23], v[12:13], v[20:21]
	v_cvt_scalef32_pk_f32_fp4 v[22:23], v31, 1.0 op_sel:[1,0,0]
	v_pk_fma_f32 v[20:21], v[22:23], v[14:15], v[20:21]
	v_cvt_scalef32_pk_f32_fp4 v[22:23], v31, 1.0 op_sel:[0,1,0]
	v_pk_fma_f32 v[20:21], v[22:23], v[16:17], v[20:21]
	v_cvt_scalef32_pk_f32_fp4 v[22:23], v31, 1.0 op_sel:[1,1,0]
	v_pk_fma_f32 v[20:21], v[22:23], v[18:19], v[20:21]
	s_waitcnt vmcnt(9)
	v_cvt_scalef32_pk_f32_fp4 v[22:23], v32, 1.0 op_sel:[1,0,0]
	v_add_f32_e32 v27, v20, v21
	v_cvt_scalef32_pk_f32_fp4 v[20:21], v32, 1.0
	v_pk_mul_f32 v[22:23], v[22:23], v[6:7]
	s_nop 0
	v_pk_fma_f32 v[20:21], v[20:21], v[4:5], v[22:23]
	v_cvt_scalef32_pk_f32_fp4 v[22:23], v32, 1.0 op_sel:[0,1,0]
	v_pk_fma_f32 v[20:21], v[22:23], v[8:9], v[20:21]
	v_cvt_scalef32_pk_f32_fp4 v[22:23], v32, 1.0 op_sel:[1,1,0]
	v_pk_fma_f32 v[20:21], v[22:23], v[10:11], v[20:21]
	v_cvt_scalef32_pk_f32_fp4 v[22:23], v33, 1.0
	v_pk_fma_f32 v[20:21], v[22:23], v[12:13], v[20:21]
	v_cvt_scalef32_pk_f32_fp4 v[22:23], v33, 1.0 op_sel:[1,0,0]
	v_pk_fma_f32 v[20:21], v[22:23], v[14:15], v[20:21]
	v_cvt_scalef32_pk_f32_fp4 v[22:23], v33, 1.0 op_sel:[0,1,0]
	v_pk_fma_f32 v[20:21], v[22:23], v[16:17], v[20:21]
	v_cvt_scalef32_pk_f32_fp4 v[22:23], v33, 1.0 op_sel:[1,1,0]
	v_pk_fma_f32 v[20:21], v[22:23], v[18:19], v[20:21]
	s_waitcnt vmcnt(8)
	v_cvt_scalef32_pk_f32_fp4 v[22:23], v34, 1.0 op_sel:[1,0,0]
	v_add_f32_e32 v28, v20, v21
	v_cvt_scalef32_pk_f32_fp4 v[20:21], v34, 1.0
	v_pk_mul_f32 v[22:23], v[22:23], v[6:7]
	s_nop 0
	v_pk_fma_f32 v[20:21], v[20:21], v[4:5], v[22:23]
	v_cvt_scalef32_pk_f32_fp4 v[22:23], v34, 1.0 op_sel:[0,1,0]
	v_pk_fma_f32 v[20:21], v[22:23], v[8:9], v[20:21]
	v_cvt_scalef32_pk_f32_fp4 v[22:23], v34, 1.0 op_sel:[1,1,0]
	v_pk_fma_f32 v[20:21], v[22:23], v[10:11], v[20:21]
	v_cvt_scalef32_pk_f32_fp4 v[22:23], v35, 1.0
	v_pk_fma_f32 v[20:21], v[22:23], v[12:13], v[20:21]
	v_cvt_scalef32_pk_f32_fp4 v[22:23], v35, 1.0 op_sel:[1,0,0]
	v_pk_fma_f32 v[20:21], v[22:23], v[14:15], v[20:21]
	v_cvt_scalef32_pk_f32_fp4 v[22:23], v35, 1.0 op_sel:[0,1,0]
	v_pk_fma_f32 v[20:21], v[22:23], v[16:17], v[20:21]
	v_cvt_scalef32_pk_f32_fp4 v[22:23], v35, 1.0 op_sel:[1,1,0]
	v_pk_fma_f32 v[20:21], v[22:23], v[18:19], v[20:21]
	s_waitcnt vmcnt(7)
	v_cvt_scalef32_pk_f32_fp4 v[22:23], v56, 1.0 op_sel:[1,0,0]
	v_add_f32_e32 v29, v20, v21
	v_cvt_scalef32_pk_f32_fp4 v[20:21], v56, 1.0
	v_pk_mul_f32 v[22:23], v[22:23], v[6:7]
	s_nop 0
	v_pk_fma_f32 v[20:21], v[20:21], v[4:5], v[22:23]
	v_cvt_scalef32_pk_f32_fp4 v[22:23], v56, 1.0 op_sel:[0,1,0]
	v_pk_fma_f32 v[20:21], v[22:23], v[8:9], v[20:21]
	v_cvt_scalef32_pk_f32_fp4 v[22:23], v56, 1.0 op_sel:[1,1,0]
	v_pk_fma_f32 v[20:21], v[22:23], v[10:11], v[20:21]
	v_cvt_scalef32_pk_f32_fp4 v[22:23], v57, 1.0
	v_pk_fma_f32 v[20:21], v[22:23], v[12:13], v[20:21]
	v_cvt_scalef32_pk_f32_fp4 v[22:23], v57, 1.0 op_sel:[1,0,0]
	v_pk_fma_f32 v[20:21], v[22:23], v[14:15], v[20:21]
	v_cvt_scalef32_pk_f32_fp4 v[22:23], v57, 1.0 op_sel:[0,1,0]
	v_pk_fma_f32 v[20:21], v[22:23], v[16:17], v[20:21]
	v_cvt_scalef32_pk_f32_fp4 v[22:23], v57, 1.0 op_sel:[1,1,0]
	v_pk_fma_f32 v[20:21], v[22:23], v[18:19], v[20:21]
	s_waitcnt vmcnt(6)
	v_cvt_scalef32_pk_f32_fp4 v[22:23], v58, 1.0 op_sel:[1,0,0]
	v_add_f32_e32 v30, v20, v21
	v_cvt_scalef32_pk_f32_fp4 v[20:21], v58, 1.0
	v_pk_mul_f32 v[22:23], v[22:23], v[6:7]
	s_nop 0
	v_pk_fma_f32 v[20:21], v[20:21], v[4:5], v[22:23]
	v_cvt_scalef32_pk_f32_fp4 v[22:23], v58, 1.0 op_sel:[0,1,0]
	v_pk_fma_f32 v[20:21], v[22:23], v[8:9], v[20:21]
	v_cvt_scalef32_pk_f32_fp4 v[22:23], v58, 1.0 op_sel:[1,1,0]
	v_pk_fma_f32 v[20:21], v[22:23], v[10:11], v[20:21]
	v_cvt_scalef32_pk_f32_fp4 v[22:23], v59, 1.0
	v_pk_fma_f32 v[20:21], v[22:23], v[12:13], v[20:21]
	v_cvt_scalef32_pk_f32_fp4 v[22:23], v59, 1.0 op_sel:[1,0,0]
	v_pk_fma_f32 v[20:21], v[22:23], v[14:15], v[20:21]
	v_cvt_scalef32_pk_f32_fp4 v[22:23], v59, 1.0 op_sel:[0,1,0]
	v_pk_fma_f32 v[20:21], v[22:23], v[16:17], v[20:21]
	v_cvt_scalef32_pk_f32_fp4 v[22:23], v59, 1.0 op_sel:[1,1,0]
	v_pk_fma_f32 v[20:21], v[22:23], v[18:19], v[20:21]
	s_waitcnt vmcnt(5)
	v_cvt_scalef32_pk_f32_fp4 v[22:23], v60, 1.0 op_sel:[1,0,0]
	v_add_f32_e32 v31, v20, v21
	v_cvt_scalef32_pk_f32_fp4 v[20:21], v60, 1.0
	v_pk_mul_f32 v[22:23], v[22:23], v[6:7]
	s_nop 0
	v_pk_fma_f32 v[20:21], v[20:21], v[4:5], v[22:23]
	v_cvt_scalef32_pk_f32_fp4 v[22:23], v60, 1.0 op_sel:[0,1,0]
	v_pk_fma_f32 v[20:21], v[22:23], v[8:9], v[20:21]
	v_cvt_scalef32_pk_f32_fp4 v[22:23], v60, 1.0 op_sel:[1,1,0]
	v_pk_fma_f32 v[20:21], v[22:23], v[10:11], v[20:21]
	v_cvt_scalef32_pk_f32_fp4 v[22:23], v61, 1.0
	v_pk_fma_f32 v[20:21], v[22:23], v[12:13], v[20:21]
	v_cvt_scalef32_pk_f32_fp4 v[22:23], v61, 1.0 op_sel:[1,0,0]
	v_pk_fma_f32 v[20:21], v[22:23], v[14:15], v[20:21]
	v_cvt_scalef32_pk_f32_fp4 v[22:23], v61, 1.0 op_sel:[0,1,0]
	v_pk_fma_f32 v[20:21], v[22:23], v[16:17], v[20:21]
	v_cvt_scalef32_pk_f32_fp4 v[22:23], v61, 1.0 op_sel:[1,1,0]
	v_pk_fma_f32 v[20:21], v[22:23], v[18:19], v[20:21]
	s_waitcnt vmcnt(4)
	v_cvt_scalef32_pk_f32_fp4 v[22:23], v62, 1.0 op_sel:[1,0,0]
	v_add_f32_e32 v32, v20, v21
	v_cvt_scalef32_pk_f32_fp4 v[20:21], v62, 1.0
	v_pk_mul_f32 v[22:23], v[22:23], v[6:7]
	s_nop 0
	v_pk_fma_f32 v[20:21], v[20:21], v[4:5], v[22:23]
	v_cvt_scalef32_pk_f32_fp4 v[22:23], v62, 1.0 op_sel:[0,1,0]
	v_pk_fma_f32 v[20:21], v[22:23], v[8:9], v[20:21]
	v_cvt_scalef32_pk_f32_fp4 v[22:23], v62, 1.0 op_sel:[1,1,0]
	v_pk_fma_f32 v[20:21], v[22:23], v[10:11], v[20:21]
	v_cvt_scalef32_pk_f32_fp4 v[22:23], v63, 1.0
	v_pk_fma_f32 v[20:21], v[22:23], v[12:13], v[20:21]
	v_cvt_scalef32_pk_f32_fp4 v[22:23], v63, 1.0 op_sel:[1,0,0]
	v_pk_fma_f32 v[20:21], v[22:23], v[14:15], v[20:21]
	v_cvt_scalef32_pk_f32_fp4 v[22:23], v63, 1.0 op_sel:[0,1,0]
	v_pk_fma_f32 v[20:21], v[22:23], v[16:17], v[20:21]
	v_cvt_scalef32_pk_f32_fp4 v[22:23], v63, 1.0 op_sel:[1,1,0]
	v_pk_fma_f32 v[20:21], v[22:23], v[18:19], v[20:21]
	s_waitcnt vmcnt(3)
	v_cvt_scalef32_pk_f32_fp4 v[22:23], v64, 1.0 op_sel:[1,0,0]
	v_add_f32_e32 v33, v20, v21
	v_cvt_scalef32_pk_f32_fp4 v[20:21], v64, 1.0
	v_pk_mul_f32 v[22:23], v[22:23], v[6:7]
	s_nop 0
	v_pk_fma_f32 v[20:21], v[20:21], v[4:5], v[22:23]
	v_cvt_scalef32_pk_f32_fp4 v[22:23], v64, 1.0 op_sel:[0,1,0]
	v_pk_fma_f32 v[20:21], v[22:23], v[8:9], v[20:21]
	v_cvt_scalef32_pk_f32_fp4 v[22:23], v64, 1.0 op_sel:[1,1,0]
	v_pk_fma_f32 v[20:21], v[22:23], v[10:11], v[20:21]
	v_cvt_scalef32_pk_f32_fp4 v[22:23], v65, 1.0
	v_pk_fma_f32 v[20:21], v[22:23], v[12:13], v[20:21]
	v_cvt_scalef32_pk_f32_fp4 v[22:23], v65, 1.0 op_sel:[1,0,0]
	v_pk_fma_f32 v[20:21], v[22:23], v[14:15], v[20:21]
	v_cvt_scalef32_pk_f32_fp4 v[22:23], v65, 1.0 op_sel:[0,1,0]
	v_pk_fma_f32 v[20:21], v[22:23], v[16:17], v[20:21]
	v_cvt_scalef32_pk_f32_fp4 v[22:23], v65, 1.0 op_sel:[1,1,0]
	v_pk_fma_f32 v[20:21], v[22:23], v[18:19], v[20:21]
	s_waitcnt vmcnt(2)
	v_cvt_scalef32_pk_f32_fp4 v[22:23], v66, 1.0 op_sel:[1,0,0]
	v_add_f32_e32 v34, v20, v21
	v_cvt_scalef32_pk_f32_fp4 v[20:21], v66, 1.0
	v_pk_mul_f32 v[22:23], v[22:23], v[6:7]
	s_nop 0
	v_pk_fma_f32 v[20:21], v[20:21], v[4:5], v[22:23]
	v_cvt_scalef32_pk_f32_fp4 v[22:23], v66, 1.0 op_sel:[0,1,0]
	v_pk_fma_f32 v[20:21], v[22:23], v[8:9], v[20:21]
	v_cvt_scalef32_pk_f32_fp4 v[22:23], v66, 1.0 op_sel:[1,1,0]
	v_pk_fma_f32 v[20:21], v[22:23], v[10:11], v[20:21]
	v_cvt_scalef32_pk_f32_fp4 v[22:23], v67, 1.0
	v_pk_fma_f32 v[20:21], v[22:23], v[12:13], v[20:21]
	v_cvt_scalef32_pk_f32_fp4 v[22:23], v67, 1.0 op_sel:[1,0,0]
	v_pk_fma_f32 v[20:21], v[22:23], v[14:15], v[20:21]
	v_cvt_scalef32_pk_f32_fp4 v[22:23], v67, 1.0 op_sel:[0,1,0]
	v_pk_fma_f32 v[20:21], v[22:23], v[16:17], v[20:21]
	v_cvt_scalef32_pk_f32_fp4 v[22:23], v67, 1.0 op_sel:[1,1,0]
	v_pk_fma_f32 v[20:21], v[22:23], v[18:19], v[20:21]
	s_waitcnt vmcnt(1)
	v_cvt_scalef32_pk_f32_fp4 v[22:23], v68, 1.0 op_sel:[1,0,0]
	v_add_f32_e32 v35, v20, v21
	v_cvt_scalef32_pk_f32_fp4 v[20:21], v68, 1.0
	v_pk_mul_f32 v[22:23], v[22:23], v[6:7]
	s_nop 0
	v_pk_fma_f32 v[20:21], v[20:21], v[4:5], v[22:23]
	v_cvt_scalef32_pk_f32_fp4 v[22:23], v68, 1.0 op_sel:[0,1,0]
	v_pk_fma_f32 v[20:21], v[22:23], v[8:9], v[20:21]
	v_cvt_scalef32_pk_f32_fp4 v[22:23], v68, 1.0 op_sel:[1,1,0]
	v_pk_fma_f32 v[20:21], v[22:23], v[10:11], v[20:21]
	v_cvt_scalef32_pk_f32_fp4 v[22:23], v69, 1.0
	v_pk_fma_f32 v[20:21], v[22:23], v[12:13], v[20:21]
	v_cvt_scalef32_pk_f32_fp4 v[22:23], v69, 1.0 op_sel:[1,0,0]
	v_pk_fma_f32 v[20:21], v[22:23], v[14:15], v[20:21]
	v_cvt_scalef32_pk_f32_fp4 v[22:23], v69, 1.0 op_sel:[0,1,0]
	v_pk_fma_f32 v[20:21], v[22:23], v[16:17], v[20:21]
	v_cvt_scalef32_pk_f32_fp4 v[22:23], v69, 1.0 op_sel:[1,1,0]
	v_pk_fma_f32 v[20:21], v[22:23], v[18:19], v[20:21]
	s_waitcnt vmcnt(0)
	v_cvt_scalef32_pk_f32_fp4 v[22:23], v70, 1.0 op_sel:[1,0,0]
	v_add_f32_e32 v56, v20, v21
	v_cvt_scalef32_pk_f32_fp4 v[20:21], v70, 1.0
	v_pk_mul_f32 v[22:23], v[22:23], v[6:7]
	s_nop 0
	v_pk_fma_f32 v[20:21], v[20:21], v[4:5], v[22:23]
	v_cvt_scalef32_pk_f32_fp4 v[22:23], v70, 1.0 op_sel:[0,1,0]
	v_pk_fma_f32 v[20:21], v[22:23], v[8:9], v[20:21]
	v_cvt_scalef32_pk_f32_fp4 v[22:23], v70, 1.0 op_sel:[1,1,0]
	v_pk_fma_f32 v[20:21], v[22:23], v[10:11], v[20:21]
	v_cvt_scalef32_pk_f32_fp4 v[22:23], v71, 1.0
	v_pk_fma_f32 v[20:21], v[22:23], v[12:13], v[20:21]
	v_cvt_scalef32_pk_f32_fp4 v[22:23], v71, 1.0 op_sel:[1,0,0]
	v_pk_fma_f32 v[20:21], v[22:23], v[14:15], v[20:21]
	v_cvt_scalef32_pk_f32_fp4 v[22:23], v71, 1.0 op_sel:[0,1,0]
	v_pk_fma_f32 v[20:21], v[22:23], v[16:17], v[20:21]
	v_cvt_scalef32_pk_f32_fp4 v[22:23], v71, 1.0 op_sel:[1,1,0]
	v_pk_fma_f32 v[20:21], v[22:23], v[18:19], v[20:21]
	v_cndmask_b32_e64 v22, v74, v30, s[0:1]
	v_add_f32_e32 v20, v20, v21
	v_cndmask_b32_e64 v21, v30, v74, s[0:1]
	v_cndmask_b32_e64 v23, v72, v31, s[0:1]
	s_nop 0
	v_add_f32_dpp v21, v22, v21 quad_perm:[1,0,3,2] row_mask:0xf bank_mask:0xf bound_ctrl:1
	v_cndmask_b32_e64 v22, v31, v72, s[0:1]
	s_nop 1
	v_add_f32_dpp v22, v23, v22 quad_perm:[1,0,3,2] row_mask:0xf bank_mask:0xf bound_ctrl:1
	v_cndmask_b32_e64 v23, v32, v24, s[0:1]
	v_cndmask_b32_e64 v24, v24, v32, s[0:1]
	s_nop 1
	v_add_f32_dpp v23, v24, v23 quad_perm:[1,0,3,2] row_mask:0xf bank_mask:0xf bound_ctrl:1
	v_cndmask_b32_e64 v24, v33, v25, s[0:1]
	v_cndmask_b32_e64 v25, v25, v33, s[0:1]
	s_nop 1
	v_add_f32_dpp v24, v25, v24 quad_perm:[1,0,3,2] row_mask:0xf bank_mask:0xf bound_ctrl:1
	v_cndmask_b32_e64 v25, v34, v26, s[0:1]
	v_cndmask_b32_e64 v26, v26, v34, s[0:1]
	s_nop 1
	v_add_f32_dpp v25, v26, v25 quad_perm:[1,0,3,2] row_mask:0xf bank_mask:0xf bound_ctrl:1
	v_cndmask_b32_e64 v26, v35, v27, s[0:1]
	v_cndmask_b32_e64 v27, v27, v35, s[0:1]
	s_nop 1
	v_add_f32_dpp v26, v27, v26 quad_perm:[1,0,3,2] row_mask:0xf bank_mask:0xf bound_ctrl:1
	v_cndmask_b32_e64 v27, v56, v28, s[0:1]
	v_cndmask_b32_e64 v28, v28, v56, s[0:1]
	s_nop 1
	v_add_f32_dpp v27, v28, v27 quad_perm:[1,0,3,2] row_mask:0xf bank_mask:0xf bound_ctrl:1
	v_cndmask_b32_e64 v28, v20, v29, s[0:1]
	v_cndmask_b32_e64 v20, v29, v20, s[0:1]
	s_nop 1
	v_add_f32_dpp v20, v20, v28 quad_perm:[1,0,3,2] row_mask:0xf bank_mask:0xf bound_ctrl:1
	v_cndmask_b32_e64 v28, v25, v21, s[4:5]
	v_cndmask_b32_e64 v21, v21, v25, s[4:5]
	v_cndmask_b32_e64 v25, v26, v22, s[4:5]
	v_cndmask_b32_e64 v22, v22, v26, s[4:5]
	v_add_f32_dpp v21, v21, v28 quad_perm:[2,3,0,1] row_mask:0xf bank_mask:0xf bound_ctrl:1
	s_nop 0
	v_add_f32_dpp v22, v22, v25 quad_perm:[2,3,0,1] row_mask:0xf bank_mask:0xf bound_ctrl:1
	v_cndmask_b32_e64 v25, v27, v23, s[4:5]
	v_cndmask_b32_e64 v23, v23, v27, s[4:5]
	s_nop 1
	v_add_f32_dpp v23, v23, v25 quad_perm:[2,3,0,1] row_mask:0xf bank_mask:0xf bound_ctrl:1
	v_cndmask_b32_e64 v25, v20, v24, s[4:5]
	v_cndmask_b32_e64 v20, v24, v20, s[4:5]
	v_cndmask_b32_e64 v24, v23, v21, s[6:7]
	v_cndmask_b32_e64 v21, v21, v23, s[6:7]
	v_add_f32_dpp v20, v20, v25 quad_perm:[2,3,0,1] row_mask:0xf bank_mask:0xf bound_ctrl:1
	v_cndmask_b32_e64 v23, v20, v22, s[6:7]
	v_cndmask_b32_e64 v20, v22, v20, s[6:7]
	v_mov_b32_dpp v21, v21 row_half_mirror row_mask:0xf bank_mask:0xf bound_ctrl:1
	s_nop 0
	v_mov_b32_dpp v20, v20 row_half_mirror row_mask:0xf bank_mask:0xf bound_ctrl:1
	v_add_f32_dpp v21, v21, v24 quad_perm:[3,2,1,0] row_mask:0xf bank_mask:0xf bound_ctrl:1
	s_nop 0
	v_add_f32_dpp v20, v20, v23 quad_perm:[3,2,1,0] row_mask:0xf bank_mask:0xf bound_ctrl:1
	v_cndmask_b32_e64 v22, v20, v21, s[8:9]
	v_cndmask_b32_e64 v20, v21, v20, s[8:9]
	s_nop 1
	v_mov_b32_dpp v20, v20 row_mirror row_mask:0xf bank_mask:0xf bound_ctrl:1
	s_nop 1
	v_add_f32_dpp v20, v20, v22 row_half_mirror row_mask:0xf bank_mask:0xf bound_ctrl:1
	ds_bpermute_b32 v21, v125, v20
	s_waitcnt lgkmcnt(0)
	v_add_f32_e32 v20, v20, v21
	ds_bpermute_b32 v21, v126, v20
	s_waitcnt lgkmcnt(0)
	v_add_f32_e32 v20, v20, v21
	v_or_b32_e32 v21, 1, v76
	v_cmp_eq_u32_e64 s[14:15], v106, v21
	v_cndmask_b32_e64 v21, v20, v77, s[12:13]
	s_and_b64 s[12:13], s[14:15], s[12:13]
	v_cndmask_b32_e64 v129, v78, v20, s[12:13]
	v_cmp_ge_u32_e64 s[12:13], v127, v115
	v_cndmask_b32_e64 v128, v77, v21, s[14:15]
	s_or_b64 s[28:29], s[12:13], s[28:29]
	s_branch .Lh3_u10_join
.Lh3_u10_hi:
	v_readlane_b32 s84, v70, 32
	v_readlane_b32 s86, v70, 33
	v_readlane_b32 s88, v70, 34
	v_readlane_b32 s90, v70, 35
	s_ashr_i32 s85, s84, 31
	s_ashr_i32 s87, s86, 31
	s_ashr_i32 s89, s88, 31
	s_ashr_i32 s91, s90, 31
	s_lshl_b64 s[84:85], s[84:85], 9
	s_lshl_b64 s[86:87], s[86:87], 9
	s_lshl_b64 s[88:89], s[88:89], 9
	s_lshl_b64 s[90:91], s[90:91], 9
	v_lshl_add_u64 v[72:73], v[38:39], 0, s[84:85]
	v_lshl_add_u64 v[74:75], v[38:39], 0, s[86:87]
	v_lshl_add_u64 v[76:77], v[38:39], 0, s[88:89]
	v_lshl_add_u64 v[78:79], v[38:39], 0, s[90:91]
	global_load_dwordx2 v[72:73], v[72:73], off
	global_load_dwordx2 v[74:75], v[74:75], off
	global_load_dwordx2 v[76:77], v[76:77], off
	global_load_dwordx2 v[78:79], v[78:79], off
	v_readlane_b32 s84, v70, 36
	v_readlane_b32 s86, v70, 37
	v_readlane_b32 s88, v70, 38
	v_readlane_b32 s90, v70, 39
	s_ashr_i32 s85, s84, 31
	s_ashr_i32 s87, s86, 31
	s_ashr_i32 s89, s88, 31
	s_ashr_i32 s91, s90, 31
	s_lshl_b64 s[84:85], s[84:85], 9
	s_lshl_b64 s[86:87], s[86:87], 9
	s_lshl_b64 s[88:89], s[88:89], 9
	s_lshl_b64 s[90:91], s[90:91], 9
	v_lshl_add_u64 v[80:81], v[38:39], 0, s[84:85]
	v_lshl_add_u64 v[82:83], v[38:39], 0, s[86:87]
	v_lshl_add_u64 v[84:85], v[38:39], 0, s[88:89]
	v_lshl_add_u64 v[86:87], v[38:39], 0, s[90:91]
	global_load_dwordx2 v[80:81], v[80:81], off
	global_load_dwordx2 v[82:83], v[82:83], off
	global_load_dwordx2 v[84:85], v[84:85], off
	global_load_dwordx2 v[86:87], v[86:87], off
	v_readlane_b32 s84, v70, 40
	v_readlane_b32 s86, v70, 41
	v_readlane_b32 s88, v70, 42
	v_readlane_b32 s90, v70, 43
	s_ashr_i32 s85, s84, 31
	s_ashr_i32 s87, s86, 31
	s_ashr_i32 s89, s88, 31
	s_ashr_i32 s91, s90, 31
	s_lshl_b64 s[84:85], s[84:85], 9
	s_lshl_b64 s[86:87], s[86:87], 9
	s_lshl_b64 s[88:89], s[88:89], 9
	s_lshl_b64 s[90:91], s[90:91], 9
	v_lshl_add_u64 v[88:89], v[38:39], 0, s[84:85]
	v_lshl_add_u64 v[90:91], v[38:39], 0, s[86:87]
	v_lshl_add_u64 v[92:93], v[38:39], 0, s[88:89]
	v_lshl_add_u64 v[94:95], v[38:39], 0, s[90:91]
	global_load_dwordx2 v[88:89], v[88:89], off
	global_load_dwordx2 v[90:91], v[90:91], off
	global_load_dwordx2 v[92:93], v[92:93], off
	global_load_dwordx2 v[94:95], v[94:95], off
	v_readlane_b32 s84, v70, 44
	v_readlane_b32 s86, v70, 45
	v_readlane_b32 s88, v70, 46
	v_readlane_b32 s90, v70, 47
	s_ashr_i32 s85, s84, 31
	s_ashr_i32 s87, s86, 31
	s_ashr_i32 s89, s88, 31
	s_ashr_i32 s91, s90, 31
	s_lshl_b64 s[84:85], s[84:85], 9
	s_lshl_b64 s[86:87], s[86:87], 9
	s_lshl_b64 s[88:89], s[88:89], 9
	s_lshl_b64 s[90:91], s[90:91], 9
	v_lshl_add_u64 v[96:97], v[38:39], 0, s[84:85]
	v_lshl_add_u64 v[98:99], v[38:39], 0, s[86:87]
	v_lshl_add_u64 v[100:101], v[38:39], 0, s[88:89]
	v_lshl_add_u64 v[102:103], v[38:39], 0, s[90:91]
	global_load_dwordx2 v[96:97], v[96:97], off
	global_load_dwordx2 v[98:99], v[98:99], off
	global_load_dwordx2 v[100:101], v[100:101], off
	global_load_dwordx2 v[102:103], v[102:103], off
	v_readlane_b32 s84, v70, 48
	v_readlane_b32 s86, v70, 49
	v_readlane_b32 s88, v70, 50
	v_readlane_b32 s90, v70, 51
	s_ashr_i32 s85, s84, 31
	s_ashr_i32 s87, s86, 31
	s_ashr_i32 s89, s88, 31
	s_ashr_i32 s91, s90, 31
	s_lshl_b64 s[84:85], s[84:85], 9
	s_lshl_b64 s[86:87], s[86:87], 9
	s_lshl_b64 s[88:89], s[88:89], 9
	s_lshl_b64 s[90:91], s[90:91], 9
	v_lshl_add_u64 v[20:21], v[38:39], 0, s[84:85]
	v_lshl_add_u64 v[22:23], v[38:39], 0, s[86:87]
	v_lshl_add_u64 v[24:25], v[38:39], 0, s[88:89]
	v_lshl_add_u64 v[26:27], v[38:39], 0, s[90:91]
	global_load_dwordx2 v[20:21], v[20:21], off
	global_load_dwordx2 v[22:23], v[22:23], off
	global_load_dwordx2 v[24:25], v[24:25], off
	global_load_dwordx2 v[26:27], v[26:27], off
	v_readlane_b32 s84, v70, 52
	v_readlane_b32 s86, v70, 53
	v_readlane_b32 s88, v70, 54
	v_readlane_b32 s90, v70, 55
	s_ashr_i32 s85, s84, 31
	s_ashr_i32 s87, s86, 31
	s_ashr_i32 s89, s88, 31
	s_ashr_i32 s91, s90, 31
	s_lshl_b64 s[84:85], s[84:85], 9
	s_lshl_b64 s[86:87], s[86:87], 9
	s_lshl_b64 s[88:89], s[88:89], 9
	s_lshl_b64 s[90:91], s[90:91], 9
	v_lshl_add_u64 v[28:29], v[38:39], 0, s[84:85]
	v_lshl_add_u64 v[30:31], v[38:39], 0, s[86:87]
	v_lshl_add_u64 v[32:33], v[38:39], 0, s[88:89]
	v_lshl_add_u64 v[34:35], v[38:39], 0, s[90:91]
	global_load_dwordx2 v[28:29], v[28:29], off
	global_load_dwordx2 v[30:31], v[30:31], off
	global_load_dwordx2 v[32:33], v[32:33], off
	global_load_dwordx2 v[34:35], v[34:35], off
	v_readlane_b32 s84, v70, 56
	v_readlane_b32 s86, v70, 57
	v_readlane_b32 s88, v70, 58
	v_readlane_b32 s90, v70, 59
	s_ashr_i32 s85, s84, 31
	s_ashr_i32 s87, s86, 31
	s_ashr_i32 s89, s88, 31
	s_ashr_i32 s91, s90, 31
	s_lshl_b64 s[84:85], s[84:85], 9
	s_lshl_b64 s[86:87], s[86:87], 9
	s_lshl_b64 s[88:89], s[88:89], 9
	s_lshl_b64 s[90:91], s[90:91], 9
	v_lshl_add_u64 v[56:57], v[38:39], 0, s[84:85]
	v_lshl_add_u64 v[58:59], v[38:39], 0, s[86:87]
	v_lshl_add_u64 v[60:61], v[38:39], 0, s[88:89]
	v_lshl_add_u64 v[62:63], v[38:39], 0, s[90:91]
	global_load_dwordx2 v[56:57], v[56:57], off
	global_load_dwordx2 v[58:59], v[58:59], off
	global_load_dwordx2 v[60:61], v[60:61], off
	global_load_dwordx2 v[62:63], v[62:63], off
	v_readlane_b32 s84, v70, 60
	v_readlane_b32 s86, v70, 61
	v_readlane_b32 s88, v70, 62
	v_readlane_b32 s90, v70, 63
	s_ashr_i32 s85, s84, 31
	s_ashr_i32 s87, s86, 31
	s_ashr_i32 s89, s88, 31
	s_ashr_i32 s91, s90, 31
	s_lshl_b64 s[84:85], s[84:85], 9
	s_lshl_b64 s[86:87], s[86:87], 9
	s_lshl_b64 s[88:89], s[88:89], 9
	s_lshl_b64 s[90:91], s[90:91], 9
	v_lshl_add_u64 v[64:65], v[38:39], 0, s[84:85]
	v_lshl_add_u64 v[66:67], v[38:39], 0, s[86:87]
	v_lshl_add_u64 v[68:69], v[38:39], 0, s[88:89]
	v_lshl_add_u64 v[70:71], v[38:39], 0, s[90:91]
	global_load_dwordx2 v[64:65], v[64:65], off
	global_load_dwordx2 v[66:67], v[66:67], off
	global_load_dwordx2 v[68:69], v[68:69], off
	global_load_dwordx2 v[70:71], v[70:71], off
	s_waitcnt vmcnt(31)
	v_cvt_scalef32_pk_f32_fp4 v[132:133], v72, 1.0 op_sel:[1,0,0]
	s_nop 0
	v_cvt_scalef32_pk_f32_fp4 v[130:131], v72, 1.0
	v_pk_mul_f32 v[132:133], v[132:133], v[6:7]
	s_nop 0
	v_pk_fma_f32 v[130:131], v[130:131], v[4:5], v[132:133]
	v_cvt_scalef32_pk_f32_fp4 v[132:133], v72, 1.0 op_sel:[0,1,0]
	v_pk_fma_f32 v[130:131], v[132:133], v[8:9], v[130:131]
	v_cvt_scalef32_pk_f32_fp4 v[132:133], v72, 1.0 op_sel:[1,1,0]
	v_pk_fma_f32 v[130:131], v[132:133], v[10:11], v[130:131]
	v_cvt_scalef32_pk_f32_fp4 v[132:133], v73, 1.0
	v_pk_fma_f32 v[130:131], v[132:133], v[12:13], v[130:131]
	v_cvt_scalef32_pk_f32_fp4 v[132:133], v73, 1.0 op_sel:[1,0,0]
	v_pk_fma_f32 v[130:131], v[132:133], v[14:15], v[130:131]
	v_cvt_scalef32_pk_f32_fp4 v[132:133], v73, 1.0 op_sel:[0,1,0]
	v_pk_fma_f32 v[130:131], v[132:133], v[16:17], v[130:131]
	v_cvt_scalef32_pk_f32_fp4 v[72:73], v73, 1.0 op_sel:[1,1,0]
	v_pk_fma_f32 v[72:73], v[72:73], v[18:19], v[130:131]
	s_waitcnt vmcnt(30)
	v_cvt_scalef32_pk_f32_fp4 v[130:131], v74, 1.0 op_sel:[1,0,0]
	v_add_f32_e32 v132, v72, v73
	v_cvt_scalef32_pk_f32_fp4 v[72:73], v74, 1.0
	v_pk_mul_f32 v[130:131], v[130:131], v[6:7]
	s_nop 0
	v_pk_fma_f32 v[72:73], v[72:73], v[4:5], v[130:131]
	v_cvt_scalef32_pk_f32_fp4 v[130:131], v74, 1.0 op_sel:[0,1,0]
	v_pk_fma_f32 v[72:73], v[130:131], v[8:9], v[72:73]
	v_cvt_scalef32_pk_f32_fp4 v[130:131], v74, 1.0 op_sel:[1,1,0]
	v_pk_fma_f32 v[72:73], v[130:131], v[10:11], v[72:73]
	v_cvt_scalef32_pk_f32_fp4 v[130:131], v75, 1.0
	v_pk_fma_f32 v[72:73], v[130:131], v[12:13], v[72:73]
	v_cvt_scalef32_pk_f32_fp4 v[130:131], v75, 1.0 op_sel:[1,0,0]
	v_pk_fma_f32 v[72:73], v[130:131], v[14:15], v[72:73]
	v_cvt_scalef32_pk_f32_fp4 v[130:131], v75, 1.0 op_sel:[0,1,0]
	v_pk_fma_f32 v[72:73], v[130:131], v[16:17], v[72:73]
	v_cvt_scalef32_pk_f32_fp4 v[74:75], v75, 1.0 op_sel:[1,1,0]
	v_pk_fma_f32 v[72:73], v[74:75], v[18:19], v[72:73]
	s_waitcnt vmcnt(29)
	v_cvt_scalef32_pk_f32_fp4 v[74:75], v76, 1.0 op_sel:[1,0,0]
	v_add_f32_e32 v130, v72, v73
	v_cvt_scalef32_pk_f32_fp4 v[72:73], v76, 1.0
	v_pk_mul_f32 v[74:75], v[74:75], v[6:7]
	s_nop 0
	v_pk_fma_f32 v[72:73], v[72:73], v[4:5], v[74:75]
	v_cvt_scalef32_pk_f32_fp4 v[74:75], v76, 1.0 op_sel:[0,1,0]
	v_pk_fma_f32 v[72:73], v[74:75], v[8:9], v[72:73]
	v_cvt_scalef32_pk_f32_fp4 v[74:75], v76, 1.0 op_sel:[1,1,0]
	v_pk_fma_f32 v[72:73], v[74:75], v[10:11], v[72:73]
	v_cvt_scalef32_pk_f32_fp4 v[74:75], v77, 1.0
	v_pk_fma_f32 v[72:73], v[74:75], v[12:13], v[72:73]
	v_cvt_scalef32_pk_f32_fp4 v[74:75], v77, 1.0 op_sel:[1,0,0]
	v_pk_fma_f32 v[72:73], v[74:75], v[14:15], v[72:73]
	v_cvt_scalef32_pk_f32_fp4 v[74:75], v77, 1.0 op_sel:[0,1,0]
	v_pk_fma_f32 v[72:73], v[74:75], v[16:17], v[72:73]
	v_cvt_scalef32_pk_f32_fp4 v[74:75], v77, 1.0 op_sel:[1,1,0]
	v_pk_fma_f32 v[72:73], v[74:75], v[18:19], v[72:73]
	s_waitcnt vmcnt(28)
	v_cvt_scalef32_pk_f32_fp4 v[74:75], v78, 1.0 op_sel:[1,0,0]
	v_add_f32_e32 v76, v72, v73
	v_cvt_scalef32_pk_f32_fp4 v[72:73], v78, 1.0
	v_pk_mul_f32 v[74:75], v[74:75], v[6:7]
	s_nop 0
	v_pk_fma_f32 v[72:73], v[72:73], v[4:5], v[74:75]
	v_cvt_scalef32_pk_f32_fp4 v[74:75], v78, 1.0 op_sel:[0,1,0]
	v_pk_fma_f32 v[72:73], v[74:75], v[8:9], v[72:73]
	v_cvt_scalef32_pk_f32_fp4 v[74:75], v78, 1.0 op_sel:[1,1,0]
	v_pk_fma_f32 v[72:73], v[74:75], v[10:11], v[72:73]
	v_cvt_scalef32_pk_f32_fp4 v[74:75], v79, 1.0
	v_pk_fma_f32 v[72:73], v[74:75], v[12:13], v[72:73]
	v_cvt_scalef32_pk_f32_fp4 v[74:75], v79, 1.0 op_sel:[1,0,0]
	v_pk_fma_f32 v[72:73], v[74:75], v[14:15], v[72:73]
	v_cvt_scalef32_pk_f32_fp4 v[74:75], v79, 1.0 op_sel:[0,1,0]
	v_pk_fma_f32 v[72:73], v[74:75], v[16:17], v[72:73]
	v_cvt_scalef32_pk_f32_fp4 v[74:75], v79, 1.0 op_sel:[1,1,0]
	v_pk_fma_f32 v[72:73], v[74:75], v[18:19], v[72:73]
	s_waitcnt vmcnt(27)
	v_cvt_scalef32_pk_f32_fp4 v[74:75], v80, 1.0 op_sel:[1,0,0]
	v_add_f32_e32 v77, v72, v73
	v_cvt_scalef32_pk_f32_fp4 v[72:73], v80, 1.0
	v_pk_mul_f32 v[74:75], v[74:75], v[6:7]
	s_nop 0
	v_pk_fma_f32 v[72:73], v[72:73], v[4:5], v[74:75]
	v_cvt_scalef32_pk_f32_fp4 v[74:75], v80, 1.0 op_sel:[0,1,0]
	v_pk_fma_f32 v[72:73], v[74:75], v[8:9], v[72:73]
	v_cvt_scalef32_pk_f32_fp4 v[74:75], v80, 1.0 op_sel:[1,1,0]
	v_pk_fma_f32 v[72:73], v[74:75], v[10:11], v[72:73]
	v_cvt_scalef32_pk_f32_fp4 v[74:75], v81, 1.0
	v_pk_fma_f32 v[72:73], v[74:75], v[12:13], v[72:73]
	v_cvt_scalef32_pk_f32_fp4 v[74:75], v81, 1.0 op_sel:[1,0,0]
	v_pk_fma_f32 v[72:73], v[74:75], v[14:15], v[72:73]
	v_cvt_scalef32_pk_f32_fp4 v[74:75], v81, 1.0 op_sel:[0,1,0]
	v_pk_fma_f32 v[72:73], v[74:75], v[16:17], v[72:73]
	v_cvt_scalef32_pk_f32_fp4 v[74:75], v81, 1.0 op_sel:[1,1,0]
	v_pk_fma_f32 v[72:73], v[74:75], v[18:19], v[72:73]
	s_waitcnt vmcnt(26)
	v_cvt_scalef32_pk_f32_fp4 v[74:75], v82, 1.0 op_sel:[1,0,0]
	v_add_f32_e32 v78, v72, v73
	v_cvt_scalef32_pk_f32_fp4 v[72:73], v82, 1.0
	v_pk_mul_f32 v[74:75], v[74:75], v[6:7]
	s_nop 0
	v_pk_fma_f32 v[72:73], v[72:73], v[4:5], v[74:75]
	v_cvt_scalef32_pk_f32_fp4 v[74:75], v82, 1.0 op_sel:[0,1,0]
	v_pk_fma_f32 v[72:73], v[74:75], v[8:9], v[72:73]
	v_cvt_scalef32_pk_f32_fp4 v[74:75], v82, 1.0 op_sel:[1,1,0]
	v_pk_fma_f32 v[72:73], v[74:75], v[10:11], v[72:73]
	v_cvt_scalef32_pk_f32_fp4 v[74:75], v83, 1.0
	v_pk_fma_f32 v[72:73], v[74:75], v[12:13], v[72:73]
	v_cvt_scalef32_pk_f32_fp4 v[74:75], v83, 1.0 op_sel:[1,0,0]
	v_pk_fma_f32 v[72:73], v[74:75], v[14:15], v[72:73]
	v_cvt_scalef32_pk_f32_fp4 v[74:75], v83, 1.0 op_sel:[0,1,0]
	v_pk_fma_f32 v[72:73], v[74:75], v[16:17], v[72:73]
	v_cvt_scalef32_pk_f32_fp4 v[74:75], v83, 1.0 op_sel:[1,1,0]
	v_pk_fma_f32 v[72:73], v[74:75], v[18:19], v[72:73]
	s_waitcnt vmcnt(25)
	v_cvt_scalef32_pk_f32_fp4 v[74:75], v84, 1.0 op_sel:[1,0,0]
	v_add_f32_e32 v79, v72, v73
	v_cvt_scalef32_pk_f32_fp4 v[72:73], v84, 1.0
	v_pk_mul_f32 v[74:75], v[74:75], v[6:7]
	s_nop 0
	v_pk_fma_f32 v[72:73], v[72:73], v[4:5], v[74:75]
	v_cvt_scalef32_pk_f32_fp4 v[74:75], v84, 1.0 op_sel:[0,1,0]
	v_pk_fma_f32 v[72:73], v[74:75], v[8:9], v[72:73]
	v_cvt_scalef32_pk_f32_fp4 v[74:75], v84, 1.0 op_sel:[1,1,0]
	v_pk_fma_f32 v[72:73], v[74:75], v[10:11], v[72:73]
	v_cvt_scalef32_pk_f32_fp4 v[74:75], v85, 1.0
	v_pk_fma_f32 v[72:73], v[74:75], v[12:13], v[72:73]
	v_cvt_scalef32_pk_f32_fp4 v[74:75], v85, 1.0 op_sel:[1,0,0]
	v_pk_fma_f32 v[72:73], v[74:75], v[14:15], v[72:73]
	v_cvt_scalef32_pk_f32_fp4 v[74:75], v85, 1.0 op_sel:[0,1,0]
	v_pk_fma_f32 v[72:73], v[74:75], v[16:17], v[72:73]
	v_cvt_scalef32_pk_f32_fp4 v[74:75], v85, 1.0 op_sel:[1,1,0]
	v_pk_fma_f32 v[72:73], v[74:75], v[18:19], v[72:73]
	s_waitcnt vmcnt(24)
	v_cvt_scalef32_pk_f32_fp4 v[74:75], v86, 1.0 op_sel:[1,0,0]
	v_add_f32_e32 v80, v72, v73
	v_cvt_scalef32_pk_f32_fp4 v[72:73], v86, 1.0
	v_pk_mul_f32 v[74:75], v[74:75], v[6:7]
	s_nop 0
	v_pk_fma_f32 v[72:73], v[72:73], v[4:5], v[74:75]
	v_cvt_scalef32_pk_f32_fp4 v[74:75], v86, 1.0 op_sel:[0,1,0]
	v_pk_fma_f32 v[72:73], v[74:75], v[8:9], v[72:73]
	v_cvt_scalef32_pk_f32_fp4 v[74:75], v86, 1.0 op_sel:[1,1,0]
	v_pk_fma_f32 v[72:73], v[74:75], v[10:11], v[72:73]
	v_cvt_scalef32_pk_f32_fp4 v[74:75], v87, 1.0
	v_pk_fma_f32 v[72:73], v[74:75], v[12:13], v[72:73]
	v_cvt_scalef32_pk_f32_fp4 v[74:75], v87, 1.0 op_sel:[1,0,0]
	v_pk_fma_f32 v[72:73], v[74:75], v[14:15], v[72:73]
	v_cvt_scalef32_pk_f32_fp4 v[74:75], v87, 1.0 op_sel:[0,1,0]
	v_pk_fma_f32 v[72:73], v[74:75], v[16:17], v[72:73]
	v_cvt_scalef32_pk_f32_fp4 v[74:75], v87, 1.0 op_sel:[1,1,0]
	v_pk_fma_f32 v[72:73], v[74:75], v[18:19], v[72:73]
	s_waitcnt vmcnt(23)
	v_cvt_scalef32_pk_f32_fp4 v[74:75], v88, 1.0 op_sel:[1,0,0]
	v_add_f32_e32 v81, v72, v73
	v_cvt_scalef32_pk_f32_fp4 v[72:73], v88, 1.0
	v_pk_mul_f32 v[74:75], v[74:75], v[6:7]
	s_nop 0
	v_pk_fma_f32 v[72:73], v[72:73], v[4:5], v[74:75]
	v_cvt_scalef32_pk_f32_fp4 v[74:75], v88, 1.0 op_sel:[0,1,0]
	v_pk_fma_f32 v[72:73], v[74:75], v[8:9], v[72:73]
	v_cvt_scalef32_pk_f32_fp4 v[74:75], v88, 1.0 op_sel:[1,1,0]
	v_pk_fma_f32 v[72:73], v[74:75], v[10:11], v[72:73]
	v_cvt_scalef32_pk_f32_fp4 v[74:75], v89, 1.0
	v_pk_fma_f32 v[72:73], v[74:75], v[12:13], v[72:73]
	v_cvt_scalef32_pk_f32_fp4 v[74:75], v89, 1.0 op_sel:[1,0,0]
	v_pk_fma_f32 v[72:73], v[74:75], v[14:15], v[72:73]
	v_cvt_scalef32_pk_f32_fp4 v[74:75], v89, 1.0 op_sel:[0,1,0]
	v_pk_fma_f32 v[72:73], v[74:75], v[16:17], v[72:73]
	v_cvt_scalef32_pk_f32_fp4 v[74:75], v89, 1.0 op_sel:[1,1,0]
	v_pk_fma_f32 v[72:73], v[74:75], v[18:19], v[72:73]
	s_waitcnt vmcnt(22)
	v_cvt_scalef32_pk_f32_fp4 v[74:75], v90, 1.0 op_sel:[1,0,0]
	v_add_f32_e32 v82, v72, v73
	v_cvt_scalef32_pk_f32_fp4 v[72:73], v90, 1.0
	v_pk_mul_f32 v[74:75], v[74:75], v[6:7]
	s_nop 0
	v_pk_fma_f32 v[72:73], v[72:73], v[4:5], v[74:75]
	v_cvt_scalef32_pk_f32_fp4 v[74:75], v90, 1.0 op_sel:[0,1,0]
	v_pk_fma_f32 v[72:73], v[74:75], v[8:9], v[72:73]
	v_cvt_scalef32_pk_f32_fp4 v[74:75], v90, 1.0 op_sel:[1,1,0]
	v_pk_fma_f32 v[72:73], v[74:75], v[10:11], v[72:73]
	v_cvt_scalef32_pk_f32_fp4 v[74:75], v91, 1.0
	v_pk_fma_f32 v[72:73], v[74:75], v[12:13], v[72:73]
	v_cvt_scalef32_pk_f32_fp4 v[74:75], v91, 1.0 op_sel:[1,0,0]
	v_pk_fma_f32 v[72:73], v[74:75], v[14:15], v[72:73]
	v_cvt_scalef32_pk_f32_fp4 v[74:75], v91, 1.0 op_sel:[0,1,0]
	v_pk_fma_f32 v[72:73], v[74:75], v[16:17], v[72:73]
	v_cvt_scalef32_pk_f32_fp4 v[74:75], v91, 1.0 op_sel:[1,1,0]
	v_pk_fma_f32 v[72:73], v[74:75], v[18:19], v[72:73]
	s_waitcnt vmcnt(21)
	v_cvt_scalef32_pk_f32_fp4 v[74:75], v92, 1.0 op_sel:[1,0,0]
	v_add_f32_e32 v83, v72, v73
	v_cvt_scalef32_pk_f32_fp4 v[72:73], v92, 1.0
	v_pk_mul_f32 v[74:75], v[74:75], v[6:7]
	s_nop 0
	v_pk_fma_f32 v[72:73], v[72:73], v[4:5], v[74:75]
	v_cvt_scalef32_pk_f32_fp4 v[74:75], v92, 1.0 op_sel:[0,1,0]
	v_pk_fma_f32 v[72:73], v[74:75], v[8:9], v[72:73]
	v_cvt_scalef32_pk_f32_fp4 v[74:75], v92, 1.0 op_sel:[1,1,0]
	v_pk_fma_f32 v[72:73], v[74:75], v[10:11], v[72:73]
	v_cvt_scalef32_pk_f32_fp4 v[74:75], v93, 1.0
	v_pk_fma_f32 v[72:73], v[74:75], v[12:13], v[72:73]
	v_cvt_scalef32_pk_f32_fp4 v[74:75], v93, 1.0 op_sel:[1,0,0]
	v_pk_fma_f32 v[72:73], v[74:75], v[14:15], v[72:73]
	v_cvt_scalef32_pk_f32_fp4 v[74:75], v93, 1.0 op_sel:[0,1,0]
	v_pk_fma_f32 v[72:73], v[74:75], v[16:17], v[72:73]
	v_cvt_scalef32_pk_f32_fp4 v[74:75], v93, 1.0 op_sel:[1,1,0]
	v_pk_fma_f32 v[72:73], v[74:75], v[18:19], v[72:73]
	s_waitcnt vmcnt(20)
	v_cvt_scalef32_pk_f32_fp4 v[74:75], v94, 1.0 op_sel:[1,0,0]
	v_add_f32_e32 v84, v72, v73
	v_cvt_scalef32_pk_f32_fp4 v[72:73], v94, 1.0
	v_pk_mul_f32 v[74:75], v[74:75], v[6:7]
	s_nop 0
	v_pk_fma_f32 v[72:73], v[72:73], v[4:5], v[74:75]
	v_cvt_scalef32_pk_f32_fp4 v[74:75], v94, 1.0 op_sel:[0,1,0]
	v_pk_fma_f32 v[72:73], v[74:75], v[8:9], v[72:73]
	v_cvt_scalef32_pk_f32_fp4 v[74:75], v94, 1.0 op_sel:[1,1,0]
	v_pk_fma_f32 v[72:73], v[74:75], v[10:11], v[72:73]
	v_cvt_scalef32_pk_f32_fp4 v[74:75], v95, 1.0
	v_pk_fma_f32 v[72:73], v[74:75], v[12:13], v[72:73]
	v_cvt_scalef32_pk_f32_fp4 v[74:75], v95, 1.0 op_sel:[1,0,0]
	v_pk_fma_f32 v[72:73], v[74:75], v[14:15], v[72:73]
	v_cvt_scalef32_pk_f32_fp4 v[74:75], v95, 1.0 op_sel:[0,1,0]
	v_pk_fma_f32 v[72:73], v[74:75], v[16:17], v[72:73]
	v_cvt_scalef32_pk_f32_fp4 v[74:75], v95, 1.0 op_sel:[1,1,0]
	v_pk_fma_f32 v[72:73], v[74:75], v[18:19], v[72:73]
	s_waitcnt vmcnt(19)
	v_cvt_scalef32_pk_f32_fp4 v[74:75], v96, 1.0 op_sel:[1,0,0]
	v_add_f32_e32 v85, v72, v73
	v_cvt_scalef32_pk_f32_fp4 v[72:73], v96, 1.0
	v_pk_mul_f32 v[74:75], v[74:75], v[6:7]
	s_nop 0
	v_pk_fma_f32 v[72:73], v[72:73], v[4:5], v[74:75]
	v_cvt_scalef32_pk_f32_fp4 v[74:75], v96, 1.0 op_sel:[0,1,0]
	v_pk_fma_f32 v[72:73], v[74:75], v[8:9], v[72:73]
	v_cvt_scalef32_pk_f32_fp4 v[74:75], v96, 1.0 op_sel:[1,1,0]
	v_pk_fma_f32 v[72:73], v[74:75], v[10:11], v[72:73]
	v_cvt_scalef32_pk_f32_fp4 v[74:75], v97, 1.0
	v_pk_fma_f32 v[72:73], v[74:75], v[12:13], v[72:73]
	v_cvt_scalef32_pk_f32_fp4 v[74:75], v97, 1.0 op_sel:[1,0,0]
	v_pk_fma_f32 v[72:73], v[74:75], v[14:15], v[72:73]
	v_cvt_scalef32_pk_f32_fp4 v[74:75], v97, 1.0 op_sel:[0,1,0]
	v_pk_fma_f32 v[72:73], v[74:75], v[16:17], v[72:73]
	v_cvt_scalef32_pk_f32_fp4 v[74:75], v97, 1.0 op_sel:[1,1,0]
	v_pk_fma_f32 v[72:73], v[74:75], v[18:19], v[72:73]
	s_waitcnt vmcnt(18)
	v_cvt_scalef32_pk_f32_fp4 v[74:75], v98, 1.0 op_sel:[1,0,0]
	v_add_f32_e32 v86, v72, v73
	v_cvt_scalef32_pk_f32_fp4 v[72:73], v98, 1.0
	v_pk_mul_f32 v[74:75], v[74:75], v[6:7]
	s_nop 0
	v_pk_fma_f32 v[72:73], v[72:73], v[4:5], v[74:75]
	v_cvt_scalef32_pk_f32_fp4 v[74:75], v98, 1.0 op_sel:[0,1,0]
	v_pk_fma_f32 v[72:73], v[74:75], v[8:9], v[72:73]
	v_cvt_scalef32_pk_f32_fp4 v[74:75], v98, 1.0 op_sel:[1,1,0]
	v_pk_fma_f32 v[72:73], v[74:75], v[10:11], v[72:73]
	v_cvt_scalef32_pk_f32_fp4 v[74:75], v99, 1.0
	v_pk_fma_f32 v[72:73], v[74:75], v[12:13], v[72:73]
	v_cvt_scalef32_pk_f32_fp4 v[74:75], v99, 1.0 op_sel:[1,0,0]
	v_pk_fma_f32 v[72:73], v[74:75], v[14:15], v[72:73]
	v_cvt_scalef32_pk_f32_fp4 v[74:75], v99, 1.0 op_sel:[0,1,0]
	v_pk_fma_f32 v[72:73], v[74:75], v[16:17], v[72:73]
	v_cvt_scalef32_pk_f32_fp4 v[74:75], v99, 1.0 op_sel:[1,1,0]
	v_pk_fma_f32 v[72:73], v[74:75], v[18:19], v[72:73]
	s_waitcnt vmcnt(17)
	v_cvt_scalef32_pk_f32_fp4 v[74:75], v100, 1.0 op_sel:[1,0,0]
	v_add_f32_e32 v87, v72, v73
	v_cvt_scalef32_pk_f32_fp4 v[72:73], v100, 1.0
	v_pk_mul_f32 v[74:75], v[74:75], v[6:7]
	s_nop 0
	v_pk_fma_f32 v[72:73], v[72:73], v[4:5], v[74:75]
	v_cvt_scalef32_pk_f32_fp4 v[74:75], v100, 1.0 op_sel:[0,1,0]
	v_pk_fma_f32 v[72:73], v[74:75], v[8:9], v[72:73]
	v_cvt_scalef32_pk_f32_fp4 v[74:75], v100, 1.0 op_sel:[1,1,0]
	v_pk_fma_f32 v[72:73], v[74:75], v[10:11], v[72:73]
	v_cvt_scalef32_pk_f32_fp4 v[74:75], v101, 1.0
	v_pk_fma_f32 v[72:73], v[74:75], v[12:13], v[72:73]
	v_cvt_scalef32_pk_f32_fp4 v[74:75], v101, 1.0 op_sel:[1,0,0]
	v_pk_fma_f32 v[72:73], v[74:75], v[14:15], v[72:73]
	v_cvt_scalef32_pk_f32_fp4 v[74:75], v101, 1.0 op_sel:[0,1,0]
	v_pk_fma_f32 v[72:73], v[74:75], v[16:17], v[72:73]
	v_cvt_scalef32_pk_f32_fp4 v[74:75], v101, 1.0 op_sel:[1,1,0]
	v_pk_fma_f32 v[72:73], v[74:75], v[18:19], v[72:73]
	s_waitcnt vmcnt(16)
	v_cvt_scalef32_pk_f32_fp4 v[74:75], v102, 1.0 op_sel:[1,0,0]
	v_add_f32_e32 v88, v72, v73
	v_cvt_scalef32_pk_f32_fp4 v[72:73], v102, 1.0
	v_pk_mul_f32 v[74:75], v[74:75], v[6:7]
	s_nop 0
	v_pk_fma_f32 v[72:73], v[72:73], v[4:5], v[74:75]
	v_cvt_scalef32_pk_f32_fp4 v[74:75], v102, 1.0 op_sel:[0,1,0]
	v_pk_fma_f32 v[72:73], v[74:75], v[8:9], v[72:73]
	v_cvt_scalef32_pk_f32_fp4 v[74:75], v102, 1.0 op_sel:[1,1,0]
	v_pk_fma_f32 v[72:73], v[74:75], v[10:11], v[72:73]
	v_cvt_scalef32_pk_f32_fp4 v[74:75], v103, 1.0
	v_pk_fma_f32 v[72:73], v[74:75], v[12:13], v[72:73]
	v_cvt_scalef32_pk_f32_fp4 v[74:75], v103, 1.0 op_sel:[1,0,0]
	v_pk_fma_f32 v[72:73], v[74:75], v[14:15], v[72:73]
	v_cvt_scalef32_pk_f32_fp4 v[74:75], v103, 1.0 op_sel:[0,1,0]
	v_pk_fma_f32 v[72:73], v[74:75], v[16:17], v[72:73]
	v_cvt_scalef32_pk_f32_fp4 v[74:75], v103, 1.0 op_sel:[1,1,0]
	v_pk_fma_f32 v[72:73], v[74:75], v[18:19], v[72:73]
	v_cndmask_b32_e64 v74, v132, v82, s[0:1]
	v_add_f32_e32 v72, v72, v73
	v_cndmask_b32_e64 v73, v82, v132, s[0:1]
	v_cndmask_b32_e64 v75, v130, v83, s[0:1]
	s_nop 0
	v_add_f32_dpp v73, v74, v73 quad_perm:[1,0,3,2] row_mask:0xf bank_mask:0xf bound_ctrl:1
	v_cndmask_b32_e64 v74, v83, v130, s[0:1]
	v_add_u32_e32 v127, 32, v127
	s_nop 0
	v_add_f32_dpp v74, v75, v74 quad_perm:[1,0,3,2] row_mask:0xf bank_mask:0xf bound_ctrl:1
	v_cndmask_b32_e64 v75, v84, v76, s[0:1]
	v_cndmask_b32_e64 v76, v76, v84, s[0:1]
	s_nop 1
	v_add_f32_dpp v75, v76, v75 quad_perm:[1,0,3,2] row_mask:0xf bank_mask:0xf bound_ctrl:1
	v_cndmask_b32_e64 v76, v85, v77, s[0:1]
	v_cndmask_b32_e64 v77, v77, v85, s[0:1]
	s_nop 1
	v_add_f32_dpp v76, v77, v76 quad_perm:[1,0,3,2] row_mask:0xf bank_mask:0xf bound_ctrl:1
	v_cndmask_b32_e64 v77, v86, v78, s[0:1]
	v_cndmask_b32_e64 v78, v78, v86, s[0:1]
	s_nop 1
	v_add_f32_dpp v77, v78, v77 quad_perm:[1,0,3,2] row_mask:0xf bank_mask:0xf bound_ctrl:1
	v_cndmask_b32_e64 v78, v87, v79, s[0:1]
	v_cndmask_b32_e64 v79, v79, v87, s[0:1]
	s_nop 0
	s_nop 0
	v_add_f32_dpp v78, v79, v78 quad_perm:[1,0,3,2] row_mask:0xf bank_mask:0xf bound_ctrl:1
	v_cndmask_b32_e64 v79, v88, v80, s[0:1]
	v_cndmask_b32_e64 v80, v80, v88, s[0:1]
	s_nop 1
	v_add_f32_dpp v79, v80, v79 quad_perm:[1,0,3,2] row_mask:0xf bank_mask:0xf bound_ctrl:1
	v_cndmask_b32_e64 v80, v72, v81, s[0:1]
	v_cndmask_b32_e64 v72, v81, v72, s[0:1]
	s_nop 1
	v_add_f32_dpp v72, v72, v80 quad_perm:[1,0,3,2] row_mask:0xf bank_mask:0xf bound_ctrl:1
	v_cndmask_b32_e64 v80, v77, v73, s[4:5]
	v_cndmask_b32_e64 v73, v73, v77, s[4:5]
	v_cndmask_b32_e64 v77, v78, v74, s[4:5]
	v_cndmask_b32_e64 v74, v74, v78, s[4:5]
	v_add_f32_dpp v73, v73, v80 quad_perm:[2,3,0,1] row_mask:0xf bank_mask:0xf bound_ctrl:1
	s_nop 0
	v_add_f32_dpp v74, v74, v77 quad_perm:[2,3,0,1] row_mask:0xf bank_mask:0xf bound_ctrl:1
	v_cndmask_b32_e64 v77, v79, v75, s[4:5]
	v_cndmask_b32_e64 v75, v75, v79, s[4:5]
	s_nop 0
	s_nop 0
	v_add_f32_dpp v75, v75, v77 quad_perm:[2,3,0,1] row_mask:0xf bank_mask:0xf bound_ctrl:1
	v_cndmask_b32_e64 v77, v72, v76, s[4:5]
	v_cndmask_b32_e64 v72, v76, v72, s[4:5]
	v_cndmask_b32_e64 v76, v75, v73, s[6:7]
	v_cndmask_b32_e64 v73, v73, v75, s[6:7]
	v_add_f32_dpp v72, v72, v77 quad_perm:[2,3,0,1] row_mask:0xf bank_mask:0xf bound_ctrl:1
	v_cndmask_b32_e64 v75, v72, v74, s[6:7]
	v_cndmask_b32_e64 v72, v74, v72, s[6:7]
	v_mov_b32_dpp v73, v73 row_half_mirror row_mask:0xf bank_mask:0xf bound_ctrl:1
	s_nop 0
	v_mov_b32_dpp v72, v72 row_half_mirror row_mask:0xf bank_mask:0xf bound_ctrl:1
	v_add_f32_dpp v73, v73, v76 quad_perm:[3,2,1,0] row_mask:0xf bank_mask:0xf bound_ctrl:1
	s_nop 0
	v_add_f32_dpp v72, v72, v75 quad_perm:[3,2,1,0] row_mask:0xf bank_mask:0xf bound_ctrl:1
	v_cndmask_b32_e64 v74, v72, v73, s[8:9]
	v_cndmask_b32_e64 v72, v73, v72, s[8:9]
	s_nop 1
	v_mov_b32_dpp v72, v72 row_mirror row_mask:0xf bank_mask:0xf bound_ctrl:1
	v_and_b32_e32 v76, 2, v124
	s_nop 0
	v_add_f32_dpp v72, v72, v74 row_half_mirror row_mask:0xf bank_mask:0xf bound_ctrl:1
	ds_bpermute_b32 v73, v125, v72
	v_cmp_eq_u32_e64 s[14:15], v106, v76
	s_waitcnt lgkmcnt(0)
	v_add_f32_e32 v72, v72, v73
	ds_bpermute_b32 v73, v126, v72
	s_waitcnt vmcnt(15)
	v_cvt_scalef32_pk_f32_fp4 v[74:75], v20, 1.0 op_sel:[1,0,0]
	v_pk_mul_f32 v[74:75], v[74:75], v[6:7]
	s_waitcnt lgkmcnt(0)
	v_add_f32_e32 v72, v72, v73
	v_cndmask_b32_e64 v73, v72, v128, s[12:13]
	v_cndmask_b32_e64 v77, v128, v73, s[14:15]
	s_and_b64 s[14:15], s[14:15], s[12:13]
	v_cndmask_b32_e64 v78, v129, v72, s[14:15]
	v_cvt_scalef32_pk_f32_fp4 v[72:73], v20, 1.0
	v_pk_fma_f32 v[72:73], v[72:73], v[4:5], v[74:75]
	v_cvt_scalef32_pk_f32_fp4 v[74:75], v20, 1.0 op_sel:[0,1,0]
	v_pk_fma_f32 v[72:73], v[74:75], v[8:9], v[72:73]
	v_cvt_scalef32_pk_f32_fp4 v[74:75], v20, 1.0 op_sel:[1,1,0]
	v_pk_fma_f32 v[72:73], v[74:75], v[10:11], v[72:73]
	v_cvt_scalef32_pk_f32_fp4 v[74:75], v21, 1.0
	v_pk_fma_f32 v[72:73], v[74:75], v[12:13], v[72:73]
	v_cvt_scalef32_pk_f32_fp4 v[74:75], v21, 1.0 op_sel:[1,0,0]
	v_pk_fma_f32 v[72:73], v[74:75], v[14:15], v[72:73]
	v_cvt_scalef32_pk_f32_fp4 v[74:75], v21, 1.0 op_sel:[0,1,0]
	v_pk_fma_f32 v[72:73], v[74:75], v[16:17], v[72:73]
	v_cvt_scalef32_pk_f32_fp4 v[20:21], v21, 1.0 op_sel:[1,1,0]
	v_pk_fma_f32 v[20:21], v[20:21], v[18:19], v[72:73]
	s_waitcnt vmcnt(14)
	v_cvt_scalef32_pk_f32_fp4 v[72:73], v22, 1.0 op_sel:[1,0,0]
	v_add_f32_e32 v74, v20, v21
	v_cvt_scalef32_pk_f32_fp4 v[20:21], v22, 1.0
	v_pk_mul_f32 v[72:73], v[72:73], v[6:7]
	s_nop 0
	v_pk_fma_f32 v[20:21], v[20:21], v[4:5], v[72:73]
	v_cvt_scalef32_pk_f32_fp4 v[72:73], v22, 1.0 op_sel:[0,1,0]
	v_pk_fma_f32 v[20:21], v[72:73], v[8:9], v[20:21]
	v_cvt_scalef32_pk_f32_fp4 v[72:73], v22, 1.0 op_sel:[1,1,0]
	v_pk_fma_f32 v[20:21], v[72:73], v[10:11], v[20:21]
	v_cvt_scalef32_pk_f32_fp4 v[72:73], v23, 1.0
	v_pk_fma_f32 v[20:21], v[72:73], v[12:13], v[20:21]
	v_cvt_scalef32_pk_f32_fp4 v[72:73], v23, 1.0 op_sel:[1,0,0]
	v_pk_fma_f32 v[20:21], v[72:73], v[14:15], v[20:21]
	v_cvt_scalef32_pk_f32_fp4 v[72:73], v23, 1.0 op_sel:[0,1,0]
	v_pk_fma_f32 v[20:21], v[72:73], v[16:17], v[20:21]
	v_cvt_scalef32_pk_f32_fp4 v[22:23], v23, 1.0 op_sel:[1,1,0]
	v_pk_fma_f32 v[20:21], v[22:23], v[18:19], v[20:21]
	s_waitcnt vmcnt(13)
	v_cvt_scalef32_pk_f32_fp4 v[22:23], v24, 1.0 op_sel:[1,0,0]
	v_add_f32_e32 v72, v20, v21
	v_cvt_scalef32_pk_f32_fp4 v[20:21], v24, 1.0
	v_pk_mul_f32 v[22:23], v[22:23], v[6:7]
	s_nop 0
	v_pk_fma_f32 v[20:21], v[20:21], v[4:5], v[22:23]
	v_cvt_scalef32_pk_f32_fp4 v[22:23], v24, 1.0 op_sel:[0,1,0]
	v_pk_fma_f32 v[20:21], v[22:23], v[8:9], v[20:21]
	v_cvt_scalef32_pk_f32_fp4 v[22:23], v24, 1.0 op_sel:[1,1,0]
	v_pk_fma_f32 v[20:21], v[22:23], v[10:11], v[20:21]
	v_cvt_scalef32_pk_f32_fp4 v[22:23], v25, 1.0
	v_pk_fma_f32 v[20:21], v[22:23], v[12:13], v[20:21]
	v_cvt_scalef32_pk_f32_fp4 v[22:23], v25, 1.0 op_sel:[1,0,0]
	v_pk_fma_f32 v[20:21], v[22:23], v[14:15], v[20:21]
	v_cvt_scalef32_pk_f32_fp4 v[22:23], v25, 1.0 op_sel:[0,1,0]
	v_pk_fma_f32 v[20:21], v[22:23], v[16:17], v[20:21]
	v_cvt_scalef32_pk_f32_fp4 v[22:23], v25, 1.0 op_sel:[1,1,0]
	v_pk_fma_f32 v[20:21], v[22:23], v[18:19], v[20:21]
	s_waitcnt vmcnt(12)
	v_cvt_scalef32_pk_f32_fp4 v[22:23], v26, 1.0 op_sel:[1,0,0]
	v_add_f32_e32 v24, v20, v21
	v_cvt_scalef32_pk_f32_fp4 v[20:21], v26, 1.0
	v_pk_mul_f32 v[22:23], v[22:23], v[6:7]
	s_nop 0
	v_pk_fma_f32 v[20:21], v[20:21], v[4:5], v[22:23]
	v_cvt_scalef32_pk_f32_fp4 v[22:23], v26, 1.0 op_sel:[0,1,0]
	v_pk_fma_f32 v[20:21], v[22:23], v[8:9], v[20:21]
	v_cvt_scalef32_pk_f32_fp4 v[22:23], v26, 1.0 op_sel:[1,1,0]
	v_pk_fma_f32 v[20:21], v[22:23], v[10:11], v[20:21]
	v_cvt_scalef32_pk_f32_fp4 v[22:23], v27, 1.0
	v_pk_fma_f32 v[20:21], v[22:23], v[12:13], v[20:21]
	v_cvt_scalef32_pk_f32_fp4 v[22:23], v27, 1.0 op_sel:[1,0,0]
	v_pk_fma_f32 v[20:21], v[22:23], v[14:15], v[20:21]
	v_cvt_scalef32_pk_f32_fp4 v[22:23], v27, 1.0 op_sel:[0,1,0]
	v_pk_fma_f32 v[20:21], v[22:23], v[16:17], v[20:21]
	v_cvt_scalef32_pk_f32_fp4 v[22:23], v27, 1.0 op_sel:[1,1,0]
	v_pk_fma_f32 v[20:21], v[22:23], v[18:19], v[20:21]
	s_waitcnt vmcnt(11)
	v_cvt_scalef32_pk_f32_fp4 v[22:23], v28, 1.0 op_sel:[1,0,0]
	v_add_f32_e32 v25, v20, v21
	v_cvt_scalef32_pk_f32_fp4 v[20:21], v28, 1.0
	v_pk_mul_f32 v[22:23], v[22:23], v[6:7]
	s_nop 0
	v_pk_fma_f32 v[20:21], v[20:21], v[4:5], v[22:23]
	v_cvt_scalef32_pk_f32_fp4 v[22:23], v28, 1.0 op_sel:[0,1,0]
	v_pk_fma_f32 v[20:21], v[22:23], v[8:9], v[20:21]
	v_cvt_scalef32_pk_f32_fp4 v[22:23], v28, 1.0 op_sel:[1,1,0]
	v_pk_fma_f32 v[20:21], v[22:23], v[10:11], v[20:21]
	v_cvt_scalef32_pk_f32_fp4 v[22:23], v29, 1.0
	v_pk_fma_f32 v[20:21], v[22:23], v[12:13], v[20:21]
	v_cvt_scalef32_pk_f32_fp4 v[22:23], v29, 1.0 op_sel:[1,0,0]
	v_pk_fma_f32 v[20:21], v[22:23], v[14:15], v[20:21]
	v_cvt_scalef32_pk_f32_fp4 v[22:23], v29, 1.0 op_sel:[0,1,0]
	v_pk_fma_f32 v[20:21], v[22:23], v[16:17], v[20:21]
	v_cvt_scalef32_pk_f32_fp4 v[22:23], v29, 1.0 op_sel:[1,1,0]
	v_pk_fma_f32 v[20:21], v[22:23], v[18:19], v[20:21]
	s_waitcnt vmcnt(10)
	v_cvt_scalef32_pk_f32_fp4 v[22:23], v30, 1.0 op_sel:[1,0,0]
	v_add_f32_e32 v26, v20, v21
	v_cvt_scalef32_pk_f32_fp4 v[20:21], v30, 1.0
	v_pk_mul_f32 v[22:23], v[22:23], v[6:7]
	v_add_u32_e32 v124, 2, v124
	v_pk_fma_f32 v[20:21], v[20:21], v[4:5], v[22:23]
	v_cvt_scalef32_pk_f32_fp4 v[22:23], v30, 1.0 op_sel:[0,1,0]
	v_pk_fma_f32 v[20:21], v[22:23], v[8:9], v[20:21]
	v_cvt_scalef32_pk_f32_fp4 v[22:23], v30, 1.0 op_sel:[1,1,0]
	v_pk_fma_f32 v[20:21], v[22:23], v[10:11], v[20:21]
	v_cvt_scalef32_pk_f32_fp4 v[22:23], v31, 1.0
	v_pk_fma_f32 v[20:21], v[22:23], v[12:13], v[20:21]
	v_cvt_scalef32_pk_f32_fp4 v[22:23], v31, 1.0 op_sel:[1,0,0]
	v_pk_fma_f32 v[20:21], v[22:23], v[14:15], v[20:21]
	v_cvt_scalef32_pk_f32_fp4 v[22:23], v31, 1.0 op_sel:[0,1,0]
	v_pk_fma_f32 v[20:21], v[22:23], v[16:17], v[20:21]
	v_cvt_scalef32_pk_f32_fp4 v[22:23], v31, 1.0 op_sel:[1,1,0]
	v_pk_fma_f32 v[20:21], v[22:23], v[18:19], v[20:21]
	s_waitcnt vmcnt(9)
	v_cvt_scalef32_pk_f32_fp4 v[22:23], v32, 1.0 op_sel:[1,0,0]
	v_add_f32_e32 v27, v20, v21
	v_cvt_scalef32_pk_f32_fp4 v[20:21], v32, 1.0
	v_pk_mul_f32 v[22:23], v[22:23], v[6:7]
	s_nop 0
	v_pk_fma_f32 v[20:21], v[20:21], v[4:5], v[22:23]
	v_cvt_scalef32_pk_f32_fp4 v[22:23], v32, 1.0 op_sel:[0,1,0]
	v_pk_fma_f32 v[20:21], v[22:23], v[8:9], v[20:21]
	v_cvt_scalef32_pk_f32_fp4 v[22:23], v32, 1.0 op_sel:[1,1,0]
	v_pk_fma_f32 v[20:21], v[22:23], v[10:11], v[20:21]
	v_cvt_scalef32_pk_f32_fp4 v[22:23], v33, 1.0
	v_pk_fma_f32 v[20:21], v[22:23], v[12:13], v[20:21]
	v_cvt_scalef32_pk_f32_fp4 v[22:23], v33, 1.0 op_sel:[1,0,0]
	v_pk_fma_f32 v[20:21], v[22:23], v[14:15], v[20:21]
	v_cvt_scalef32_pk_f32_fp4 v[22:23], v33, 1.0 op_sel:[0,1,0]
	v_pk_fma_f32 v[20:21], v[22:23], v[16:17], v[20:21]
	v_cvt_scalef32_pk_f32_fp4 v[22:23], v33, 1.0 op_sel:[1,1,0]
	v_pk_fma_f32 v[20:21], v[22:23], v[18:19], v[20:21]
	s_waitcnt vmcnt(8)
	v_cvt_scalef32_pk_f32_fp4 v[22:23], v34, 1.0 op_sel:[1,0,0]
	v_add_f32_e32 v28, v20, v21
	v_cvt_scalef32_pk_f32_fp4 v[20:21], v34, 1.0
	v_pk_mul_f32 v[22:23], v[22:23], v[6:7]
	s_nop 0
	v_pk_fma_f32 v[20:21], v[20:21], v[4:5], v[22:23]
	v_cvt_scalef32_pk_f32_fp4 v[22:23], v34, 1.0 op_sel:[0,1,0]
	v_pk_fma_f32 v[20:21], v[22:23], v[8:9], v[20:21]
	v_cvt_scalef32_pk_f32_fp4 v[22:23], v34, 1.0 op_sel:[1,1,0]
	v_pk_fma_f32 v[20:21], v[22:23], v[10:11], v[20:21]
	v_cvt_scalef32_pk_f32_fp4 v[22:23], v35, 1.0
	v_pk_fma_f32 v[20:21], v[22:23], v[12:13], v[20:21]
	v_cvt_scalef32_pk_f32_fp4 v[22:23], v35, 1.0 op_sel:[1,0,0]
	v_pk_fma_f32 v[20:21], v[22:23], v[14:15], v[20:21]
	v_cvt_scalef32_pk_f32_fp4 v[22:23], v35, 1.0 op_sel:[0,1,0]
	v_pk_fma_f32 v[20:21], v[22:23], v[16:17], v[20:21]
	v_cvt_scalef32_pk_f32_fp4 v[22:23], v35, 1.0 op_sel:[1,1,0]
	v_pk_fma_f32 v[20:21], v[22:23], v[18:19], v[20:21]
	s_waitcnt vmcnt(7)
	v_cvt_scalef32_pk_f32_fp4 v[22:23], v56, 1.0 op_sel:[1,0,0]
	v_add_f32_e32 v29, v20, v21
	v_cvt_scalef32_pk_f32_fp4 v[20:21], v56, 1.0
	v_pk_mul_f32 v[22:23], v[22:23], v[6:7]
	s_nop 0
	v_pk_fma_f32 v[20:21], v[20:21], v[4:5], v[22:23]
	v_cvt_scalef32_pk_f32_fp4 v[22:23], v56, 1.0 op_sel:[0,1,0]
	v_pk_fma_f32 v[20:21], v[22:23], v[8:9], v[20:21]
	v_cvt_scalef32_pk_f32_fp4 v[22:23], v56, 1.0 op_sel:[1,1,0]
	v_pk_fma_f32 v[20:21], v[22:23], v[10:11], v[20:21]
	v_cvt_scalef32_pk_f32_fp4 v[22:23], v57, 1.0
	v_pk_fma_f32 v[20:21], v[22:23], v[12:13], v[20:21]
	v_cvt_scalef32_pk_f32_fp4 v[22:23], v57, 1.0 op_sel:[1,0,0]
	v_pk_fma_f32 v[20:21], v[22:23], v[14:15], v[20:21]
	v_cvt_scalef32_pk_f32_fp4 v[22:23], v57, 1.0 op_sel:[0,1,0]
	v_pk_fma_f32 v[20:21], v[22:23], v[16:17], v[20:21]
	v_cvt_scalef32_pk_f32_fp4 v[22:23], v57, 1.0 op_sel:[1,1,0]
	v_pk_fma_f32 v[20:21], v[22:23], v[18:19], v[20:21]
	s_waitcnt vmcnt(6)
	v_cvt_scalef32_pk_f32_fp4 v[22:23], v58, 1.0 op_sel:[1,0,0]
	v_add_f32_e32 v30, v20, v21
	v_cvt_scalef32_pk_f32_fp4 v[20:21], v58, 1.0
	v_pk_mul_f32 v[22:23], v[22:23], v[6:7]
	s_nop 0
	v_pk_fma_f32 v[20:21], v[20:21], v[4:5], v[22:23]
	v_cvt_scalef32_pk_f32_fp4 v[22:23], v58, 1.0 op_sel:[0,1,0]
	v_pk_fma_f32 v[20:21], v[22:23], v[8:9], v[20:21]
	v_cvt_scalef32_pk_f32_fp4 v[22:23], v58, 1.0 op_sel:[1,1,0]
	v_pk_fma_f32 v[20:21], v[22:23], v[10:11], v[20:21]
	v_cvt_scalef32_pk_f32_fp4 v[22:23], v59, 1.0
	v_pk_fma_f32 v[20:21], v[22:23], v[12:13], v[20:21]
	v_cvt_scalef32_pk_f32_fp4 v[22:23], v59, 1.0 op_sel:[1,0,0]
	v_pk_fma_f32 v[20:21], v[22:23], v[14:15], v[20:21]
	v_cvt_scalef32_pk_f32_fp4 v[22:23], v59, 1.0 op_sel:[0,1,0]
	v_pk_fma_f32 v[20:21], v[22:23], v[16:17], v[20:21]
	v_cvt_scalef32_pk_f32_fp4 v[22:23], v59, 1.0 op_sel:[1,1,0]
	v_pk_fma_f32 v[20:21], v[22:23], v[18:19], v[20:21]
	s_waitcnt vmcnt(5)
	v_cvt_scalef32_pk_f32_fp4 v[22:23], v60, 1.0 op_sel:[1,0,0]
	v_add_f32_e32 v31, v20, v21
	v_cvt_scalef32_pk_f32_fp4 v[20:21], v60, 1.0
	v_pk_mul_f32 v[22:23], v[22:23], v[6:7]
	s_nop 0
	v_pk_fma_f32 v[20:21], v[20:21], v[4:5], v[22:23]
	v_cvt_scalef32_pk_f32_fp4 v[22:23], v60, 1.0 op_sel:[0,1,0]
	v_pk_fma_f32 v[20:21], v[22:23], v[8:9], v[20:21]
	v_cvt_scalef32_pk_f32_fp4 v[22:23], v60, 1.0 op_sel:[1,1,0]
	v_pk_fma_f32 v[20:21], v[22:23], v[10:11], v[20:21]
	v_cvt_scalef32_pk_f32_fp4 v[22:23], v61, 1.0
	v_pk_fma_f32 v[20:21], v[22:23], v[12:13], v[20:21]
	v_cvt_scalef32_pk_f32_fp4 v[22:23], v61, 1.0 op_sel:[1,0,0]
	v_pk_fma_f32 v[20:21], v[22:23], v[14:15], v[20:21]
	v_cvt_scalef32_pk_f32_fp4 v[22:23], v61, 1.0 op_sel:[0,1,0]
	v_pk_fma_f32 v[20:21], v[22:23], v[16:17], v[20:21]
	v_cvt_scalef32_pk_f32_fp4 v[22:23], v61, 1.0 op_sel:[1,1,0]
	v_pk_fma_f32 v[20:21], v[22:23], v[18:19], v[20:21]
	s_waitcnt vmcnt(4)
	v_cvt_scalef32_pk_f32_fp4 v[22:23], v62, 1.0 op_sel:[1,0,0]
	v_add_f32_e32 v32, v20, v21
	v_cvt_scalef32_pk_f32_fp4 v[20:21], v62, 1.0
	v_pk_mul_f32 v[22:23], v[22:23], v[6:7]
	s_nop 0
	v_pk_fma_f32 v[20:21], v[20:21], v[4:5], v[22:23]
	v_cvt_scalef32_pk_f32_fp4 v[22:23], v62, 1.0 op_sel:[0,1,0]
	v_pk_fma_f32 v[20:21], v[22:23], v[8:9], v[20:21]
	v_cvt_scalef32_pk_f32_fp4 v[22:23], v62, 1.0 op_sel:[1,1,0]
	v_pk_fma_f32 v[20:21], v[22:23], v[10:11], v[20:21]
	v_cvt_scalef32_pk_f32_fp4 v[22:23], v63, 1.0
	v_pk_fma_f32 v[20:21], v[22:23], v[12:13], v[20:21]
	v_cvt_scalef32_pk_f32_fp4 v[22:23], v63, 1.0 op_sel:[1,0,0]
	v_pk_fma_f32 v[20:21], v[22:23], v[14:15], v[20:21]
	v_cvt_scalef32_pk_f32_fp4 v[22:23], v63, 1.0 op_sel:[0,1,0]
	v_pk_fma_f32 v[20:21], v[22:23], v[16:17], v[20:21]
	v_cvt_scalef32_pk_f32_fp4 v[22:23], v63, 1.0 op_sel:[1,1,0]
	v_pk_fma_f32 v[20:21], v[22:23], v[18:19], v[20:21]
	s_waitcnt vmcnt(3)
	v_cvt_scalef32_pk_f32_fp4 v[22:23], v64, 1.0 op_sel:[1,0,0]
	v_add_f32_e32 v33, v20, v21
	v_cvt_scalef32_pk_f32_fp4 v[20:21], v64, 1.0
	v_pk_mul_f32 v[22:23], v[22:23], v[6:7]
	s_nop 0
	v_pk_fma_f32 v[20:21], v[20:21], v[4:5], v[22:23]
	v_cvt_scalef32_pk_f32_fp4 v[22:23], v64, 1.0 op_sel:[0,1,0]
	v_pk_fma_f32 v[20:21], v[22:23], v[8:9], v[20:21]
	v_cvt_scalef32_pk_f32_fp4 v[22:23], v64, 1.0 op_sel:[1,1,0]
	v_pk_fma_f32 v[20:21], v[22:23], v[10:11], v[20:21]
	v_cvt_scalef32_pk_f32_fp4 v[22:23], v65, 1.0
	v_pk_fma_f32 v[20:21], v[22:23], v[12:13], v[20:21]
	v_cvt_scalef32_pk_f32_fp4 v[22:23], v65, 1.0 op_sel:[1,0,0]
	v_pk_fma_f32 v[20:21], v[22:23], v[14:15], v[20:21]
	v_cvt_scalef32_pk_f32_fp4 v[22:23], v65, 1.0 op_sel:[0,1,0]
	v_pk_fma_f32 v[20:21], v[22:23], v[16:17], v[20:21]
	v_cvt_scalef32_pk_f32_fp4 v[22:23], v65, 1.0 op_sel:[1,1,0]
	v_pk_fma_f32 v[20:21], v[22:23], v[18:19], v[20:21]
	s_waitcnt vmcnt(2)
	v_cvt_scalef32_pk_f32_fp4 v[22:23], v66, 1.0 op_sel:[1,0,0]
	v_add_f32_e32 v34, v20, v21
	v_cvt_scalef32_pk_f32_fp4 v[20:21], v66, 1.0
	v_pk_mul_f32 v[22:23], v[22:23], v[6:7]
	s_nop 0
	v_pk_fma_f32 v[20:21], v[20:21], v[4:5], v[22:23]
	v_cvt_scalef32_pk_f32_fp4 v[22:23], v66, 1.0 op_sel:[0,1,0]
	v_pk_fma_f32 v[20:21], v[22:23], v[8:9], v[20:21]
	v_cvt_scalef32_pk_f32_fp4 v[22:23], v66, 1.0 op_sel:[1,1,0]
	v_pk_fma_f32 v[20:21], v[22:23], v[10:11], v[20:21]
	v_cvt_scalef32_pk_f32_fp4 v[22:23], v67, 1.0
	v_pk_fma_f32 v[20:21], v[22:23], v[12:13], v[20:21]
	v_cvt_scalef32_pk_f32_fp4 v[22:23], v67, 1.0 op_sel:[1,0,0]
	v_pk_fma_f32 v[20:21], v[22:23], v[14:15], v[20:21]
	v_cvt_scalef32_pk_f32_fp4 v[22:23], v67, 1.0 op_sel:[0,1,0]
	v_pk_fma_f32 v[20:21], v[22:23], v[16:17], v[20:21]
	v_cvt_scalef32_pk_f32_fp4 v[22:23], v67, 1.0 op_sel:[1,1,0]
	v_pk_fma_f32 v[20:21], v[22:23], v[18:19], v[20:21]
	s_waitcnt vmcnt(1)
	v_cvt_scalef32_pk_f32_fp4 v[22:23], v68, 1.0 op_sel:[1,0,0]
	v_add_f32_e32 v35, v20, v21
	v_cvt_scalef32_pk_f32_fp4 v[20:21], v68, 1.0
	v_pk_mul_f32 v[22:23], v[22:23], v[6:7]
	s_nop 0
	v_pk_fma_f32 v[20:21], v[20:21], v[4:5], v[22:23]
	v_cvt_scalef32_pk_f32_fp4 v[22:23], v68, 1.0 op_sel:[0,1,0]
	v_pk_fma_f32 v[20:21], v[22:23], v[8:9], v[20:21]
	v_cvt_scalef32_pk_f32_fp4 v[22:23], v68, 1.0 op_sel:[1,1,0]
	v_pk_fma_f32 v[20:21], v[22:23], v[10:11], v[20:21]
	v_cvt_scalef32_pk_f32_fp4 v[22:23], v69, 1.0
	v_pk_fma_f32 v[20:21], v[22:23], v[12:13], v[20:21]
	v_cvt_scalef32_pk_f32_fp4 v[22:23], v69, 1.0 op_sel:[1,0,0]
	v_pk_fma_f32 v[20:21], v[22:23], v[14:15], v[20:21]
	v_cvt_scalef32_pk_f32_fp4 v[22:23], v69, 1.0 op_sel:[0,1,0]
	v_pk_fma_f32 v[20:21], v[22:23], v[16:17], v[20:21]
	v_cvt_scalef32_pk_f32_fp4 v[22:23], v69, 1.0 op_sel:[1,1,0]
	v_pk_fma_f32 v[20:21], v[22:23], v[18:19], v[20:21]
	s_waitcnt vmcnt(0)
	v_cvt_scalef32_pk_f32_fp4 v[22:23], v70, 1.0 op_sel:[1,0,0]
	v_add_f32_e32 v56, v20, v21
	v_cvt_scalef32_pk_f32_fp4 v[20:21], v70, 1.0
	v_pk_mul_f32 v[22:23], v[22:23], v[6:7]
	s_nop 0
	v_pk_fma_f32 v[20:21], v[20:21], v[4:5], v[22:23]
	v_cvt_scalef32_pk_f32_fp4 v[22:23], v70, 1.0 op_sel:[0,1,0]
	v_pk_fma_f32 v[20:21], v[22:23], v[8:9], v[20:21]
	v_cvt_scalef32_pk_f32_fp4 v[22:23], v70, 1.0 op_sel:[1,1,0]
	v_pk_fma_f32 v[20:21], v[22:23], v[10:11], v[20:21]
	v_cvt_scalef32_pk_f32_fp4 v[22:23], v71, 1.0
	v_pk_fma_f32 v[20:21], v[22:23], v[12:13], v[20:21]
	v_cvt_scalef32_pk_f32_fp4 v[22:23], v71, 1.0 op_sel:[1,0,0]
	v_pk_fma_f32 v[20:21], v[22:23], v[14:15], v[20:21]
	v_cvt_scalef32_pk_f32_fp4 v[22:23], v71, 1.0 op_sel:[0,1,0]
	v_pk_fma_f32 v[20:21], v[22:23], v[16:17], v[20:21]
	v_cvt_scalef32_pk_f32_fp4 v[22:23], v71, 1.0 op_sel:[1,1,0]
	v_pk_fma_f32 v[20:21], v[22:23], v[18:19], v[20:21]
	v_cndmask_b32_e64 v22, v74, v30, s[0:1]
	v_add_f32_e32 v20, v20, v21
	v_cndmask_b32_e64 v21, v30, v74, s[0:1]
	v_cndmask_b32_e64 v23, v72, v31, s[0:1]
	s_nop 0
	v_add_f32_dpp v21, v22, v21 quad_perm:[1,0,3,2] row_mask:0xf bank_mask:0xf bound_ctrl:1
	v_cndmask_b32_e64 v22, v31, v72, s[0:1]
	s_nop 1
	v_add_f32_dpp v22, v23, v22 quad_perm:[1,0,3,2] row_mask:0xf bank_mask:0xf bound_ctrl:1
	v_cndmask_b32_e64 v23, v32, v24, s[0:1]
	v_cndmask_b32_e64 v24, v24, v32, s[0:1]
	s_nop 1
	v_add_f32_dpp v23, v24, v23 quad_perm:[1,0,3,2] row_mask:0xf bank_mask:0xf bound_ctrl:1
	v_cndmask_b32_e64 v24, v33, v25, s[0:1]
	v_cndmask_b32_e64 v25, v25, v33, s[0:1]
	s_nop 1
	v_add_f32_dpp v24, v25, v24 quad_perm:[1,0,3,2] row_mask:0xf bank_mask:0xf bound_ctrl:1
	v_cndmask_b32_e64 v25, v34, v26, s[0:1]
	v_cndmask_b32_e64 v26, v26, v34, s[0:1]
	s_nop 1
	v_add_f32_dpp v25, v26, v25 quad_perm:[1,0,3,2] row_mask:0xf bank_mask:0xf bound_ctrl:1
	v_cndmask_b32_e64 v26, v35, v27, s[0:1]
	v_cndmask_b32_e64 v27, v27, v35, s[0:1]
	s_nop 1
	v_add_f32_dpp v26, v27, v26 quad_perm:[1,0,3,2] row_mask:0xf bank_mask:0xf bound_ctrl:1
	v_cndmask_b32_e64 v27, v56, v28, s[0:1]
	v_cndmask_b32_e64 v28, v28, v56, s[0:1]
	s_nop 1
	v_add_f32_dpp v27, v28, v27 quad_perm:[1,0,3,2] row_mask:0xf bank_mask:0xf bound_ctrl:1
	v_cndmask_b32_e64 v28, v20, v29, s[0:1]
	v_cndmask_b32_e64 v20, v29, v20, s[0:1]
	s_nop 1
	v_add_f32_dpp v20, v20, v28 quad_perm:[1,0,3,2] row_mask:0xf bank_mask:0xf bound_ctrl:1
	v_cndmask_b32_e64 v28, v25, v21, s[4:5]
	v_cndmask_b32_e64 v21, v21, v25, s[4:5]
	v_cndmask_b32_e64 v25, v26, v22, s[4:5]
	v_cndmask_b32_e64 v22, v22, v26, s[4:5]
	v_add_f32_dpp v21, v21, v28 quad_perm:[2,3,0,1] row_mask:0xf bank_mask:0xf bound_ctrl:1
	s_nop 0
	v_add_f32_dpp v22, v22, v25 quad_perm:[2,3,0,1] row_mask:0xf bank_mask:0xf bound_ctrl:1
	v_cndmask_b32_e64 v25, v27, v23, s[4:5]
	v_cndmask_b32_e64 v23, v23, v27, s[4:5]
	s_nop 1
	v_add_f32_dpp v23, v23, v25 quad_perm:[2,3,0,1] row_mask:0xf bank_mask:0xf bound_ctrl:1
	v_cndmask_b32_e64 v25, v20, v24, s[4:5]
	v_cndmask_b32_e64 v20, v24, v20, s[4:5]
	v_cndmask_b32_e64 v24, v23, v21, s[6:7]
	v_cndmask_b32_e64 v21, v21, v23, s[6:7]
	v_add_f32_dpp v20, v20, v25 quad_perm:[2,3,0,1] row_mask:0xf bank_mask:0xf bound_ctrl:1
	v_cndmask_b32_e64 v23, v20, v22, s[6:7]
	v_cndmask_b32_e64 v20, v22, v20, s[6:7]
	v_mov_b32_dpp v21, v21 row_half_mirror row_mask:0xf bank_mask:0xf bound_ctrl:1
	s_nop 0
	v_mov_b32_dpp v20, v20 row_half_mirror row_mask:0xf bank_mask:0xf bound_ctrl:1
	v_add_f32_dpp v21, v21, v24 quad_perm:[3,2,1,0] row_mask:0xf bank_mask:0xf bound_ctrl:1
	s_nop 0
	v_add_f32_dpp v20, v20, v23 quad_perm:[3,2,1,0] row_mask:0xf bank_mask:0xf bound_ctrl:1
	v_cndmask_b32_e64 v22, v20, v21, s[8:9]
	v_cndmask_b32_e64 v20, v21, v20, s[8:9]
	s_nop 1
	v_mov_b32_dpp v20, v20 row_mirror row_mask:0xf bank_mask:0xf bound_ctrl:1
	s_nop 1
	v_add_f32_dpp v20, v20, v22 row_half_mirror row_mask:0xf bank_mask:0xf bound_ctrl:1
	ds_bpermute_b32 v21, v125, v20
	s_waitcnt lgkmcnt(0)
	v_add_f32_e32 v20, v20, v21
	ds_bpermute_b32 v21, v126, v20
	s_waitcnt lgkmcnt(0)
	v_add_f32_e32 v20, v20, v21
	v_or_b32_e32 v21, 1, v76
	v_cmp_eq_u32_e64 s[14:15], v106, v21
	v_cndmask_b32_e64 v21, v20, v77, s[12:13]
	s_and_b64 s[12:13], s[14:15], s[12:13]
	v_cndmask_b32_e64 v129, v78, v20, s[12:13]
	v_cmp_ge_u32_e64 s[12:13], v127, v115
	v_cndmask_b32_e64 v128, v77, v21, s[14:15]
	s_or_b64 s[28:29], s[12:13], s[28:29]
.Lh3_u10_join:
	s_andn2_b64 exec, exec, s[28:29]
	s_cbranch_execnz .LBB0_2100
	s_or_b64 exec, exec, s[28:29]

.LBB0_2112:
	v_cmp_gt_u32_e32 vcc, 64, v116
	s_nop 1
	v_cndmask_b32_e32 v102, v118, v117, vcc
	v_readfirstlane_b32 s92, v116
	s_nop 1
	s_and_b32 s92, s92, 32
	s_cbranch_scc1 .Lh3_v10_hi
	v_readlane_b32 s84, v102, 0
	v_readlane_b32 s86, v102, 1
	v_readlane_b32 s88, v102, 2
	v_readlane_b32 s90, v102, 3
	s_ashr_i32 s85, s84, 31
	s_ashr_i32 s87, s86, 31
	s_ashr_i32 s89, s88, 31
	s_ashr_i32 s91, s90, 31
	s_lshl_b64 s[84:85], s[84:85], 9
	s_lshl_b64 s[86:87], s[86:87], 9
	s_lshl_b64 s[88:89], s[88:89], 9
	s_lshl_b64 s[90:91], s[90:91], 9
	v_lshl_add_u64 v[20:21], v[40:41], 0, s[84:85]
	v_lshl_add_u64 v[22:23], v[40:41], 0, s[86:87]
	v_lshl_add_u64 v[24:25], v[40:41], 0, s[88:89]
	v_lshl_add_u64 v[26:27], v[40:41], 0, s[90:91]
	global_load_dwordx2 v[20:21], v[20:21], off
	global_load_dwordx2 v[22:23], v[22:23], off
	global_load_dwordx2 v[24:25], v[24:25], off
	global_load_dwordx2 v[26:27], v[26:27], off
	v_readlane_b32 s84, v102, 4
	v_readlane_b32 s86, v102, 5
	v_readlane_b32 s88, v102, 6
	v_readlane_b32 s90, v102, 7
	s_ashr_i32 s85, s84, 31
	s_ashr_i32 s87, s86, 31
	s_ashr_i32 s89, s88, 31
	s_ashr_i32 s91, s90, 31
	s_lshl_b64 s[84:85], s[84:85], 9
	s_lshl_b64 s[86:87], s[86:87], 9
	s_lshl_b64 s[88:89], s[88:89], 9
	s_lshl_b64 s[90:91], s[90:91], 9
	v_lshl_add_u64 v[28:29], v[40:41], 0, s[84:85]
	v_lshl_add_u64 v[30:31], v[40:41], 0, s[86:87]
	v_lshl_add_u64 v[32:33], v[40:41], 0, s[88:89]
	v_lshl_add_u64 v[34:35], v[40:41], 0, s[90:91]
	global_load_dwordx2 v[28:29], v[28:29], off
	global_load_dwordx2 v[30:31], v[30:31], off
	global_load_dwordx2 v[32:33], v[32:33], off
	global_load_dwordx2 v[34:35], v[34:35], off
	v_readlane_b32 s84, v102, 8
	v_readlane_b32 s86, v102, 9
	v_readlane_b32 s88, v102, 10
	v_readlane_b32 s90, v102, 11
	s_ashr_i32 s85, s84, 31
	s_ashr_i32 s87, s86, 31
	s_ashr_i32 s89, s88, 31
	s_ashr_i32 s91, s90, 31
	s_lshl_b64 s[84:85], s[84:85], 9
	s_lshl_b64 s[86:87], s[86:87], 9
	s_lshl_b64 s[88:89], s[88:89], 9
	s_lshl_b64 s[90:91], s[90:91], 9
	v_lshl_add_u64 v[56:57], v[40:41], 0, s[84:85]
	v_lshl_add_u64 v[58:59], v[40:41], 0, s[86:87]
	v_lshl_add_u64 v[60:61], v[40:41], 0, s[88:89]
	v_lshl_add_u64 v[62:63], v[40:41], 0, s[90:91]
	global_load_dwordx2 v[56:57], v[56:57], off
	global_load_dwordx2 v[58:59], v[58:59], off
	global_load_dwordx2 v[60:61], v[60:61], off
	global_load_dwordx2 v[62:63], v[62:63], off
	v_readlane_b32 s84, v102, 12
	v_readlane_b32 s86, v102, 13
	v_readlane_b32 s88, v102, 14
	v_readlane_b32 s90, v102, 15
	s_ashr_i32 s85, s84, 31
	s_ashr_i32 s87, s86, 31
	s_ashr_i32 s89, s88, 31
	s_ashr_i32 s91, s90, 31
	s_lshl_b64 s[84:85], s[84:85], 9
	s_lshl_b64 s[86:87], s[86:87], 9
	s_lshl_b64 s[88:89], s[88:89], 9
	s_lshl_b64 s[90:91], s[90:91], 9
	v_lshl_add_u64 v[64:65], v[40:41], 0, s[84:85]
	v_lshl_add_u64 v[66:67], v[40:41], 0, s[86:87]
	v_lshl_add_u64 v[68:69], v[40:41], 0, s[88:89]
	v_lshl_add_u64 v[70:71], v[40:41], 0, s[90:91]
	global_load_dwordx2 v[64:65], v[64:65], off
	global_load_dwordx2 v[66:67], v[66:67], off
	global_load_dwordx2 v[68:69], v[68:69], off
	global_load_dwordx2 v[70:71], v[70:71], off
	v_readlane_b32 s84, v102, 16
	v_readlane_b32 s86, v102, 17
	v_readlane_b32 s88, v102, 18
	v_readlane_b32 s90, v102, 19
	s_ashr_i32 s85, s84, 31
	s_ashr_i32 s87, s86, 31
	s_ashr_i32 s89, s88, 31
	s_ashr_i32 s91, s90, 31
	s_lshl_b64 s[84:85], s[84:85], 9
	s_lshl_b64 s[86:87], s[86:87], 9
	s_lshl_b64 s[88:89], s[88:89], 9
	s_lshl_b64 s[90:91], s[90:91], 9
	v_lshl_add_u64 v[72:73], v[40:41], 0, s[84:85]
	v_lshl_add_u64 v[74:75], v[40:41], 0, s[86:87]
	v_lshl_add_u64 v[76:77], v[40:41], 0, s[88:89]
	v_lshl_add_u64 v[78:79], v[40:41], 0, s[90:91]
	global_load_dwordx2 v[72:73], v[72:73], off
	global_load_dwordx2 v[74:75], v[74:75], off
	global_load_dwordx2 v[76:77], v[76:77], off
	global_load_dwordx2 v[78:79], v[78:79], off
	v_readlane_b32 s84, v102, 20
	v_readlane_b32 s86, v102, 21
	v_readlane_b32 s88, v102, 22
	v_readlane_b32 s90, v102, 23
	s_ashr_i32 s85, s84, 31
	s_ashr_i32 s87, s86, 31
	s_ashr_i32 s89, s88, 31
	s_ashr_i32 s91, s90, 31
	s_lshl_b64 s[84:85], s[84:85], 9
	s_lshl_b64 s[86:87], s[86:87], 9
	s_lshl_b64 s[88:89], s[88:89], 9
	s_lshl_b64 s[90:91], s[90:91], 9
	v_lshl_add_u64 v[80:81], v[40:41], 0, s[84:85]
	v_lshl_add_u64 v[82:83], v[40:41], 0, s[86:87]
	v_lshl_add_u64 v[84:85], v[40:41], 0, s[88:89]
	v_lshl_add_u64 v[86:87], v[40:41], 0, s[90:91]
	global_load_dwordx2 v[80:81], v[80:81], off
	global_load_dwordx2 v[82:83], v[82:83], off
	global_load_dwordx2 v[84:85], v[84:85], off
	global_load_dwordx2 v[86:87], v[86:87], off
	v_readlane_b32 s84, v102, 24
	v_readlane_b32 s86, v102, 25
	v_readlane_b32 s88, v102, 26
	v_readlane_b32 s90, v102, 27
	s_ashr_i32 s85, s84, 31
	s_ashr_i32 s87, s86, 31
	s_ashr_i32 s89, s88, 31
	s_ashr_i32 s91, s90, 31
	s_lshl_b64 s[84:85], s[84:85], 9
	s_lshl_b64 s[86:87], s[86:87], 9
	s_lshl_b64 s[88:89], s[88:89], 9
	s_lshl_b64 s[90:91], s[90:91], 9
	v_lshl_add_u64 v[88:89], v[40:41], 0, s[84:85]
	v_lshl_add_u64 v[90:91], v[40:41], 0, s[86:87]
	v_lshl_add_u64 v[92:93], v[40:41], 0, s[88:89]
	v_lshl_add_u64 v[94:95], v[40:41], 0, s[90:91]
	global_load_dwordx2 v[88:89], v[88:89], off
	global_load_dwordx2 v[90:91], v[90:91], off
	global_load_dwordx2 v[92:93], v[92:93], off
	global_load_dwordx2 v[94:95], v[94:95], off
	v_readlane_b32 s84, v102, 28
	v_readlane_b32 s86, v102, 29
	v_readlane_b32 s88, v102, 30
	v_readlane_b32 s90, v102, 31
	s_ashr_i32 s85, s84, 31
	s_ashr_i32 s87, s86, 31
	s_ashr_i32 s89, s88, 31
	s_ashr_i32 s91, s90, 31
	s_lshl_b64 s[84:85], s[84:85], 9
	s_lshl_b64 s[86:87], s[86:87], 9
	s_lshl_b64 s[88:89], s[88:89], 9
	s_lshl_b64 s[90:91], s[90:91], 9
	v_lshl_add_u64 v[96:97], v[40:41], 0, s[84:85]
	v_lshl_add_u64 v[98:99], v[40:41], 0, s[86:87]
	v_lshl_add_u64 v[100:101], v[40:41], 0, s[88:89]
	v_lshl_add_u64 v[102:103], v[40:41], 0, s[90:91]
	global_load_dwordx2 v[96:97], v[96:97], off
	global_load_dwordx2 v[98:99], v[98:99], off
	global_load_dwordx2 v[100:101], v[100:101], off
	global_load_dwordx2 v[102:103], v[102:103], off
	v_cndmask_b32_e32 v127, v3, v119, vcc
	s_waitcnt vmcnt(31)
	v_cvt_scalef32_pk_f32_fp4 v[130:131], v20, 1.0
	v_readlane_b32 s28, v127, 2
	v_readlane_b32 s2, v127, 3
	v_add_u32_e32 v116, 32, v116
	v_cmp_ge_u32_e32 vcc, v116, v115
	s_nop 0
	s_nop 0
	s_nop 0
	v_readlane_b32 s64, v127, 0
	s_or_b64 s[14:15], vcc, s[14:15]
	s_nop 0
	v_pk_fma_f32 v[4:5], v[130:131], s[64:65], v[4:5] op_sel_hi:[1,0,1]
	v_cvt_scalef32_pk_f32_fp4 v[130:131], v20, 1.0 op_sel:[1,0,0]
	v_pk_fma_f32 v[6:7], s[64:65], v[130:131], v[6:7] op_sel_hi:[0,1,1]
	v_cvt_scalef32_pk_f32_fp4 v[130:131], v20, 1.0 op_sel:[0,1,0]
	v_pk_fma_f32 v[8:9], s[64:65], v[130:131], v[8:9] op_sel_hi:[0,1,1]
	v_cvt_scalef32_pk_f32_fp4 v[130:131], v20, 1.0 op_sel:[1,1,0]
	v_pk_fma_f32 v[10:11], s[64:65], v[130:131], v[10:11] op_sel_hi:[0,1,1]
	v_cvt_scalef32_pk_f32_fp4 v[130:131], v21, 1.0
	v_pk_fma_f32 v[12:13], s[64:65], v[130:131], v[12:13] op_sel_hi:[0,1,1]
	v_cvt_scalef32_pk_f32_fp4 v[130:131], v21, 1.0 op_sel:[1,0,0]
	v_pk_fma_f32 v[14:15], s[64:65], v[130:131], v[14:15] op_sel_hi:[0,1,1]
	v_cvt_scalef32_pk_f32_fp4 v[130:131], v21, 1.0 op_sel:[0,1,0]
	v_cvt_scalef32_pk_f32_fp4 v[20:21], v21, 1.0 op_sel:[1,1,0]
	v_pk_fma_f32 v[16:17], s[64:65], v[130:131], v[16:17] op_sel_hi:[0,1,1]
	v_pk_fma_f32 v[18:19], s[64:65], v[20:21], v[18:19] op_sel_hi:[0,1,1]
	v_readlane_b32 s64, v127, 8
	s_waitcnt vmcnt(30)
	v_cvt_scalef32_pk_f32_fp4 v[20:21], v22, 1.0
	v_pk_fma_f32 v[4:5], v[20:21], s[64:65], v[4:5] op_sel_hi:[1,0,1]
	v_cvt_scalef32_pk_f32_fp4 v[20:21], v22, 1.0 op_sel:[1,0,0]
	v_pk_fma_f32 v[6:7], s[64:65], v[20:21], v[6:7] op_sel_hi:[0,1,1]
	v_cvt_scalef32_pk_f32_fp4 v[20:21], v22, 1.0 op_sel:[0,1,0]
	v_pk_fma_f32 v[8:9], s[64:65], v[20:21], v[8:9] op_sel_hi:[0,1,1]
	v_cvt_scalef32_pk_f32_fp4 v[20:21], v22, 1.0 op_sel:[1,1,0]
	v_pk_fma_f32 v[10:11], s[64:65], v[20:21], v[10:11] op_sel_hi:[0,1,1]
	v_cvt_scalef32_pk_f32_fp4 v[20:21], v23, 1.0
	v_pk_fma_f32 v[12:13], s[64:65], v[20:21], v[12:13] op_sel_hi:[0,1,1]
	v_cvt_scalef32_pk_f32_fp4 v[20:21], v23, 1.0 op_sel:[1,0,0]
	v_pk_fma_f32 v[14:15], s[64:65], v[20:21], v[14:15] op_sel_hi:[0,1,1]
	v_cvt_scalef32_pk_f32_fp4 v[20:21], v23, 1.0 op_sel:[0,1,0]
	v_pk_fma_f32 v[16:17], s[64:65], v[20:21], v[16:17] op_sel_hi:[0,1,1]
	v_cvt_scalef32_pk_f32_fp4 v[20:21], v23, 1.0 op_sel:[1,1,0]
	v_pk_fma_f32 v[18:19], s[64:65], v[20:21], v[18:19] op_sel_hi:[0,1,1]
	v_readlane_b32 s64, v127, 4
	s_waitcnt vmcnt(29)
	v_cvt_scalef32_pk_f32_fp4 v[20:21], v24, 1.0
	v_pk_fma_f32 v[4:5], v[20:21], s[64:65], v[4:5] op_sel_hi:[1,0,1]
	v_cvt_scalef32_pk_f32_fp4 v[20:21], v24, 1.0 op_sel:[1,0,0]
	v_pk_fma_f32 v[6:7], s[64:65], v[20:21], v[6:7] op_sel_hi:[0,1,1]
	v_cvt_scalef32_pk_f32_fp4 v[20:21], v24, 1.0 op_sel:[0,1,0]
	v_pk_fma_f32 v[8:9], s[64:65], v[20:21], v[8:9] op_sel_hi:[0,1,1]
	v_cvt_scalef32_pk_f32_fp4 v[20:21], v24, 1.0 op_sel:[1,1,0]
	v_pk_fma_f32 v[10:11], s[64:65], v[20:21], v[10:11] op_sel_hi:[0,1,1]
	v_cvt_scalef32_pk_f32_fp4 v[20:21], v25, 1.0
	v_pk_fma_f32 v[12:13], s[64:65], v[20:21], v[12:13] op_sel_hi:[0,1,1]
	v_cvt_scalef32_pk_f32_fp4 v[20:21], v25, 1.0 op_sel:[1,0,0]
	v_pk_fma_f32 v[14:15], s[64:65], v[20:21], v[14:15] op_sel_hi:[0,1,1]
	v_cvt_scalef32_pk_f32_fp4 v[20:21], v25, 1.0 op_sel:[0,1,0]
	v_pk_fma_f32 v[16:17], s[64:65], v[20:21], v[16:17] op_sel_hi:[0,1,1]
	v_cvt_scalef32_pk_f32_fp4 v[20:21], v25, 1.0 op_sel:[1,1,0]
	v_pk_fma_f32 v[18:19], s[64:65], v[20:21], v[18:19] op_sel_hi:[0,1,1]
	v_readlane_b32 s64, v127, 12
	s_waitcnt vmcnt(28)
	v_cvt_scalef32_pk_f32_fp4 v[20:21], v26, 1.0
	v_pk_fma_f32 v[4:5], v[20:21], s[64:65], v[4:5] op_sel_hi:[1,0,1]
	v_cvt_scalef32_pk_f32_fp4 v[20:21], v26, 1.0 op_sel:[1,0,0]
	v_pk_fma_f32 v[6:7], s[64:65], v[20:21], v[6:7] op_sel_hi:[0,1,1]
	v_cvt_scalef32_pk_f32_fp4 v[20:21], v26, 1.0 op_sel:[0,1,0]
	v_pk_fma_f32 v[8:9], s[64:65], v[20:21], v[8:9] op_sel_hi:[0,1,1]
	v_cvt_scalef32_pk_f32_fp4 v[20:21], v26, 1.0 op_sel:[1,1,0]
	v_pk_fma_f32 v[10:11], s[64:65], v[20:21], v[10:11] op_sel_hi:[0,1,1]
	v_cvt_scalef32_pk_f32_fp4 v[20:21], v27, 1.0
	v_pk_fma_f32 v[12:13], s[64:65], v[20:21], v[12:13] op_sel_hi:[0,1,1]
	v_cvt_scalef32_pk_f32_fp4 v[20:21], v27, 1.0 op_sel:[1,0,0]
	v_pk_fma_f32 v[14:15], s[64:65], v[20:21], v[14:15] op_sel_hi:[0,1,1]
	v_cvt_scalef32_pk_f32_fp4 v[20:21], v27, 1.0 op_sel:[0,1,0]
	v_pk_fma_f32 v[16:17], s[64:65], v[20:21], v[16:17] op_sel_hi:[0,1,1]
	v_cvt_scalef32_pk_f32_fp4 v[20:21], v27, 1.0 op_sel:[1,1,0]
	v_pk_fma_f32 v[18:19], s[64:65], v[20:21], v[18:19] op_sel_hi:[0,1,1]
	s_waitcnt vmcnt(27)
	v_cvt_scalef32_pk_f32_fp4 v[20:21], v28, 1.0
	v_pk_fma_f32 v[4:5], v[20:21], s[28:29], v[4:5] op_sel_hi:[1,0,1]
	v_cvt_scalef32_pk_f32_fp4 v[20:21], v28, 1.0 op_sel:[1,0,0]
	v_pk_fma_f32 v[6:7], s[28:29], v[20:21], v[6:7] op_sel_hi:[0,1,1]
	v_cvt_scalef32_pk_f32_fp4 v[20:21], v28, 1.0 op_sel:[0,1,0]
	v_pk_fma_f32 v[8:9], s[28:29], v[20:21], v[8:9] op_sel_hi:[0,1,1]
	v_cvt_scalef32_pk_f32_fp4 v[20:21], v28, 1.0 op_sel:[1,1,0]
	v_pk_fma_f32 v[10:11], s[28:29], v[20:21], v[10:11] op_sel_hi:[0,1,1]
	v_cvt_scalef32_pk_f32_fp4 v[20:21], v29, 1.0
	v_pk_fma_f32 v[12:13], s[28:29], v[20:21], v[12:13] op_sel_hi:[0,1,1]
	v_cvt_scalef32_pk_f32_fp4 v[20:21], v29, 1.0 op_sel:[1,0,0]
	v_pk_fma_f32 v[14:15], s[28:29], v[20:21], v[14:15] op_sel_hi:[0,1,1]
	v_cvt_scalef32_pk_f32_fp4 v[20:21], v29, 1.0 op_sel:[0,1,0]
	v_pk_fma_f32 v[16:17], s[28:29], v[20:21], v[16:17] op_sel_hi:[0,1,1]
	v_cvt_scalef32_pk_f32_fp4 v[20:21], v29, 1.0 op_sel:[1,1,0]
	v_pk_fma_f32 v[18:19], s[28:29], v[20:21], v[18:19] op_sel_hi:[0,1,1]
	v_readlane_b32 s28, v127, 10
	s_waitcnt vmcnt(26)
	v_cvt_scalef32_pk_f32_fp4 v[20:21], v30, 1.0
	v_pk_fma_f32 v[4:5], v[20:21], s[28:29], v[4:5] op_sel_hi:[1,0,1]
	v_cvt_scalef32_pk_f32_fp4 v[20:21], v30, 1.0 op_sel:[1,0,0]
	v_pk_fma_f32 v[6:7], s[28:29], v[20:21], v[6:7] op_sel_hi:[0,1,1]
	v_cvt_scalef32_pk_f32_fp4 v[20:21], v30, 1.0 op_sel:[0,1,0]
	v_pk_fma_f32 v[8:9], s[28:29], v[20:21], v[8:9] op_sel_hi:[0,1,1]
	v_cvt_scalef32_pk_f32_fp4 v[20:21], v30, 1.0 op_sel:[1,1,0]
	v_pk_fma_f32 v[10:11], s[28:29], v[20:21], v[10:11] op_sel_hi:[0,1,1]
	v_cvt_scalef32_pk_f32_fp4 v[20:21], v31, 1.0
	v_pk_fma_f32 v[12:13], s[28:29], v[20:21], v[12:13] op_sel_hi:[0,1,1]
	v_cvt_scalef32_pk_f32_fp4 v[20:21], v31, 1.0 op_sel:[1,0,0]
	v_pk_fma_f32 v[14:15], s[28:29], v[20:21], v[14:15] op_sel_hi:[0,1,1]
	v_cvt_scalef32_pk_f32_fp4 v[20:21], v31, 1.0 op_sel:[0,1,0]
	v_pk_fma_f32 v[16:17], s[28:29], v[20:21], v[16:17] op_sel_hi:[0,1,1]
	v_cvt_scalef32_pk_f32_fp4 v[20:21], v31, 1.0 op_sel:[1,1,0]
	v_pk_fma_f32 v[18:19], s[28:29], v[20:21], v[18:19] op_sel_hi:[0,1,1]
	v_readlane_b32 s28, v127, 6
	s_waitcnt vmcnt(25)
	v_cvt_scalef32_pk_f32_fp4 v[20:21], v32, 1.0
	v_pk_fma_f32 v[4:5], v[20:21], s[28:29], v[4:5] op_sel_hi:[1,0,1]
	v_cvt_scalef32_pk_f32_fp4 v[20:21], v32, 1.0 op_sel:[1,0,0]
	v_pk_fma_f32 v[6:7], s[28:29], v[20:21], v[6:7] op_sel_hi:[0,1,1]
	v_cvt_scalef32_pk_f32_fp4 v[20:21], v32, 1.0 op_sel:[0,1,0]
	v_pk_fma_f32 v[8:9], s[28:29], v[20:21], v[8:9] op_sel_hi:[0,1,1]
	v_cvt_scalef32_pk_f32_fp4 v[20:21], v32, 1.0 op_sel:[1,1,0]
	v_pk_fma_f32 v[10:11], s[28:29], v[20:21], v[10:11] op_sel_hi:[0,1,1]
	v_cvt_scalef32_pk_f32_fp4 v[20:21], v33, 1.0
	v_pk_fma_f32 v[12:13], s[28:29], v[20:21], v[12:13] op_sel_hi:[0,1,1]
	v_cvt_scalef32_pk_f32_fp4 v[20:21], v33, 1.0 op_sel:[1,0,0]
	v_pk_fma_f32 v[14:15], s[28:29], v[20:21], v[14:15] op_sel_hi:[0,1,1]
	v_cvt_scalef32_pk_f32_fp4 v[20:21], v33, 1.0 op_sel:[0,1,0]
	v_pk_fma_f32 v[16:17], s[28:29], v[20:21], v[16:17] op_sel_hi:[0,1,1]
	v_cvt_scalef32_pk_f32_fp4 v[20:21], v33, 1.0 op_sel:[1,1,0]
	v_pk_fma_f32 v[18:19], s[28:29], v[20:21], v[18:19] op_sel_hi:[0,1,1]
	v_readlane_b32 s28, v127, 14
	s_waitcnt vmcnt(24)
	v_cvt_scalef32_pk_f32_fp4 v[20:21], v34, 1.0
	v_pk_fma_f32 v[4:5], v[20:21], s[28:29], v[4:5] op_sel_hi:[1,0,1]
	v_cvt_scalef32_pk_f32_fp4 v[20:21], v34, 1.0 op_sel:[1,0,0]
	v_pk_fma_f32 v[6:7], s[28:29], v[20:21], v[6:7] op_sel_hi:[0,1,1]
	v_cvt_scalef32_pk_f32_fp4 v[20:21], v34, 1.0 op_sel:[0,1,0]
	v_pk_fma_f32 v[8:9], s[28:29], v[20:21], v[8:9] op_sel_hi:[0,1,1]
	v_cvt_scalef32_pk_f32_fp4 v[20:21], v34, 1.0 op_sel:[1,1,0]
	v_pk_fma_f32 v[10:11], s[28:29], v[20:21], v[10:11] op_sel_hi:[0,1,1]
	v_cvt_scalef32_pk_f32_fp4 v[20:21], v35, 1.0
	v_pk_fma_f32 v[12:13], s[28:29], v[20:21], v[12:13] op_sel_hi:[0,1,1]
	v_cvt_scalef32_pk_f32_fp4 v[20:21], v35, 1.0 op_sel:[1,0,0]
	v_pk_fma_f32 v[14:15], s[28:29], v[20:21], v[14:15] op_sel_hi:[0,1,1]
	v_cvt_scalef32_pk_f32_fp4 v[20:21], v35, 1.0 op_sel:[0,1,0]
	v_pk_fma_f32 v[16:17], s[28:29], v[20:21], v[16:17] op_sel_hi:[0,1,1]
	v_cvt_scalef32_pk_f32_fp4 v[20:21], v35, 1.0 op_sel:[1,1,0]
	v_pk_fma_f32 v[18:19], s[28:29], v[20:21], v[18:19] op_sel_hi:[0,1,1]
	v_readlane_b32 s28, v127, 1
	s_waitcnt vmcnt(23)
	v_cvt_scalef32_pk_f32_fp4 v[20:21], v56, 1.0
	v_pk_fma_f32 v[4:5], v[20:21], s[28:29], v[4:5] op_sel_hi:[1,0,1]
	v_cvt_scalef32_pk_f32_fp4 v[20:21], v56, 1.0 op_sel:[1,0,0]
	v_pk_fma_f32 v[6:7], s[28:29], v[20:21], v[6:7] op_sel_hi:[0,1,1]
	v_cvt_scalef32_pk_f32_fp4 v[20:21], v56, 1.0 op_sel:[0,1,0]
	v_pk_fma_f32 v[8:9], s[28:29], v[20:21], v[8:9] op_sel_hi:[0,1,1]
	v_cvt_scalef32_pk_f32_fp4 v[20:21], v56, 1.0 op_sel:[1,1,0]
	v_pk_fma_f32 v[10:11], s[28:29], v[20:21], v[10:11] op_sel_hi:[0,1,1]
	v_cvt_scalef32_pk_f32_fp4 v[20:21], v57, 1.0
	v_pk_fma_f32 v[12:13], s[28:29], v[20:21], v[12:13] op_sel_hi:[0,1,1]
	v_cvt_scalef32_pk_f32_fp4 v[20:21], v57, 1.0 op_sel:[1,0,0]
	v_pk_fma_f32 v[14:15], s[28:29], v[20:21], v[14:15] op_sel_hi:[0,1,1]
	v_cvt_scalef32_pk_f32_fp4 v[20:21], v57, 1.0 op_sel:[0,1,0]
	v_pk_fma_f32 v[16:17], s[28:29], v[20:21], v[16:17] op_sel_hi:[0,1,1]
	v_cvt_scalef32_pk_f32_fp4 v[20:21], v57, 1.0 op_sel:[1,1,0]
	v_pk_fma_f32 v[18:19], s[28:29], v[20:21], v[18:19] op_sel_hi:[0,1,1]
	v_readlane_b32 s28, v127, 9
	s_waitcnt vmcnt(22)
	v_cvt_scalef32_pk_f32_fp4 v[20:21], v58, 1.0
	v_pk_fma_f32 v[4:5], v[20:21], s[28:29], v[4:5] op_sel_hi:[1,0,1]
	v_cvt_scalef32_pk_f32_fp4 v[20:21], v58, 1.0 op_sel:[1,0,0]
	v_pk_fma_f32 v[6:7], s[28:29], v[20:21], v[6:7] op_sel_hi:[0,1,1]
	v_cvt_scalef32_pk_f32_fp4 v[20:21], v58, 1.0 op_sel:[0,1,0]
	v_pk_fma_f32 v[8:9], s[28:29], v[20:21], v[8:9] op_sel_hi:[0,1,1]
	v_cvt_scalef32_pk_f32_fp4 v[20:21], v58, 1.0 op_sel:[1,1,0]
	v_pk_fma_f32 v[10:11], s[28:29], v[20:21], v[10:11] op_sel_hi:[0,1,1]
	v_cvt_scalef32_pk_f32_fp4 v[20:21], v59, 1.0
	v_pk_fma_f32 v[12:13], s[28:29], v[20:21], v[12:13] op_sel_hi:[0,1,1]
	v_cvt_scalef32_pk_f32_fp4 v[20:21], v59, 1.0 op_sel:[1,0,0]
	v_pk_fma_f32 v[14:15], s[28:29], v[20:21], v[14:15] op_sel_hi:[0,1,1]
	v_cvt_scalef32_pk_f32_fp4 v[20:21], v59, 1.0 op_sel:[0,1,0]
	v_pk_fma_f32 v[16:17], s[28:29], v[20:21], v[16:17] op_sel_hi:[0,1,1]
	v_cvt_scalef32_pk_f32_fp4 v[20:21], v59, 1.0 op_sel:[1,1,0]
	v_pk_fma_f32 v[18:19], s[28:29], v[20:21], v[18:19] op_sel_hi:[0,1,1]
	v_readlane_b32 s28, v127, 5
	s_waitcnt vmcnt(21)
	v_cvt_scalef32_pk_f32_fp4 v[20:21], v60, 1.0
	v_pk_fma_f32 v[4:5], v[20:21], s[28:29], v[4:5] op_sel_hi:[1,0,1]
	v_cvt_scalef32_pk_f32_fp4 v[20:21], v60, 1.0 op_sel:[1,0,0]
	v_pk_fma_f32 v[6:7], s[28:29], v[20:21], v[6:7] op_sel_hi:[0,1,1]
	v_cvt_scalef32_pk_f32_fp4 v[20:21], v60, 1.0 op_sel:[0,1,0]
	v_pk_fma_f32 v[8:9], s[28:29], v[20:21], v[8:9] op_sel_hi:[0,1,1]
	v_cvt_scalef32_pk_f32_fp4 v[20:21], v60, 1.0 op_sel:[1,1,0]
	v_pk_fma_f32 v[10:11], s[28:29], v[20:21], v[10:11] op_sel_hi:[0,1,1]
	v_cvt_scalef32_pk_f32_fp4 v[20:21], v61, 1.0
	v_pk_fma_f32 v[12:13], s[28:29], v[20:21], v[12:13] op_sel_hi:[0,1,1]
	v_cvt_scalef32_pk_f32_fp4 v[20:21], v61, 1.0 op_sel:[1,0,0]
	v_pk_fma_f32 v[14:15], s[28:29], v[20:21], v[14:15] op_sel_hi:[0,1,1]
	v_cvt_scalef32_pk_f32_fp4 v[20:21], v61, 1.0 op_sel:[0,1,0]
	v_pk_fma_f32 v[16:17], s[28:29], v[20:21], v[16:17] op_sel_hi:[0,1,1]
	v_cvt_scalef32_pk_f32_fp4 v[20:21], v61, 1.0 op_sel:[1,1,0]
	v_pk_fma_f32 v[18:19], s[28:29], v[20:21], v[18:19] op_sel_hi:[0,1,1]
	v_readlane_b32 s28, v127, 13
	s_waitcnt vmcnt(20)
	v_cvt_scalef32_pk_f32_fp4 v[20:21], v62, 1.0
	v_pk_fma_f32 v[4:5], v[20:21], s[28:29], v[4:5] op_sel_hi:[1,0,1]
	v_cvt_scalef32_pk_f32_fp4 v[20:21], v62, 1.0 op_sel:[1,0,0]
	v_pk_fma_f32 v[6:7], s[28:29], v[20:21], v[6:7] op_sel_hi:[0,1,1]
	v_cvt_scalef32_pk_f32_fp4 v[20:21], v62, 1.0 op_sel:[0,1,0]
	v_pk_fma_f32 v[8:9], s[28:29], v[20:21], v[8:9] op_sel_hi:[0,1,1]
	v_cvt_scalef32_pk_f32_fp4 v[20:21], v62, 1.0 op_sel:[1,1,0]
	v_pk_fma_f32 v[10:11], s[28:29], v[20:21], v[10:11] op_sel_hi:[0,1,1]
	v_cvt_scalef32_pk_f32_fp4 v[20:21], v63, 1.0
	v_pk_fma_f32 v[12:13], s[28:29], v[20:21], v[12:13] op_sel_hi:[0,1,1]
	v_cvt_scalef32_pk_f32_fp4 v[20:21], v63, 1.0 op_sel:[1,0,0]
	v_pk_fma_f32 v[14:15], s[28:29], v[20:21], v[14:15] op_sel_hi:[0,1,1]
	v_cvt_scalef32_pk_f32_fp4 v[20:21], v63, 1.0 op_sel:[0,1,0]
	v_pk_fma_f32 v[16:17], s[28:29], v[20:21], v[16:17] op_sel_hi:[0,1,1]
	v_cvt_scalef32_pk_f32_fp4 v[20:21], v63, 1.0 op_sel:[1,1,0]
	v_pk_fma_f32 v[18:19], s[28:29], v[20:21], v[18:19] op_sel_hi:[0,1,1]
	s_waitcnt vmcnt(19)
	v_cvt_scalef32_pk_f32_fp4 v[20:21], v64, 1.0
	v_pk_fma_f32 v[4:5], v[20:21], s[2:3], v[4:5] op_sel_hi:[1,0,1]
	v_cvt_scalef32_pk_f32_fp4 v[20:21], v64, 1.0 op_sel:[1,0,0]
	v_pk_fma_f32 v[6:7], s[2:3], v[20:21], v[6:7] op_sel_hi:[0,1,1]
	v_cvt_scalef32_pk_f32_fp4 v[20:21], v64, 1.0 op_sel:[0,1,0]
	v_pk_fma_f32 v[8:9], s[2:3], v[20:21], v[8:9] op_sel_hi:[0,1,1]
	v_cvt_scalef32_pk_f32_fp4 v[20:21], v64, 1.0 op_sel:[1,1,0]
	v_pk_fma_f32 v[10:11], s[2:3], v[20:21], v[10:11] op_sel_hi:[0,1,1]
	v_cvt_scalef32_pk_f32_fp4 v[20:21], v65, 1.0
	v_pk_fma_f32 v[12:13], s[2:3], v[20:21], v[12:13] op_sel_hi:[0,1,1]
	v_cvt_scalef32_pk_f32_fp4 v[20:21], v65, 1.0 op_sel:[1,0,0]
	v_pk_fma_f32 v[14:15], s[2:3], v[20:21], v[14:15] op_sel_hi:[0,1,1]
	v_cvt_scalef32_pk_f32_fp4 v[20:21], v65, 1.0 op_sel:[0,1,0]
	v_pk_fma_f32 v[16:17], s[2:3], v[20:21], v[16:17] op_sel_hi:[0,1,1]
	v_cvt_scalef32_pk_f32_fp4 v[20:21], v65, 1.0 op_sel:[1,1,0]
	v_pk_fma_f32 v[18:19], s[2:3], v[20:21], v[18:19] op_sel_hi:[0,1,1]
	v_readlane_b32 s2, v127, 11
	s_waitcnt vmcnt(18)
	v_cvt_scalef32_pk_f32_fp4 v[20:21], v66, 1.0
	v_pk_fma_f32 v[4:5], v[20:21], s[2:3], v[4:5] op_sel_hi:[1,0,1]
	v_cvt_scalef32_pk_f32_fp4 v[20:21], v66, 1.0 op_sel:[1,0,0]
	v_pk_fma_f32 v[6:7], s[2:3], v[20:21], v[6:7] op_sel_hi:[0,1,1]
	v_cvt_scalef32_pk_f32_fp4 v[20:21], v66, 1.0 op_sel:[0,1,0]
	v_pk_fma_f32 v[8:9], s[2:3], v[20:21], v[8:9] op_sel_hi:[0,1,1]
	v_cvt_scalef32_pk_f32_fp4 v[20:21], v66, 1.0 op_sel:[1,1,0]
	v_pk_fma_f32 v[10:11], s[2:3], v[20:21], v[10:11] op_sel_hi:[0,1,1]
	v_cvt_scalef32_pk_f32_fp4 v[20:21], v67, 1.0
	v_pk_fma_f32 v[12:13], s[2:3], v[20:21], v[12:13] op_sel_hi:[0,1,1]
	v_cvt_scalef32_pk_f32_fp4 v[20:21], v67, 1.0 op_sel:[1,0,0]
	v_pk_fma_f32 v[14:15], s[2:3], v[20:21], v[14:15] op_sel_hi:[0,1,1]
	v_cvt_scalef32_pk_f32_fp4 v[20:21], v67, 1.0 op_sel:[0,1,0]
	v_pk_fma_f32 v[16:17], s[2:3], v[20:21], v[16:17] op_sel_hi:[0,1,1]
	v_cvt_scalef32_pk_f32_fp4 v[20:21], v67, 1.0 op_sel:[1,1,0]
	v_pk_fma_f32 v[18:19], s[2:3], v[20:21], v[18:19] op_sel_hi:[0,1,1]
	v_readlane_b32 s2, v127, 7
	s_waitcnt vmcnt(17)
	v_cvt_scalef32_pk_f32_fp4 v[20:21], v68, 1.0
	v_pk_fma_f32 v[4:5], v[20:21], s[2:3], v[4:5] op_sel_hi:[1,0,1]
	v_cvt_scalef32_pk_f32_fp4 v[20:21], v68, 1.0 op_sel:[1,0,0]
	v_pk_fma_f32 v[6:7], s[2:3], v[20:21], v[6:7] op_sel_hi:[0,1,1]
	v_cvt_scalef32_pk_f32_fp4 v[20:21], v68, 1.0 op_sel:[0,1,0]
	v_pk_fma_f32 v[8:9], s[2:3], v[20:21], v[8:9] op_sel_hi:[0,1,1]
	v_cvt_scalef32_pk_f32_fp4 v[20:21], v68, 1.0 op_sel:[1,1,0]
	v_pk_fma_f32 v[10:11], s[2:3], v[20:21], v[10:11] op_sel_hi:[0,1,1]
	v_cvt_scalef32_pk_f32_fp4 v[20:21], v69, 1.0
	v_pk_fma_f32 v[12:13], s[2:3], v[20:21], v[12:13] op_sel_hi:[0,1,1]
	v_cvt_scalef32_pk_f32_fp4 v[20:21], v69, 1.0 op_sel:[1,0,0]
	v_pk_fma_f32 v[14:15], s[2:3], v[20:21], v[14:15] op_sel_hi:[0,1,1]
	v_cvt_scalef32_pk_f32_fp4 v[20:21], v69, 1.0 op_sel:[0,1,0]
	v_pk_fma_f32 v[16:17], s[2:3], v[20:21], v[16:17] op_sel_hi:[0,1,1]
	v_cvt_scalef32_pk_f32_fp4 v[20:21], v69, 1.0 op_sel:[1,1,0]
	v_pk_fma_f32 v[18:19], s[2:3], v[20:21], v[18:19] op_sel_hi:[0,1,1]
	v_readlane_b32 s2, v127, 15
	s_waitcnt vmcnt(16)
	v_cvt_scalef32_pk_f32_fp4 v[20:21], v70, 1.0
	v_pk_fma_f32 v[4:5], v[20:21], s[2:3], v[4:5] op_sel_hi:[1,0,1]
	v_cvt_scalef32_pk_f32_fp4 v[20:21], v70, 1.0 op_sel:[1,0,0]
	v_pk_fma_f32 v[6:7], s[2:3], v[20:21], v[6:7] op_sel_hi:[0,1,1]
	v_cvt_scalef32_pk_f32_fp4 v[20:21], v70, 1.0 op_sel:[0,1,0]
	v_pk_fma_f32 v[8:9], s[2:3], v[20:21], v[8:9] op_sel_hi:[0,1,1]
	v_cvt_scalef32_pk_f32_fp4 v[20:21], v70, 1.0 op_sel:[1,1,0]
	v_pk_fma_f32 v[10:11], s[2:3], v[20:21], v[10:11] op_sel_hi:[0,1,1]
	v_cvt_scalef32_pk_f32_fp4 v[20:21], v71, 1.0
	v_pk_fma_f32 v[12:13], s[2:3], v[20:21], v[12:13] op_sel_hi:[0,1,1]
	v_cvt_scalef32_pk_f32_fp4 v[20:21], v71, 1.0 op_sel:[1,0,0]
	v_pk_fma_f32 v[14:15], s[2:3], v[20:21], v[14:15] op_sel_hi:[0,1,1]
	v_cvt_scalef32_pk_f32_fp4 v[20:21], v71, 1.0 op_sel:[0,1,0]
	v_pk_fma_f32 v[16:17], s[2:3], v[20:21], v[16:17] op_sel_hi:[0,1,1]
	v_cvt_scalef32_pk_f32_fp4 v[20:21], v71, 1.0 op_sel:[1,1,0]
	v_pk_fma_f32 v[18:19], s[2:3], v[20:21], v[18:19] op_sel_hi:[0,1,1]
	v_readlane_b32 s2, v127, 16
	s_waitcnt vmcnt(15)
	v_cvt_scalef32_pk_f32_fp4 v[20:21], v72, 1.0
	v_pk_fma_f32 v[4:5], v[20:21], s[2:3], v[4:5] op_sel_hi:[1,0,1]
	v_cvt_scalef32_pk_f32_fp4 v[20:21], v72, 1.0 op_sel:[1,0,0]
	v_pk_fma_f32 v[6:7], s[2:3], v[20:21], v[6:7] op_sel_hi:[0,1,1]
	v_cvt_scalef32_pk_f32_fp4 v[20:21], v72, 1.0 op_sel:[0,1,0]
	v_pk_fma_f32 v[8:9], s[2:3], v[20:21], v[8:9] op_sel_hi:[0,1,1]
	v_cvt_scalef32_pk_f32_fp4 v[20:21], v72, 1.0 op_sel:[1,1,0]
	v_pk_fma_f32 v[10:11], s[2:3], v[20:21], v[10:11] op_sel_hi:[0,1,1]
	v_cvt_scalef32_pk_f32_fp4 v[20:21], v73, 1.0
	v_pk_fma_f32 v[12:13], s[2:3], v[20:21], v[12:13] op_sel_hi:[0,1,1]
	v_cvt_scalef32_pk_f32_fp4 v[20:21], v73, 1.0 op_sel:[1,0,0]
	v_pk_fma_f32 v[14:15], s[2:3], v[20:21], v[14:15] op_sel_hi:[0,1,1]
	v_cvt_scalef32_pk_f32_fp4 v[20:21], v73, 1.0 op_sel:[0,1,0]
	v_pk_fma_f32 v[16:17], s[2:3], v[20:21], v[16:17] op_sel_hi:[0,1,1]
	v_cvt_scalef32_pk_f32_fp4 v[20:21], v73, 1.0 op_sel:[1,1,0]
	v_pk_fma_f32 v[18:19], s[2:3], v[20:21], v[18:19] op_sel_hi:[0,1,1]
	v_readlane_b32 s2, v127, 24
	s_waitcnt vmcnt(14)
	v_cvt_scalef32_pk_f32_fp4 v[20:21], v74, 1.0
	v_pk_fma_f32 v[4:5], v[20:21], s[2:3], v[4:5] op_sel_hi:[1,0,1]
	v_cvt_scalef32_pk_f32_fp4 v[20:21], v74, 1.0 op_sel:[1,0,0]
	v_pk_fma_f32 v[6:7], s[2:3], v[20:21], v[6:7] op_sel_hi:[0,1,1]
	v_cvt_scalef32_pk_f32_fp4 v[20:21], v74, 1.0 op_sel:[0,1,0]
	v_pk_fma_f32 v[8:9], s[2:3], v[20:21], v[8:9] op_sel_hi:[0,1,1]
	v_cvt_scalef32_pk_f32_fp4 v[20:21], v74, 1.0 op_sel:[1,1,0]
	v_pk_fma_f32 v[10:11], s[2:3], v[20:21], v[10:11] op_sel_hi:[0,1,1]
	v_cvt_scalef32_pk_f32_fp4 v[20:21], v75, 1.0
	v_pk_fma_f32 v[12:13], s[2:3], v[20:21], v[12:13] op_sel_hi:[0,1,1]
	v_cvt_scalef32_pk_f32_fp4 v[20:21], v75, 1.0 op_sel:[1,0,0]
	v_pk_fma_f32 v[14:15], s[2:3], v[20:21], v[14:15] op_sel_hi:[0,1,1]
	v_cvt_scalef32_pk_f32_fp4 v[20:21], v75, 1.0 op_sel:[0,1,0]
	v_pk_fma_f32 v[16:17], s[2:3], v[20:21], v[16:17] op_sel_hi:[0,1,1]
	v_cvt_scalef32_pk_f32_fp4 v[20:21], v75, 1.0 op_sel:[1,1,0]
	v_pk_fma_f32 v[18:19], s[2:3], v[20:21], v[18:19] op_sel_hi:[0,1,1]
	v_readlane_b32 s2, v127, 20
	s_waitcnt vmcnt(13)
	v_cvt_scalef32_pk_f32_fp4 v[20:21], v76, 1.0
	v_pk_fma_f32 v[4:5], v[20:21], s[2:3], v[4:5] op_sel_hi:[1,0,1]
	v_cvt_scalef32_pk_f32_fp4 v[20:21], v76, 1.0 op_sel:[1,0,0]
	v_pk_fma_f32 v[6:7], s[2:3], v[20:21], v[6:7] op_sel_hi:[0,1,1]
	v_cvt_scalef32_pk_f32_fp4 v[20:21], v76, 1.0 op_sel:[0,1,0]
	v_pk_fma_f32 v[8:9], s[2:3], v[20:21], v[8:9] op_sel_hi:[0,1,1]
	v_cvt_scalef32_pk_f32_fp4 v[20:21], v76, 1.0 op_sel:[1,1,0]
	v_pk_fma_f32 v[10:11], s[2:3], v[20:21], v[10:11] op_sel_hi:[0,1,1]
	v_cvt_scalef32_pk_f32_fp4 v[20:21], v77, 1.0
	v_pk_fma_f32 v[12:13], s[2:3], v[20:21], v[12:13] op_sel_hi:[0,1,1]
	v_cvt_scalef32_pk_f32_fp4 v[20:21], v77, 1.0 op_sel:[1,0,0]
	v_pk_fma_f32 v[14:15], s[2:3], v[20:21], v[14:15] op_sel_hi:[0,1,1]
	v_cvt_scalef32_pk_f32_fp4 v[20:21], v77, 1.0 op_sel:[0,1,0]
	v_pk_fma_f32 v[16:17], s[2:3], v[20:21], v[16:17] op_sel_hi:[0,1,1]
	v_cvt_scalef32_pk_f32_fp4 v[20:21], v77, 1.0 op_sel:[1,1,0]
	v_pk_fma_f32 v[18:19], s[2:3], v[20:21], v[18:19] op_sel_hi:[0,1,1]
	v_readlane_b32 s2, v127, 28
	s_waitcnt vmcnt(12)
	v_cvt_scalef32_pk_f32_fp4 v[20:21], v78, 1.0
	v_pk_fma_f32 v[4:5], v[20:21], s[2:3], v[4:5] op_sel_hi:[1,0,1]
	v_cvt_scalef32_pk_f32_fp4 v[20:21], v78, 1.0 op_sel:[1,0,0]
	v_pk_fma_f32 v[6:7], s[2:3], v[20:21], v[6:7] op_sel_hi:[0,1,1]
	v_cvt_scalef32_pk_f32_fp4 v[20:21], v78, 1.0 op_sel:[0,1,0]
	v_pk_fma_f32 v[8:9], s[2:3], v[20:21], v[8:9] op_sel_hi:[0,1,1]
	v_cvt_scalef32_pk_f32_fp4 v[20:21], v78, 1.0 op_sel:[1,1,0]
	v_pk_fma_f32 v[10:11], s[2:3], v[20:21], v[10:11] op_sel_hi:[0,1,1]
	v_cvt_scalef32_pk_f32_fp4 v[20:21], v79, 1.0
	v_pk_fma_f32 v[12:13], s[2:3], v[20:21], v[12:13] op_sel_hi:[0,1,1]
	v_cvt_scalef32_pk_f32_fp4 v[20:21], v79, 1.0 op_sel:[1,0,0]
	v_pk_fma_f32 v[14:15], s[2:3], v[20:21], v[14:15] op_sel_hi:[0,1,1]
	v_cvt_scalef32_pk_f32_fp4 v[20:21], v79, 1.0 op_sel:[0,1,0]
	v_pk_fma_f32 v[16:17], s[2:3], v[20:21], v[16:17] op_sel_hi:[0,1,1]
	v_cvt_scalef32_pk_f32_fp4 v[20:21], v79, 1.0 op_sel:[1,1,0]
	v_pk_fma_f32 v[18:19], s[2:3], v[20:21], v[18:19] op_sel_hi:[0,1,1]
	v_readlane_b32 s2, v127, 18
	s_waitcnt vmcnt(11)
	v_cvt_scalef32_pk_f32_fp4 v[20:21], v80, 1.0
	v_pk_fma_f32 v[4:5], v[20:21], s[2:3], v[4:5] op_sel_hi:[1,0,1]
	v_cvt_scalef32_pk_f32_fp4 v[20:21], v80, 1.0 op_sel:[1,0,0]
	v_pk_fma_f32 v[6:7], s[2:3], v[20:21], v[6:7] op_sel_hi:[0,1,1]
	v_cvt_scalef32_pk_f32_fp4 v[20:21], v80, 1.0 op_sel:[0,1,0]
	v_pk_fma_f32 v[8:9], s[2:3], v[20:21], v[8:9] op_sel_hi:[0,1,1]
	v_cvt_scalef32_pk_f32_fp4 v[20:21], v80, 1.0 op_sel:[1,1,0]
	v_pk_fma_f32 v[10:11], s[2:3], v[20:21], v[10:11] op_sel_hi:[0,1,1]
	v_cvt_scalef32_pk_f32_fp4 v[20:21], v81, 1.0
	v_pk_fma_f32 v[12:13], s[2:3], v[20:21], v[12:13] op_sel_hi:[0,1,1]
	v_cvt_scalef32_pk_f32_fp4 v[20:21], v81, 1.0 op_sel:[1,0,0]
	v_pk_fma_f32 v[14:15], s[2:3], v[20:21], v[14:15] op_sel_hi:[0,1,1]
	v_cvt_scalef32_pk_f32_fp4 v[20:21], v81, 1.0 op_sel:[0,1,0]
	v_pk_fma_f32 v[16:17], s[2:3], v[20:21], v[16:17] op_sel_hi:[0,1,1]
	v_cvt_scalef32_pk_f32_fp4 v[20:21], v81, 1.0 op_sel:[1,1,0]
	v_pk_fma_f32 v[18:19], s[2:3], v[20:21], v[18:19] op_sel_hi:[0,1,1]
	v_readlane_b32 s2, v127, 26
	s_waitcnt vmcnt(10)
	v_cvt_scalef32_pk_f32_fp4 v[20:21], v82, 1.0
	v_pk_fma_f32 v[4:5], v[20:21], s[2:3], v[4:5] op_sel_hi:[1,0,1]
	v_cvt_scalef32_pk_f32_fp4 v[20:21], v82, 1.0 op_sel:[1,0,0]
	v_pk_fma_f32 v[6:7], s[2:3], v[20:21], v[6:7] op_sel_hi:[0,1,1]
	v_cvt_scalef32_pk_f32_fp4 v[20:21], v82, 1.0 op_sel:[0,1,0]
	v_pk_fma_f32 v[8:9], s[2:3], v[20:21], v[8:9] op_sel_hi:[0,1,1]
	v_cvt_scalef32_pk_f32_fp4 v[20:21], v82, 1.0 op_sel:[1,1,0]
	v_pk_fma_f32 v[10:11], s[2:3], v[20:21], v[10:11] op_sel_hi:[0,1,1]
	v_cvt_scalef32_pk_f32_fp4 v[20:21], v83, 1.0
	v_pk_fma_f32 v[12:13], s[2:3], v[20:21], v[12:13] op_sel_hi:[0,1,1]
	v_cvt_scalef32_pk_f32_fp4 v[20:21], v83, 1.0 op_sel:[1,0,0]
	v_pk_fma_f32 v[14:15], s[2:3], v[20:21], v[14:15] op_sel_hi:[0,1,1]
	v_cvt_scalef32_pk_f32_fp4 v[20:21], v83, 1.0 op_sel:[0,1,0]
	v_pk_fma_f32 v[16:17], s[2:3], v[20:21], v[16:17] op_sel_hi:[0,1,1]
	v_cvt_scalef32_pk_f32_fp4 v[20:21], v83, 1.0 op_sel:[1,1,0]
	v_pk_fma_f32 v[18:19], s[2:3], v[20:21], v[18:19] op_sel_hi:[0,1,1]
	v_readlane_b32 s2, v127, 22
	s_waitcnt vmcnt(9)
	v_cvt_scalef32_pk_f32_fp4 v[20:21], v84, 1.0
	v_pk_fma_f32 v[4:5], v[20:21], s[2:3], v[4:5] op_sel_hi:[1,0,1]
	v_cvt_scalef32_pk_f32_fp4 v[20:21], v84, 1.0 op_sel:[1,0,0]
	v_pk_fma_f32 v[6:7], s[2:3], v[20:21], v[6:7] op_sel_hi:[0,1,1]
	v_cvt_scalef32_pk_f32_fp4 v[20:21], v84, 1.0 op_sel:[0,1,0]
	v_pk_fma_f32 v[8:9], s[2:3], v[20:21], v[8:9] op_sel_hi:[0,1,1]
	v_cvt_scalef32_pk_f32_fp4 v[20:21], v84, 1.0 op_sel:[1,1,0]
	v_pk_fma_f32 v[10:11], s[2:3], v[20:21], v[10:11] op_sel_hi:[0,1,1]
	v_cvt_scalef32_pk_f32_fp4 v[20:21], v85, 1.0
	v_pk_fma_f32 v[12:13], s[2:3], v[20:21], v[12:13] op_sel_hi:[0,1,1]
	v_cvt_scalef32_pk_f32_fp4 v[20:21], v85, 1.0 op_sel:[1,0,0]
	v_pk_fma_f32 v[14:15], s[2:3], v[20:21], v[14:15] op_sel_hi:[0,1,1]
	v_cvt_scalef32_pk_f32_fp4 v[20:21], v85, 1.0 op_sel:[0,1,0]
	v_pk_fma_f32 v[16:17], s[2:3], v[20:21], v[16:17] op_sel_hi:[0,1,1]
	v_cvt_scalef32_pk_f32_fp4 v[20:21], v85, 1.0 op_sel:[1,1,0]
	v_pk_fma_f32 v[18:19], s[2:3], v[20:21], v[18:19] op_sel_hi:[0,1,1]
	v_readlane_b32 s2, v127, 30
	s_waitcnt vmcnt(8)
	v_cvt_scalef32_pk_f32_fp4 v[20:21], v86, 1.0
	v_pk_fma_f32 v[4:5], v[20:21], s[2:3], v[4:5] op_sel_hi:[1,0,1]
	v_cvt_scalef32_pk_f32_fp4 v[20:21], v86, 1.0 op_sel:[1,0,0]
	v_pk_fma_f32 v[6:7], s[2:3], v[20:21], v[6:7] op_sel_hi:[0,1,1]
	v_cvt_scalef32_pk_f32_fp4 v[20:21], v86, 1.0 op_sel:[0,1,0]
	v_pk_fma_f32 v[8:9], s[2:3], v[20:21], v[8:9] op_sel_hi:[0,1,1]
	v_cvt_scalef32_pk_f32_fp4 v[20:21], v86, 1.0 op_sel:[1,1,0]
	v_pk_fma_f32 v[10:11], s[2:3], v[20:21], v[10:11] op_sel_hi:[0,1,1]
	v_cvt_scalef32_pk_f32_fp4 v[20:21], v87, 1.0
	v_pk_fma_f32 v[12:13], s[2:3], v[20:21], v[12:13] op_sel_hi:[0,1,1]
	v_cvt_scalef32_pk_f32_fp4 v[20:21], v87, 1.0 op_sel:[1,0,0]
	v_pk_fma_f32 v[14:15], s[2:3], v[20:21], v[14:15] op_sel_hi:[0,1,1]
	v_cvt_scalef32_pk_f32_fp4 v[20:21], v87, 1.0 op_sel:[0,1,0]
	v_pk_fma_f32 v[16:17], s[2:3], v[20:21], v[16:17] op_sel_hi:[0,1,1]
	v_cvt_scalef32_pk_f32_fp4 v[20:21], v87, 1.0 op_sel:[1,1,0]
	v_pk_fma_f32 v[18:19], s[2:3], v[20:21], v[18:19] op_sel_hi:[0,1,1]
	s_waitcnt vmcnt(7)
	v_cvt_scalef32_pk_f32_fp4 v[20:21], v88, 1.0
	s_nop 1
	v_readlane_b32 s2, v127, 17
	s_nop 1
	v_pk_fma_f32 v[4:5], v[20:21], s[2:3], v[4:5] op_sel_hi:[1,0,1]
	v_cvt_scalef32_pk_f32_fp4 v[20:21], v88, 1.0 op_sel:[1,0,0]
	v_pk_fma_f32 v[6:7], s[2:3], v[20:21], v[6:7] op_sel_hi:[0,1,1]
	v_cvt_scalef32_pk_f32_fp4 v[20:21], v88, 1.0 op_sel:[0,1,0]
	v_pk_fma_f32 v[8:9], s[2:3], v[20:21], v[8:9] op_sel_hi:[0,1,1]
	v_cvt_scalef32_pk_f32_fp4 v[20:21], v88, 1.0 op_sel:[1,1,0]
	v_pk_fma_f32 v[10:11], s[2:3], v[20:21], v[10:11] op_sel_hi:[0,1,1]
	v_cvt_scalef32_pk_f32_fp4 v[20:21], v89, 1.0
	v_pk_fma_f32 v[12:13], s[2:3], v[20:21], v[12:13] op_sel_hi:[0,1,1]
	v_cvt_scalef32_pk_f32_fp4 v[20:21], v89, 1.0 op_sel:[1,0,0]
	v_pk_fma_f32 v[14:15], s[2:3], v[20:21], v[14:15] op_sel_hi:[0,1,1]
	v_cvt_scalef32_pk_f32_fp4 v[20:21], v89, 1.0 op_sel:[0,1,0]
	v_pk_fma_f32 v[16:17], s[2:3], v[20:21], v[16:17] op_sel_hi:[0,1,1]
	v_cvt_scalef32_pk_f32_fp4 v[20:21], v89, 1.0 op_sel:[1,1,0]
	v_pk_fma_f32 v[18:19], s[2:3], v[20:21], v[18:19] op_sel_hi:[0,1,1]
	s_waitcnt vmcnt(6)
	v_cvt_scalef32_pk_f32_fp4 v[20:21], v90, 1.0
	s_nop 1
	v_readlane_b32 s2, v127, 25
	s_nop 1
	v_pk_fma_f32 v[4:5], v[20:21], s[2:3], v[4:5] op_sel_hi:[1,0,1]
	v_cvt_scalef32_pk_f32_fp4 v[20:21], v90, 1.0 op_sel:[1,0,0]
	v_pk_fma_f32 v[6:7], s[2:3], v[20:21], v[6:7] op_sel_hi:[0,1,1]
	v_cvt_scalef32_pk_f32_fp4 v[20:21], v90, 1.0 op_sel:[0,1,0]
	v_pk_fma_f32 v[8:9], s[2:3], v[20:21], v[8:9] op_sel_hi:[0,1,1]
	v_cvt_scalef32_pk_f32_fp4 v[20:21], v90, 1.0 op_sel:[1,1,0]
	v_pk_fma_f32 v[10:11], s[2:3], v[20:21], v[10:11] op_sel_hi:[0,1,1]
	v_cvt_scalef32_pk_f32_fp4 v[20:21], v91, 1.0
	v_pk_fma_f32 v[12:13], s[2:3], v[20:21], v[12:13] op_sel_hi:[0,1,1]
	v_cvt_scalef32_pk_f32_fp4 v[20:21], v91, 1.0 op_sel:[1,0,0]
	v_pk_fma_f32 v[14:15], s[2:3], v[20:21], v[14:15] op_sel_hi:[0,1,1]
	v_cvt_scalef32_pk_f32_fp4 v[20:21], v91, 1.0 op_sel:[0,1,0]
	v_pk_fma_f32 v[16:17], s[2:3], v[20:21], v[16:17] op_sel_hi:[0,1,1]
	v_cvt_scalef32_pk_f32_fp4 v[20:21], v91, 1.0 op_sel:[1,1,0]
	v_pk_fma_f32 v[18:19], s[2:3], v[20:21], v[18:19] op_sel_hi:[0,1,1]
	s_waitcnt vmcnt(5)
	v_cvt_scalef32_pk_f32_fp4 v[20:21], v92, 1.0
	s_nop 1
	v_readlane_b32 s2, v127, 21
	s_nop 1
	v_pk_fma_f32 v[4:5], v[20:21], s[2:3], v[4:5] op_sel_hi:[1,0,1]
	v_cvt_scalef32_pk_f32_fp4 v[20:21], v92, 1.0 op_sel:[1,0,0]
	v_pk_fma_f32 v[6:7], s[2:3], v[20:21], v[6:7] op_sel_hi:[0,1,1]
	v_cvt_scalef32_pk_f32_fp4 v[20:21], v92, 1.0 op_sel:[0,1,0]
	v_pk_fma_f32 v[8:9], s[2:3], v[20:21], v[8:9] op_sel_hi:[0,1,1]
	v_cvt_scalef32_pk_f32_fp4 v[20:21], v92, 1.0 op_sel:[1,1,0]
	v_pk_fma_f32 v[10:11], s[2:3], v[20:21], v[10:11] op_sel_hi:[0,1,1]
	v_cvt_scalef32_pk_f32_fp4 v[20:21], v93, 1.0
	v_pk_fma_f32 v[12:13], s[2:3], v[20:21], v[12:13] op_sel_hi:[0,1,1]
	v_cvt_scalef32_pk_f32_fp4 v[20:21], v93, 1.0 op_sel:[1,0,0]
	v_pk_fma_f32 v[14:15], s[2:3], v[20:21], v[14:15] op_sel_hi:[0,1,1]
	v_cvt_scalef32_pk_f32_fp4 v[20:21], v93, 1.0 op_sel:[0,1,0]
	v_pk_fma_f32 v[16:17], s[2:3], v[20:21], v[16:17] op_sel_hi:[0,1,1]
	v_cvt_scalef32_pk_f32_fp4 v[20:21], v93, 1.0 op_sel:[1,1,0]
	v_pk_fma_f32 v[18:19], s[2:3], v[20:21], v[18:19] op_sel_hi:[0,1,1]
	s_waitcnt vmcnt(4)
	v_cvt_scalef32_pk_f32_fp4 v[20:21], v94, 1.0
	s_nop 1
	v_readlane_b32 s2, v127, 29
	s_nop 1
	v_pk_fma_f32 v[4:5], v[20:21], s[2:3], v[4:5] op_sel_hi:[1,0,1]
	v_cvt_scalef32_pk_f32_fp4 v[20:21], v94, 1.0 op_sel:[1,0,0]
	v_pk_fma_f32 v[6:7], s[2:3], v[20:21], v[6:7] op_sel_hi:[0,1,1]
	v_cvt_scalef32_pk_f32_fp4 v[20:21], v94, 1.0 op_sel:[0,1,0]
	v_pk_fma_f32 v[8:9], s[2:3], v[20:21], v[8:9] op_sel_hi:[0,1,1]
	v_cvt_scalef32_pk_f32_fp4 v[20:21], v94, 1.0 op_sel:[1,1,0]
	v_pk_fma_f32 v[10:11], s[2:3], v[20:21], v[10:11] op_sel_hi:[0,1,1]
	v_cvt_scalef32_pk_f32_fp4 v[20:21], v95, 1.0
	v_pk_fma_f32 v[12:13], s[2:3], v[20:21], v[12:13] op_sel_hi:[0,1,1]
	v_cvt_scalef32_pk_f32_fp4 v[20:21], v95, 1.0 op_sel:[1,0,0]
	v_pk_fma_f32 v[14:15], s[2:3], v[20:21], v[14:15] op_sel_hi:[0,1,1]
	v_cvt_scalef32_pk_f32_fp4 v[20:21], v95, 1.0 op_sel:[0,1,0]
	v_pk_fma_f32 v[16:17], s[2:3], v[20:21], v[16:17] op_sel_hi:[0,1,1]
	v_cvt_scalef32_pk_f32_fp4 v[20:21], v95, 1.0 op_sel:[1,1,0]
	v_pk_fma_f32 v[18:19], s[2:3], v[20:21], v[18:19] op_sel_hi:[0,1,1]
	s_waitcnt vmcnt(3)
	v_cvt_scalef32_pk_f32_fp4 v[20:21], v96, 1.0
	s_nop 1
	v_readlane_b32 s2, v127, 19
	s_nop 1
	v_pk_fma_f32 v[4:5], v[20:21], s[2:3], v[4:5] op_sel_hi:[1,0,1]
	v_cvt_scalef32_pk_f32_fp4 v[20:21], v96, 1.0 op_sel:[1,0,0]
	v_pk_fma_f32 v[6:7], s[2:3], v[20:21], v[6:7] op_sel_hi:[0,1,1]
	v_cvt_scalef32_pk_f32_fp4 v[20:21], v96, 1.0 op_sel:[0,1,0]
	v_pk_fma_f32 v[8:9], s[2:3], v[20:21], v[8:9] op_sel_hi:[0,1,1]
	v_cvt_scalef32_pk_f32_fp4 v[20:21], v96, 1.0 op_sel:[1,1,0]
	v_pk_fma_f32 v[10:11], s[2:3], v[20:21], v[10:11] op_sel_hi:[0,1,1]
	v_cvt_scalef32_pk_f32_fp4 v[20:21], v97, 1.0
	v_pk_fma_f32 v[12:13], s[2:3], v[20:21], v[12:13] op_sel_hi:[0,1,1]
	v_cvt_scalef32_pk_f32_fp4 v[20:21], v97, 1.0 op_sel:[1,0,0]
	v_pk_fma_f32 v[14:15], s[2:3], v[20:21], v[14:15] op_sel_hi:[0,1,1]
	v_cvt_scalef32_pk_f32_fp4 v[20:21], v97, 1.0 op_sel:[0,1,0]
	v_pk_fma_f32 v[16:17], s[2:3], v[20:21], v[16:17] op_sel_hi:[0,1,1]
	v_cvt_scalef32_pk_f32_fp4 v[20:21], v97, 1.0 op_sel:[1,1,0]
	v_pk_fma_f32 v[18:19], s[2:3], v[20:21], v[18:19] op_sel_hi:[0,1,1]
	s_waitcnt vmcnt(2)
	v_cvt_scalef32_pk_f32_fp4 v[20:21], v98, 1.0
	s_nop 1
	v_readlane_b32 s2, v127, 27
	s_nop 1
	v_pk_fma_f32 v[4:5], v[20:21], s[2:3], v[4:5] op_sel_hi:[1,0,1]
	v_cvt_scalef32_pk_f32_fp4 v[20:21], v98, 1.0 op_sel:[1,0,0]
	v_pk_fma_f32 v[6:7], s[2:3], v[20:21], v[6:7] op_sel_hi:[0,1,1]
	v_cvt_scalef32_pk_f32_fp4 v[20:21], v98, 1.0 op_sel:[0,1,0]
	v_pk_fma_f32 v[8:9], s[2:3], v[20:21], v[8:9] op_sel_hi:[0,1,1]
	v_cvt_scalef32_pk_f32_fp4 v[20:21], v98, 1.0 op_sel:[1,1,0]
	v_pk_fma_f32 v[10:11], s[2:3], v[20:21], v[10:11] op_sel_hi:[0,1,1]
	v_cvt_scalef32_pk_f32_fp4 v[20:21], v99, 1.0
	v_pk_fma_f32 v[12:13], s[2:3], v[20:21], v[12:13] op_sel_hi:[0,1,1]
	v_cvt_scalef32_pk_f32_fp4 v[20:21], v99, 1.0 op_sel:[1,0,0]
	v_pk_fma_f32 v[14:15], s[2:3], v[20:21], v[14:15] op_sel_hi:[0,1,1]
	v_cvt_scalef32_pk_f32_fp4 v[20:21], v99, 1.0 op_sel:[0,1,0]
	v_pk_fma_f32 v[16:17], s[2:3], v[20:21], v[16:17] op_sel_hi:[0,1,1]
	v_cvt_scalef32_pk_f32_fp4 v[20:21], v99, 1.0 op_sel:[1,1,0]
	v_pk_fma_f32 v[18:19], s[2:3], v[20:21], v[18:19] op_sel_hi:[0,1,1]
	s_waitcnt vmcnt(1)
	v_cvt_scalef32_pk_f32_fp4 v[20:21], v100, 1.0
	s_nop 1
	v_readlane_b32 s2, v127, 23
	s_nop 1
	v_pk_fma_f32 v[4:5], v[20:21], s[2:3], v[4:5] op_sel_hi:[1,0,1]
	v_cvt_scalef32_pk_f32_fp4 v[20:21], v100, 1.0 op_sel:[1,0,0]
	v_pk_fma_f32 v[6:7], s[2:3], v[20:21], v[6:7] op_sel_hi:[0,1,1]
	v_cvt_scalef32_pk_f32_fp4 v[20:21], v100, 1.0 op_sel:[0,1,0]
	v_pk_fma_f32 v[8:9], s[2:3], v[20:21], v[8:9] op_sel_hi:[0,1,1]
	v_cvt_scalef32_pk_f32_fp4 v[20:21], v100, 1.0 op_sel:[1,1,0]
	v_pk_fma_f32 v[10:11], s[2:3], v[20:21], v[10:11] op_sel_hi:[0,1,1]
	v_cvt_scalef32_pk_f32_fp4 v[20:21], v101, 1.0
	v_pk_fma_f32 v[12:13], s[2:3], v[20:21], v[12:13] op_sel_hi:[0,1,1]
	v_cvt_scalef32_pk_f32_fp4 v[20:21], v101, 1.0 op_sel:[1,0,0]
	v_pk_fma_f32 v[14:15], s[2:3], v[20:21], v[14:15] op_sel_hi:[0,1,1]
	v_cvt_scalef32_pk_f32_fp4 v[20:21], v101, 1.0 op_sel:[0,1,0]
	v_pk_fma_f32 v[16:17], s[2:3], v[20:21], v[16:17] op_sel_hi:[0,1,1]
	v_cvt_scalef32_pk_f32_fp4 v[20:21], v101, 1.0 op_sel:[1,1,0]
	v_pk_fma_f32 v[18:19], s[2:3], v[20:21], v[18:19] op_sel_hi:[0,1,1]
	s_waitcnt vmcnt(0)
	v_cvt_scalef32_pk_f32_fp4 v[20:21], v102, 1.0
	s_nop 1
	v_readlane_b32 s2, v127, 31
	s_nop 1
	v_pk_fma_f32 v[4:5], v[20:21], s[2:3], v[4:5] op_sel_hi:[1,0,1]
	v_cvt_scalef32_pk_f32_fp4 v[20:21], v102, 1.0 op_sel:[1,0,0]
	v_pk_fma_f32 v[6:7], s[2:3], v[20:21], v[6:7] op_sel_hi:[0,1,1]
	v_cvt_scalef32_pk_f32_fp4 v[20:21], v102, 1.0 op_sel:[0,1,0]
	v_pk_fma_f32 v[8:9], s[2:3], v[20:21], v[8:9] op_sel_hi:[0,1,1]
	v_cvt_scalef32_pk_f32_fp4 v[20:21], v102, 1.0 op_sel:[1,1,0]
	v_pk_fma_f32 v[10:11], s[2:3], v[20:21], v[10:11] op_sel_hi:[0,1,1]
	v_cvt_scalef32_pk_f32_fp4 v[20:21], v103, 1.0
	v_pk_fma_f32 v[12:13], s[2:3], v[20:21], v[12:13] op_sel_hi:[0,1,1]
	v_cvt_scalef32_pk_f32_fp4 v[20:21], v103, 1.0 op_sel:[1,0,0]
	v_pk_fma_f32 v[14:15], s[2:3], v[20:21], v[14:15] op_sel_hi:[0,1,1]
	v_cvt_scalef32_pk_f32_fp4 v[20:21], v103, 1.0 op_sel:[0,1,0]
	v_pk_fma_f32 v[16:17], s[2:3], v[20:21], v[16:17] op_sel_hi:[0,1,1]
	v_cvt_scalef32_pk_f32_fp4 v[20:21], v103, 1.0 op_sel:[1,1,0]
	v_pk_fma_f32 v[18:19], s[2:3], v[20:21], v[18:19] op_sel_hi:[0,1,1]
	s_branch .Lh3_v10_join
.Lh3_v10_hi:
	v_readlane_b32 s84, v102, 32
	v_readlane_b32 s86, v102, 33
	v_readlane_b32 s88, v102, 34
	v_readlane_b32 s90, v102, 35
	s_ashr_i32 s85, s84, 31
	s_ashr_i32 s87, s86, 31
	s_ashr_i32 s89, s88, 31
	s_ashr_i32 s91, s90, 31
	s_lshl_b64 s[84:85], s[84:85], 9
	s_lshl_b64 s[86:87], s[86:87], 9
	s_lshl_b64 s[88:89], s[88:89], 9
	s_lshl_b64 s[90:91], s[90:91], 9
	v_lshl_add_u64 v[20:21], v[40:41], 0, s[84:85]
	v_lshl_add_u64 v[22:23], v[40:41], 0, s[86:87]
	v_lshl_add_u64 v[24:25], v[40:41], 0, s[88:89]
	v_lshl_add_u64 v[26:27], v[40:41], 0, s[90:91]
	global_load_dwordx2 v[20:21], v[20:21], off
	global_load_dwordx2 v[22:23], v[22:23], off
	global_load_dwordx2 v[24:25], v[24:25], off
	global_load_dwordx2 v[26:27], v[26:27], off
	v_readlane_b32 s84, v102, 36
	v_readlane_b32 s86, v102, 37
	v_readlane_b32 s88, v102, 38
	v_readlane_b32 s90, v102, 39
	s_ashr_i32 s85, s84, 31
	s_ashr_i32 s87, s86, 31
	s_ashr_i32 s89, s88, 31
	s_ashr_i32 s91, s90, 31
	s_lshl_b64 s[84:85], s[84:85], 9
	s_lshl_b64 s[86:87], s[86:87], 9
	s_lshl_b64 s[88:89], s[88:89], 9
	s_lshl_b64 s[90:91], s[90:91], 9
	v_lshl_add_u64 v[28:29], v[40:41], 0, s[84:85]
	v_lshl_add_u64 v[30:31], v[40:41], 0, s[86:87]
	v_lshl_add_u64 v[32:33], v[40:41], 0, s[88:89]
	v_lshl_add_u64 v[34:35], v[40:41], 0, s[90:91]
	global_load_dwordx2 v[28:29], v[28:29], off
	global_load_dwordx2 v[30:31], v[30:31], off
	global_load_dwordx2 v[32:33], v[32:33], off
	global_load_dwordx2 v[34:35], v[34:35], off
	v_readlane_b32 s84, v102, 40
	v_readlane_b32 s86, v102, 41
	v_readlane_b32 s88, v102, 42
	v_readlane_b32 s90, v102, 43
	s_ashr_i32 s85, s84, 31
	s_ashr_i32 s87, s86, 31
	s_ashr_i32 s89, s88, 31
	s_ashr_i32 s91, s90, 31
	s_lshl_b64 s[84:85], s[84:85], 9
	s_lshl_b64 s[86:87], s[86:87], 9
	s_lshl_b64 s[88:89], s[88:89], 9
	s_lshl_b64 s[90:91], s[90:91], 9
	v_lshl_add_u64 v[56:57], v[40:41], 0, s[84:85]
	v_lshl_add_u64 v[58:59], v[40:41], 0, s[86:87]
	v_lshl_add_u64 v[60:61], v[40:41], 0, s[88:89]
	v_lshl_add_u64 v[62:63], v[40:41], 0, s[90:91]
	global_load_dwordx2 v[56:57], v[56:57], off
	global_load_dwordx2 v[58:59], v[58:59], off
	global_load_dwordx2 v[60:61], v[60:61], off
	global_load_dwordx2 v[62:63], v[62:63], off
	v_readlane_b32 s84, v102, 44
	v_readlane_b32 s86, v102, 45
	v_readlane_b32 s88, v102, 46
	v_readlane_b32 s90, v102, 47
	s_ashr_i32 s85, s84, 31
	s_ashr_i32 s87, s86, 31
	s_ashr_i32 s89, s88, 31
	s_ashr_i32 s91, s90, 31
	s_lshl_b64 s[84:85], s[84:85], 9
	s_lshl_b64 s[86:87], s[86:87], 9
	s_lshl_b64 s[88:89], s[88:89], 9
	s_lshl_b64 s[90:91], s[90:91], 9
	v_lshl_add_u64 v[64:65], v[40:41], 0, s[84:85]
	v_lshl_add_u64 v[66:67], v[40:41], 0, s[86:87]
	v_lshl_add_u64 v[68:69], v[40:41], 0, s[88:89]
	v_lshl_add_u64 v[70:71], v[40:41], 0, s[90:91]
	global_load_dwordx2 v[64:65], v[64:65], off
	global_load_dwordx2 v[66:67], v[66:67], off
	global_load_dwordx2 v[68:69], v[68:69], off
	global_load_dwordx2 v[70:71], v[70:71], off
	v_readlane_b32 s84, v102, 48
	v_readlane_b32 s86, v102, 49
	v_readlane_b32 s88, v102, 50
	v_readlane_b32 s90, v102, 51
	s_ashr_i32 s85, s84, 31
	s_ashr_i32 s87, s86, 31
	s_ashr_i32 s89, s88, 31
	s_ashr_i32 s91, s90, 31
	s_lshl_b64 s[84:85], s[84:85], 9
	s_lshl_b64 s[86:87], s[86:87], 9
	s_lshl_b64 s[88:89], s[88:89], 9
	s_lshl_b64 s[90:91], s[90:91], 9
	v_lshl_add_u64 v[72:73], v[40:41], 0, s[84:85]
	v_lshl_add_u64 v[74:75], v[40:41], 0, s[86:87]
	v_lshl_add_u64 v[76:77], v[40:41], 0, s[88:89]
	v_lshl_add_u64 v[78:79], v[40:41], 0, s[90:91]
	global_load_dwordx2 v[72:73], v[72:73], off
	global_load_dwordx2 v[74:75], v[74:75], off
	global_load_dwordx2 v[76:77], v[76:77], off
	global_load_dwordx2 v[78:79], v[78:79], off
	v_readlane_b32 s84, v102, 52
	v_readlane_b32 s86, v102, 53
	v_readlane_b32 s88, v102, 54
	v_readlane_b32 s90, v102, 55
	s_ashr_i32 s85, s84, 31
	s_ashr_i32 s87, s86, 31
	s_ashr_i32 s89, s88, 31
	s_ashr_i32 s91, s90, 31
	s_lshl_b64 s[84:85], s[84:85], 9
	s_lshl_b64 s[86:87], s[86:87], 9
	s_lshl_b64 s[88:89], s[88:89], 9
	s_lshl_b64 s[90:91], s[90:91], 9
	v_lshl_add_u64 v[80:81], v[40:41], 0, s[84:85]
	v_lshl_add_u64 v[82:83], v[40:41], 0, s[86:87]
	v_lshl_add_u64 v[84:85], v[40:41], 0, s[88:89]
	v_lshl_add_u64 v[86:87], v[40:41], 0, s[90:91]
	global_load_dwordx2 v[80:81], v[80:81], off
	global_load_dwordx2 v[82:83], v[82:83], off
	global_load_dwordx2 v[84:85], v[84:85], off
	global_load_dwordx2 v[86:87], v[86:87], off
	v_readlane_b32 s84, v102, 56
	v_readlane_b32 s86, v102, 57
	v_readlane_b32 s88, v102, 58
	v_readlane_b32 s90, v102, 59
	s_ashr_i32 s85, s84, 31
	s_ashr_i32 s87, s86, 31
	s_ashr_i32 s89, s88, 31
	s_ashr_i32 s91, s90, 31
	s_lshl_b64 s[84:85], s[84:85], 9
	s_lshl_b64 s[86:87], s[86:87], 9
	s_lshl_b64 s[88:89], s[88:89], 9
	s_lshl_b64 s[90:91], s[90:91], 9
	v_lshl_add_u64 v[88:89], v[40:41], 0, s[84:85]
	v_lshl_add_u64 v[90:91], v[40:41], 0, s[86:87]
	v_lshl_add_u64 v[92:93], v[40:41], 0, s[88:89]
	v_lshl_add_u64 v[94:95], v[40:41], 0, s[90:91]
	global_load_dwordx2 v[88:89], v[88:89], off
	global_load_dwordx2 v[90:91], v[90:91], off
	global_load_dwordx2 v[92:93], v[92:93], off
	global_load_dwordx2 v[94:95], v[94:95], off
	v_readlane_b32 s84, v102, 60
	v_readlane_b32 s86, v102, 61
	v_readlane_b32 s88, v102, 62
	v_readlane_b32 s90, v102, 63
	s_ashr_i32 s85, s84, 31
	s_ashr_i32 s87, s86, 31
	s_ashr_i32 s89, s88, 31
	s_ashr_i32 s91, s90, 31
	s_lshl_b64 s[84:85], s[84:85], 9
	s_lshl_b64 s[86:87], s[86:87], 9
	s_lshl_b64 s[88:89], s[88:89], 9
	s_lshl_b64 s[90:91], s[90:91], 9
	v_lshl_add_u64 v[96:97], v[40:41], 0, s[84:85]
	v_lshl_add_u64 v[98:99], v[40:41], 0, s[86:87]
	v_lshl_add_u64 v[100:101], v[40:41], 0, s[88:89]
	v_lshl_add_u64 v[102:103], v[40:41], 0, s[90:91]
	global_load_dwordx2 v[96:97], v[96:97], off
	global_load_dwordx2 v[98:99], v[98:99], off
	global_load_dwordx2 v[100:101], v[100:101], off
	global_load_dwordx2 v[102:103], v[102:103], off
	v_cndmask_b32_e32 v127, v3, v119, vcc
	s_waitcnt vmcnt(31)
	v_cvt_scalef32_pk_f32_fp4 v[130:131], v20, 1.0
	v_readlane_b32 s28, v127, 34
	v_readlane_b32 s2, v127, 35
	v_add_u32_e32 v116, 32, v116
	v_cmp_ge_u32_e32 vcc, v116, v115
	s_nop 0
	s_nop 0
	s_nop 0
	v_readlane_b32 s64, v127, 32
	s_or_b64 s[14:15], vcc, s[14:15]
	s_nop 0
	v_pk_fma_f32 v[4:5], v[130:131], s[64:65], v[4:5] op_sel_hi:[1,0,1]
	v_cvt_scalef32_pk_f32_fp4 v[130:131], v20, 1.0 op_sel:[1,0,0]
	v_pk_fma_f32 v[6:7], s[64:65], v[130:131], v[6:7] op_sel_hi:[0,1,1]
	v_cvt_scalef32_pk_f32_fp4 v[130:131], v20, 1.0 op_sel:[0,1,0]
	v_pk_fma_f32 v[8:9], s[64:65], v[130:131], v[8:9] op_sel_hi:[0,1,1]
	v_cvt_scalef32_pk_f32_fp4 v[130:131], v20, 1.0 op_sel:[1,1,0]
	v_pk_fma_f32 v[10:11], s[64:65], v[130:131], v[10:11] op_sel_hi:[0,1,1]
	v_cvt_scalef32_pk_f32_fp4 v[130:131], v21, 1.0
	v_pk_fma_f32 v[12:13], s[64:65], v[130:131], v[12:13] op_sel_hi:[0,1,1]
	v_cvt_scalef32_pk_f32_fp4 v[130:131], v21, 1.0 op_sel:[1,0,0]
	v_pk_fma_f32 v[14:15], s[64:65], v[130:131], v[14:15] op_sel_hi:[0,1,1]
	v_cvt_scalef32_pk_f32_fp4 v[130:131], v21, 1.0 op_sel:[0,1,0]
	v_cvt_scalef32_pk_f32_fp4 v[20:21], v21, 1.0 op_sel:[1,1,0]
	v_pk_fma_f32 v[16:17], s[64:65], v[130:131], v[16:17] op_sel_hi:[0,1,1]
	v_pk_fma_f32 v[18:19], s[64:65], v[20:21], v[18:19] op_sel_hi:[0,1,1]
	v_readlane_b32 s64, v127, 40
	s_waitcnt vmcnt(30)
	v_cvt_scalef32_pk_f32_fp4 v[20:21], v22, 1.0
	v_pk_fma_f32 v[4:5], v[20:21], s[64:65], v[4:5] op_sel_hi:[1,0,1]
	v_cvt_scalef32_pk_f32_fp4 v[20:21], v22, 1.0 op_sel:[1,0,0]
	v_pk_fma_f32 v[6:7], s[64:65], v[20:21], v[6:7] op_sel_hi:[0,1,1]
	v_cvt_scalef32_pk_f32_fp4 v[20:21], v22, 1.0 op_sel:[0,1,0]
	v_pk_fma_f32 v[8:9], s[64:65], v[20:21], v[8:9] op_sel_hi:[0,1,1]
	v_cvt_scalef32_pk_f32_fp4 v[20:21], v22, 1.0 op_sel:[1,1,0]
	v_pk_fma_f32 v[10:11], s[64:65], v[20:21], v[10:11] op_sel_hi:[0,1,1]
	v_cvt_scalef32_pk_f32_fp4 v[20:21], v23, 1.0
	v_pk_fma_f32 v[12:13], s[64:65], v[20:21], v[12:13] op_sel_hi:[0,1,1]
	v_cvt_scalef32_pk_f32_fp4 v[20:21], v23, 1.0 op_sel:[1,0,0]
	v_pk_fma_f32 v[14:15], s[64:65], v[20:21], v[14:15] op_sel_hi:[0,1,1]
	v_cvt_scalef32_pk_f32_fp4 v[20:21], v23, 1.0 op_sel:[0,1,0]
	v_pk_fma_f32 v[16:17], s[64:65], v[20:21], v[16:17] op_sel_hi:[0,1,1]
	v_cvt_scalef32_pk_f32_fp4 v[20:21], v23, 1.0 op_sel:[1,1,0]
	v_pk_fma_f32 v[18:19], s[64:65], v[20:21], v[18:19] op_sel_hi:[0,1,1]
	v_readlane_b32 s64, v127, 36
	s_waitcnt vmcnt(29)
	v_cvt_scalef32_pk_f32_fp4 v[20:21], v24, 1.0
	v_pk_fma_f32 v[4:5], v[20:21], s[64:65], v[4:5] op_sel_hi:[1,0,1]
	v_cvt_scalef32_pk_f32_fp4 v[20:21], v24, 1.0 op_sel:[1,0,0]
	v_pk_fma_f32 v[6:7], s[64:65], v[20:21], v[6:7] op_sel_hi:[0,1,1]
	v_cvt_scalef32_pk_f32_fp4 v[20:21], v24, 1.0 op_sel:[0,1,0]
	v_pk_fma_f32 v[8:9], s[64:65], v[20:21], v[8:9] op_sel_hi:[0,1,1]
	v_cvt_scalef32_pk_f32_fp4 v[20:21], v24, 1.0 op_sel:[1,1,0]
	v_pk_fma_f32 v[10:11], s[64:65], v[20:21], v[10:11] op_sel_hi:[0,1,1]
	v_cvt_scalef32_pk_f32_fp4 v[20:21], v25, 1.0
	v_pk_fma_f32 v[12:13], s[64:65], v[20:21], v[12:13] op_sel_hi:[0,1,1]
	v_cvt_scalef32_pk_f32_fp4 v[20:21], v25, 1.0 op_sel:[1,0,0]
	v_pk_fma_f32 v[14:15], s[64:65], v[20:21], v[14:15] op_sel_hi:[0,1,1]
	v_cvt_scalef32_pk_f32_fp4 v[20:21], v25, 1.0 op_sel:[0,1,0]
	v_pk_fma_f32 v[16:17], s[64:65], v[20:21], v[16:17] op_sel_hi:[0,1,1]
	v_cvt_scalef32_pk_f32_fp4 v[20:21], v25, 1.0 op_sel:[1,1,0]
	v_pk_fma_f32 v[18:19], s[64:65], v[20:21], v[18:19] op_sel_hi:[0,1,1]
	v_readlane_b32 s64, v127, 44
	s_waitcnt vmcnt(28)
	v_cvt_scalef32_pk_f32_fp4 v[20:21], v26, 1.0
	v_pk_fma_f32 v[4:5], v[20:21], s[64:65], v[4:5] op_sel_hi:[1,0,1]
	v_cvt_scalef32_pk_f32_fp4 v[20:21], v26, 1.0 op_sel:[1,0,0]
	v_pk_fma_f32 v[6:7], s[64:65], v[20:21], v[6:7] op_sel_hi:[0,1,1]
	v_cvt_scalef32_pk_f32_fp4 v[20:21], v26, 1.0 op_sel:[0,1,0]
	v_pk_fma_f32 v[8:9], s[64:65], v[20:21], v[8:9] op_sel_hi:[0,1,1]
	v_cvt_scalef32_pk_f32_fp4 v[20:21], v26, 1.0 op_sel:[1,1,0]
	v_pk_fma_f32 v[10:11], s[64:65], v[20:21], v[10:11] op_sel_hi:[0,1,1]
	v_cvt_scalef32_pk_f32_fp4 v[20:21], v27, 1.0
	v_pk_fma_f32 v[12:13], s[64:65], v[20:21], v[12:13] op_sel_hi:[0,1,1]
	v_cvt_scalef32_pk_f32_fp4 v[20:21], v27, 1.0 op_sel:[1,0,0]
	v_pk_fma_f32 v[14:15], s[64:65], v[20:21], v[14:15] op_sel_hi:[0,1,1]
	v_cvt_scalef32_pk_f32_fp4 v[20:21], v27, 1.0 op_sel:[0,1,0]
	v_pk_fma_f32 v[16:17], s[64:65], v[20:21], v[16:17] op_sel_hi:[0,1,1]
	v_cvt_scalef32_pk_f32_fp4 v[20:21], v27, 1.0 op_sel:[1,1,0]
	v_pk_fma_f32 v[18:19], s[64:65], v[20:21], v[18:19] op_sel_hi:[0,1,1]
	s_waitcnt vmcnt(27)
	v_cvt_scalef32_pk_f32_fp4 v[20:21], v28, 1.0
	v_pk_fma_f32 v[4:5], v[20:21], s[28:29], v[4:5] op_sel_hi:[1,0,1]
	v_cvt_scalef32_pk_f32_fp4 v[20:21], v28, 1.0 op_sel:[1,0,0]
	v_pk_fma_f32 v[6:7], s[28:29], v[20:21], v[6:7] op_sel_hi:[0,1,1]
	v_cvt_scalef32_pk_f32_fp4 v[20:21], v28, 1.0 op_sel:[0,1,0]
	v_pk_fma_f32 v[8:9], s[28:29], v[20:21], v[8:9] op_sel_hi:[0,1,1]
	v_cvt_scalef32_pk_f32_fp4 v[20:21], v28, 1.0 op_sel:[1,1,0]
	v_pk_fma_f32 v[10:11], s[28:29], v[20:21], v[10:11] op_sel_hi:[0,1,1]
	v_cvt_scalef32_pk_f32_fp4 v[20:21], v29, 1.0
	v_pk_fma_f32 v[12:13], s[28:29], v[20:21], v[12:13] op_sel_hi:[0,1,1]
	v_cvt_scalef32_pk_f32_fp4 v[20:21], v29, 1.0 op_sel:[1,0,0]
	v_pk_fma_f32 v[14:15], s[28:29], v[20:21], v[14:15] op_sel_hi:[0,1,1]
	v_cvt_scalef32_pk_f32_fp4 v[20:21], v29, 1.0 op_sel:[0,1,0]
	v_pk_fma_f32 v[16:17], s[28:29], v[20:21], v[16:17] op_sel_hi:[0,1,1]
	v_cvt_scalef32_pk_f32_fp4 v[20:21], v29, 1.0 op_sel:[1,1,0]
	v_pk_fma_f32 v[18:19], s[28:29], v[20:21], v[18:19] op_sel_hi:[0,1,1]
	v_readlane_b32 s28, v127, 42
	s_waitcnt vmcnt(26)
	v_cvt_scalef32_pk_f32_fp4 v[20:21], v30, 1.0
	v_pk_fma_f32 v[4:5], v[20:21], s[28:29], v[4:5] op_sel_hi:[1,0,1]
	v_cvt_scalef32_pk_f32_fp4 v[20:21], v30, 1.0 op_sel:[1,0,0]
	v_pk_fma_f32 v[6:7], s[28:29], v[20:21], v[6:7] op_sel_hi:[0,1,1]
	v_cvt_scalef32_pk_f32_fp4 v[20:21], v30, 1.0 op_sel:[0,1,0]
	v_pk_fma_f32 v[8:9], s[28:29], v[20:21], v[8:9] op_sel_hi:[0,1,1]
	v_cvt_scalef32_pk_f32_fp4 v[20:21], v30, 1.0 op_sel:[1,1,0]
	v_pk_fma_f32 v[10:11], s[28:29], v[20:21], v[10:11] op_sel_hi:[0,1,1]
	v_cvt_scalef32_pk_f32_fp4 v[20:21], v31, 1.0
	v_pk_fma_f32 v[12:13], s[28:29], v[20:21], v[12:13] op_sel_hi:[0,1,1]
	v_cvt_scalef32_pk_f32_fp4 v[20:21], v31, 1.0 op_sel:[1,0,0]
	v_pk_fma_f32 v[14:15], s[28:29], v[20:21], v[14:15] op_sel_hi:[0,1,1]
	v_cvt_scalef32_pk_f32_fp4 v[20:21], v31, 1.0 op_sel:[0,1,0]
	v_pk_fma_f32 v[16:17], s[28:29], v[20:21], v[16:17] op_sel_hi:[0,1,1]
	v_cvt_scalef32_pk_f32_fp4 v[20:21], v31, 1.0 op_sel:[1,1,0]
	v_pk_fma_f32 v[18:19], s[28:29], v[20:21], v[18:19] op_sel_hi:[0,1,1]
	v_readlane_b32 s28, v127, 38
	s_waitcnt vmcnt(25)
	v_cvt_scalef32_pk_f32_fp4 v[20:21], v32, 1.0
	v_pk_fma_f32 v[4:5], v[20:21], s[28:29], v[4:5] op_sel_hi:[1,0,1]
	v_cvt_scalef32_pk_f32_fp4 v[20:21], v32, 1.0 op_sel:[1,0,0]
	v_pk_fma_f32 v[6:7], s[28:29], v[20:21], v[6:7] op_sel_hi:[0,1,1]
	v_cvt_scalef32_pk_f32_fp4 v[20:21], v32, 1.0 op_sel:[0,1,0]
	v_pk_fma_f32 v[8:9], s[28:29], v[20:21], v[8:9] op_sel_hi:[0,1,1]
	v_cvt_scalef32_pk_f32_fp4 v[20:21], v32, 1.0 op_sel:[1,1,0]
	v_pk_fma_f32 v[10:11], s[28:29], v[20:21], v[10:11] op_sel_hi:[0,1,1]
	v_cvt_scalef32_pk_f32_fp4 v[20:21], v33, 1.0
	v_pk_fma_f32 v[12:13], s[28:29], v[20:21], v[12:13] op_sel_hi:[0,1,1]
	v_cvt_scalef32_pk_f32_fp4 v[20:21], v33, 1.0 op_sel:[1,0,0]
	v_pk_fma_f32 v[14:15], s[28:29], v[20:21], v[14:15] op_sel_hi:[0,1,1]
	v_cvt_scalef32_pk_f32_fp4 v[20:21], v33, 1.0 op_sel:[0,1,0]
	v_pk_fma_f32 v[16:17], s[28:29], v[20:21], v[16:17] op_sel_hi:[0,1,1]
	v_cvt_scalef32_pk_f32_fp4 v[20:21], v33, 1.0 op_sel:[1,1,0]
	v_pk_fma_f32 v[18:19], s[28:29], v[20:21], v[18:19] op_sel_hi:[0,1,1]
	v_readlane_b32 s28, v127, 46
	s_waitcnt vmcnt(24)
	v_cvt_scalef32_pk_f32_fp4 v[20:21], v34, 1.0
	v_pk_fma_f32 v[4:5], v[20:21], s[28:29], v[4:5] op_sel_hi:[1,0,1]
	v_cvt_scalef32_pk_f32_fp4 v[20:21], v34, 1.0 op_sel:[1,0,0]
	v_pk_fma_f32 v[6:7], s[28:29], v[20:21], v[6:7] op_sel_hi:[0,1,1]
	v_cvt_scalef32_pk_f32_fp4 v[20:21], v34, 1.0 op_sel:[0,1,0]
	v_pk_fma_f32 v[8:9], s[28:29], v[20:21], v[8:9] op_sel_hi:[0,1,1]
	v_cvt_scalef32_pk_f32_fp4 v[20:21], v34, 1.0 op_sel:[1,1,0]
	v_pk_fma_f32 v[10:11], s[28:29], v[20:21], v[10:11] op_sel_hi:[0,1,1]
	v_cvt_scalef32_pk_f32_fp4 v[20:21], v35, 1.0
	v_pk_fma_f32 v[12:13], s[28:29], v[20:21], v[12:13] op_sel_hi:[0,1,1]
	v_cvt_scalef32_pk_f32_fp4 v[20:21], v35, 1.0 op_sel:[1,0,0]
	v_pk_fma_f32 v[14:15], s[28:29], v[20:21], v[14:15] op_sel_hi:[0,1,1]
	v_cvt_scalef32_pk_f32_fp4 v[20:21], v35, 1.0 op_sel:[0,1,0]
	v_pk_fma_f32 v[16:17], s[28:29], v[20:21], v[16:17] op_sel_hi:[0,1,1]
	v_cvt_scalef32_pk_f32_fp4 v[20:21], v35, 1.0 op_sel:[1,1,0]
	v_pk_fma_f32 v[18:19], s[28:29], v[20:21], v[18:19] op_sel_hi:[0,1,1]
	v_readlane_b32 s28, v127, 33
	s_waitcnt vmcnt(23)
	v_cvt_scalef32_pk_f32_fp4 v[20:21], v56, 1.0
	v_pk_fma_f32 v[4:5], v[20:21], s[28:29], v[4:5] op_sel_hi:[1,0,1]
	v_cvt_scalef32_pk_f32_fp4 v[20:21], v56, 1.0 op_sel:[1,0,0]
	v_pk_fma_f32 v[6:7], s[28:29], v[20:21], v[6:7] op_sel_hi:[0,1,1]
	v_cvt_scalef32_pk_f32_fp4 v[20:21], v56, 1.0 op_sel:[0,1,0]
	v_pk_fma_f32 v[8:9], s[28:29], v[20:21], v[8:9] op_sel_hi:[0,1,1]
	v_cvt_scalef32_pk_f32_fp4 v[20:21], v56, 1.0 op_sel:[1,1,0]
	v_pk_fma_f32 v[10:11], s[28:29], v[20:21], v[10:11] op_sel_hi:[0,1,1]
	v_cvt_scalef32_pk_f32_fp4 v[20:21], v57, 1.0
	v_pk_fma_f32 v[12:13], s[28:29], v[20:21], v[12:13] op_sel_hi:[0,1,1]
	v_cvt_scalef32_pk_f32_fp4 v[20:21], v57, 1.0 op_sel:[1,0,0]
	v_pk_fma_f32 v[14:15], s[28:29], v[20:21], v[14:15] op_sel_hi:[0,1,1]
	v_cvt_scalef32_pk_f32_fp4 v[20:21], v57, 1.0 op_sel:[0,1,0]
	v_pk_fma_f32 v[16:17], s[28:29], v[20:21], v[16:17] op_sel_hi:[0,1,1]
	v_cvt_scalef32_pk_f32_fp4 v[20:21], v57, 1.0 op_sel:[1,1,0]
	v_pk_fma_f32 v[18:19], s[28:29], v[20:21], v[18:19] op_sel_hi:[0,1,1]
	v_readlane_b32 s28, v127, 41
	s_waitcnt vmcnt(22)
	v_cvt_scalef32_pk_f32_fp4 v[20:21], v58, 1.0
	v_pk_fma_f32 v[4:5], v[20:21], s[28:29], v[4:5] op_sel_hi:[1,0,1]
	v_cvt_scalef32_pk_f32_fp4 v[20:21], v58, 1.0 op_sel:[1,0,0]
	v_pk_fma_f32 v[6:7], s[28:29], v[20:21], v[6:7] op_sel_hi:[0,1,1]
	v_cvt_scalef32_pk_f32_fp4 v[20:21], v58, 1.0 op_sel:[0,1,0]
	v_pk_fma_f32 v[8:9], s[28:29], v[20:21], v[8:9] op_sel_hi:[0,1,1]
	v_cvt_scalef32_pk_f32_fp4 v[20:21], v58, 1.0 op_sel:[1,1,0]
	v_pk_fma_f32 v[10:11], s[28:29], v[20:21], v[10:11] op_sel_hi:[0,1,1]
	v_cvt_scalef32_pk_f32_fp4 v[20:21], v59, 1.0
	v_pk_fma_f32 v[12:13], s[28:29], v[20:21], v[12:13] op_sel_hi:[0,1,1]
	v_cvt_scalef32_pk_f32_fp4 v[20:21], v59, 1.0 op_sel:[1,0,0]
	v_pk_fma_f32 v[14:15], s[28:29], v[20:21], v[14:15] op_sel_hi:[0,1,1]
	v_cvt_scalef32_pk_f32_fp4 v[20:21], v59, 1.0 op_sel:[0,1,0]
	v_pk_fma_f32 v[16:17], s[28:29], v[20:21], v[16:17] op_sel_hi:[0,1,1]
	v_cvt_scalef32_pk_f32_fp4 v[20:21], v59, 1.0 op_sel:[1,1,0]
	v_pk_fma_f32 v[18:19], s[28:29], v[20:21], v[18:19] op_sel_hi:[0,1,1]
	v_readlane_b32 s28, v127, 37
	s_waitcnt vmcnt(21)
	v_cvt_scalef32_pk_f32_fp4 v[20:21], v60, 1.0
	v_pk_fma_f32 v[4:5], v[20:21], s[28:29], v[4:5] op_sel_hi:[1,0,1]
	v_cvt_scalef32_pk_f32_fp4 v[20:21], v60, 1.0 op_sel:[1,0,0]
	v_pk_fma_f32 v[6:7], s[28:29], v[20:21], v[6:7] op_sel_hi:[0,1,1]
	v_cvt_scalef32_pk_f32_fp4 v[20:21], v60, 1.0 op_sel:[0,1,0]
	v_pk_fma_f32 v[8:9], s[28:29], v[20:21], v[8:9] op_sel_hi:[0,1,1]
	v_cvt_scalef32_pk_f32_fp4 v[20:21], v60, 1.0 op_sel:[1,1,0]
	v_pk_fma_f32 v[10:11], s[28:29], v[20:21], v[10:11] op_sel_hi:[0,1,1]
	v_cvt_scalef32_pk_f32_fp4 v[20:21], v61, 1.0
	v_pk_fma_f32 v[12:13], s[28:29], v[20:21], v[12:13] op_sel_hi:[0,1,1]
	v_cvt_scalef32_pk_f32_fp4 v[20:21], v61, 1.0 op_sel:[1,0,0]
	v_pk_fma_f32 v[14:15], s[28:29], v[20:21], v[14:15] op_sel_hi:[0,1,1]
	v_cvt_scalef32_pk_f32_fp4 v[20:21], v61, 1.0 op_sel:[0,1,0]
	v_pk_fma_f32 v[16:17], s[28:29], v[20:21], v[16:17] op_sel_hi:[0,1,1]
	v_cvt_scalef32_pk_f32_fp4 v[20:21], v61, 1.0 op_sel:[1,1,0]
	v_pk_fma_f32 v[18:19], s[28:29], v[20:21], v[18:19] op_sel_hi:[0,1,1]
	v_readlane_b32 s28, v127, 45
	s_waitcnt vmcnt(20)
	v_cvt_scalef32_pk_f32_fp4 v[20:21], v62, 1.0
	v_pk_fma_f32 v[4:5], v[20:21], s[28:29], v[4:5] op_sel_hi:[1,0,1]
	v_cvt_scalef32_pk_f32_fp4 v[20:21], v62, 1.0 op_sel:[1,0,0]
	v_pk_fma_f32 v[6:7], s[28:29], v[20:21], v[6:7] op_sel_hi:[0,1,1]
	v_cvt_scalef32_pk_f32_fp4 v[20:21], v62, 1.0 op_sel:[0,1,0]
	v_pk_fma_f32 v[8:9], s[28:29], v[20:21], v[8:9] op_sel_hi:[0,1,1]
	v_cvt_scalef32_pk_f32_fp4 v[20:21], v62, 1.0 op_sel:[1,1,0]
	v_pk_fma_f32 v[10:11], s[28:29], v[20:21], v[10:11] op_sel_hi:[0,1,1]
	v_cvt_scalef32_pk_f32_fp4 v[20:21], v63, 1.0
	v_pk_fma_f32 v[12:13], s[28:29], v[20:21], v[12:13] op_sel_hi:[0,1,1]
	v_cvt_scalef32_pk_f32_fp4 v[20:21], v63, 1.0 op_sel:[1,0,0]
	v_pk_fma_f32 v[14:15], s[28:29], v[20:21], v[14:15] op_sel_hi:[0,1,1]
	v_cvt_scalef32_pk_f32_fp4 v[20:21], v63, 1.0 op_sel:[0,1,0]
	v_pk_fma_f32 v[16:17], s[28:29], v[20:21], v[16:17] op_sel_hi:[0,1,1]
	v_cvt_scalef32_pk_f32_fp4 v[20:21], v63, 1.0 op_sel:[1,1,0]
	v_pk_fma_f32 v[18:19], s[28:29], v[20:21], v[18:19] op_sel_hi:[0,1,1]
	s_waitcnt vmcnt(19)
	v_cvt_scalef32_pk_f32_fp4 v[20:21], v64, 1.0
	v_pk_fma_f32 v[4:5], v[20:21], s[2:3], v[4:5] op_sel_hi:[1,0,1]
	v_cvt_scalef32_pk_f32_fp4 v[20:21], v64, 1.0 op_sel:[1,0,0]
	v_pk_fma_f32 v[6:7], s[2:3], v[20:21], v[6:7] op_sel_hi:[0,1,1]
	v_cvt_scalef32_pk_f32_fp4 v[20:21], v64, 1.0 op_sel:[0,1,0]
	v_pk_fma_f32 v[8:9], s[2:3], v[20:21], v[8:9] op_sel_hi:[0,1,1]
	v_cvt_scalef32_pk_f32_fp4 v[20:21], v64, 1.0 op_sel:[1,1,0]
	v_pk_fma_f32 v[10:11], s[2:3], v[20:21], v[10:11] op_sel_hi:[0,1,1]
	v_cvt_scalef32_pk_f32_fp4 v[20:21], v65, 1.0
	v_pk_fma_f32 v[12:13], s[2:3], v[20:21], v[12:13] op_sel_hi:[0,1,1]
	v_cvt_scalef32_pk_f32_fp4 v[20:21], v65, 1.0 op_sel:[1,0,0]
	v_pk_fma_f32 v[14:15], s[2:3], v[20:21], v[14:15] op_sel_hi:[0,1,1]
	v_cvt_scalef32_pk_f32_fp4 v[20:21], v65, 1.0 op_sel:[0,1,0]
	v_pk_fma_f32 v[16:17], s[2:3], v[20:21], v[16:17] op_sel_hi:[0,1,1]
	v_cvt_scalef32_pk_f32_fp4 v[20:21], v65, 1.0 op_sel:[1,1,0]
	v_pk_fma_f32 v[18:19], s[2:3], v[20:21], v[18:19] op_sel_hi:[0,1,1]
	v_readlane_b32 s2, v127, 43
	s_waitcnt vmcnt(18)
	v_cvt_scalef32_pk_f32_fp4 v[20:21], v66, 1.0
	v_pk_fma_f32 v[4:5], v[20:21], s[2:3], v[4:5] op_sel_hi:[1,0,1]
	v_cvt_scalef32_pk_f32_fp4 v[20:21], v66, 1.0 op_sel:[1,0,0]
	v_pk_fma_f32 v[6:7], s[2:3], v[20:21], v[6:7] op_sel_hi:[0,1,1]
	v_cvt_scalef32_pk_f32_fp4 v[20:21], v66, 1.0 op_sel:[0,1,0]
	v_pk_fma_f32 v[8:9], s[2:3], v[20:21], v[8:9] op_sel_hi:[0,1,1]
	v_cvt_scalef32_pk_f32_fp4 v[20:21], v66, 1.0 op_sel:[1,1,0]
	v_pk_fma_f32 v[10:11], s[2:3], v[20:21], v[10:11] op_sel_hi:[0,1,1]
	v_cvt_scalef32_pk_f32_fp4 v[20:21], v67, 1.0
	v_pk_fma_f32 v[12:13], s[2:3], v[20:21], v[12:13] op_sel_hi:[0,1,1]
	v_cvt_scalef32_pk_f32_fp4 v[20:21], v67, 1.0 op_sel:[1,0,0]
	v_pk_fma_f32 v[14:15], s[2:3], v[20:21], v[14:15] op_sel_hi:[0,1,1]
	v_cvt_scalef32_pk_f32_fp4 v[20:21], v67, 1.0 op_sel:[0,1,0]
	v_pk_fma_f32 v[16:17], s[2:3], v[20:21], v[16:17] op_sel_hi:[0,1,1]
	v_cvt_scalef32_pk_f32_fp4 v[20:21], v67, 1.0 op_sel:[1,1,0]
	v_pk_fma_f32 v[18:19], s[2:3], v[20:21], v[18:19] op_sel_hi:[0,1,1]
	v_readlane_b32 s2, v127, 39
	s_waitcnt vmcnt(17)
	v_cvt_scalef32_pk_f32_fp4 v[20:21], v68, 1.0
	v_pk_fma_f32 v[4:5], v[20:21], s[2:3], v[4:5] op_sel_hi:[1,0,1]
	v_cvt_scalef32_pk_f32_fp4 v[20:21], v68, 1.0 op_sel:[1,0,0]
	v_pk_fma_f32 v[6:7], s[2:3], v[20:21], v[6:7] op_sel_hi:[0,1,1]
	v_cvt_scalef32_pk_f32_fp4 v[20:21], v68, 1.0 op_sel:[0,1,0]
	v_pk_fma_f32 v[8:9], s[2:3], v[20:21], v[8:9] op_sel_hi:[0,1,1]
	v_cvt_scalef32_pk_f32_fp4 v[20:21], v68, 1.0 op_sel:[1,1,0]
	v_pk_fma_f32 v[10:11], s[2:3], v[20:21], v[10:11] op_sel_hi:[0,1,1]
	v_cvt_scalef32_pk_f32_fp4 v[20:21], v69, 1.0
	v_pk_fma_f32 v[12:13], s[2:3], v[20:21], v[12:13] op_sel_hi:[0,1,1]
	v_cvt_scalef32_pk_f32_fp4 v[20:21], v69, 1.0 op_sel:[1,0,0]
	v_pk_fma_f32 v[14:15], s[2:3], v[20:21], v[14:15] op_sel_hi:[0,1,1]
	v_cvt_scalef32_pk_f32_fp4 v[20:21], v69, 1.0 op_sel:[0,1,0]
	v_pk_fma_f32 v[16:17], s[2:3], v[20:21], v[16:17] op_sel_hi:[0,1,1]
	v_cvt_scalef32_pk_f32_fp4 v[20:21], v69, 1.0 op_sel:[1,1,0]
	v_pk_fma_f32 v[18:19], s[2:3], v[20:21], v[18:19] op_sel_hi:[0,1,1]
	v_readlane_b32 s2, v127, 47
	s_waitcnt vmcnt(16)
	v_cvt_scalef32_pk_f32_fp4 v[20:21], v70, 1.0
	v_pk_fma_f32 v[4:5], v[20:21], s[2:3], v[4:5] op_sel_hi:[1,0,1]
	v_cvt_scalef32_pk_f32_fp4 v[20:21], v70, 1.0 op_sel:[1,0,0]
	v_pk_fma_f32 v[6:7], s[2:3], v[20:21], v[6:7] op_sel_hi:[0,1,1]
	v_cvt_scalef32_pk_f32_fp4 v[20:21], v70, 1.0 op_sel:[0,1,0]
	v_pk_fma_f32 v[8:9], s[2:3], v[20:21], v[8:9] op_sel_hi:[0,1,1]
	v_cvt_scalef32_pk_f32_fp4 v[20:21], v70, 1.0 op_sel:[1,1,0]
	v_pk_fma_f32 v[10:11], s[2:3], v[20:21], v[10:11] op_sel_hi:[0,1,1]
	v_cvt_scalef32_pk_f32_fp4 v[20:21], v71, 1.0
	v_pk_fma_f32 v[12:13], s[2:3], v[20:21], v[12:13] op_sel_hi:[0,1,1]
	v_cvt_scalef32_pk_f32_fp4 v[20:21], v71, 1.0 op_sel:[1,0,0]
	v_pk_fma_f32 v[14:15], s[2:3], v[20:21], v[14:15] op_sel_hi:[0,1,1]
	v_cvt_scalef32_pk_f32_fp4 v[20:21], v71, 1.0 op_sel:[0,1,0]
	v_pk_fma_f32 v[16:17], s[2:3], v[20:21], v[16:17] op_sel_hi:[0,1,1]
	v_cvt_scalef32_pk_f32_fp4 v[20:21], v71, 1.0 op_sel:[1,1,0]
	v_pk_fma_f32 v[18:19], s[2:3], v[20:21], v[18:19] op_sel_hi:[0,1,1]
	v_readlane_b32 s2, v127, 48
	s_waitcnt vmcnt(15)
	v_cvt_scalef32_pk_f32_fp4 v[20:21], v72, 1.0
	v_pk_fma_f32 v[4:5], v[20:21], s[2:3], v[4:5] op_sel_hi:[1,0,1]
	v_cvt_scalef32_pk_f32_fp4 v[20:21], v72, 1.0 op_sel:[1,0,0]
	v_pk_fma_f32 v[6:7], s[2:3], v[20:21], v[6:7] op_sel_hi:[0,1,1]
	v_cvt_scalef32_pk_f32_fp4 v[20:21], v72, 1.0 op_sel:[0,1,0]
	v_pk_fma_f32 v[8:9], s[2:3], v[20:21], v[8:9] op_sel_hi:[0,1,1]
	v_cvt_scalef32_pk_f32_fp4 v[20:21], v72, 1.0 op_sel:[1,1,0]
	v_pk_fma_f32 v[10:11], s[2:3], v[20:21], v[10:11] op_sel_hi:[0,1,1]
	v_cvt_scalef32_pk_f32_fp4 v[20:21], v73, 1.0
	v_pk_fma_f32 v[12:13], s[2:3], v[20:21], v[12:13] op_sel_hi:[0,1,1]
	v_cvt_scalef32_pk_f32_fp4 v[20:21], v73, 1.0 op_sel:[1,0,0]
	v_pk_fma_f32 v[14:15], s[2:3], v[20:21], v[14:15] op_sel_hi:[0,1,1]
	v_cvt_scalef32_pk_f32_fp4 v[20:21], v73, 1.0 op_sel:[0,1,0]
	v_pk_fma_f32 v[16:17], s[2:3], v[20:21], v[16:17] op_sel_hi:[0,1,1]
	v_cvt_scalef32_pk_f32_fp4 v[20:21], v73, 1.0 op_sel:[1,1,0]
	v_pk_fma_f32 v[18:19], s[2:3], v[20:21], v[18:19] op_sel_hi:[0,1,1]
	v_readlane_b32 s2, v127, 56
	s_waitcnt vmcnt(14)
	v_cvt_scalef32_pk_f32_fp4 v[20:21], v74, 1.0
	v_pk_fma_f32 v[4:5], v[20:21], s[2:3], v[4:5] op_sel_hi:[1,0,1]
	v_cvt_scalef32_pk_f32_fp4 v[20:21], v74, 1.0 op_sel:[1,0,0]
	v_pk_fma_f32 v[6:7], s[2:3], v[20:21], v[6:7] op_sel_hi:[0,1,1]
	v_cvt_scalef32_pk_f32_fp4 v[20:21], v74, 1.0 op_sel:[0,1,0]
	v_pk_fma_f32 v[8:9], s[2:3], v[20:21], v[8:9] op_sel_hi:[0,1,1]
	v_cvt_scalef32_pk_f32_fp4 v[20:21], v74, 1.0 op_sel:[1,1,0]
	v_pk_fma_f32 v[10:11], s[2:3], v[20:21], v[10:11] op_sel_hi:[0,1,1]
	v_cvt_scalef32_pk_f32_fp4 v[20:21], v75, 1.0
	v_pk_fma_f32 v[12:13], s[2:3], v[20:21], v[12:13] op_sel_hi:[0,1,1]
	v_cvt_scalef32_pk_f32_fp4 v[20:21], v75, 1.0 op_sel:[1,0,0]
	v_pk_fma_f32 v[14:15], s[2:3], v[20:21], v[14:15] op_sel_hi:[0,1,1]
	v_cvt_scalef32_pk_f32_fp4 v[20:21], v75, 1.0 op_sel:[0,1,0]
	v_pk_fma_f32 v[16:17], s[2:3], v[20:21], v[16:17] op_sel_hi:[0,1,1]
	v_cvt_scalef32_pk_f32_fp4 v[20:21], v75, 1.0 op_sel:[1,1,0]
	v_pk_fma_f32 v[18:19], s[2:3], v[20:21], v[18:19] op_sel_hi:[0,1,1]
	v_readlane_b32 s2, v127, 52
	s_waitcnt vmcnt(13)
	v_cvt_scalef32_pk_f32_fp4 v[20:21], v76, 1.0
	v_pk_fma_f32 v[4:5], v[20:21], s[2:3], v[4:5] op_sel_hi:[1,0,1]
	v_cvt_scalef32_pk_f32_fp4 v[20:21], v76, 1.0 op_sel:[1,0,0]
	v_pk_fma_f32 v[6:7], s[2:3], v[20:21], v[6:7] op_sel_hi:[0,1,1]
	v_cvt_scalef32_pk_f32_fp4 v[20:21], v76, 1.0 op_sel:[0,1,0]
	v_pk_fma_f32 v[8:9], s[2:3], v[20:21], v[8:9] op_sel_hi:[0,1,1]
	v_cvt_scalef32_pk_f32_fp4 v[20:21], v76, 1.0 op_sel:[1,1,0]
	v_pk_fma_f32 v[10:11], s[2:3], v[20:21], v[10:11] op_sel_hi:[0,1,1]
	v_cvt_scalef32_pk_f32_fp4 v[20:21], v77, 1.0
	v_pk_fma_f32 v[12:13], s[2:3], v[20:21], v[12:13] op_sel_hi:[0,1,1]
	v_cvt_scalef32_pk_f32_fp4 v[20:21], v77, 1.0 op_sel:[1,0,0]
	v_pk_fma_f32 v[14:15], s[2:3], v[20:21], v[14:15] op_sel_hi:[0,1,1]
	v_cvt_scalef32_pk_f32_fp4 v[20:21], v77, 1.0 op_sel:[0,1,0]
	v_pk_fma_f32 v[16:17], s[2:3], v[20:21], v[16:17] op_sel_hi:[0,1,1]
	v_cvt_scalef32_pk_f32_fp4 v[20:21], v77, 1.0 op_sel:[1,1,0]
	v_pk_fma_f32 v[18:19], s[2:3], v[20:21], v[18:19] op_sel_hi:[0,1,1]
	v_readlane_b32 s2, v127, 60
	s_waitcnt vmcnt(12)
	v_cvt_scalef32_pk_f32_fp4 v[20:21], v78, 1.0
	v_pk_fma_f32 v[4:5], v[20:21], s[2:3], v[4:5] op_sel_hi:[1,0,1]
	v_cvt_scalef32_pk_f32_fp4 v[20:21], v78, 1.0 op_sel:[1,0,0]
	v_pk_fma_f32 v[6:7], s[2:3], v[20:21], v[6:7] op_sel_hi:[0,1,1]
	v_cvt_scalef32_pk_f32_fp4 v[20:21], v78, 1.0 op_sel:[0,1,0]
	v_pk_fma_f32 v[8:9], s[2:3], v[20:21], v[8:9] op_sel_hi:[0,1,1]
	v_cvt_scalef32_pk_f32_fp4 v[20:21], v78, 1.0 op_sel:[1,1,0]
	v_pk_fma_f32 v[10:11], s[2:3], v[20:21], v[10:11] op_sel_hi:[0,1,1]
	v_cvt_scalef32_pk_f32_fp4 v[20:21], v79, 1.0
	v_pk_fma_f32 v[12:13], s[2:3], v[20:21], v[12:13] op_sel_hi:[0,1,1]
	v_cvt_scalef32_pk_f32_fp4 v[20:21], v79, 1.0 op_sel:[1,0,0]
	v_pk_fma_f32 v[14:15], s[2:3], v[20:21], v[14:15] op_sel_hi:[0,1,1]
	v_cvt_scalef32_pk_f32_fp4 v[20:21], v79, 1.0 op_sel:[0,1,0]
	v_pk_fma_f32 v[16:17], s[2:3], v[20:21], v[16:17] op_sel_hi:[0,1,1]
	v_cvt_scalef32_pk_f32_fp4 v[20:21], v79, 1.0 op_sel:[1,1,0]
	v_pk_fma_f32 v[18:19], s[2:3], v[20:21], v[18:19] op_sel_hi:[0,1,1]
	v_readlane_b32 s2, v127, 50
	s_waitcnt vmcnt(11)
	v_cvt_scalef32_pk_f32_fp4 v[20:21], v80, 1.0
	v_pk_fma_f32 v[4:5], v[20:21], s[2:3], v[4:5] op_sel_hi:[1,0,1]
	v_cvt_scalef32_pk_f32_fp4 v[20:21], v80, 1.0 op_sel:[1,0,0]
	v_pk_fma_f32 v[6:7], s[2:3], v[20:21], v[6:7] op_sel_hi:[0,1,1]
	v_cvt_scalef32_pk_f32_fp4 v[20:21], v80, 1.0 op_sel:[0,1,0]
	v_pk_fma_f32 v[8:9], s[2:3], v[20:21], v[8:9] op_sel_hi:[0,1,1]
	v_cvt_scalef32_pk_f32_fp4 v[20:21], v80, 1.0 op_sel:[1,1,0]
	v_pk_fma_f32 v[10:11], s[2:3], v[20:21], v[10:11] op_sel_hi:[0,1,1]
	v_cvt_scalef32_pk_f32_fp4 v[20:21], v81, 1.0
	v_pk_fma_f32 v[12:13], s[2:3], v[20:21], v[12:13] op_sel_hi:[0,1,1]
	v_cvt_scalef32_pk_f32_fp4 v[20:21], v81, 1.0 op_sel:[1,0,0]
	v_pk_fma_f32 v[14:15], s[2:3], v[20:21], v[14:15] op_sel_hi:[0,1,1]
	v_cvt_scalef32_pk_f32_fp4 v[20:21], v81, 1.0 op_sel:[0,1,0]
	v_pk_fma_f32 v[16:17], s[2:3], v[20:21], v[16:17] op_sel_hi:[0,1,1]
	v_cvt_scalef32_pk_f32_fp4 v[20:21], v81, 1.0 op_sel:[1,1,0]
	v_pk_fma_f32 v[18:19], s[2:3], v[20:21], v[18:19] op_sel_hi:[0,1,1]
	v_readlane_b32 s2, v127, 58
	s_waitcnt vmcnt(10)
	v_cvt_scalef32_pk_f32_fp4 v[20:21], v82, 1.0
	v_pk_fma_f32 v[4:5], v[20:21], s[2:3], v[4:5] op_sel_hi:[1,0,1]
	v_cvt_scalef32_pk_f32_fp4 v[20:21], v82, 1.0 op_sel:[1,0,0]
	v_pk_fma_f32 v[6:7], s[2:3], v[20:21], v[6:7] op_sel_hi:[0,1,1]
	v_cvt_scalef32_pk_f32_fp4 v[20:21], v82, 1.0 op_sel:[0,1,0]
	v_pk_fma_f32 v[8:9], s[2:3], v[20:21], v[8:9] op_sel_hi:[0,1,1]
	v_cvt_scalef32_pk_f32_fp4 v[20:21], v82, 1.0 op_sel:[1,1,0]
	v_pk_fma_f32 v[10:11], s[2:3], v[20:21], v[10:11] op_sel_hi:[0,1,1]
	v_cvt_scalef32_pk_f32_fp4 v[20:21], v83, 1.0
	v_pk_fma_f32 v[12:13], s[2:3], v[20:21], v[12:13] op_sel_hi:[0,1,1]
	v_cvt_scalef32_pk_f32_fp4 v[20:21], v83, 1.0 op_sel:[1,0,0]
	v_pk_fma_f32 v[14:15], s[2:3], v[20:21], v[14:15] op_sel_hi:[0,1,1]
	v_cvt_scalef32_pk_f32_fp4 v[20:21], v83, 1.0 op_sel:[0,1,0]
	v_pk_fma_f32 v[16:17], s[2:3], v[20:21], v[16:17] op_sel_hi:[0,1,1]
	v_cvt_scalef32_pk_f32_fp4 v[20:21], v83, 1.0 op_sel:[1,1,0]
	v_pk_fma_f32 v[18:19], s[2:3], v[20:21], v[18:19] op_sel_hi:[0,1,1]
	v_readlane_b32 s2, v127, 54
	s_waitcnt vmcnt(9)
	v_cvt_scalef32_pk_f32_fp4 v[20:21], v84, 1.0
	v_pk_fma_f32 v[4:5], v[20:21], s[2:3], v[4:5] op_sel_hi:[1,0,1]
	v_cvt_scalef32_pk_f32_fp4 v[20:21], v84, 1.0 op_sel:[1,0,0]
	v_pk_fma_f32 v[6:7], s[2:3], v[20:21], v[6:7] op_sel_hi:[0,1,1]
	v_cvt_scalef32_pk_f32_fp4 v[20:21], v84, 1.0 op_sel:[0,1,0]
	v_pk_fma_f32 v[8:9], s[2:3], v[20:21], v[8:9] op_sel_hi:[0,1,1]
	v_cvt_scalef32_pk_f32_fp4 v[20:21], v84, 1.0 op_sel:[1,1,0]
	v_pk_fma_f32 v[10:11], s[2:3], v[20:21], v[10:11] op_sel_hi:[0,1,1]
	v_cvt_scalef32_pk_f32_fp4 v[20:21], v85, 1.0
	v_pk_fma_f32 v[12:13], s[2:3], v[20:21], v[12:13] op_sel_hi:[0,1,1]
	v_cvt_scalef32_pk_f32_fp4 v[20:21], v85, 1.0 op_sel:[1,0,0]
	v_pk_fma_f32 v[14:15], s[2:3], v[20:21], v[14:15] op_sel_hi:[0,1,1]
	v_cvt_scalef32_pk_f32_fp4 v[20:21], v85, 1.0 op_sel:[0,1,0]
	v_pk_fma_f32 v[16:17], s[2:3], v[20:21], v[16:17] op_sel_hi:[0,1,1]
	v_cvt_scalef32_pk_f32_fp4 v[20:21], v85, 1.0 op_sel:[1,1,0]
	v_pk_fma_f32 v[18:19], s[2:3], v[20:21], v[18:19] op_sel_hi:[0,1,1]
	v_readlane_b32 s2, v127, 62
	s_waitcnt vmcnt(8)
	v_cvt_scalef32_pk_f32_fp4 v[20:21], v86, 1.0
	v_pk_fma_f32 v[4:5], v[20:21], s[2:3], v[4:5] op_sel_hi:[1,0,1]
	v_cvt_scalef32_pk_f32_fp4 v[20:21], v86, 1.0 op_sel:[1,0,0]
	v_pk_fma_f32 v[6:7], s[2:3], v[20:21], v[6:7] op_sel_hi:[0,1,1]
	v_cvt_scalef32_pk_f32_fp4 v[20:21], v86, 1.0 op_sel:[0,1,0]
	v_pk_fma_f32 v[8:9], s[2:3], v[20:21], v[8:9] op_sel_hi:[0,1,1]
	v_cvt_scalef32_pk_f32_fp4 v[20:21], v86, 1.0 op_sel:[1,1,0]
	v_pk_fma_f32 v[10:11], s[2:3], v[20:21], v[10:11] op_sel_hi:[0,1,1]
	v_cvt_scalef32_pk_f32_fp4 v[20:21], v87, 1.0
	v_pk_fma_f32 v[12:13], s[2:3], v[20:21], v[12:13] op_sel_hi:[0,1,1]
	v_cvt_scalef32_pk_f32_fp4 v[20:21], v87, 1.0 op_sel:[1,0,0]
	v_pk_fma_f32 v[14:15], s[2:3], v[20:21], v[14:15] op_sel_hi:[0,1,1]
	v_cvt_scalef32_pk_f32_fp4 v[20:21], v87, 1.0 op_sel:[0,1,0]
	v_pk_fma_f32 v[16:17], s[2:3], v[20:21], v[16:17] op_sel_hi:[0,1,1]
	v_cvt_scalef32_pk_f32_fp4 v[20:21], v87, 1.0 op_sel:[1,1,0]
	v_pk_fma_f32 v[18:19], s[2:3], v[20:21], v[18:19] op_sel_hi:[0,1,1]
	s_waitcnt vmcnt(7)
	v_cvt_scalef32_pk_f32_fp4 v[20:21], v88, 1.0
	s_nop 1
	v_readlane_b32 s2, v127, 49
	s_nop 1
	v_pk_fma_f32 v[4:5], v[20:21], s[2:3], v[4:5] op_sel_hi:[1,0,1]
	v_cvt_scalef32_pk_f32_fp4 v[20:21], v88, 1.0 op_sel:[1,0,0]
	v_pk_fma_f32 v[6:7], s[2:3], v[20:21], v[6:7] op_sel_hi:[0,1,1]
	v_cvt_scalef32_pk_f32_fp4 v[20:21], v88, 1.0 op_sel:[0,1,0]
	v_pk_fma_f32 v[8:9], s[2:3], v[20:21], v[8:9] op_sel_hi:[0,1,1]
	v_cvt_scalef32_pk_f32_fp4 v[20:21], v88, 1.0 op_sel:[1,1,0]
	v_pk_fma_f32 v[10:11], s[2:3], v[20:21], v[10:11] op_sel_hi:[0,1,1]
	v_cvt_scalef32_pk_f32_fp4 v[20:21], v89, 1.0
	v_pk_fma_f32 v[12:13], s[2:3], v[20:21], v[12:13] op_sel_hi:[0,1,1]
	v_cvt_scalef32_pk_f32_fp4 v[20:21], v89, 1.0 op_sel:[1,0,0]
	v_pk_fma_f32 v[14:15], s[2:3], v[20:21], v[14:15] op_sel_hi:[0,1,1]
	v_cvt_scalef32_pk_f32_fp4 v[20:21], v89, 1.0 op_sel:[0,1,0]
	v_pk_fma_f32 v[16:17], s[2:3], v[20:21], v[16:17] op_sel_hi:[0,1,1]
	v_cvt_scalef32_pk_f32_fp4 v[20:21], v89, 1.0 op_sel:[1,1,0]
	v_pk_fma_f32 v[18:19], s[2:3], v[20:21], v[18:19] op_sel_hi:[0,1,1]
	s_waitcnt vmcnt(6)
	v_cvt_scalef32_pk_f32_fp4 v[20:21], v90, 1.0
	s_nop 1
	v_readlane_b32 s2, v127, 57
	s_nop 1
	v_pk_fma_f32 v[4:5], v[20:21], s[2:3], v[4:5] op_sel_hi:[1,0,1]
	v_cvt_scalef32_pk_f32_fp4 v[20:21], v90, 1.0 op_sel:[1,0,0]
	v_pk_fma_f32 v[6:7], s[2:3], v[20:21], v[6:7] op_sel_hi:[0,1,1]
	v_cvt_scalef32_pk_f32_fp4 v[20:21], v90, 1.0 op_sel:[0,1,0]
	v_pk_fma_f32 v[8:9], s[2:3], v[20:21], v[8:9] op_sel_hi:[0,1,1]
	v_cvt_scalef32_pk_f32_fp4 v[20:21], v90, 1.0 op_sel:[1,1,0]
	v_pk_fma_f32 v[10:11], s[2:3], v[20:21], v[10:11] op_sel_hi:[0,1,1]
	v_cvt_scalef32_pk_f32_fp4 v[20:21], v91, 1.0
	v_pk_fma_f32 v[12:13], s[2:3], v[20:21], v[12:13] op_sel_hi:[0,1,1]
	v_cvt_scalef32_pk_f32_fp4 v[20:21], v91, 1.0 op_sel:[1,0,0]
	v_pk_fma_f32 v[14:15], s[2:3], v[20:21], v[14:15] op_sel_hi:[0,1,1]
	v_cvt_scalef32_pk_f32_fp4 v[20:21], v91, 1.0 op_sel:[0,1,0]
	v_pk_fma_f32 v[16:17], s[2:3], v[20:21], v[16:17] op_sel_hi:[0,1,1]
	v_cvt_scalef32_pk_f32_fp4 v[20:21], v91, 1.0 op_sel:[1,1,0]
	v_pk_fma_f32 v[18:19], s[2:3], v[20:21], v[18:19] op_sel_hi:[0,1,1]
	s_waitcnt vmcnt(5)
	v_cvt_scalef32_pk_f32_fp4 v[20:21], v92, 1.0
	s_nop 1
	v_readlane_b32 s2, v127, 53
	s_nop 1
	v_pk_fma_f32 v[4:5], v[20:21], s[2:3], v[4:5] op_sel_hi:[1,0,1]
	v_cvt_scalef32_pk_f32_fp4 v[20:21], v92, 1.0 op_sel:[1,0,0]
	v_pk_fma_f32 v[6:7], s[2:3], v[20:21], v[6:7] op_sel_hi:[0,1,1]
	v_cvt_scalef32_pk_f32_fp4 v[20:21], v92, 1.0 op_sel:[0,1,0]
	v_pk_fma_f32 v[8:9], s[2:3], v[20:21], v[8:9] op_sel_hi:[0,1,1]
	v_cvt_scalef32_pk_f32_fp4 v[20:21], v92, 1.0 op_sel:[1,1,0]
	v_pk_fma_f32 v[10:11], s[2:3], v[20:21], v[10:11] op_sel_hi:[0,1,1]
	v_cvt_scalef32_pk_f32_fp4 v[20:21], v93, 1.0
	v_pk_fma_f32 v[12:13], s[2:3], v[20:21], v[12:13] op_sel_hi:[0,1,1]
	v_cvt_scalef32_pk_f32_fp4 v[20:21], v93, 1.0 op_sel:[1,0,0]
	v_pk_fma_f32 v[14:15], s[2:3], v[20:21], v[14:15] op_sel_hi:[0,1,1]
	v_cvt_scalef32_pk_f32_fp4 v[20:21], v93, 1.0 op_sel:[0,1,0]
	v_pk_fma_f32 v[16:17], s[2:3], v[20:21], v[16:17] op_sel_hi:[0,1,1]
	v_cvt_scalef32_pk_f32_fp4 v[20:21], v93, 1.0 op_sel:[1,1,0]
	v_pk_fma_f32 v[18:19], s[2:3], v[20:21], v[18:19] op_sel_hi:[0,1,1]
	s_waitcnt vmcnt(4)
	v_cvt_scalef32_pk_f32_fp4 v[20:21], v94, 1.0
	s_nop 1
	v_readlane_b32 s2, v127, 61
	s_nop 1
	v_pk_fma_f32 v[4:5], v[20:21], s[2:3], v[4:5] op_sel_hi:[1,0,1]
	v_cvt_scalef32_pk_f32_fp4 v[20:21], v94, 1.0 op_sel:[1,0,0]
	v_pk_fma_f32 v[6:7], s[2:3], v[20:21], v[6:7] op_sel_hi:[0,1,1]
	v_cvt_scalef32_pk_f32_fp4 v[20:21], v94, 1.0 op_sel:[0,1,0]
	v_pk_fma_f32 v[8:9], s[2:3], v[20:21], v[8:9] op_sel_hi:[0,1,1]
	v_cvt_scalef32_pk_f32_fp4 v[20:21], v94, 1.0 op_sel:[1,1,0]
	v_pk_fma_f32 v[10:11], s[2:3], v[20:21], v[10:11] op_sel_hi:[0,1,1]
	v_cvt_scalef32_pk_f32_fp4 v[20:21], v95, 1.0
	v_pk_fma_f32 v[12:13], s[2:3], v[20:21], v[12:13] op_sel_hi:[0,1,1]
	v_cvt_scalef32_pk_f32_fp4 v[20:21], v95, 1.0 op_sel:[1,0,0]
	v_pk_fma_f32 v[14:15], s[2:3], v[20:21], v[14:15] op_sel_hi:[0,1,1]
	v_cvt_scalef32_pk_f32_fp4 v[20:21], v95, 1.0 op_sel:[0,1,0]
	v_pk_fma_f32 v[16:17], s[2:3], v[20:21], v[16:17] op_sel_hi:[0,1,1]
	v_cvt_scalef32_pk_f32_fp4 v[20:21], v95, 1.0 op_sel:[1,1,0]
	v_pk_fma_f32 v[18:19], s[2:3], v[20:21], v[18:19] op_sel_hi:[0,1,1]
	s_waitcnt vmcnt(3)
	v_cvt_scalef32_pk_f32_fp4 v[20:21], v96, 1.0
	s_nop 1
	v_readlane_b32 s2, v127, 51
	s_nop 1
	v_pk_fma_f32 v[4:5], v[20:21], s[2:3], v[4:5] op_sel_hi:[1,0,1]
	v_cvt_scalef32_pk_f32_fp4 v[20:21], v96, 1.0 op_sel:[1,0,0]
	v_pk_fma_f32 v[6:7], s[2:3], v[20:21], v[6:7] op_sel_hi:[0,1,1]
	v_cvt_scalef32_pk_f32_fp4 v[20:21], v96, 1.0 op_sel:[0,1,0]
	v_pk_fma_f32 v[8:9], s[2:3], v[20:21], v[8:9] op_sel_hi:[0,1,1]
	v_cvt_scalef32_pk_f32_fp4 v[20:21], v96, 1.0 op_sel:[1,1,0]
	v_pk_fma_f32 v[10:11], s[2:3], v[20:21], v[10:11] op_sel_hi:[0,1,1]
	v_cvt_scalef32_pk_f32_fp4 v[20:21], v97, 1.0
	v_pk_fma_f32 v[12:13], s[2:3], v[20:21], v[12:13] op_sel_hi:[0,1,1]
	v_cvt_scalef32_pk_f32_fp4 v[20:21], v97, 1.0 op_sel:[1,0,0]
	v_pk_fma_f32 v[14:15], s[2:3], v[20:21], v[14:15] op_sel_hi:[0,1,1]
	v_cvt_scalef32_pk_f32_fp4 v[20:21], v97, 1.0 op_sel:[0,1,0]
	v_pk_fma_f32 v[16:17], s[2:3], v[20:21], v[16:17] op_sel_hi:[0,1,1]
	v_cvt_scalef32_pk_f32_fp4 v[20:21], v97, 1.0 op_sel:[1,1,0]
	v_pk_fma_f32 v[18:19], s[2:3], v[20:21], v[18:19] op_sel_hi:[0,1,1]
	s_waitcnt vmcnt(2)
	v_cvt_scalef32_pk_f32_fp4 v[20:21], v98, 1.0
	s_nop 1
	v_readlane_b32 s2, v127, 59
	s_nop 1
	v_pk_fma_f32 v[4:5], v[20:21], s[2:3], v[4:5] op_sel_hi:[1,0,1]
	v_cvt_scalef32_pk_f32_fp4 v[20:21], v98, 1.0 op_sel:[1,0,0]
	v_pk_fma_f32 v[6:7], s[2:3], v[20:21], v[6:7] op_sel_hi:[0,1,1]
	v_cvt_scalef32_pk_f32_fp4 v[20:21], v98, 1.0 op_sel:[0,1,0]
	v_pk_fma_f32 v[8:9], s[2:3], v[20:21], v[8:9] op_sel_hi:[0,1,1]
	v_cvt_scalef32_pk_f32_fp4 v[20:21], v98, 1.0 op_sel:[1,1,0]
	v_pk_fma_f32 v[10:11], s[2:3], v[20:21], v[10:11] op_sel_hi:[0,1,1]
	v_cvt_scalef32_pk_f32_fp4 v[20:21], v99, 1.0
	v_pk_fma_f32 v[12:13], s[2:3], v[20:21], v[12:13] op_sel_hi:[0,1,1]
	v_cvt_scalef32_pk_f32_fp4 v[20:21], v99, 1.0 op_sel:[1,0,0]
	v_pk_fma_f32 v[14:15], s[2:3], v[20:21], v[14:15] op_sel_hi:[0,1,1]
	v_cvt_scalef32_pk_f32_fp4 v[20:21], v99, 1.0 op_sel:[0,1,0]
	v_pk_fma_f32 v[16:17], s[2:3], v[20:21], v[16:17] op_sel_hi:[0,1,1]
	v_cvt_scalef32_pk_f32_fp4 v[20:21], v99, 1.0 op_sel:[1,1,0]
	v_pk_fma_f32 v[18:19], s[2:3], v[20:21], v[18:19] op_sel_hi:[0,1,1]
	s_waitcnt vmcnt(1)
	v_cvt_scalef32_pk_f32_fp4 v[20:21], v100, 1.0
	s_nop 1
	v_readlane_b32 s2, v127, 55
	s_nop 1
	v_pk_fma_f32 v[4:5], v[20:21], s[2:3], v[4:5] op_sel_hi:[1,0,1]
	v_cvt_scalef32_pk_f32_fp4 v[20:21], v100, 1.0 op_sel:[1,0,0]
	v_pk_fma_f32 v[6:7], s[2:3], v[20:21], v[6:7] op_sel_hi:[0,1,1]
	v_cvt_scalef32_pk_f32_fp4 v[20:21], v100, 1.0 op_sel:[0,1,0]
	v_pk_fma_f32 v[8:9], s[2:3], v[20:21], v[8:9] op_sel_hi:[0,1,1]
	v_cvt_scalef32_pk_f32_fp4 v[20:21], v100, 1.0 op_sel:[1,1,0]
	v_pk_fma_f32 v[10:11], s[2:3], v[20:21], v[10:11] op_sel_hi:[0,1,1]
	v_cvt_scalef32_pk_f32_fp4 v[20:21], v101, 1.0
	v_pk_fma_f32 v[12:13], s[2:3], v[20:21], v[12:13] op_sel_hi:[0,1,1]
	v_cvt_scalef32_pk_f32_fp4 v[20:21], v101, 1.0 op_sel:[1,0,0]
	v_pk_fma_f32 v[14:15], s[2:3], v[20:21], v[14:15] op_sel_hi:[0,1,1]
	v_cvt_scalef32_pk_f32_fp4 v[20:21], v101, 1.0 op_sel:[0,1,0]
	v_pk_fma_f32 v[16:17], s[2:3], v[20:21], v[16:17] op_sel_hi:[0,1,1]
	v_cvt_scalef32_pk_f32_fp4 v[20:21], v101, 1.0 op_sel:[1,1,0]
	v_pk_fma_f32 v[18:19], s[2:3], v[20:21], v[18:19] op_sel_hi:[0,1,1]
	s_waitcnt vmcnt(0)
	v_cvt_scalef32_pk_f32_fp4 v[20:21], v102, 1.0
	s_nop 1
	v_readlane_b32 s2, v127, 63
	s_nop 1
	v_pk_fma_f32 v[4:5], v[20:21], s[2:3], v[4:5] op_sel_hi:[1,0,1]
	v_cvt_scalef32_pk_f32_fp4 v[20:21], v102, 1.0 op_sel:[1,0,0]
	v_pk_fma_f32 v[6:7], s[2:3], v[20:21], v[6:7] op_sel_hi:[0,1,1]
	v_cvt_scalef32_pk_f32_fp4 v[20:21], v102, 1.0 op_sel:[0,1,0]
	v_pk_fma_f32 v[8:9], s[2:3], v[20:21], v[8:9] op_sel_hi:[0,1,1]
	v_cvt_scalef32_pk_f32_fp4 v[20:21], v102, 1.0 op_sel:[1,1,0]
	v_pk_fma_f32 v[10:11], s[2:3], v[20:21], v[10:11] op_sel_hi:[0,1,1]
	v_cvt_scalef32_pk_f32_fp4 v[20:21], v103, 1.0
	v_pk_fma_f32 v[12:13], s[2:3], v[20:21], v[12:13] op_sel_hi:[0,1,1]
	v_cvt_scalef32_pk_f32_fp4 v[20:21], v103, 1.0 op_sel:[1,0,0]
	v_pk_fma_f32 v[14:15], s[2:3], v[20:21], v[14:15] op_sel_hi:[0,1,1]
	v_cvt_scalef32_pk_f32_fp4 v[20:21], v103, 1.0 op_sel:[0,1,0]
	v_pk_fma_f32 v[16:17], s[2:3], v[20:21], v[16:17] op_sel_hi:[0,1,1]
	v_cvt_scalef32_pk_f32_fp4 v[20:21], v103, 1.0 op_sel:[1,1,0]
	v_pk_fma_f32 v[18:19], s[2:3], v[20:21], v[18:19] op_sel_hi:[0,1,1]
.Lh3_v10_join:
	s_andn2_b64 exec, exec, s[14:15]
	s_cbranch_execnz .LBB0_2112
	s_or_b64 exec, exec, s[14:15]
	v_mov_b64_e32 v[34:35], v[18:19]
	v_mov_b64_e32 v[32:33], v[16:17]
	v_mov_b64_e32 v[30:31], v[14:15]
	v_mov_b64_e32 v[28:29], v[12:13]
	v_mov_b64_e32 v[26:27], v[10:11]
	v_mov_b64_e32 v[24:25], v[8:9]
	v_mov_b64_e32 v[22:23], v[6:7]
	v_mov_b64_e32 v[20:21], v[4:5]
	s_or_b64 exec, exec, s[12:13]
	s_mov_b64 s[12:13], -1
	s_and_b64 vcc, exec, s[24:25]
	s_cbranch_vccnz .LBB0_2116

.LBB0_3301:
	v_cmp_gt_u32_e64 s[10:11], 64, v126
	s_nop 1
	v_cndmask_b32_e64 v70, v117, v53, s[10:11]
	v_readfirstlane_b32 s92, v126
	s_nop 1
	s_and_b32 s92, s92, 32
	s_cbranch_scc1 .Lh2_u19_hi
	v_readlane_b32 s84, v70, 0
	v_readlane_b32 s86, v70, 1
	v_readlane_b32 s88, v70, 2
	v_readlane_b32 s90, v70, 3
	s_ashr_i32 s85, s84, 31
	s_ashr_i32 s87, s86, 31
	s_ashr_i32 s89, s88, 31
	s_ashr_i32 s91, s90, 31
	s_lshl_b64 s[84:85], s[84:85], 9
	s_lshl_b64 s[86:87], s[86:87], 9
	s_lshl_b64 s[88:89], s[88:89], 9
	s_lshl_b64 s[90:91], s[90:91], 9
	v_lshl_add_u64 v[72:73], v[36:37], 0, s[84:85]
	v_lshl_add_u64 v[74:75], v[36:37], 0, s[86:87]
	v_lshl_add_u64 v[76:77], v[36:37], 0, s[88:89]
	v_lshl_add_u64 v[78:79], v[36:37], 0, s[90:91]
	global_load_dwordx2 v[72:73], v[72:73], off
	global_load_dwordx2 v[74:75], v[74:75], off
	global_load_dwordx2 v[76:77], v[76:77], off
	global_load_dwordx2 v[78:79], v[78:79], off
	v_readlane_b32 s84, v70, 4
	v_readlane_b32 s86, v70, 5
	v_readlane_b32 s88, v70, 6
	v_readlane_b32 s90, v70, 7
	s_ashr_i32 s85, s84, 31
	s_ashr_i32 s87, s86, 31
	s_ashr_i32 s89, s88, 31
	s_ashr_i32 s91, s90, 31
	s_lshl_b64 s[84:85], s[84:85], 9
	s_lshl_b64 s[86:87], s[86:87], 9
	s_lshl_b64 s[88:89], s[88:89], 9
	s_lshl_b64 s[90:91], s[90:91], 9
	v_lshl_add_u64 v[80:81], v[36:37], 0, s[84:85]
	v_lshl_add_u64 v[82:83], v[36:37], 0, s[86:87]
	v_lshl_add_u64 v[84:85], v[36:37], 0, s[88:89]
	v_lshl_add_u64 v[86:87], v[36:37], 0, s[90:91]
	global_load_dwordx2 v[80:81], v[80:81], off
	global_load_dwordx2 v[82:83], v[82:83], off
	global_load_dwordx2 v[84:85], v[84:85], off
	global_load_dwordx2 v[86:87], v[86:87], off
	v_readlane_b32 s84, v70, 8
	v_readlane_b32 s86, v70, 9
	v_readlane_b32 s88, v70, 10
	v_readlane_b32 s90, v70, 11
	s_ashr_i32 s85, s84, 31
	s_ashr_i32 s87, s86, 31
	s_ashr_i32 s89, s88, 31
	s_ashr_i32 s91, s90, 31
	s_lshl_b64 s[84:85], s[84:85], 9
	s_lshl_b64 s[86:87], s[86:87], 9
	s_lshl_b64 s[88:89], s[88:89], 9
	s_lshl_b64 s[90:91], s[90:91], 9
	v_lshl_add_u64 v[88:89], v[36:37], 0, s[84:85]
	v_lshl_add_u64 v[90:91], v[36:37], 0, s[86:87]
	v_lshl_add_u64 v[92:93], v[36:37], 0, s[88:89]
	v_lshl_add_u64 v[94:95], v[36:37], 0, s[90:91]
	global_load_dwordx2 v[88:89], v[88:89], off
	global_load_dwordx2 v[90:91], v[90:91], off
	global_load_dwordx2 v[92:93], v[92:93], off
	global_load_dwordx2 v[94:95], v[94:95], off
	v_readlane_b32 s84, v70, 12
	v_readlane_b32 s86, v70, 13
	v_readlane_b32 s88, v70, 14
	v_readlane_b32 s90, v70, 15
	s_ashr_i32 s85, s84, 31
	s_ashr_i32 s87, s86, 31
	s_ashr_i32 s89, s88, 31
	s_ashr_i32 s91, s90, 31
	s_lshl_b64 s[84:85], s[84:85], 9
	s_lshl_b64 s[86:87], s[86:87], 9
	s_lshl_b64 s[88:89], s[88:89], 9
	s_lshl_b64 s[90:91], s[90:91], 9
	v_lshl_add_u64 v[96:97], v[36:37], 0, s[84:85]
	v_lshl_add_u64 v[98:99], v[36:37], 0, s[86:87]
	v_lshl_add_u64 v[100:101], v[36:37], 0, s[88:89]
	v_lshl_add_u64 v[102:103], v[36:37], 0, s[90:91]
	global_load_dwordx2 v[96:97], v[96:97], off
	global_load_dwordx2 v[98:99], v[98:99], off
	global_load_dwordx2 v[100:101], v[100:101], off
	global_load_dwordx2 v[102:103], v[102:103], off
	v_readlane_b32 s84, v70, 16
	v_readlane_b32 s86, v70, 17
	v_readlane_b32 s88, v70, 18
	v_readlane_b32 s90, v70, 19
	s_ashr_i32 s85, s84, 31
	s_ashr_i32 s87, s86, 31
	s_ashr_i32 s89, s88, 31
	s_ashr_i32 s91, s90, 31
	s_lshl_b64 s[84:85], s[84:85], 9
	s_lshl_b64 s[86:87], s[86:87], 9
	s_lshl_b64 s[88:89], s[88:89], 9
	s_lshl_b64 s[90:91], s[90:91], 9
	v_lshl_add_u64 v[18:19], v[36:37], 0, s[84:85]
	v_lshl_add_u64 v[20:21], v[36:37], 0, s[86:87]
	v_lshl_add_u64 v[22:23], v[36:37], 0, s[88:89]
	v_lshl_add_u64 v[24:25], v[36:37], 0, s[90:91]
	global_load_dwordx2 v[18:19], v[18:19], off
	global_load_dwordx2 v[20:21], v[20:21], off
	global_load_dwordx2 v[22:23], v[22:23], off
	global_load_dwordx2 v[24:25], v[24:25], off
	v_readlane_b32 s84, v70, 20
	v_readlane_b32 s86, v70, 21
	v_readlane_b32 s88, v70, 22
	v_readlane_b32 s90, v70, 23
	s_ashr_i32 s85, s84, 31
	s_ashr_i32 s87, s86, 31
	s_ashr_i32 s89, s88, 31
	s_ashr_i32 s91, s90, 31
	s_lshl_b64 s[84:85], s[84:85], 9
	s_lshl_b64 s[86:87], s[86:87], 9
	s_lshl_b64 s[88:89], s[88:89], 9
	s_lshl_b64 s[90:91], s[90:91], 9
	v_lshl_add_u64 v[26:27], v[36:37], 0, s[84:85]
	v_lshl_add_u64 v[28:29], v[36:37], 0, s[86:87]
	v_lshl_add_u64 v[30:31], v[36:37], 0, s[88:89]
	v_lshl_add_u64 v[32:33], v[36:37], 0, s[90:91]
	global_load_dwordx2 v[26:27], v[26:27], off
	global_load_dwordx2 v[28:29], v[28:29], off
	global_load_dwordx2 v[30:31], v[30:31], off
	global_load_dwordx2 v[32:33], v[32:33], off
	v_readlane_b32 s84, v70, 24
	v_readlane_b32 s86, v70, 25
	v_readlane_b32 s88, v70, 26
	v_readlane_b32 s90, v70, 27
	s_ashr_i32 s85, s84, 31
	s_ashr_i32 s87, s86, 31
	s_ashr_i32 s89, s88, 31
	s_ashr_i32 s91, s90, 31
	s_lshl_b64 s[84:85], s[84:85], 9
	s_lshl_b64 s[86:87], s[86:87], 9
	s_lshl_b64 s[88:89], s[88:89], 9
	s_lshl_b64 s[90:91], s[90:91], 9
	v_lshl_add_u64 v[56:57], v[36:37], 0, s[84:85]
	v_lshl_add_u64 v[58:59], v[36:37], 0, s[86:87]
	v_lshl_add_u64 v[60:61], v[36:37], 0, s[88:89]
	v_lshl_add_u64 v[62:63], v[36:37], 0, s[90:91]
	global_load_dwordx2 v[56:57], v[56:57], off
	global_load_dwordx2 v[58:59], v[58:59], off
	global_load_dwordx2 v[60:61], v[60:61], off
	global_load_dwordx2 v[62:63], v[62:63], off
	v_readlane_b32 s84, v70, 28
	v_readlane_b32 s86, v70, 29
	v_readlane_b32 s88, v70, 30
	v_readlane_b32 s90, v70, 31
	s_ashr_i32 s85, s84, 31
	s_ashr_i32 s87, s86, 31
	s_ashr_i32 s89, s88, 31
	s_ashr_i32 s91, s90, 31
	s_lshl_b64 s[84:85], s[84:85], 9
	s_lshl_b64 s[86:87], s[86:87], 9
	s_lshl_b64 s[88:89], s[88:89], 9
	s_lshl_b64 s[90:91], s[90:91], 9
	v_lshl_add_u64 v[64:65], v[36:37], 0, s[84:85]
	v_lshl_add_u64 v[66:67], v[36:37], 0, s[86:87]
	v_lshl_add_u64 v[68:69], v[36:37], 0, s[88:89]
	v_lshl_add_u64 v[70:71], v[36:37], 0, s[90:91]
	global_load_dwordx2 v[64:65], v[64:65], off
	global_load_dwordx2 v[66:67], v[66:67], off
	global_load_dwordx2 v[68:69], v[68:69], off
	global_load_dwordx2 v[70:71], v[70:71], off
	s_branch .Lh2_u19_join
.Lh2_u19_hi:
	v_readlane_b32 s84, v70, 32
	v_readlane_b32 s86, v70, 33
	v_readlane_b32 s88, v70, 34
	v_readlane_b32 s90, v70, 35
	s_ashr_i32 s85, s84, 31
	s_ashr_i32 s87, s86, 31
	s_ashr_i32 s89, s88, 31
	s_ashr_i32 s91, s90, 31
	s_lshl_b64 s[84:85], s[84:85], 9
	s_lshl_b64 s[86:87], s[86:87], 9
	s_lshl_b64 s[88:89], s[88:89], 9
	s_lshl_b64 s[90:91], s[90:91], 9
	v_lshl_add_u64 v[72:73], v[36:37], 0, s[84:85]
	v_lshl_add_u64 v[74:75], v[36:37], 0, s[86:87]
	v_lshl_add_u64 v[76:77], v[36:37], 0, s[88:89]
	v_lshl_add_u64 v[78:79], v[36:37], 0, s[90:91]
	global_load_dwordx2 v[72:73], v[72:73], off
	global_load_dwordx2 v[74:75], v[74:75], off
	global_load_dwordx2 v[76:77], v[76:77], off
	global_load_dwordx2 v[78:79], v[78:79], off
	v_readlane_b32 s84, v70, 36
	v_readlane_b32 s86, v70, 37
	v_readlane_b32 s88, v70, 38
	v_readlane_b32 s90, v70, 39
	s_ashr_i32 s85, s84, 31
	s_ashr_i32 s87, s86, 31
	s_ashr_i32 s89, s88, 31
	s_ashr_i32 s91, s90, 31
	s_lshl_b64 s[84:85], s[84:85], 9
	s_lshl_b64 s[86:87], s[86:87], 9
	s_lshl_b64 s[88:89], s[88:89], 9
	s_lshl_b64 s[90:91], s[90:91], 9
	v_lshl_add_u64 v[80:81], v[36:37], 0, s[84:85]
	v_lshl_add_u64 v[82:83], v[36:37], 0, s[86:87]
	v_lshl_add_u64 v[84:85], v[36:37], 0, s[88:89]
	v_lshl_add_u64 v[86:87], v[36:37], 0, s[90:91]
	global_load_dwordx2 v[80:81], v[80:81], off
	global_load_dwordx2 v[82:83], v[82:83], off
	global_load_dwordx2 v[84:85], v[84:85], off
	global_load_dwordx2 v[86:87], v[86:87], off
	v_readlane_b32 s84, v70, 40
	v_readlane_b32 s86, v70, 41
	v_readlane_b32 s88, v70, 42
	v_readlane_b32 s90, v70, 43
	s_ashr_i32 s85, s84, 31
	s_ashr_i32 s87, s86, 31
	s_ashr_i32 s89, s88, 31
	s_ashr_i32 s91, s90, 31
	s_lshl_b64 s[84:85], s[84:85], 9
	s_lshl_b64 s[86:87], s[86:87], 9
	s_lshl_b64 s[88:89], s[88:89], 9
	s_lshl_b64 s[90:91], s[90:91], 9
	v_lshl_add_u64 v[88:89], v[36:37], 0, s[84:85]
	v_lshl_add_u64 v[90:91], v[36:37], 0, s[86:87]
	v_lshl_add_u64 v[92:93], v[36:37], 0, s[88:89]
	v_lshl_add_u64 v[94:95], v[36:37], 0, s[90:91]
	global_load_dwordx2 v[88:89], v[88:89], off
	global_load_dwordx2 v[90:91], v[90:91], off
	global_load_dwordx2 v[92:93], v[92:93], off
	global_load_dwordx2 v[94:95], v[94:95], off
	v_readlane_b32 s84, v70, 44
	v_readlane_b32 s86, v70, 45
	v_readlane_b32 s88, v70, 46
	v_readlane_b32 s90, v70, 47
	s_ashr_i32 s85, s84, 31
	s_ashr_i32 s87, s86, 31
	s_ashr_i32 s89, s88, 31
	s_ashr_i32 s91, s90, 31
	s_lshl_b64 s[84:85], s[84:85], 9
	s_lshl_b64 s[86:87], s[86:87], 9
	s_lshl_b64 s[88:89], s[88:89], 9
	s_lshl_b64 s[90:91], s[90:91], 9
	v_lshl_add_u64 v[96:97], v[36:37], 0, s[84:85]
	v_lshl_add_u64 v[98:99], v[36:37], 0, s[86:87]
	v_lshl_add_u64 v[100:101], v[36:37], 0, s[88:89]
	v_lshl_add_u64 v[102:103], v[36:37], 0, s[90:91]
	global_load_dwordx2 v[96:97], v[96:97], off
	global_load_dwordx2 v[98:99], v[98:99], off
	global_load_dwordx2 v[100:101], v[100:101], off
	global_load_dwordx2 v[102:103], v[102:103], off
	v_readlane_b32 s84, v70, 48
	v_readlane_b32 s86, v70, 49
	v_readlane_b32 s88, v70, 50
	v_readlane_b32 s90, v70, 51
	s_ashr_i32 s85, s84, 31
	s_ashr_i32 s87, s86, 31
	s_ashr_i32 s89, s88, 31
	s_ashr_i32 s91, s90, 31
	s_lshl_b64 s[84:85], s[84:85], 9
	s_lshl_b64 s[86:87], s[86:87], 9
	s_lshl_b64 s[88:89], s[88:89], 9
	s_lshl_b64 s[90:91], s[90:91], 9
	v_lshl_add_u64 v[18:19], v[36:37], 0, s[84:85]
	v_lshl_add_u64 v[20:21], v[36:37], 0, s[86:87]
	v_lshl_add_u64 v[22:23], v[36:37], 0, s[88:89]
	v_lshl_add_u64 v[24:25], v[36:37], 0, s[90:91]
	global_load_dwordx2 v[18:19], v[18:19], off
	global_load_dwordx2 v[20:21], v[20:21], off
	global_load_dwordx2 v[22:23], v[22:23], off
	global_load_dwordx2 v[24:25], v[24:25], off
	v_readlane_b32 s84, v70, 52
	v_readlane_b32 s86, v70, 53
	v_readlane_b32 s88, v70, 54
	v_readlane_b32 s90, v70, 55
	s_ashr_i32 s85, s84, 31
	s_ashr_i32 s87, s86, 31
	s_ashr_i32 s89, s88, 31
	s_ashr_i32 s91, s90, 31
	s_lshl_b64 s[84:85], s[84:85], 9
	s_lshl_b64 s[86:87], s[86:87], 9
	s_lshl_b64 s[88:89], s[88:89], 9
	s_lshl_b64 s[90:91], s[90:91], 9
	v_lshl_add_u64 v[26:27], v[36:37], 0, s[84:85]
	v_lshl_add_u64 v[28:29], v[36:37], 0, s[86:87]
	v_lshl_add_u64 v[30:31], v[36:37], 0, s[88:89]
	v_lshl_add_u64 v[32:33], v[36:37], 0, s[90:91]
	global_load_dwordx2 v[26:27], v[26:27], off
	global_load_dwordx2 v[28:29], v[28:29], off
	global_load_dwordx2 v[30:31], v[30:31], off
	global_load_dwordx2 v[32:33], v[32:33], off
	v_readlane_b32 s84, v70, 56
	v_readlane_b32 s86, v70, 57
	v_readlane_b32 s88, v70, 58
	v_readlane_b32 s90, v70, 59
	s_ashr_i32 s85, s84, 31
	s_ashr_i32 s87, s86, 31
	s_ashr_i32 s89, s88, 31
	s_ashr_i32 s91, s90, 31
	s_lshl_b64 s[84:85], s[84:85], 9
	s_lshl_b64 s[86:87], s[86:87], 9
	s_lshl_b64 s[88:89], s[88:89], 9
	s_lshl_b64 s[90:91], s[90:91], 9
	v_lshl_add_u64 v[56:57], v[36:37], 0, s[84:85]
	v_lshl_add_u64 v[58:59], v[36:37], 0, s[86:87]
	v_lshl_add_u64 v[60:61], v[36:37], 0, s[88:89]
	v_lshl_add_u64 v[62:63], v[36:37], 0, s[90:91]
	global_load_dwordx2 v[56:57], v[56:57], off
	global_load_dwordx2 v[58:59], v[58:59], off
	global_load_dwordx2 v[60:61], v[60:61], off
	global_load_dwordx2 v[62:63], v[62:63], off
	v_readlane_b32 s84, v70, 60
	v_readlane_b32 s86, v70, 61
	v_readlane_b32 s88, v70, 62
	v_readlane_b32 s90, v70, 63
	s_ashr_i32 s85, s84, 31
	s_ashr_i32 s87, s86, 31
	s_ashr_i32 s89, s88, 31
	s_ashr_i32 s91, s90, 31
	s_lshl_b64 s[84:85], s[84:85], 9
	s_lshl_b64 s[86:87], s[86:87], 9
	s_lshl_b64 s[88:89], s[88:89], 9
	s_lshl_b64 s[90:91], s[90:91], 9
	v_lshl_add_u64 v[64:65], v[36:37], 0, s[84:85]
	v_lshl_add_u64 v[66:67], v[36:37], 0, s[86:87]
	v_lshl_add_u64 v[68:69], v[36:37], 0, s[88:89]
	v_lshl_add_u64 v[70:71], v[36:37], 0, s[90:91]
	global_load_dwordx2 v[64:65], v[64:65], off
	global_load_dwordx2 v[66:67], v[66:67], off
	global_load_dwordx2 v[68:69], v[68:69], off
	global_load_dwordx2 v[70:71], v[70:71], off
.Lh2_u19_join:
	s_waitcnt vmcnt(31)
	v_cvt_scalef32_pk_f32_fp4 v[132:133], v72, 1.0 op_sel:[1,0,0]
	s_nop 0
	v_cvt_scalef32_pk_f32_fp4 v[130:131], v72, 1.0
	v_pk_mul_f32 v[132:133], v[132:133], v[4:5]
	s_nop 0
	v_pk_fma_f32 v[130:131], v[130:131], v[2:3], v[132:133]
	v_cvt_scalef32_pk_f32_fp4 v[132:133], v72, 1.0 op_sel:[0,1,0]
	v_pk_fma_f32 v[130:131], v[132:133], v[6:7], v[130:131]
	v_cvt_scalef32_pk_f32_fp4 v[132:133], v72, 1.0 op_sel:[1,1,0]
	v_pk_fma_f32 v[130:131], v[132:133], v[8:9], v[130:131]
	v_cvt_scalef32_pk_f32_fp4 v[132:133], v73, 1.0
	v_pk_fma_f32 v[130:131], v[132:133], v[10:11], v[130:131]
	v_cvt_scalef32_pk_f32_fp4 v[132:133], v73, 1.0 op_sel:[1,0,0]
	v_pk_fma_f32 v[130:131], v[132:133], v[12:13], v[130:131]
	v_cvt_scalef32_pk_f32_fp4 v[132:133], v73, 1.0 op_sel:[0,1,0]
	v_pk_fma_f32 v[130:131], v[132:133], v[14:15], v[130:131]
	v_cvt_scalef32_pk_f32_fp4 v[72:73], v73, 1.0 op_sel:[1,1,0]
	v_pk_fma_f32 v[72:73], v[72:73], v[16:17], v[130:131]
	s_waitcnt vmcnt(30)
	v_cvt_scalef32_pk_f32_fp4 v[130:131], v74, 1.0 op_sel:[1,0,0]
	v_add_f32_e32 v129, v72, v73
	v_cvt_scalef32_pk_f32_fp4 v[72:73], v74, 1.0
	v_pk_mul_f32 v[130:131], v[130:131], v[4:5]
	s_nop 0
	v_pk_fma_f32 v[72:73], v[72:73], v[2:3], v[130:131]
	v_cvt_scalef32_pk_f32_fp4 v[130:131], v74, 1.0 op_sel:[0,1,0]
	v_pk_fma_f32 v[72:73], v[130:131], v[6:7], v[72:73]
	v_cvt_scalef32_pk_f32_fp4 v[130:131], v74, 1.0 op_sel:[1,1,0]
	v_pk_fma_f32 v[72:73], v[130:131], v[8:9], v[72:73]
	v_cvt_scalef32_pk_f32_fp4 v[130:131], v75, 1.0
	v_pk_fma_f32 v[72:73], v[130:131], v[10:11], v[72:73]
	v_cvt_scalef32_pk_f32_fp4 v[130:131], v75, 1.0 op_sel:[1,0,0]
	v_pk_fma_f32 v[72:73], v[130:131], v[12:13], v[72:73]
	v_cvt_scalef32_pk_f32_fp4 v[130:131], v75, 1.0 op_sel:[0,1,0]
	v_pk_fma_f32 v[72:73], v[130:131], v[14:15], v[72:73]
	v_cvt_scalef32_pk_f32_fp4 v[74:75], v75, 1.0 op_sel:[1,1,0]
	v_pk_fma_f32 v[72:73], v[74:75], v[16:17], v[72:73]
	s_waitcnt vmcnt(29)
	v_cvt_scalef32_pk_f32_fp4 v[74:75], v76, 1.0 op_sel:[1,0,0]
	v_add_f32_e32 v130, v72, v73
	v_cvt_scalef32_pk_f32_fp4 v[72:73], v76, 1.0
	v_pk_mul_f32 v[74:75], v[74:75], v[4:5]
	s_nop 0
	v_pk_fma_f32 v[72:73], v[72:73], v[2:3], v[74:75]
	v_cvt_scalef32_pk_f32_fp4 v[74:75], v76, 1.0 op_sel:[0,1,0]
	v_pk_fma_f32 v[72:73], v[74:75], v[6:7], v[72:73]
	v_cvt_scalef32_pk_f32_fp4 v[74:75], v76, 1.0 op_sel:[1,1,0]
	v_pk_fma_f32 v[72:73], v[74:75], v[8:9], v[72:73]
	v_cvt_scalef32_pk_f32_fp4 v[74:75], v77, 1.0
	v_pk_fma_f32 v[72:73], v[74:75], v[10:11], v[72:73]
	v_cvt_scalef32_pk_f32_fp4 v[74:75], v77, 1.0 op_sel:[1,0,0]
	v_pk_fma_f32 v[72:73], v[74:75], v[12:13], v[72:73]
	v_cvt_scalef32_pk_f32_fp4 v[74:75], v77, 1.0 op_sel:[0,1,0]
	v_pk_fma_f32 v[72:73], v[74:75], v[14:15], v[72:73]
	v_cvt_scalef32_pk_f32_fp4 v[74:75], v77, 1.0 op_sel:[1,1,0]
	v_pk_fma_f32 v[72:73], v[74:75], v[16:17], v[72:73]
	s_waitcnt vmcnt(28)
	v_cvt_scalef32_pk_f32_fp4 v[74:75], v78, 1.0 op_sel:[1,0,0]
	v_add_f32_e32 v76, v72, v73
	v_cvt_scalef32_pk_f32_fp4 v[72:73], v78, 1.0
	v_pk_mul_f32 v[74:75], v[74:75], v[4:5]
	s_nop 0
	v_pk_fma_f32 v[72:73], v[72:73], v[2:3], v[74:75]
	v_cvt_scalef32_pk_f32_fp4 v[74:75], v78, 1.0 op_sel:[0,1,0]
	v_pk_fma_f32 v[72:73], v[74:75], v[6:7], v[72:73]
	v_cvt_scalef32_pk_f32_fp4 v[74:75], v78, 1.0 op_sel:[1,1,0]
	v_pk_fma_f32 v[72:73], v[74:75], v[8:9], v[72:73]
	v_cvt_scalef32_pk_f32_fp4 v[74:75], v79, 1.0
	v_pk_fma_f32 v[72:73], v[74:75], v[10:11], v[72:73]
	v_cvt_scalef32_pk_f32_fp4 v[74:75], v79, 1.0 op_sel:[1,0,0]
	v_pk_fma_f32 v[72:73], v[74:75], v[12:13], v[72:73]
	v_cvt_scalef32_pk_f32_fp4 v[74:75], v79, 1.0 op_sel:[0,1,0]
	v_pk_fma_f32 v[72:73], v[74:75], v[14:15], v[72:73]
	v_cvt_scalef32_pk_f32_fp4 v[74:75], v79, 1.0 op_sel:[1,1,0]
	v_pk_fma_f32 v[72:73], v[74:75], v[16:17], v[72:73]
	s_waitcnt vmcnt(27)
	v_cvt_scalef32_pk_f32_fp4 v[74:75], v80, 1.0 op_sel:[1,0,0]
	v_add_f32_e32 v77, v72, v73
	v_cvt_scalef32_pk_f32_fp4 v[72:73], v80, 1.0
	v_pk_mul_f32 v[74:75], v[74:75], v[4:5]
	s_nop 0
	v_pk_fma_f32 v[72:73], v[72:73], v[2:3], v[74:75]
	v_cvt_scalef32_pk_f32_fp4 v[74:75], v80, 1.0 op_sel:[0,1,0]
	v_pk_fma_f32 v[72:73], v[74:75], v[6:7], v[72:73]
	v_cvt_scalef32_pk_f32_fp4 v[74:75], v80, 1.0 op_sel:[1,1,0]
	v_pk_fma_f32 v[72:73], v[74:75], v[8:9], v[72:73]
	v_cvt_scalef32_pk_f32_fp4 v[74:75], v81, 1.0
	v_pk_fma_f32 v[72:73], v[74:75], v[10:11], v[72:73]
	v_cvt_scalef32_pk_f32_fp4 v[74:75], v81, 1.0 op_sel:[1,0,0]
	v_pk_fma_f32 v[72:73], v[74:75], v[12:13], v[72:73]
	v_cvt_scalef32_pk_f32_fp4 v[74:75], v81, 1.0 op_sel:[0,1,0]
	v_pk_fma_f32 v[72:73], v[74:75], v[14:15], v[72:73]
	v_cvt_scalef32_pk_f32_fp4 v[74:75], v81, 1.0 op_sel:[1,1,0]
	v_pk_fma_f32 v[72:73], v[74:75], v[16:17], v[72:73]
	s_waitcnt vmcnt(26)
	v_cvt_scalef32_pk_f32_fp4 v[74:75], v82, 1.0 op_sel:[1,0,0]
	v_add_f32_e32 v78, v72, v73
	v_cvt_scalef32_pk_f32_fp4 v[72:73], v82, 1.0
	v_pk_mul_f32 v[74:75], v[74:75], v[4:5]
	s_nop 0
	v_pk_fma_f32 v[72:73], v[72:73], v[2:3], v[74:75]
	v_cvt_scalef32_pk_f32_fp4 v[74:75], v82, 1.0 op_sel:[0,1,0]
	v_pk_fma_f32 v[72:73], v[74:75], v[6:7], v[72:73]
	v_cvt_scalef32_pk_f32_fp4 v[74:75], v82, 1.0 op_sel:[1,1,0]
	v_pk_fma_f32 v[72:73], v[74:75], v[8:9], v[72:73]
	v_cvt_scalef32_pk_f32_fp4 v[74:75], v83, 1.0
	v_pk_fma_f32 v[72:73], v[74:75], v[10:11], v[72:73]
	v_cvt_scalef32_pk_f32_fp4 v[74:75], v83, 1.0 op_sel:[1,0,0]
	v_pk_fma_f32 v[72:73], v[74:75], v[12:13], v[72:73]
	v_cvt_scalef32_pk_f32_fp4 v[74:75], v83, 1.0 op_sel:[0,1,0]
	v_pk_fma_f32 v[72:73], v[74:75], v[14:15], v[72:73]
	v_cvt_scalef32_pk_f32_fp4 v[74:75], v83, 1.0 op_sel:[1,1,0]
	v_pk_fma_f32 v[72:73], v[74:75], v[16:17], v[72:73]
	s_waitcnt vmcnt(25)
	v_cvt_scalef32_pk_f32_fp4 v[74:75], v84, 1.0 op_sel:[1,0,0]
	v_add_f32_e32 v79, v72, v73
	v_cvt_scalef32_pk_f32_fp4 v[72:73], v84, 1.0
	v_pk_mul_f32 v[74:75], v[74:75], v[4:5]
	s_nop 0
	v_pk_fma_f32 v[72:73], v[72:73], v[2:3], v[74:75]
	v_cvt_scalef32_pk_f32_fp4 v[74:75], v84, 1.0 op_sel:[0,1,0]
	v_pk_fma_f32 v[72:73], v[74:75], v[6:7], v[72:73]
	v_cvt_scalef32_pk_f32_fp4 v[74:75], v84, 1.0 op_sel:[1,1,0]
	v_pk_fma_f32 v[72:73], v[74:75], v[8:9], v[72:73]
	v_cvt_scalef32_pk_f32_fp4 v[74:75], v85, 1.0
	v_pk_fma_f32 v[72:73], v[74:75], v[10:11], v[72:73]
	v_cvt_scalef32_pk_f32_fp4 v[74:75], v85, 1.0 op_sel:[1,0,0]
	v_pk_fma_f32 v[72:73], v[74:75], v[12:13], v[72:73]
	v_cvt_scalef32_pk_f32_fp4 v[74:75], v85, 1.0 op_sel:[0,1,0]
	v_pk_fma_f32 v[72:73], v[74:75], v[14:15], v[72:73]
	v_cvt_scalef32_pk_f32_fp4 v[74:75], v85, 1.0 op_sel:[1,1,0]
	v_pk_fma_f32 v[72:73], v[74:75], v[16:17], v[72:73]
	s_waitcnt vmcnt(24)
	v_cvt_scalef32_pk_f32_fp4 v[74:75], v86, 1.0 op_sel:[1,0,0]
	v_add_f32_e32 v80, v72, v73
	v_cvt_scalef32_pk_f32_fp4 v[72:73], v86, 1.0
	v_pk_mul_f32 v[74:75], v[74:75], v[4:5]
	s_nop 0
	v_pk_fma_f32 v[72:73], v[72:73], v[2:3], v[74:75]
	v_cvt_scalef32_pk_f32_fp4 v[74:75], v86, 1.0 op_sel:[0,1,0]
	v_pk_fma_f32 v[72:73], v[74:75], v[6:7], v[72:73]
	v_cvt_scalef32_pk_f32_fp4 v[74:75], v86, 1.0 op_sel:[1,1,0]
	v_pk_fma_f32 v[72:73], v[74:75], v[8:9], v[72:73]
	v_cvt_scalef32_pk_f32_fp4 v[74:75], v87, 1.0
	v_pk_fma_f32 v[72:73], v[74:75], v[10:11], v[72:73]
	v_cvt_scalef32_pk_f32_fp4 v[74:75], v87, 1.0 op_sel:[1,0,0]
	v_pk_fma_f32 v[72:73], v[74:75], v[12:13], v[72:73]
	v_cvt_scalef32_pk_f32_fp4 v[74:75], v87, 1.0 op_sel:[0,1,0]
	v_pk_fma_f32 v[72:73], v[74:75], v[14:15], v[72:73]
	v_cvt_scalef32_pk_f32_fp4 v[74:75], v87, 1.0 op_sel:[1,1,0]
	v_pk_fma_f32 v[72:73], v[74:75], v[16:17], v[72:73]
	s_waitcnt vmcnt(23)
	v_cvt_scalef32_pk_f32_fp4 v[74:75], v88, 1.0 op_sel:[1,0,0]
	v_add_f32_e32 v81, v72, v73
	v_cvt_scalef32_pk_f32_fp4 v[72:73], v88, 1.0
	v_pk_mul_f32 v[74:75], v[74:75], v[4:5]
	s_nop 0
	v_pk_fma_f32 v[72:73], v[72:73], v[2:3], v[74:75]
	v_cvt_scalef32_pk_f32_fp4 v[74:75], v88, 1.0 op_sel:[0,1,0]
	v_pk_fma_f32 v[72:73], v[74:75], v[6:7], v[72:73]
	v_cvt_scalef32_pk_f32_fp4 v[74:75], v88, 1.0 op_sel:[1,1,0]
	v_pk_fma_f32 v[72:73], v[74:75], v[8:9], v[72:73]
	v_cvt_scalef32_pk_f32_fp4 v[74:75], v89, 1.0
	v_pk_fma_f32 v[72:73], v[74:75], v[10:11], v[72:73]
	v_cvt_scalef32_pk_f32_fp4 v[74:75], v89, 1.0 op_sel:[1,0,0]
	v_pk_fma_f32 v[72:73], v[74:75], v[12:13], v[72:73]
	v_cvt_scalef32_pk_f32_fp4 v[74:75], v89, 1.0 op_sel:[0,1,0]
	v_pk_fma_f32 v[72:73], v[74:75], v[14:15], v[72:73]
	v_cvt_scalef32_pk_f32_fp4 v[74:75], v89, 1.0 op_sel:[1,1,0]
	v_pk_fma_f32 v[72:73], v[74:75], v[16:17], v[72:73]
	s_waitcnt vmcnt(22)
	v_cvt_scalef32_pk_f32_fp4 v[74:75], v90, 1.0 op_sel:[1,0,0]
	v_add_f32_e32 v82, v72, v73
	v_cvt_scalef32_pk_f32_fp4 v[72:73], v90, 1.0
	v_pk_mul_f32 v[74:75], v[74:75], v[4:5]
	s_nop 0
	v_pk_fma_f32 v[72:73], v[72:73], v[2:3], v[74:75]
	v_cvt_scalef32_pk_f32_fp4 v[74:75], v90, 1.0 op_sel:[0,1,0]
	v_pk_fma_f32 v[72:73], v[74:75], v[6:7], v[72:73]
	v_cvt_scalef32_pk_f32_fp4 v[74:75], v90, 1.0 op_sel:[1,1,0]
	v_pk_fma_f32 v[72:73], v[74:75], v[8:9], v[72:73]
	v_cvt_scalef32_pk_f32_fp4 v[74:75], v91, 1.0
	v_pk_fma_f32 v[72:73], v[74:75], v[10:11], v[72:73]
	v_cvt_scalef32_pk_f32_fp4 v[74:75], v91, 1.0 op_sel:[1,0,0]
	v_pk_fma_f32 v[72:73], v[74:75], v[12:13], v[72:73]
	v_cvt_scalef32_pk_f32_fp4 v[74:75], v91, 1.0 op_sel:[0,1,0]
	v_pk_fma_f32 v[72:73], v[74:75], v[14:15], v[72:73]
	v_cvt_scalef32_pk_f32_fp4 v[74:75], v91, 1.0 op_sel:[1,1,0]
	v_pk_fma_f32 v[72:73], v[74:75], v[16:17], v[72:73]
	s_waitcnt vmcnt(21)
	v_cvt_scalef32_pk_f32_fp4 v[74:75], v92, 1.0 op_sel:[1,0,0]
	v_add_f32_e32 v83, v72, v73
	v_cvt_scalef32_pk_f32_fp4 v[72:73], v92, 1.0
	v_pk_mul_f32 v[74:75], v[74:75], v[4:5]
	s_nop 0
	v_pk_fma_f32 v[72:73], v[72:73], v[2:3], v[74:75]
	v_cvt_scalef32_pk_f32_fp4 v[74:75], v92, 1.0 op_sel:[0,1,0]
	v_pk_fma_f32 v[72:73], v[74:75], v[6:7], v[72:73]
	v_cvt_scalef32_pk_f32_fp4 v[74:75], v92, 1.0 op_sel:[1,1,0]
	v_pk_fma_f32 v[72:73], v[74:75], v[8:9], v[72:73]
	v_cvt_scalef32_pk_f32_fp4 v[74:75], v93, 1.0
	v_pk_fma_f32 v[72:73], v[74:75], v[10:11], v[72:73]
	v_cvt_scalef32_pk_f32_fp4 v[74:75], v93, 1.0 op_sel:[1,0,0]
	v_pk_fma_f32 v[72:73], v[74:75], v[12:13], v[72:73]
	v_cvt_scalef32_pk_f32_fp4 v[74:75], v93, 1.0 op_sel:[0,1,0]
	v_pk_fma_f32 v[72:73], v[74:75], v[14:15], v[72:73]
	v_cvt_scalef32_pk_f32_fp4 v[74:75], v93, 1.0 op_sel:[1,1,0]
	v_pk_fma_f32 v[72:73], v[74:75], v[16:17], v[72:73]
	s_waitcnt vmcnt(20)
	v_cvt_scalef32_pk_f32_fp4 v[74:75], v94, 1.0 op_sel:[1,0,0]
	v_add_f32_e32 v84, v72, v73
	v_cvt_scalef32_pk_f32_fp4 v[72:73], v94, 1.0
	v_pk_mul_f32 v[74:75], v[74:75], v[4:5]
	s_nop 0
	v_pk_fma_f32 v[72:73], v[72:73], v[2:3], v[74:75]
	v_cvt_scalef32_pk_f32_fp4 v[74:75], v94, 1.0 op_sel:[0,1,0]
	v_pk_fma_f32 v[72:73], v[74:75], v[6:7], v[72:73]
	v_cvt_scalef32_pk_f32_fp4 v[74:75], v94, 1.0 op_sel:[1,1,0]
	v_pk_fma_f32 v[72:73], v[74:75], v[8:9], v[72:73]
	v_cvt_scalef32_pk_f32_fp4 v[74:75], v95, 1.0
	v_pk_fma_f32 v[72:73], v[74:75], v[10:11], v[72:73]
	v_cvt_scalef32_pk_f32_fp4 v[74:75], v95, 1.0 op_sel:[1,0,0]
	v_pk_fma_f32 v[72:73], v[74:75], v[12:13], v[72:73]
	v_cvt_scalef32_pk_f32_fp4 v[74:75], v95, 1.0 op_sel:[0,1,0]
	v_pk_fma_f32 v[72:73], v[74:75], v[14:15], v[72:73]
	v_cvt_scalef32_pk_f32_fp4 v[74:75], v95, 1.0 op_sel:[1,1,0]
	v_pk_fma_f32 v[72:73], v[74:75], v[16:17], v[72:73]
	s_waitcnt vmcnt(19)
	v_cvt_scalef32_pk_f32_fp4 v[74:75], v96, 1.0 op_sel:[1,0,0]
	v_add_f32_e32 v85, v72, v73
	v_cvt_scalef32_pk_f32_fp4 v[72:73], v96, 1.0
	v_pk_mul_f32 v[74:75], v[74:75], v[4:5]
	s_nop 0
	v_pk_fma_f32 v[72:73], v[72:73], v[2:3], v[74:75]
	v_cvt_scalef32_pk_f32_fp4 v[74:75], v96, 1.0 op_sel:[0,1,0]
	v_pk_fma_f32 v[72:73], v[74:75], v[6:7], v[72:73]
	v_cvt_scalef32_pk_f32_fp4 v[74:75], v96, 1.0 op_sel:[1,1,0]
	v_pk_fma_f32 v[72:73], v[74:75], v[8:9], v[72:73]
	v_cvt_scalef32_pk_f32_fp4 v[74:75], v97, 1.0
	v_pk_fma_f32 v[72:73], v[74:75], v[10:11], v[72:73]
	v_cvt_scalef32_pk_f32_fp4 v[74:75], v97, 1.0 op_sel:[1,0,0]
	v_pk_fma_f32 v[72:73], v[74:75], v[12:13], v[72:73]
	v_cvt_scalef32_pk_f32_fp4 v[74:75], v97, 1.0 op_sel:[0,1,0]
	v_pk_fma_f32 v[72:73], v[74:75], v[14:15], v[72:73]
	v_cvt_scalef32_pk_f32_fp4 v[74:75], v97, 1.0 op_sel:[1,1,0]
	v_pk_fma_f32 v[72:73], v[74:75], v[16:17], v[72:73]
	s_waitcnt vmcnt(18)
	v_cvt_scalef32_pk_f32_fp4 v[74:75], v98, 1.0 op_sel:[1,0,0]
	v_add_f32_e32 v86, v72, v73
	v_cvt_scalef32_pk_f32_fp4 v[72:73], v98, 1.0
	v_pk_mul_f32 v[74:75], v[74:75], v[4:5]
	s_nop 0
	v_pk_fma_f32 v[72:73], v[72:73], v[2:3], v[74:75]
	v_cvt_scalef32_pk_f32_fp4 v[74:75], v98, 1.0 op_sel:[0,1,0]
	v_pk_fma_f32 v[72:73], v[74:75], v[6:7], v[72:73]
	v_cvt_scalef32_pk_f32_fp4 v[74:75], v98, 1.0 op_sel:[1,1,0]
	v_pk_fma_f32 v[72:73], v[74:75], v[8:9], v[72:73]
	v_cvt_scalef32_pk_f32_fp4 v[74:75], v99, 1.0
	v_pk_fma_f32 v[72:73], v[74:75], v[10:11], v[72:73]
	v_cvt_scalef32_pk_f32_fp4 v[74:75], v99, 1.0 op_sel:[1,0,0]
	v_pk_fma_f32 v[72:73], v[74:75], v[12:13], v[72:73]
	v_cvt_scalef32_pk_f32_fp4 v[74:75], v99, 1.0 op_sel:[0,1,0]
	v_pk_fma_f32 v[72:73], v[74:75], v[14:15], v[72:73]
	v_cvt_scalef32_pk_f32_fp4 v[74:75], v99, 1.0 op_sel:[1,1,0]
	v_pk_fma_f32 v[72:73], v[74:75], v[16:17], v[72:73]
	s_waitcnt vmcnt(17)
	v_cvt_scalef32_pk_f32_fp4 v[74:75], v100, 1.0 op_sel:[1,0,0]
	v_add_f32_e32 v87, v72, v73
	v_cvt_scalef32_pk_f32_fp4 v[72:73], v100, 1.0
	v_pk_mul_f32 v[74:75], v[74:75], v[4:5]
	s_nop 0
	v_pk_fma_f32 v[72:73], v[72:73], v[2:3], v[74:75]
	v_cvt_scalef32_pk_f32_fp4 v[74:75], v100, 1.0 op_sel:[0,1,0]
	v_pk_fma_f32 v[72:73], v[74:75], v[6:7], v[72:73]
	v_cvt_scalef32_pk_f32_fp4 v[74:75], v100, 1.0 op_sel:[1,1,0]
	v_pk_fma_f32 v[72:73], v[74:75], v[8:9], v[72:73]
	v_cvt_scalef32_pk_f32_fp4 v[74:75], v101, 1.0
	v_pk_fma_f32 v[72:73], v[74:75], v[10:11], v[72:73]
	v_cvt_scalef32_pk_f32_fp4 v[74:75], v101, 1.0 op_sel:[1,0,0]
	v_pk_fma_f32 v[72:73], v[74:75], v[12:13], v[72:73]
	v_cvt_scalef32_pk_f32_fp4 v[74:75], v101, 1.0 op_sel:[0,1,0]
	v_pk_fma_f32 v[72:73], v[74:75], v[14:15], v[72:73]
	v_cvt_scalef32_pk_f32_fp4 v[74:75], v101, 1.0 op_sel:[1,1,0]
	v_pk_fma_f32 v[72:73], v[74:75], v[16:17], v[72:73]
	s_waitcnt vmcnt(16)
	v_cvt_scalef32_pk_f32_fp4 v[74:75], v102, 1.0 op_sel:[1,0,0]
	v_add_f32_e32 v88, v72, v73
	v_cvt_scalef32_pk_f32_fp4 v[72:73], v102, 1.0
	v_pk_mul_f32 v[74:75], v[74:75], v[4:5]
	s_nop 0
	v_pk_fma_f32 v[72:73], v[72:73], v[2:3], v[74:75]
	v_cvt_scalef32_pk_f32_fp4 v[74:75], v102, 1.0 op_sel:[0,1,0]
	v_pk_fma_f32 v[72:73], v[74:75], v[6:7], v[72:73]
	v_cvt_scalef32_pk_f32_fp4 v[74:75], v102, 1.0 op_sel:[1,1,0]
	v_pk_fma_f32 v[72:73], v[74:75], v[8:9], v[72:73]
	v_cvt_scalef32_pk_f32_fp4 v[74:75], v103, 1.0
	v_pk_fma_f32 v[72:73], v[74:75], v[10:11], v[72:73]
	v_cvt_scalef32_pk_f32_fp4 v[74:75], v103, 1.0 op_sel:[1,0,0]
	v_pk_fma_f32 v[72:73], v[74:75], v[12:13], v[72:73]
	v_cvt_scalef32_pk_f32_fp4 v[74:75], v103, 1.0 op_sel:[0,1,0]
	v_pk_fma_f32 v[72:73], v[74:75], v[14:15], v[72:73]
	v_cvt_scalef32_pk_f32_fp4 v[74:75], v103, 1.0 op_sel:[1,1,0]
	v_pk_fma_f32 v[72:73], v[74:75], v[16:17], v[72:73]
	v_add_f32_e32 v72, v72, v73
	v_cndmask_b32_e64 v73, v82, v129, s[0:1]
	v_cndmask_b32_e64 v74, v129, v82, s[0:1]
	v_cndmask_b32_e64 v75, v130, v83, s[0:1]
	s_nop 0
	v_add_f32_dpp v73, v74, v73 quad_perm:[1,0,3,2] row_mask:0xf bank_mask:0xf bound_ctrl:1
	v_cndmask_b32_e64 v74, v83, v130, s[0:1]
	s_nop 1
	v_add_f32_dpp v74, v75, v74 quad_perm:[1,0,3,2] row_mask:0xf bank_mask:0xf bound_ctrl:1
	v_cndmask_b32_e64 v75, v84, v76, s[0:1]
	v_cndmask_b32_e64 v76, v76, v84, s[0:1]
	s_nop 1
	v_add_f32_dpp v75, v76, v75 quad_perm:[1,0,3,2] row_mask:0xf bank_mask:0xf bound_ctrl:1
	v_cndmask_b32_e64 v76, v85, v77, s[0:1]
	v_cndmask_b32_e64 v77, v77, v85, s[0:1]
	s_nop 1
	v_add_f32_dpp v76, v77, v76 quad_perm:[1,0,3,2] row_mask:0xf bank_mask:0xf bound_ctrl:1
	v_cndmask_b32_e64 v77, v86, v78, s[0:1]
	v_cndmask_b32_e64 v78, v78, v86, s[0:1]
	s_nop 1
	v_add_f32_dpp v77, v78, v77 quad_perm:[1,0,3,2] row_mask:0xf bank_mask:0xf bound_ctrl:1
	v_cndmask_b32_e64 v78, v87, v79, s[0:1]
	v_cndmask_b32_e64 v79, v79, v87, s[0:1]
	s_nop 1
	v_add_f32_dpp v78, v79, v78 quad_perm:[1,0,3,2] row_mask:0xf bank_mask:0xf bound_ctrl:1
	v_cndmask_b32_e64 v79, v88, v80, s[0:1]
	v_cndmask_b32_e64 v80, v80, v88, s[0:1]
	s_nop 1
	v_add_f32_dpp v79, v80, v79 quad_perm:[1,0,3,2] row_mask:0xf bank_mask:0xf bound_ctrl:1
	v_cndmask_b32_e64 v80, v72, v81, s[0:1]
	v_cndmask_b32_e64 v72, v81, v72, s[0:1]
	s_nop 1
	v_add_f32_dpp v72, v72, v80 quad_perm:[1,0,3,2] row_mask:0xf bank_mask:0xf bound_ctrl:1
	v_cndmask_b32_e64 v80, v77, v73, s[2:3]
	v_cndmask_b32_e64 v73, v73, v77, s[2:3]
	v_cndmask_b32_e64 v77, v78, v74, s[2:3]
	v_cndmask_b32_e64 v74, v74, v78, s[2:3]
	v_add_f32_dpp v73, v73, v80 quad_perm:[2,3,0,1] row_mask:0xf bank_mask:0xf bound_ctrl:1
	s_nop 0
	v_add_f32_dpp v74, v74, v77 quad_perm:[2,3,0,1] row_mask:0xf bank_mask:0xf bound_ctrl:1
	v_cndmask_b32_e64 v77, v79, v75, s[2:3]
	v_cndmask_b32_e64 v75, v75, v79, s[2:3]
	s_nop 1
	v_add_f32_dpp v75, v75, v77 quad_perm:[2,3,0,1] row_mask:0xf bank_mask:0xf bound_ctrl:1
	v_cndmask_b32_e64 v77, v72, v76, s[2:3]
	v_cndmask_b32_e64 v72, v76, v72, s[2:3]
	v_cndmask_b32_e64 v76, v75, v73, s[4:5]
	v_cndmask_b32_e64 v73, v73, v75, s[4:5]
	v_add_f32_dpp v72, v72, v77 quad_perm:[2,3,0,1] row_mask:0xf bank_mask:0xf bound_ctrl:1
	v_cndmask_b32_e64 v75, v72, v74, s[4:5]
	v_cndmask_b32_e64 v72, v74, v72, s[4:5]
	v_mov_b32_dpp v73, v73 row_half_mirror row_mask:0xf bank_mask:0xf bound_ctrl:1
	s_nop 0
	v_mov_b32_dpp v72, v72 row_half_mirror row_mask:0xf bank_mask:0xf bound_ctrl:1
	v_add_f32_dpp v73, v73, v76 quad_perm:[3,2,1,0] row_mask:0xf bank_mask:0xf bound_ctrl:1
	s_nop 0
	v_add_f32_dpp v72, v72, v75 quad_perm:[3,2,1,0] row_mask:0xf bank_mask:0xf bound_ctrl:1
	v_cndmask_b32_e64 v74, v72, v73, s[6:7]
	v_cndmask_b32_e64 v72, v73, v72, s[6:7]
	s_nop 1
	v_mov_b32_dpp v72, v72 row_mirror row_mask:0xf bank_mask:0xf bound_ctrl:1
	s_nop 1
	v_add_f32_dpp v72, v72, v74 row_half_mirror row_mask:0xf bank_mask:0xf bound_ctrl:1
	ds_bpermute_b32 v73, v124, v72
	v_and_b32_e32 v76, 2, v123
	s_waitcnt lgkmcnt(0)
	v_add_f32_e32 v72, v72, v73
	ds_bpermute_b32 v73, v125, v72
	s_waitcnt vmcnt(15)
	v_cvt_scalef32_pk_f32_fp4 v[74:75], v18, 1.0 op_sel:[1,0,0]
	v_pk_mul_f32 v[74:75], v[74:75], v[4:5]
	s_waitcnt lgkmcnt(0)
	v_add_f32_e32 v72, v72, v73
	v_cndmask_b32_e64 v73, v72, v127, s[10:11]
	v_add_u32_e32 v126, 32, v126
	v_cmp_eq_u32_e64 s[12:13], v107, v76
	v_add_u32_e32 v123, 2, v123
	s_nop 0
	v_cndmask_b32_e64 v77, v127, v73, s[12:13]
	s_and_b64 s[12:13], s[12:13], s[10:11]
	v_cndmask_b32_e64 v78, v128, v72, s[12:13]
	v_cvt_scalef32_pk_f32_fp4 v[72:73], v18, 1.0
	v_pk_fma_f32 v[72:73], v[72:73], v[2:3], v[74:75]
	v_cvt_scalef32_pk_f32_fp4 v[74:75], v18, 1.0 op_sel:[0,1,0]
	v_pk_fma_f32 v[72:73], v[74:75], v[6:7], v[72:73]
	v_cvt_scalef32_pk_f32_fp4 v[74:75], v18, 1.0 op_sel:[1,1,0]
	v_pk_fma_f32 v[72:73], v[74:75], v[8:9], v[72:73]
	v_cvt_scalef32_pk_f32_fp4 v[74:75], v19, 1.0
	v_pk_fma_f32 v[72:73], v[74:75], v[10:11], v[72:73]
	v_cvt_scalef32_pk_f32_fp4 v[74:75], v19, 1.0 op_sel:[1,0,0]
	v_pk_fma_f32 v[72:73], v[74:75], v[12:13], v[72:73]
	v_cvt_scalef32_pk_f32_fp4 v[74:75], v19, 1.0 op_sel:[0,1,0]
	v_pk_fma_f32 v[72:73], v[74:75], v[14:15], v[72:73]
	v_cvt_scalef32_pk_f32_fp4 v[18:19], v19, 1.0 op_sel:[1,1,0]
	v_pk_fma_f32 v[18:19], v[18:19], v[16:17], v[72:73]
	s_waitcnt vmcnt(14)
	v_cvt_scalef32_pk_f32_fp4 v[72:73], v20, 1.0 op_sel:[1,0,0]
	v_add_f32_e32 v74, v18, v19
	v_cvt_scalef32_pk_f32_fp4 v[18:19], v20, 1.0
	v_pk_mul_f32 v[72:73], v[72:73], v[4:5]
	s_nop 0
	v_pk_fma_f32 v[18:19], v[18:19], v[2:3], v[72:73]
	v_cvt_scalef32_pk_f32_fp4 v[72:73], v20, 1.0 op_sel:[0,1,0]
	v_pk_fma_f32 v[18:19], v[72:73], v[6:7], v[18:19]
	v_cvt_scalef32_pk_f32_fp4 v[72:73], v20, 1.0 op_sel:[1,1,0]
	v_pk_fma_f32 v[18:19], v[72:73], v[8:9], v[18:19]
	v_cvt_scalef32_pk_f32_fp4 v[72:73], v21, 1.0
	v_pk_fma_f32 v[18:19], v[72:73], v[10:11], v[18:19]
	v_cvt_scalef32_pk_f32_fp4 v[72:73], v21, 1.0 op_sel:[1,0,0]
	v_pk_fma_f32 v[18:19], v[72:73], v[12:13], v[18:19]
	v_cvt_scalef32_pk_f32_fp4 v[72:73], v21, 1.0 op_sel:[0,1,0]
	v_pk_fma_f32 v[18:19], v[72:73], v[14:15], v[18:19]
	v_cvt_scalef32_pk_f32_fp4 v[20:21], v21, 1.0 op_sel:[1,1,0]
	v_pk_fma_f32 v[18:19], v[20:21], v[16:17], v[18:19]
	s_waitcnt vmcnt(13)
	v_cvt_scalef32_pk_f32_fp4 v[20:21], v22, 1.0 op_sel:[1,0,0]
	v_add_f32_e32 v72, v18, v19
	v_cvt_scalef32_pk_f32_fp4 v[18:19], v22, 1.0
	v_pk_mul_f32 v[20:21], v[20:21], v[4:5]
	s_nop 0
	v_pk_fma_f32 v[18:19], v[18:19], v[2:3], v[20:21]
	v_cvt_scalef32_pk_f32_fp4 v[20:21], v22, 1.0 op_sel:[0,1,0]
	v_pk_fma_f32 v[18:19], v[20:21], v[6:7], v[18:19]
	v_cvt_scalef32_pk_f32_fp4 v[20:21], v22, 1.0 op_sel:[1,1,0]
	v_pk_fma_f32 v[18:19], v[20:21], v[8:9], v[18:19]
	v_cvt_scalef32_pk_f32_fp4 v[20:21], v23, 1.0
	v_pk_fma_f32 v[18:19], v[20:21], v[10:11], v[18:19]
	v_cvt_scalef32_pk_f32_fp4 v[20:21], v23, 1.0 op_sel:[1,0,0]
	v_pk_fma_f32 v[18:19], v[20:21], v[12:13], v[18:19]
	v_cvt_scalef32_pk_f32_fp4 v[20:21], v23, 1.0 op_sel:[0,1,0]
	v_pk_fma_f32 v[18:19], v[20:21], v[14:15], v[18:19]
	v_cvt_scalef32_pk_f32_fp4 v[20:21], v23, 1.0 op_sel:[1,1,0]
	v_pk_fma_f32 v[18:19], v[20:21], v[16:17], v[18:19]
	s_waitcnt vmcnt(12)
	v_cvt_scalef32_pk_f32_fp4 v[20:21], v24, 1.0 op_sel:[1,0,0]
	v_add_f32_e32 v22, v18, v19
	v_cvt_scalef32_pk_f32_fp4 v[18:19], v24, 1.0
	v_pk_mul_f32 v[20:21], v[20:21], v[4:5]
	s_nop 0
	v_pk_fma_f32 v[18:19], v[18:19], v[2:3], v[20:21]
	v_cvt_scalef32_pk_f32_fp4 v[20:21], v24, 1.0 op_sel:[0,1,0]
	v_pk_fma_f32 v[18:19], v[20:21], v[6:7], v[18:19]
	v_cvt_scalef32_pk_f32_fp4 v[20:21], v24, 1.0 op_sel:[1,1,0]
	v_pk_fma_f32 v[18:19], v[20:21], v[8:9], v[18:19]
	v_cvt_scalef32_pk_f32_fp4 v[20:21], v25, 1.0
	v_pk_fma_f32 v[18:19], v[20:21], v[10:11], v[18:19]
	v_cvt_scalef32_pk_f32_fp4 v[20:21], v25, 1.0 op_sel:[1,0,0]
	v_pk_fma_f32 v[18:19], v[20:21], v[12:13], v[18:19]
	v_cvt_scalef32_pk_f32_fp4 v[20:21], v25, 1.0 op_sel:[0,1,0]
	v_pk_fma_f32 v[18:19], v[20:21], v[14:15], v[18:19]
	v_cvt_scalef32_pk_f32_fp4 v[20:21], v25, 1.0 op_sel:[1,1,0]
	v_pk_fma_f32 v[18:19], v[20:21], v[16:17], v[18:19]
	s_waitcnt vmcnt(11)
	v_cvt_scalef32_pk_f32_fp4 v[20:21], v26, 1.0 op_sel:[1,0,0]
	v_add_f32_e32 v23, v18, v19
	v_cvt_scalef32_pk_f32_fp4 v[18:19], v26, 1.0
	v_pk_mul_f32 v[20:21], v[20:21], v[4:5]
	s_nop 0
	v_pk_fma_f32 v[18:19], v[18:19], v[2:3], v[20:21]
	v_cvt_scalef32_pk_f32_fp4 v[20:21], v26, 1.0 op_sel:[0,1,0]
	v_pk_fma_f32 v[18:19], v[20:21], v[6:7], v[18:19]
	v_cvt_scalef32_pk_f32_fp4 v[20:21], v26, 1.0 op_sel:[1,1,0]
	v_pk_fma_f32 v[18:19], v[20:21], v[8:9], v[18:19]
	v_cvt_scalef32_pk_f32_fp4 v[20:21], v27, 1.0
	v_pk_fma_f32 v[18:19], v[20:21], v[10:11], v[18:19]
	v_cvt_scalef32_pk_f32_fp4 v[20:21], v27, 1.0 op_sel:[1,0,0]
	v_pk_fma_f32 v[18:19], v[20:21], v[12:13], v[18:19]
	v_cvt_scalef32_pk_f32_fp4 v[20:21], v27, 1.0 op_sel:[0,1,0]
	v_pk_fma_f32 v[18:19], v[20:21], v[14:15], v[18:19]
	v_cvt_scalef32_pk_f32_fp4 v[20:21], v27, 1.0 op_sel:[1,1,0]
	v_pk_fma_f32 v[18:19], v[20:21], v[16:17], v[18:19]
	s_waitcnt vmcnt(10)
	v_cvt_scalef32_pk_f32_fp4 v[20:21], v28, 1.0 op_sel:[1,0,0]
	v_add_f32_e32 v24, v18, v19
	v_cvt_scalef32_pk_f32_fp4 v[18:19], v28, 1.0
	v_pk_mul_f32 v[20:21], v[20:21], v[4:5]
	s_nop 0
	v_pk_fma_f32 v[18:19], v[18:19], v[2:3], v[20:21]
	v_cvt_scalef32_pk_f32_fp4 v[20:21], v28, 1.0 op_sel:[0,1,0]
	v_pk_fma_f32 v[18:19], v[20:21], v[6:7], v[18:19]
	v_cvt_scalef32_pk_f32_fp4 v[20:21], v28, 1.0 op_sel:[1,1,0]
	v_pk_fma_f32 v[18:19], v[20:21], v[8:9], v[18:19]
	v_cvt_scalef32_pk_f32_fp4 v[20:21], v29, 1.0
	v_pk_fma_f32 v[18:19], v[20:21], v[10:11], v[18:19]
	v_cvt_scalef32_pk_f32_fp4 v[20:21], v29, 1.0 op_sel:[1,0,0]
	v_pk_fma_f32 v[18:19], v[20:21], v[12:13], v[18:19]
	v_cvt_scalef32_pk_f32_fp4 v[20:21], v29, 1.0 op_sel:[0,1,0]
	v_pk_fma_f32 v[18:19], v[20:21], v[14:15], v[18:19]
	v_cvt_scalef32_pk_f32_fp4 v[20:21], v29, 1.0 op_sel:[1,1,0]
	v_pk_fma_f32 v[18:19], v[20:21], v[16:17], v[18:19]
	s_waitcnt vmcnt(9)
	v_cvt_scalef32_pk_f32_fp4 v[20:21], v30, 1.0 op_sel:[1,0,0]
	v_add_f32_e32 v25, v18, v19
	v_cvt_scalef32_pk_f32_fp4 v[18:19], v30, 1.0
	v_pk_mul_f32 v[20:21], v[20:21], v[4:5]
	s_nop 0
	v_pk_fma_f32 v[18:19], v[18:19], v[2:3], v[20:21]
	v_cvt_scalef32_pk_f32_fp4 v[20:21], v30, 1.0 op_sel:[0,1,0]
	v_pk_fma_f32 v[18:19], v[20:21], v[6:7], v[18:19]
	v_cvt_scalef32_pk_f32_fp4 v[20:21], v30, 1.0 op_sel:[1,1,0]
	v_pk_fma_f32 v[18:19], v[20:21], v[8:9], v[18:19]
	v_cvt_scalef32_pk_f32_fp4 v[20:21], v31, 1.0
	v_pk_fma_f32 v[18:19], v[20:21], v[10:11], v[18:19]
	v_cvt_scalef32_pk_f32_fp4 v[20:21], v31, 1.0 op_sel:[1,0,0]
	v_pk_fma_f32 v[18:19], v[20:21], v[12:13], v[18:19]
	v_cvt_scalef32_pk_f32_fp4 v[20:21], v31, 1.0 op_sel:[0,1,0]
	v_pk_fma_f32 v[18:19], v[20:21], v[14:15], v[18:19]
	v_cvt_scalef32_pk_f32_fp4 v[20:21], v31, 1.0 op_sel:[1,1,0]
	v_pk_fma_f32 v[18:19], v[20:21], v[16:17], v[18:19]
	s_waitcnt vmcnt(8)
	v_cvt_scalef32_pk_f32_fp4 v[20:21], v32, 1.0 op_sel:[1,0,0]
	v_add_f32_e32 v26, v18, v19
	v_cvt_scalef32_pk_f32_fp4 v[18:19], v32, 1.0
	v_pk_mul_f32 v[20:21], v[20:21], v[4:5]
	s_nop 0
	v_pk_fma_f32 v[18:19], v[18:19], v[2:3], v[20:21]
	v_cvt_scalef32_pk_f32_fp4 v[20:21], v32, 1.0 op_sel:[0,1,0]
	v_pk_fma_f32 v[18:19], v[20:21], v[6:7], v[18:19]
	v_cvt_scalef32_pk_f32_fp4 v[20:21], v32, 1.0 op_sel:[1,1,0]
	v_pk_fma_f32 v[18:19], v[20:21], v[8:9], v[18:19]
	v_cvt_scalef32_pk_f32_fp4 v[20:21], v33, 1.0
	v_pk_fma_f32 v[18:19], v[20:21], v[10:11], v[18:19]
	v_cvt_scalef32_pk_f32_fp4 v[20:21], v33, 1.0 op_sel:[1,0,0]
	v_pk_fma_f32 v[18:19], v[20:21], v[12:13], v[18:19]
	v_cvt_scalef32_pk_f32_fp4 v[20:21], v33, 1.0 op_sel:[0,1,0]
	v_pk_fma_f32 v[18:19], v[20:21], v[14:15], v[18:19]
	v_cvt_scalef32_pk_f32_fp4 v[20:21], v33, 1.0 op_sel:[1,1,0]
	v_pk_fma_f32 v[18:19], v[20:21], v[16:17], v[18:19]
	s_waitcnt vmcnt(7)
	v_cvt_scalef32_pk_f32_fp4 v[20:21], v56, 1.0 op_sel:[1,0,0]
	v_add_f32_e32 v27, v18, v19
	v_cvt_scalef32_pk_f32_fp4 v[18:19], v56, 1.0
	v_pk_mul_f32 v[20:21], v[20:21], v[4:5]
	s_nop 0
	v_pk_fma_f32 v[18:19], v[18:19], v[2:3], v[20:21]
	v_cvt_scalef32_pk_f32_fp4 v[20:21], v56, 1.0 op_sel:[0,1,0]
	v_pk_fma_f32 v[18:19], v[20:21], v[6:7], v[18:19]
	v_cvt_scalef32_pk_f32_fp4 v[20:21], v56, 1.0 op_sel:[1,1,0]
	v_pk_fma_f32 v[18:19], v[20:21], v[8:9], v[18:19]
	v_cvt_scalef32_pk_f32_fp4 v[20:21], v57, 1.0
	v_pk_fma_f32 v[18:19], v[20:21], v[10:11], v[18:19]
	v_cvt_scalef32_pk_f32_fp4 v[20:21], v57, 1.0 op_sel:[1,0,0]
	v_pk_fma_f32 v[18:19], v[20:21], v[12:13], v[18:19]
	v_cvt_scalef32_pk_f32_fp4 v[20:21], v57, 1.0 op_sel:[0,1,0]
	v_pk_fma_f32 v[18:19], v[20:21], v[14:15], v[18:19]
	v_cvt_scalef32_pk_f32_fp4 v[20:21], v57, 1.0 op_sel:[1,1,0]
	v_pk_fma_f32 v[18:19], v[20:21], v[16:17], v[18:19]
	s_waitcnt vmcnt(6)
	v_cvt_scalef32_pk_f32_fp4 v[20:21], v58, 1.0 op_sel:[1,0,0]
	v_add_f32_e32 v28, v18, v19
	v_cvt_scalef32_pk_f32_fp4 v[18:19], v58, 1.0
	v_pk_mul_f32 v[20:21], v[20:21], v[4:5]
	s_nop 0
	v_pk_fma_f32 v[18:19], v[18:19], v[2:3], v[20:21]
	v_cvt_scalef32_pk_f32_fp4 v[20:21], v58, 1.0 op_sel:[0,1,0]
	v_pk_fma_f32 v[18:19], v[20:21], v[6:7], v[18:19]
	v_cvt_scalef32_pk_f32_fp4 v[20:21], v58, 1.0 op_sel:[1,1,0]
	v_pk_fma_f32 v[18:19], v[20:21], v[8:9], v[18:19]
	v_cvt_scalef32_pk_f32_fp4 v[20:21], v59, 1.0
	v_pk_fma_f32 v[18:19], v[20:21], v[10:11], v[18:19]
	v_cvt_scalef32_pk_f32_fp4 v[20:21], v59, 1.0 op_sel:[1,0,0]
	v_pk_fma_f32 v[18:19], v[20:21], v[12:13], v[18:19]
	v_cvt_scalef32_pk_f32_fp4 v[20:21], v59, 1.0 op_sel:[0,1,0]
	v_pk_fma_f32 v[18:19], v[20:21], v[14:15], v[18:19]
	v_cvt_scalef32_pk_f32_fp4 v[20:21], v59, 1.0 op_sel:[1,1,0]
	v_pk_fma_f32 v[18:19], v[20:21], v[16:17], v[18:19]
	s_waitcnt vmcnt(5)
	v_cvt_scalef32_pk_f32_fp4 v[20:21], v60, 1.0 op_sel:[1,0,0]
	v_add_f32_e32 v29, v18, v19
	v_cvt_scalef32_pk_f32_fp4 v[18:19], v60, 1.0
	v_pk_mul_f32 v[20:21], v[20:21], v[4:5]
	s_nop 0
	v_pk_fma_f32 v[18:19], v[18:19], v[2:3], v[20:21]
	v_cvt_scalef32_pk_f32_fp4 v[20:21], v60, 1.0 op_sel:[0,1,0]
	v_pk_fma_f32 v[18:19], v[20:21], v[6:7], v[18:19]
	v_cvt_scalef32_pk_f32_fp4 v[20:21], v60, 1.0 op_sel:[1,1,0]
	v_pk_fma_f32 v[18:19], v[20:21], v[8:9], v[18:19]
	v_cvt_scalef32_pk_f32_fp4 v[20:21], v61, 1.0
	v_pk_fma_f32 v[18:19], v[20:21], v[10:11], v[18:19]
	v_cvt_scalef32_pk_f32_fp4 v[20:21], v61, 1.0 op_sel:[1,0,0]
	v_pk_fma_f32 v[18:19], v[20:21], v[12:13], v[18:19]
	v_cvt_scalef32_pk_f32_fp4 v[20:21], v61, 1.0 op_sel:[0,1,0]
	v_pk_fma_f32 v[18:19], v[20:21], v[14:15], v[18:19]
	v_cvt_scalef32_pk_f32_fp4 v[20:21], v61, 1.0 op_sel:[1,1,0]
	v_pk_fma_f32 v[18:19], v[20:21], v[16:17], v[18:19]
	s_waitcnt vmcnt(4)
	v_cvt_scalef32_pk_f32_fp4 v[20:21], v62, 1.0 op_sel:[1,0,0]
	v_add_f32_e32 v30, v18, v19
	v_cvt_scalef32_pk_f32_fp4 v[18:19], v62, 1.0
	v_pk_mul_f32 v[20:21], v[20:21], v[4:5]
	s_nop 0
	v_pk_fma_f32 v[18:19], v[18:19], v[2:3], v[20:21]
	v_cvt_scalef32_pk_f32_fp4 v[20:21], v62, 1.0 op_sel:[0,1,0]
	v_pk_fma_f32 v[18:19], v[20:21], v[6:7], v[18:19]
	v_cvt_scalef32_pk_f32_fp4 v[20:21], v62, 1.0 op_sel:[1,1,0]
	v_pk_fma_f32 v[18:19], v[20:21], v[8:9], v[18:19]
	v_cvt_scalef32_pk_f32_fp4 v[20:21], v63, 1.0
	v_pk_fma_f32 v[18:19], v[20:21], v[10:11], v[18:19]
	v_cvt_scalef32_pk_f32_fp4 v[20:21], v63, 1.0 op_sel:[1,0,0]
	v_pk_fma_f32 v[18:19], v[20:21], v[12:13], v[18:19]
	v_cvt_scalef32_pk_f32_fp4 v[20:21], v63, 1.0 op_sel:[0,1,0]
	v_pk_fma_f32 v[18:19], v[20:21], v[14:15], v[18:19]
	v_cvt_scalef32_pk_f32_fp4 v[20:21], v63, 1.0 op_sel:[1,1,0]
	v_pk_fma_f32 v[18:19], v[20:21], v[16:17], v[18:19]
	s_waitcnt vmcnt(3)
	v_cvt_scalef32_pk_f32_fp4 v[20:21], v64, 1.0 op_sel:[1,0,0]
	v_add_f32_e32 v31, v18, v19
	v_cvt_scalef32_pk_f32_fp4 v[18:19], v64, 1.0
	v_pk_mul_f32 v[20:21], v[20:21], v[4:5]
	s_nop 0
	v_pk_fma_f32 v[18:19], v[18:19], v[2:3], v[20:21]
	v_cvt_scalef32_pk_f32_fp4 v[20:21], v64, 1.0 op_sel:[0,1,0]
	v_pk_fma_f32 v[18:19], v[20:21], v[6:7], v[18:19]
	v_cvt_scalef32_pk_f32_fp4 v[20:21], v64, 1.0 op_sel:[1,1,0]
	v_pk_fma_f32 v[18:19], v[20:21], v[8:9], v[18:19]
	v_cvt_scalef32_pk_f32_fp4 v[20:21], v65, 1.0
	v_pk_fma_f32 v[18:19], v[20:21], v[10:11], v[18:19]
	v_cvt_scalef32_pk_f32_fp4 v[20:21], v65, 1.0 op_sel:[1,0,0]
	v_pk_fma_f32 v[18:19], v[20:21], v[12:13], v[18:19]
	v_cvt_scalef32_pk_f32_fp4 v[20:21], v65, 1.0 op_sel:[0,1,0]
	v_pk_fma_f32 v[18:19], v[20:21], v[14:15], v[18:19]
	v_cvt_scalef32_pk_f32_fp4 v[20:21], v65, 1.0 op_sel:[1,1,0]
	v_pk_fma_f32 v[18:19], v[20:21], v[16:17], v[18:19]
	s_waitcnt vmcnt(2)
	v_cvt_scalef32_pk_f32_fp4 v[20:21], v66, 1.0 op_sel:[1,0,0]
	v_add_f32_e32 v32, v18, v19
	v_cvt_scalef32_pk_f32_fp4 v[18:19], v66, 1.0
	v_pk_mul_f32 v[20:21], v[20:21], v[4:5]
	s_nop 0
	v_pk_fma_f32 v[18:19], v[18:19], v[2:3], v[20:21]
	v_cvt_scalef32_pk_f32_fp4 v[20:21], v66, 1.0 op_sel:[0,1,0]
	v_pk_fma_f32 v[18:19], v[20:21], v[6:7], v[18:19]
	v_cvt_scalef32_pk_f32_fp4 v[20:21], v66, 1.0 op_sel:[1,1,0]
	v_pk_fma_f32 v[18:19], v[20:21], v[8:9], v[18:19]
	v_cvt_scalef32_pk_f32_fp4 v[20:21], v67, 1.0
	v_pk_fma_f32 v[18:19], v[20:21], v[10:11], v[18:19]
	v_cvt_scalef32_pk_f32_fp4 v[20:21], v67, 1.0 op_sel:[1,0,0]
	v_pk_fma_f32 v[18:19], v[20:21], v[12:13], v[18:19]
	v_cvt_scalef32_pk_f32_fp4 v[20:21], v67, 1.0 op_sel:[0,1,0]
	v_pk_fma_f32 v[18:19], v[20:21], v[14:15], v[18:19]
	v_cvt_scalef32_pk_f32_fp4 v[20:21], v67, 1.0 op_sel:[1,1,0]
	v_pk_fma_f32 v[18:19], v[20:21], v[16:17], v[18:19]
	s_waitcnt vmcnt(1)
	v_cvt_scalef32_pk_f32_fp4 v[20:21], v68, 1.0 op_sel:[1,0,0]
	v_add_f32_e32 v33, v18, v19
	v_cvt_scalef32_pk_f32_fp4 v[18:19], v68, 1.0
	v_pk_mul_f32 v[20:21], v[20:21], v[4:5]
	s_nop 0
	v_pk_fma_f32 v[18:19], v[18:19], v[2:3], v[20:21]
	v_cvt_scalef32_pk_f32_fp4 v[20:21], v68, 1.0 op_sel:[0,1,0]
	v_pk_fma_f32 v[18:19], v[20:21], v[6:7], v[18:19]
	v_cvt_scalef32_pk_f32_fp4 v[20:21], v68, 1.0 op_sel:[1,1,0]
	v_pk_fma_f32 v[18:19], v[20:21], v[8:9], v[18:19]
	v_cvt_scalef32_pk_f32_fp4 v[20:21], v69, 1.0
	v_pk_fma_f32 v[18:19], v[20:21], v[10:11], v[18:19]
	v_cvt_scalef32_pk_f32_fp4 v[20:21], v69, 1.0 op_sel:[1,0,0]
	v_pk_fma_f32 v[18:19], v[20:21], v[12:13], v[18:19]
	v_cvt_scalef32_pk_f32_fp4 v[20:21], v69, 1.0 op_sel:[0,1,0]
	v_pk_fma_f32 v[18:19], v[20:21], v[14:15], v[18:19]
	v_cvt_scalef32_pk_f32_fp4 v[20:21], v69, 1.0 op_sel:[1,1,0]
	v_pk_fma_f32 v[18:19], v[20:21], v[16:17], v[18:19]
	s_waitcnt vmcnt(0)
	v_cvt_scalef32_pk_f32_fp4 v[20:21], v70, 1.0 op_sel:[1,0,0]
	v_add_f32_e32 v56, v18, v19
	v_cvt_scalef32_pk_f32_fp4 v[18:19], v70, 1.0
	v_pk_mul_f32 v[20:21], v[20:21], v[4:5]
	s_nop 0
	v_pk_fma_f32 v[18:19], v[18:19], v[2:3], v[20:21]
	v_cvt_scalef32_pk_f32_fp4 v[20:21], v70, 1.0 op_sel:[0,1,0]
	v_pk_fma_f32 v[18:19], v[20:21], v[6:7], v[18:19]
	v_cvt_scalef32_pk_f32_fp4 v[20:21], v70, 1.0 op_sel:[1,1,0]
	v_pk_fma_f32 v[18:19], v[20:21], v[8:9], v[18:19]
	v_cvt_scalef32_pk_f32_fp4 v[20:21], v71, 1.0
	v_pk_fma_f32 v[18:19], v[20:21], v[10:11], v[18:19]
	v_cvt_scalef32_pk_f32_fp4 v[20:21], v71, 1.0 op_sel:[1,0,0]
	v_pk_fma_f32 v[18:19], v[20:21], v[12:13], v[18:19]
	v_cvt_scalef32_pk_f32_fp4 v[20:21], v71, 1.0 op_sel:[0,1,0]
	v_pk_fma_f32 v[18:19], v[20:21], v[14:15], v[18:19]
	v_cvt_scalef32_pk_f32_fp4 v[20:21], v71, 1.0 op_sel:[1,1,0]
	v_pk_fma_f32 v[18:19], v[20:21], v[16:17], v[18:19]
	v_cndmask_b32_e64 v20, v74, v28, s[0:1]
	v_add_f32_e32 v18, v18, v19
	v_cndmask_b32_e64 v19, v28, v74, s[0:1]
	v_cndmask_b32_e64 v21, v72, v29, s[0:1]
	s_nop 0
	v_add_f32_dpp v19, v20, v19 quad_perm:[1,0,3,2] row_mask:0xf bank_mask:0xf bound_ctrl:1
	v_cndmask_b32_e64 v20, v29, v72, s[0:1]
	s_nop 1
	v_add_f32_dpp v20, v21, v20 quad_perm:[1,0,3,2] row_mask:0xf bank_mask:0xf bound_ctrl:1
	v_cndmask_b32_e64 v21, v30, v22, s[0:1]
	v_cndmask_b32_e64 v22, v22, v30, s[0:1]
	s_nop 1
	v_add_f32_dpp v21, v22, v21 quad_perm:[1,0,3,2] row_mask:0xf bank_mask:0xf bound_ctrl:1
	v_cndmask_b32_e64 v22, v31, v23, s[0:1]
	v_cndmask_b32_e64 v23, v23, v31, s[0:1]
	s_nop 1
	v_add_f32_dpp v22, v23, v22 quad_perm:[1,0,3,2] row_mask:0xf bank_mask:0xf bound_ctrl:1
	v_cndmask_b32_e64 v23, v32, v24, s[0:1]
	v_cndmask_b32_e64 v24, v24, v32, s[0:1]
	s_nop 1
	v_add_f32_dpp v23, v24, v23 quad_perm:[1,0,3,2] row_mask:0xf bank_mask:0xf bound_ctrl:1
	v_cndmask_b32_e64 v24, v33, v25, s[0:1]
	v_cndmask_b32_e64 v25, v25, v33, s[0:1]
	s_nop 1
	v_add_f32_dpp v24, v25, v24 quad_perm:[1,0,3,2] row_mask:0xf bank_mask:0xf bound_ctrl:1
	v_cndmask_b32_e64 v25, v56, v26, s[0:1]
	v_cndmask_b32_e64 v26, v26, v56, s[0:1]
	s_nop 1
	v_add_f32_dpp v25, v26, v25 quad_perm:[1,0,3,2] row_mask:0xf bank_mask:0xf bound_ctrl:1
	v_cndmask_b32_e64 v26, v18, v27, s[0:1]
	v_cndmask_b32_e64 v18, v27, v18, s[0:1]
	s_nop 1
	v_add_f32_dpp v18, v18, v26 quad_perm:[1,0,3,2] row_mask:0xf bank_mask:0xf bound_ctrl:1
	v_cndmask_b32_e64 v26, v23, v19, s[2:3]
	v_cndmask_b32_e64 v19, v19, v23, s[2:3]
	v_cndmask_b32_e64 v23, v24, v20, s[2:3]
	v_cndmask_b32_e64 v20, v20, v24, s[2:3]
	v_add_f32_dpp v19, v19, v26 quad_perm:[2,3,0,1] row_mask:0xf bank_mask:0xf bound_ctrl:1
	s_nop 0
	v_add_f32_dpp v20, v20, v23 quad_perm:[2,3,0,1] row_mask:0xf bank_mask:0xf bound_ctrl:1
	v_cndmask_b32_e64 v23, v25, v21, s[2:3]
	v_cndmask_b32_e64 v21, v21, v25, s[2:3]
	s_nop 1
	v_add_f32_dpp v21, v21, v23 quad_perm:[2,3,0,1] row_mask:0xf bank_mask:0xf bound_ctrl:1
	v_cndmask_b32_e64 v23, v18, v22, s[2:3]
	v_cndmask_b32_e64 v18, v22, v18, s[2:3]
	v_cndmask_b32_e64 v22, v21, v19, s[4:5]
	v_cndmask_b32_e64 v19, v19, v21, s[4:5]
	v_add_f32_dpp v18, v18, v23 quad_perm:[2,3,0,1] row_mask:0xf bank_mask:0xf bound_ctrl:1
	v_cndmask_b32_e64 v21, v18, v20, s[4:5]
	v_cndmask_b32_e64 v18, v20, v18, s[4:5]
	v_mov_b32_dpp v19, v19 row_half_mirror row_mask:0xf bank_mask:0xf bound_ctrl:1
	s_nop 0
	v_mov_b32_dpp v18, v18 row_half_mirror row_mask:0xf bank_mask:0xf bound_ctrl:1
	v_add_f32_dpp v19, v19, v22 quad_perm:[3,2,1,0] row_mask:0xf bank_mask:0xf bound_ctrl:1
	s_nop 0
	v_add_f32_dpp v18, v18, v21 quad_perm:[3,2,1,0] row_mask:0xf bank_mask:0xf bound_ctrl:1
	v_cndmask_b32_e64 v20, v18, v19, s[6:7]
	v_cndmask_b32_e64 v18, v19, v18, s[6:7]
	s_nop 1
	v_mov_b32_dpp v18, v18 row_mirror row_mask:0xf bank_mask:0xf bound_ctrl:1
	s_nop 1
	v_add_f32_dpp v18, v18, v20 row_half_mirror row_mask:0xf bank_mask:0xf bound_ctrl:1
	ds_bpermute_b32 v19, v124, v18
	s_waitcnt lgkmcnt(0)
	v_add_f32_e32 v18, v18, v19
	ds_bpermute_b32 v19, v125, v18
	s_waitcnt lgkmcnt(0)
	v_add_f32_e32 v18, v18, v19
	v_or_b32_e32 v19, 1, v76
	v_cmp_eq_u32_e64 s[12:13], v107, v19
	v_cndmask_b32_e64 v19, v18, v77, s[10:11]
	s_and_b64 s[10:11], s[12:13], s[10:11]
	v_cndmask_b32_e64 v128, v78, v18, s[10:11]
	v_cmp_ge_u32_e64 s[10:11], v126, v51
	v_cndmask_b32_e64 v127, v77, v19, s[12:13]
	s_or_b64 s[26:27], s[10:11], s[26:27]
	s_andn2_b64 exec, exec, s[26:27]
	s_cbranch_execnz .LBB0_3301
	s_or_b64 exec, exec, s[26:27]

.LBB0_3313:
	v_cmp_gt_u32_e32 vcc, 64, v116
	s_nop 1
	v_cndmask_b32_e32 v102, v117, v53, vcc
	v_readfirstlane_b32 s92, v116
	s_nop 1
	s_and_b32 s92, s92, 32
	s_cbranch_scc1 .Lh3_v19_hi
	v_readlane_b32 s84, v102, 0
	v_readlane_b32 s86, v102, 1
	v_readlane_b32 s88, v102, 2
	v_readlane_b32 s90, v102, 3
	s_ashr_i32 s85, s84, 31
	s_ashr_i32 s87, s86, 31
	s_ashr_i32 s89, s88, 31
	s_ashr_i32 s91, s90, 31
	s_lshl_b64 s[84:85], s[84:85], 9
	s_lshl_b64 s[86:87], s[86:87], 9
	s_lshl_b64 s[88:89], s[88:89], 9
	s_lshl_b64 s[90:91], s[90:91], 9
	v_lshl_add_u64 v[18:19], v[38:39], 0, s[84:85]
	v_lshl_add_u64 v[20:21], v[38:39], 0, s[86:87]
	v_lshl_add_u64 v[22:23], v[38:39], 0, s[88:89]
	v_lshl_add_u64 v[24:25], v[38:39], 0, s[90:91]
	global_load_dwordx2 v[18:19], v[18:19], off
	global_load_dwordx2 v[20:21], v[20:21], off
	global_load_dwordx2 v[22:23], v[22:23], off
	global_load_dwordx2 v[24:25], v[24:25], off
	v_readlane_b32 s84, v102, 4
	v_readlane_b32 s86, v102, 5
	v_readlane_b32 s88, v102, 6
	v_readlane_b32 s90, v102, 7
	s_ashr_i32 s85, s84, 31
	s_ashr_i32 s87, s86, 31
	s_ashr_i32 s89, s88, 31
	s_ashr_i32 s91, s90, 31
	s_lshl_b64 s[84:85], s[84:85], 9
	s_lshl_b64 s[86:87], s[86:87], 9
	s_lshl_b64 s[88:89], s[88:89], 9
	s_lshl_b64 s[90:91], s[90:91], 9
	v_lshl_add_u64 v[26:27], v[38:39], 0, s[84:85]
	v_lshl_add_u64 v[28:29], v[38:39], 0, s[86:87]
	v_lshl_add_u64 v[30:31], v[38:39], 0, s[88:89]
	v_lshl_add_u64 v[32:33], v[38:39], 0, s[90:91]
	global_load_dwordx2 v[26:27], v[26:27], off
	global_load_dwordx2 v[28:29], v[28:29], off
	global_load_dwordx2 v[30:31], v[30:31], off
	global_load_dwordx2 v[32:33], v[32:33], off
	v_readlane_b32 s84, v102, 8
	v_readlane_b32 s86, v102, 9
	v_readlane_b32 s88, v102, 10
	v_readlane_b32 s90, v102, 11
	s_ashr_i32 s85, s84, 31
	s_ashr_i32 s87, s86, 31
	s_ashr_i32 s89, s88, 31
	s_ashr_i32 s91, s90, 31
	s_lshl_b64 s[84:85], s[84:85], 9
	s_lshl_b64 s[86:87], s[86:87], 9
	s_lshl_b64 s[88:89], s[88:89], 9
	s_lshl_b64 s[90:91], s[90:91], 9
	v_lshl_add_u64 v[56:57], v[38:39], 0, s[84:85]
	v_lshl_add_u64 v[58:59], v[38:39], 0, s[86:87]
	v_lshl_add_u64 v[60:61], v[38:39], 0, s[88:89]
	v_lshl_add_u64 v[62:63], v[38:39], 0, s[90:91]
	global_load_dwordx2 v[56:57], v[56:57], off
	global_load_dwordx2 v[58:59], v[58:59], off
	global_load_dwordx2 v[60:61], v[60:61], off
	global_load_dwordx2 v[62:63], v[62:63], off
	v_readlane_b32 s84, v102, 12
	v_readlane_b32 s86, v102, 13
	v_readlane_b32 s88, v102, 14
	v_readlane_b32 s90, v102, 15
	s_ashr_i32 s85, s84, 31
	s_ashr_i32 s87, s86, 31
	s_ashr_i32 s89, s88, 31
	s_ashr_i32 s91, s90, 31
	s_lshl_b64 s[84:85], s[84:85], 9
	s_lshl_b64 s[86:87], s[86:87], 9
	s_lshl_b64 s[88:89], s[88:89], 9
	s_lshl_b64 s[90:91], s[90:91], 9
	v_lshl_add_u64 v[64:65], v[38:39], 0, s[84:85]
	v_lshl_add_u64 v[66:67], v[38:39], 0, s[86:87]
	v_lshl_add_u64 v[68:69], v[38:39], 0, s[88:89]
	v_lshl_add_u64 v[70:71], v[38:39], 0, s[90:91]
	global_load_dwordx2 v[64:65], v[64:65], off
	global_load_dwordx2 v[66:67], v[66:67], off
	global_load_dwordx2 v[68:69], v[68:69], off
	global_load_dwordx2 v[70:71], v[70:71], off
	v_readlane_b32 s84, v102, 16
	v_readlane_b32 s86, v102, 17
	v_readlane_b32 s88, v102, 18
	v_readlane_b32 s90, v102, 19
	s_ashr_i32 s85, s84, 31
	s_ashr_i32 s87, s86, 31
	s_ashr_i32 s89, s88, 31
	s_ashr_i32 s91, s90, 31
	s_lshl_b64 s[84:85], s[84:85], 9
	s_lshl_b64 s[86:87], s[86:87], 9
	s_lshl_b64 s[88:89], s[88:89], 9
	s_lshl_b64 s[90:91], s[90:91], 9
	v_lshl_add_u64 v[72:73], v[38:39], 0, s[84:85]
	v_lshl_add_u64 v[74:75], v[38:39], 0, s[86:87]
	v_lshl_add_u64 v[76:77], v[38:39], 0, s[88:89]
	v_lshl_add_u64 v[78:79], v[38:39], 0, s[90:91]
	global_load_dwordx2 v[72:73], v[72:73], off
	global_load_dwordx2 v[74:75], v[74:75], off
	global_load_dwordx2 v[76:77], v[76:77], off
	global_load_dwordx2 v[78:79], v[78:79], off
	v_readlane_b32 s84, v102, 20
	v_readlane_b32 s86, v102, 21
	v_readlane_b32 s88, v102, 22
	v_readlane_b32 s90, v102, 23
	s_ashr_i32 s85, s84, 31
	s_ashr_i32 s87, s86, 31
	s_ashr_i32 s89, s88, 31
	s_ashr_i32 s91, s90, 31
	s_lshl_b64 s[84:85], s[84:85], 9
	s_lshl_b64 s[86:87], s[86:87], 9
	s_lshl_b64 s[88:89], s[88:89], 9
	s_lshl_b64 s[90:91], s[90:91], 9
	v_lshl_add_u64 v[80:81], v[38:39], 0, s[84:85]
	v_lshl_add_u64 v[82:83], v[38:39], 0, s[86:87]
	v_lshl_add_u64 v[84:85], v[38:39], 0, s[88:89]
	v_lshl_add_u64 v[86:87], v[38:39], 0, s[90:91]
	global_load_dwordx2 v[80:81], v[80:81], off
	global_load_dwordx2 v[82:83], v[82:83], off
	global_load_dwordx2 v[84:85], v[84:85], off
	global_load_dwordx2 v[86:87], v[86:87], off
	v_readlane_b32 s84, v102, 24
	v_readlane_b32 s86, v102, 25
	v_readlane_b32 s88, v102, 26
	v_readlane_b32 s90, v102, 27
	s_ashr_i32 s85, s84, 31
	s_ashr_i32 s87, s86, 31
	s_ashr_i32 s89, s88, 31
	s_ashr_i32 s91, s90, 31
	s_lshl_b64 s[84:85], s[84:85], 9
	s_lshl_b64 s[86:87], s[86:87], 9
	s_lshl_b64 s[88:89], s[88:89], 9
	s_lshl_b64 s[90:91], s[90:91], 9
	v_lshl_add_u64 v[88:89], v[38:39], 0, s[84:85]
	v_lshl_add_u64 v[90:91], v[38:39], 0, s[86:87]
	v_lshl_add_u64 v[92:93], v[38:39], 0, s[88:89]
	v_lshl_add_u64 v[94:95], v[38:39], 0, s[90:91]
	global_load_dwordx2 v[88:89], v[88:89], off
	global_load_dwordx2 v[90:91], v[90:91], off
	global_load_dwordx2 v[92:93], v[92:93], off
	global_load_dwordx2 v[94:95], v[94:95], off
	v_readlane_b32 s84, v102, 28
	v_readlane_b32 s86, v102, 29
	v_readlane_b32 s88, v102, 30
	v_readlane_b32 s90, v102, 31
	s_ashr_i32 s85, s84, 31
	s_ashr_i32 s87, s86, 31
	s_ashr_i32 s89, s88, 31
	s_ashr_i32 s91, s90, 31
	s_lshl_b64 s[84:85], s[84:85], 9
	s_lshl_b64 s[86:87], s[86:87], 9
	s_lshl_b64 s[88:89], s[88:89], 9
	s_lshl_b64 s[90:91], s[90:91], 9
	v_lshl_add_u64 v[96:97], v[38:39], 0, s[84:85]
	v_lshl_add_u64 v[98:99], v[38:39], 0, s[86:87]
	v_lshl_add_u64 v[100:101], v[38:39], 0, s[88:89]
	v_lshl_add_u64 v[102:103], v[38:39], 0, s[90:91]
	global_load_dwordx2 v[96:97], v[96:97], off
	global_load_dwordx2 v[98:99], v[98:99], off
	global_load_dwordx2 v[100:101], v[100:101], off
	global_load_dwordx2 v[102:103], v[102:103], off
	v_cndmask_b32_e32 v126, v1, v118, vcc
	s_nop 0
	v_readlane_b32 s48, v126, 0
	s_waitcnt vmcnt(31)
	v_cvt_scalef32_pk_f32_fp4 v[128:129], v18, 1.0
	v_pk_fma_f32 v[2:3], v[128:129], s[48:49], v[2:3] op_sel_hi:[1,0,1]
	v_cvt_scalef32_pk_f32_fp4 v[128:129], v18, 1.0 op_sel:[1,0,0]
	v_pk_fma_f32 v[4:5], s[48:49], v[128:129], v[4:5] op_sel_hi:[0,1,1]
	v_cvt_scalef32_pk_f32_fp4 v[128:129], v18, 1.0 op_sel:[0,1,0]
	v_pk_fma_f32 v[6:7], s[48:49], v[128:129], v[6:7] op_sel_hi:[0,1,1]
	v_cvt_scalef32_pk_f32_fp4 v[128:129], v18, 1.0 op_sel:[1,1,0]
	v_pk_fma_f32 v[8:9], s[48:49], v[128:129], v[8:9] op_sel_hi:[0,1,1]
	v_cvt_scalef32_pk_f32_fp4 v[128:129], v19, 1.0
	v_pk_fma_f32 v[10:11], s[48:49], v[128:129], v[10:11] op_sel_hi:[0,1,1]
	v_cvt_scalef32_pk_f32_fp4 v[128:129], v19, 1.0 op_sel:[1,0,0]
	v_pk_fma_f32 v[12:13], s[48:49], v[128:129], v[12:13] op_sel_hi:[0,1,1]
	v_cvt_scalef32_pk_f32_fp4 v[128:129], v19, 1.0 op_sel:[0,1,0]
	v_cvt_scalef32_pk_f32_fp4 v[18:19], v19, 1.0 op_sel:[1,1,0]
	v_pk_fma_f32 v[14:15], s[48:49], v[128:129], v[14:15] op_sel_hi:[0,1,1]
	v_pk_fma_f32 v[16:17], s[48:49], v[18:19], v[16:17] op_sel_hi:[0,1,1]
	v_readlane_b32 s48, v126, 8
	s_waitcnt vmcnt(30)
	v_cvt_scalef32_pk_f32_fp4 v[18:19], v20, 1.0
	v_pk_fma_f32 v[2:3], v[18:19], s[48:49], v[2:3] op_sel_hi:[1,0,1]
	v_cvt_scalef32_pk_f32_fp4 v[18:19], v20, 1.0 op_sel:[1,0,0]
	v_pk_fma_f32 v[4:5], s[48:49], v[18:19], v[4:5] op_sel_hi:[0,1,1]
	v_cvt_scalef32_pk_f32_fp4 v[18:19], v20, 1.0 op_sel:[0,1,0]
	v_pk_fma_f32 v[6:7], s[48:49], v[18:19], v[6:7] op_sel_hi:[0,1,1]
	v_cvt_scalef32_pk_f32_fp4 v[18:19], v20, 1.0 op_sel:[1,1,0]
	v_pk_fma_f32 v[8:9], s[48:49], v[18:19], v[8:9] op_sel_hi:[0,1,1]
	v_cvt_scalef32_pk_f32_fp4 v[18:19], v21, 1.0
	v_pk_fma_f32 v[10:11], s[48:49], v[18:19], v[10:11] op_sel_hi:[0,1,1]
	v_cvt_scalef32_pk_f32_fp4 v[18:19], v21, 1.0 op_sel:[1,0,0]
	v_pk_fma_f32 v[12:13], s[48:49], v[18:19], v[12:13] op_sel_hi:[0,1,1]
	v_cvt_scalef32_pk_f32_fp4 v[18:19], v21, 1.0 op_sel:[0,1,0]
	v_pk_fma_f32 v[14:15], s[48:49], v[18:19], v[14:15] op_sel_hi:[0,1,1]
	v_cvt_scalef32_pk_f32_fp4 v[18:19], v21, 1.0 op_sel:[1,1,0]
	v_pk_fma_f32 v[16:17], s[48:49], v[18:19], v[16:17] op_sel_hi:[0,1,1]
	v_readlane_b32 s48, v126, 4
	s_waitcnt vmcnt(29)
	v_cvt_scalef32_pk_f32_fp4 v[18:19], v22, 1.0
	v_pk_fma_f32 v[2:3], v[18:19], s[48:49], v[2:3] op_sel_hi:[1,0,1]
	v_cvt_scalef32_pk_f32_fp4 v[18:19], v22, 1.0 op_sel:[1,0,0]
	v_pk_fma_f32 v[4:5], s[48:49], v[18:19], v[4:5] op_sel_hi:[0,1,1]
	v_cvt_scalef32_pk_f32_fp4 v[18:19], v22, 1.0 op_sel:[0,1,0]
	v_pk_fma_f32 v[6:7], s[48:49], v[18:19], v[6:7] op_sel_hi:[0,1,1]
	v_cvt_scalef32_pk_f32_fp4 v[18:19], v22, 1.0 op_sel:[1,1,0]
	v_pk_fma_f32 v[8:9], s[48:49], v[18:19], v[8:9] op_sel_hi:[0,1,1]
	v_cvt_scalef32_pk_f32_fp4 v[18:19], v23, 1.0
	v_pk_fma_f32 v[10:11], s[48:49], v[18:19], v[10:11] op_sel_hi:[0,1,1]
	v_cvt_scalef32_pk_f32_fp4 v[18:19], v23, 1.0 op_sel:[1,0,0]
	v_pk_fma_f32 v[12:13], s[48:49], v[18:19], v[12:13] op_sel_hi:[0,1,1]
	v_cvt_scalef32_pk_f32_fp4 v[18:19], v23, 1.0 op_sel:[0,1,0]
	v_pk_fma_f32 v[14:15], s[48:49], v[18:19], v[14:15] op_sel_hi:[0,1,1]
	v_cvt_scalef32_pk_f32_fp4 v[18:19], v23, 1.0 op_sel:[1,1,0]
	v_pk_fma_f32 v[16:17], s[48:49], v[18:19], v[16:17] op_sel_hi:[0,1,1]
	v_readlane_b32 s48, v126, 12
	s_waitcnt vmcnt(28)
	v_cvt_scalef32_pk_f32_fp4 v[18:19], v24, 1.0
	v_pk_fma_f32 v[2:3], v[18:19], s[48:49], v[2:3] op_sel_hi:[1,0,1]
	v_cvt_scalef32_pk_f32_fp4 v[18:19], v24, 1.0 op_sel:[1,0,0]
	v_pk_fma_f32 v[4:5], s[48:49], v[18:19], v[4:5] op_sel_hi:[0,1,1]
	v_cvt_scalef32_pk_f32_fp4 v[18:19], v24, 1.0 op_sel:[0,1,0]
	v_pk_fma_f32 v[6:7], s[48:49], v[18:19], v[6:7] op_sel_hi:[0,1,1]
	v_cvt_scalef32_pk_f32_fp4 v[18:19], v24, 1.0 op_sel:[1,1,0]
	v_pk_fma_f32 v[8:9], s[48:49], v[18:19], v[8:9] op_sel_hi:[0,1,1]
	v_cvt_scalef32_pk_f32_fp4 v[18:19], v25, 1.0
	v_pk_fma_f32 v[10:11], s[48:49], v[18:19], v[10:11] op_sel_hi:[0,1,1]
	v_cvt_scalef32_pk_f32_fp4 v[18:19], v25, 1.0 op_sel:[1,0,0]
	v_pk_fma_f32 v[12:13], s[48:49], v[18:19], v[12:13] op_sel_hi:[0,1,1]
	v_cvt_scalef32_pk_f32_fp4 v[18:19], v25, 1.0 op_sel:[0,1,0]
	v_pk_fma_f32 v[14:15], s[48:49], v[18:19], v[14:15] op_sel_hi:[0,1,1]
	v_cvt_scalef32_pk_f32_fp4 v[18:19], v25, 1.0 op_sel:[1,1,0]
	v_pk_fma_f32 v[16:17], s[48:49], v[18:19], v[16:17] op_sel_hi:[0,1,1]
	v_readlane_b32 s48, v126, 2
	s_waitcnt vmcnt(27)
	v_cvt_scalef32_pk_f32_fp4 v[18:19], v26, 1.0
	v_pk_fma_f32 v[2:3], v[18:19], s[48:49], v[2:3] op_sel_hi:[1,0,1]
	v_cvt_scalef32_pk_f32_fp4 v[18:19], v26, 1.0 op_sel:[1,0,0]
	v_pk_fma_f32 v[4:5], s[48:49], v[18:19], v[4:5] op_sel_hi:[0,1,1]
	v_cvt_scalef32_pk_f32_fp4 v[18:19], v26, 1.0 op_sel:[0,1,0]
	v_pk_fma_f32 v[6:7], s[48:49], v[18:19], v[6:7] op_sel_hi:[0,1,1]
	v_cvt_scalef32_pk_f32_fp4 v[18:19], v26, 1.0 op_sel:[1,1,0]
	v_pk_fma_f32 v[8:9], s[48:49], v[18:19], v[8:9] op_sel_hi:[0,1,1]
	v_cvt_scalef32_pk_f32_fp4 v[18:19], v27, 1.0
	v_pk_fma_f32 v[10:11], s[48:49], v[18:19], v[10:11] op_sel_hi:[0,1,1]
	v_cvt_scalef32_pk_f32_fp4 v[18:19], v27, 1.0 op_sel:[1,0,0]
	v_pk_fma_f32 v[12:13], s[48:49], v[18:19], v[12:13] op_sel_hi:[0,1,1]
	v_cvt_scalef32_pk_f32_fp4 v[18:19], v27, 1.0 op_sel:[0,1,0]
	v_pk_fma_f32 v[14:15], s[48:49], v[18:19], v[14:15] op_sel_hi:[0,1,1]
	v_cvt_scalef32_pk_f32_fp4 v[18:19], v27, 1.0 op_sel:[1,1,0]
	v_pk_fma_f32 v[16:17], s[48:49], v[18:19], v[16:17] op_sel_hi:[0,1,1]
	v_readlane_b32 s48, v126, 10
	s_waitcnt vmcnt(26)
	v_cvt_scalef32_pk_f32_fp4 v[18:19], v28, 1.0
	v_pk_fma_f32 v[2:3], v[18:19], s[48:49], v[2:3] op_sel_hi:[1,0,1]
	v_cvt_scalef32_pk_f32_fp4 v[18:19], v28, 1.0 op_sel:[1,0,0]
	v_pk_fma_f32 v[4:5], s[48:49], v[18:19], v[4:5] op_sel_hi:[0,1,1]
	v_cvt_scalef32_pk_f32_fp4 v[18:19], v28, 1.0 op_sel:[0,1,0]
	v_pk_fma_f32 v[6:7], s[48:49], v[18:19], v[6:7] op_sel_hi:[0,1,1]
	v_cvt_scalef32_pk_f32_fp4 v[18:19], v28, 1.0 op_sel:[1,1,0]
	v_pk_fma_f32 v[8:9], s[48:49], v[18:19], v[8:9] op_sel_hi:[0,1,1]
	v_cvt_scalef32_pk_f32_fp4 v[18:19], v29, 1.0
	v_pk_fma_f32 v[10:11], s[48:49], v[18:19], v[10:11] op_sel_hi:[0,1,1]
	v_cvt_scalef32_pk_f32_fp4 v[18:19], v29, 1.0 op_sel:[1,0,0]
	v_pk_fma_f32 v[12:13], s[48:49], v[18:19], v[12:13] op_sel_hi:[0,1,1]
	v_cvt_scalef32_pk_f32_fp4 v[18:19], v29, 1.0 op_sel:[0,1,0]
	v_pk_fma_f32 v[14:15], s[48:49], v[18:19], v[14:15] op_sel_hi:[0,1,1]
	v_cvt_scalef32_pk_f32_fp4 v[18:19], v29, 1.0 op_sel:[1,1,0]
	v_pk_fma_f32 v[16:17], s[48:49], v[18:19], v[16:17] op_sel_hi:[0,1,1]
	v_readlane_b32 s48, v126, 6
	s_waitcnt vmcnt(25)
	v_cvt_scalef32_pk_f32_fp4 v[18:19], v30, 1.0
	v_pk_fma_f32 v[2:3], v[18:19], s[48:49], v[2:3] op_sel_hi:[1,0,1]
	v_cvt_scalef32_pk_f32_fp4 v[18:19], v30, 1.0 op_sel:[1,0,0]
	v_pk_fma_f32 v[4:5], s[48:49], v[18:19], v[4:5] op_sel_hi:[0,1,1]
	v_cvt_scalef32_pk_f32_fp4 v[18:19], v30, 1.0 op_sel:[0,1,0]
	v_pk_fma_f32 v[6:7], s[48:49], v[18:19], v[6:7] op_sel_hi:[0,1,1]
	v_cvt_scalef32_pk_f32_fp4 v[18:19], v30, 1.0 op_sel:[1,1,0]
	v_pk_fma_f32 v[8:9], s[48:49], v[18:19], v[8:9] op_sel_hi:[0,1,1]
	v_cvt_scalef32_pk_f32_fp4 v[18:19], v31, 1.0
	v_pk_fma_f32 v[10:11], s[48:49], v[18:19], v[10:11] op_sel_hi:[0,1,1]
	v_cvt_scalef32_pk_f32_fp4 v[18:19], v31, 1.0 op_sel:[1,0,0]
	v_pk_fma_f32 v[12:13], s[48:49], v[18:19], v[12:13] op_sel_hi:[0,1,1]
	v_cvt_scalef32_pk_f32_fp4 v[18:19], v31, 1.0 op_sel:[0,1,0]
	v_pk_fma_f32 v[14:15], s[48:49], v[18:19], v[14:15] op_sel_hi:[0,1,1]
	v_cvt_scalef32_pk_f32_fp4 v[18:19], v31, 1.0 op_sel:[1,1,0]
	v_pk_fma_f32 v[16:17], s[48:49], v[18:19], v[16:17] op_sel_hi:[0,1,1]
	v_readlane_b32 s48, v126, 14
	s_waitcnt vmcnt(24)
	v_cvt_scalef32_pk_f32_fp4 v[18:19], v32, 1.0
	v_pk_fma_f32 v[2:3], v[18:19], s[48:49], v[2:3] op_sel_hi:[1,0,1]
	v_cvt_scalef32_pk_f32_fp4 v[18:19], v32, 1.0 op_sel:[1,0,0]
	v_pk_fma_f32 v[4:5], s[48:49], v[18:19], v[4:5] op_sel_hi:[0,1,1]
	v_cvt_scalef32_pk_f32_fp4 v[18:19], v32, 1.0 op_sel:[0,1,0]
	v_pk_fma_f32 v[6:7], s[48:49], v[18:19], v[6:7] op_sel_hi:[0,1,1]
	v_cvt_scalef32_pk_f32_fp4 v[18:19], v32, 1.0 op_sel:[1,1,0]
	v_pk_fma_f32 v[8:9], s[48:49], v[18:19], v[8:9] op_sel_hi:[0,1,1]
	v_cvt_scalef32_pk_f32_fp4 v[18:19], v33, 1.0
	v_pk_fma_f32 v[10:11], s[48:49], v[18:19], v[10:11] op_sel_hi:[0,1,1]
	v_cvt_scalef32_pk_f32_fp4 v[18:19], v33, 1.0 op_sel:[1,0,0]
	v_pk_fma_f32 v[12:13], s[48:49], v[18:19], v[12:13] op_sel_hi:[0,1,1]
	v_cvt_scalef32_pk_f32_fp4 v[18:19], v33, 1.0 op_sel:[0,1,0]
	v_pk_fma_f32 v[14:15], s[48:49], v[18:19], v[14:15] op_sel_hi:[0,1,1]
	v_cvt_scalef32_pk_f32_fp4 v[18:19], v33, 1.0 op_sel:[1,1,0]
	v_pk_fma_f32 v[16:17], s[48:49], v[18:19], v[16:17] op_sel_hi:[0,1,1]
	v_readlane_b32 s48, v126, 1
	s_waitcnt vmcnt(23)
	v_cvt_scalef32_pk_f32_fp4 v[18:19], v56, 1.0
	v_pk_fma_f32 v[2:3], v[18:19], s[48:49], v[2:3] op_sel_hi:[1,0,1]
	v_cvt_scalef32_pk_f32_fp4 v[18:19], v56, 1.0 op_sel:[1,0,0]
	v_pk_fma_f32 v[4:5], s[48:49], v[18:19], v[4:5] op_sel_hi:[0,1,1]
	v_cvt_scalef32_pk_f32_fp4 v[18:19], v56, 1.0 op_sel:[0,1,0]
	v_pk_fma_f32 v[6:7], s[48:49], v[18:19], v[6:7] op_sel_hi:[0,1,1]
	v_cvt_scalef32_pk_f32_fp4 v[18:19], v56, 1.0 op_sel:[1,1,0]
	v_pk_fma_f32 v[8:9], s[48:49], v[18:19], v[8:9] op_sel_hi:[0,1,1]
	v_cvt_scalef32_pk_f32_fp4 v[18:19], v57, 1.0
	v_pk_fma_f32 v[10:11], s[48:49], v[18:19], v[10:11] op_sel_hi:[0,1,1]
	v_cvt_scalef32_pk_f32_fp4 v[18:19], v57, 1.0 op_sel:[1,0,0]
	v_pk_fma_f32 v[12:13], s[48:49], v[18:19], v[12:13] op_sel_hi:[0,1,1]
	v_cvt_scalef32_pk_f32_fp4 v[18:19], v57, 1.0 op_sel:[0,1,0]
	v_pk_fma_f32 v[14:15], s[48:49], v[18:19], v[14:15] op_sel_hi:[0,1,1]
	v_cvt_scalef32_pk_f32_fp4 v[18:19], v57, 1.0 op_sel:[1,1,0]
	v_pk_fma_f32 v[16:17], s[48:49], v[18:19], v[16:17] op_sel_hi:[0,1,1]
	v_readlane_b32 s48, v126, 9
	s_waitcnt vmcnt(22)
	v_cvt_scalef32_pk_f32_fp4 v[18:19], v58, 1.0
	v_pk_fma_f32 v[2:3], v[18:19], s[48:49], v[2:3] op_sel_hi:[1,0,1]
	v_cvt_scalef32_pk_f32_fp4 v[18:19], v58, 1.0 op_sel:[1,0,0]
	v_pk_fma_f32 v[4:5], s[48:49], v[18:19], v[4:5] op_sel_hi:[0,1,1]
	v_cvt_scalef32_pk_f32_fp4 v[18:19], v58, 1.0 op_sel:[0,1,0]
	v_pk_fma_f32 v[6:7], s[48:49], v[18:19], v[6:7] op_sel_hi:[0,1,1]
	v_cvt_scalef32_pk_f32_fp4 v[18:19], v58, 1.0 op_sel:[1,1,0]
	v_pk_fma_f32 v[8:9], s[48:49], v[18:19], v[8:9] op_sel_hi:[0,1,1]
	v_cvt_scalef32_pk_f32_fp4 v[18:19], v59, 1.0
	v_pk_fma_f32 v[10:11], s[48:49], v[18:19], v[10:11] op_sel_hi:[0,1,1]
	v_cvt_scalef32_pk_f32_fp4 v[18:19], v59, 1.0 op_sel:[1,0,0]
	v_pk_fma_f32 v[12:13], s[48:49], v[18:19], v[12:13] op_sel_hi:[0,1,1]
	v_cvt_scalef32_pk_f32_fp4 v[18:19], v59, 1.0 op_sel:[0,1,0]
	v_pk_fma_f32 v[14:15], s[48:49], v[18:19], v[14:15] op_sel_hi:[0,1,1]
	v_cvt_scalef32_pk_f32_fp4 v[18:19], v59, 1.0 op_sel:[1,1,0]
	v_pk_fma_f32 v[16:17], s[48:49], v[18:19], v[16:17] op_sel_hi:[0,1,1]
	v_readlane_b32 s48, v126, 5
	s_waitcnt vmcnt(21)
	v_cvt_scalef32_pk_f32_fp4 v[18:19], v60, 1.0
	v_pk_fma_f32 v[2:3], v[18:19], s[48:49], v[2:3] op_sel_hi:[1,0,1]
	v_cvt_scalef32_pk_f32_fp4 v[18:19], v60, 1.0 op_sel:[1,0,0]
	v_pk_fma_f32 v[4:5], s[48:49], v[18:19], v[4:5] op_sel_hi:[0,1,1]
	v_cvt_scalef32_pk_f32_fp4 v[18:19], v60, 1.0 op_sel:[0,1,0]
	v_pk_fma_f32 v[6:7], s[48:49], v[18:19], v[6:7] op_sel_hi:[0,1,1]
	v_cvt_scalef32_pk_f32_fp4 v[18:19], v60, 1.0 op_sel:[1,1,0]
	v_pk_fma_f32 v[8:9], s[48:49], v[18:19], v[8:9] op_sel_hi:[0,1,1]
	v_cvt_scalef32_pk_f32_fp4 v[18:19], v61, 1.0
	v_pk_fma_f32 v[10:11], s[48:49], v[18:19], v[10:11] op_sel_hi:[0,1,1]
	v_cvt_scalef32_pk_f32_fp4 v[18:19], v61, 1.0 op_sel:[1,0,0]
	v_pk_fma_f32 v[12:13], s[48:49], v[18:19], v[12:13] op_sel_hi:[0,1,1]
	v_cvt_scalef32_pk_f32_fp4 v[18:19], v61, 1.0 op_sel:[0,1,0]
	v_pk_fma_f32 v[14:15], s[48:49], v[18:19], v[14:15] op_sel_hi:[0,1,1]
	v_cvt_scalef32_pk_f32_fp4 v[18:19], v61, 1.0 op_sel:[1,1,0]
	v_pk_fma_f32 v[16:17], s[48:49], v[18:19], v[16:17] op_sel_hi:[0,1,1]
	v_readlane_b32 s48, v126, 13
	s_waitcnt vmcnt(20)
	v_cvt_scalef32_pk_f32_fp4 v[18:19], v62, 1.0
	v_pk_fma_f32 v[2:3], v[18:19], s[48:49], v[2:3] op_sel_hi:[1,0,1]
	v_cvt_scalef32_pk_f32_fp4 v[18:19], v62, 1.0 op_sel:[1,0,0]
	v_pk_fma_f32 v[4:5], s[48:49], v[18:19], v[4:5] op_sel_hi:[0,1,1]
	v_cvt_scalef32_pk_f32_fp4 v[18:19], v62, 1.0 op_sel:[0,1,0]
	v_pk_fma_f32 v[6:7], s[48:49], v[18:19], v[6:7] op_sel_hi:[0,1,1]
	v_cvt_scalef32_pk_f32_fp4 v[18:19], v62, 1.0 op_sel:[1,1,0]
	v_pk_fma_f32 v[8:9], s[48:49], v[18:19], v[8:9] op_sel_hi:[0,1,1]
	v_cvt_scalef32_pk_f32_fp4 v[18:19], v63, 1.0
	v_pk_fma_f32 v[10:11], s[48:49], v[18:19], v[10:11] op_sel_hi:[0,1,1]
	v_cvt_scalef32_pk_f32_fp4 v[18:19], v63, 1.0 op_sel:[1,0,0]
	v_pk_fma_f32 v[12:13], s[48:49], v[18:19], v[12:13] op_sel_hi:[0,1,1]
	v_cvt_scalef32_pk_f32_fp4 v[18:19], v63, 1.0 op_sel:[0,1,0]
	v_pk_fma_f32 v[14:15], s[48:49], v[18:19], v[14:15] op_sel_hi:[0,1,1]
	v_cvt_scalef32_pk_f32_fp4 v[18:19], v63, 1.0 op_sel:[1,1,0]
	v_pk_fma_f32 v[16:17], s[48:49], v[18:19], v[16:17] op_sel_hi:[0,1,1]
	v_readlane_b32 s24, v126, 3
	s_waitcnt vmcnt(19)
	v_cvt_scalef32_pk_f32_fp4 v[18:19], v64, 1.0
	v_pk_fma_f32 v[2:3], v[18:19], s[24:25], v[2:3] op_sel_hi:[1,0,1]
	v_cvt_scalef32_pk_f32_fp4 v[18:19], v64, 1.0 op_sel:[1,0,0]
	v_pk_fma_f32 v[4:5], s[24:25], v[18:19], v[4:5] op_sel_hi:[0,1,1]
	v_cvt_scalef32_pk_f32_fp4 v[18:19], v64, 1.0 op_sel:[0,1,0]
	v_pk_fma_f32 v[6:7], s[24:25], v[18:19], v[6:7] op_sel_hi:[0,1,1]
	v_cvt_scalef32_pk_f32_fp4 v[18:19], v64, 1.0 op_sel:[1,1,0]
	v_pk_fma_f32 v[8:9], s[24:25], v[18:19], v[8:9] op_sel_hi:[0,1,1]
	v_cvt_scalef32_pk_f32_fp4 v[18:19], v65, 1.0
	v_pk_fma_f32 v[10:11], s[24:25], v[18:19], v[10:11] op_sel_hi:[0,1,1]
	v_cvt_scalef32_pk_f32_fp4 v[18:19], v65, 1.0 op_sel:[1,0,0]
	v_pk_fma_f32 v[12:13], s[24:25], v[18:19], v[12:13] op_sel_hi:[0,1,1]
	v_cvt_scalef32_pk_f32_fp4 v[18:19], v65, 1.0 op_sel:[0,1,0]
	v_pk_fma_f32 v[14:15], s[24:25], v[18:19], v[14:15] op_sel_hi:[0,1,1]
	v_cvt_scalef32_pk_f32_fp4 v[18:19], v65, 1.0 op_sel:[1,1,0]
	v_pk_fma_f32 v[16:17], s[24:25], v[18:19], v[16:17] op_sel_hi:[0,1,1]
	v_readlane_b32 s24, v126, 11
	s_waitcnt vmcnt(18)
	v_cvt_scalef32_pk_f32_fp4 v[18:19], v66, 1.0
	v_pk_fma_f32 v[2:3], v[18:19], s[24:25], v[2:3] op_sel_hi:[1,0,1]
	v_cvt_scalef32_pk_f32_fp4 v[18:19], v66, 1.0 op_sel:[1,0,0]
	v_pk_fma_f32 v[4:5], s[24:25], v[18:19], v[4:5] op_sel_hi:[0,1,1]
	v_cvt_scalef32_pk_f32_fp4 v[18:19], v66, 1.0 op_sel:[0,1,0]
	v_pk_fma_f32 v[6:7], s[24:25], v[18:19], v[6:7] op_sel_hi:[0,1,1]
	v_cvt_scalef32_pk_f32_fp4 v[18:19], v66, 1.0 op_sel:[1,1,0]
	v_pk_fma_f32 v[8:9], s[24:25], v[18:19], v[8:9] op_sel_hi:[0,1,1]
	v_cvt_scalef32_pk_f32_fp4 v[18:19], v67, 1.0
	v_pk_fma_f32 v[10:11], s[24:25], v[18:19], v[10:11] op_sel_hi:[0,1,1]
	v_cvt_scalef32_pk_f32_fp4 v[18:19], v67, 1.0 op_sel:[1,0,0]
	v_pk_fma_f32 v[12:13], s[24:25], v[18:19], v[12:13] op_sel_hi:[0,1,1]
	v_cvt_scalef32_pk_f32_fp4 v[18:19], v67, 1.0 op_sel:[0,1,0]
	v_pk_fma_f32 v[14:15], s[24:25], v[18:19], v[14:15] op_sel_hi:[0,1,1]
	v_cvt_scalef32_pk_f32_fp4 v[18:19], v67, 1.0 op_sel:[1,1,0]
	v_pk_fma_f32 v[16:17], s[24:25], v[18:19], v[16:17] op_sel_hi:[0,1,1]
	v_readlane_b32 s24, v126, 7
	s_waitcnt vmcnt(17)
	v_cvt_scalef32_pk_f32_fp4 v[18:19], v68, 1.0
	v_pk_fma_f32 v[2:3], v[18:19], s[24:25], v[2:3] op_sel_hi:[1,0,1]
	v_cvt_scalef32_pk_f32_fp4 v[18:19], v68, 1.0 op_sel:[1,0,0]
	v_pk_fma_f32 v[4:5], s[24:25], v[18:19], v[4:5] op_sel_hi:[0,1,1]
	v_cvt_scalef32_pk_f32_fp4 v[18:19], v68, 1.0 op_sel:[0,1,0]
	v_pk_fma_f32 v[6:7], s[24:25], v[18:19], v[6:7] op_sel_hi:[0,1,1]
	v_cvt_scalef32_pk_f32_fp4 v[18:19], v68, 1.0 op_sel:[1,1,0]
	v_pk_fma_f32 v[8:9], s[24:25], v[18:19], v[8:9] op_sel_hi:[0,1,1]
	v_cvt_scalef32_pk_f32_fp4 v[18:19], v69, 1.0
	v_pk_fma_f32 v[10:11], s[24:25], v[18:19], v[10:11] op_sel_hi:[0,1,1]
	v_cvt_scalef32_pk_f32_fp4 v[18:19], v69, 1.0 op_sel:[1,0,0]
	v_pk_fma_f32 v[12:13], s[24:25], v[18:19], v[12:13] op_sel_hi:[0,1,1]
	v_cvt_scalef32_pk_f32_fp4 v[18:19], v69, 1.0 op_sel:[0,1,0]
	v_pk_fma_f32 v[14:15], s[24:25], v[18:19], v[14:15] op_sel_hi:[0,1,1]
	v_cvt_scalef32_pk_f32_fp4 v[18:19], v69, 1.0 op_sel:[1,1,0]
	v_pk_fma_f32 v[16:17], s[24:25], v[18:19], v[16:17] op_sel_hi:[0,1,1]
	v_readlane_b32 s24, v126, 15
	s_waitcnt vmcnt(16)
	v_cvt_scalef32_pk_f32_fp4 v[18:19], v70, 1.0
	v_pk_fma_f32 v[2:3], v[18:19], s[24:25], v[2:3] op_sel_hi:[1,0,1]
	v_cvt_scalef32_pk_f32_fp4 v[18:19], v70, 1.0 op_sel:[1,0,0]
	v_pk_fma_f32 v[4:5], s[24:25], v[18:19], v[4:5] op_sel_hi:[0,1,1]
	v_cvt_scalef32_pk_f32_fp4 v[18:19], v70, 1.0 op_sel:[0,1,0]
	v_pk_fma_f32 v[6:7], s[24:25], v[18:19], v[6:7] op_sel_hi:[0,1,1]
	v_cvt_scalef32_pk_f32_fp4 v[18:19], v70, 1.0 op_sel:[1,1,0]
	v_pk_fma_f32 v[8:9], s[24:25], v[18:19], v[8:9] op_sel_hi:[0,1,1]
	v_cvt_scalef32_pk_f32_fp4 v[18:19], v71, 1.0
	v_pk_fma_f32 v[10:11], s[24:25], v[18:19], v[10:11] op_sel_hi:[0,1,1]
	v_cvt_scalef32_pk_f32_fp4 v[18:19], v71, 1.0 op_sel:[1,0,0]
	v_pk_fma_f32 v[12:13], s[24:25], v[18:19], v[12:13] op_sel_hi:[0,1,1]
	v_cvt_scalef32_pk_f32_fp4 v[18:19], v71, 1.0 op_sel:[0,1,0]
	v_pk_fma_f32 v[14:15], s[24:25], v[18:19], v[14:15] op_sel_hi:[0,1,1]
	v_cvt_scalef32_pk_f32_fp4 v[18:19], v71, 1.0 op_sel:[1,1,0]
	v_pk_fma_f32 v[16:17], s[24:25], v[18:19], v[16:17] op_sel_hi:[0,1,1]
	v_readlane_b32 s24, v126, 16
	s_waitcnt vmcnt(15)
	v_cvt_scalef32_pk_f32_fp4 v[18:19], v72, 1.0
	v_pk_fma_f32 v[2:3], v[18:19], s[24:25], v[2:3] op_sel_hi:[1,0,1]
	v_cvt_scalef32_pk_f32_fp4 v[18:19], v72, 1.0 op_sel:[1,0,0]
	v_pk_fma_f32 v[4:5], s[24:25], v[18:19], v[4:5] op_sel_hi:[0,1,1]
	v_cvt_scalef32_pk_f32_fp4 v[18:19], v72, 1.0 op_sel:[0,1,0]
	v_pk_fma_f32 v[6:7], s[24:25], v[18:19], v[6:7] op_sel_hi:[0,1,1]
	v_cvt_scalef32_pk_f32_fp4 v[18:19], v72, 1.0 op_sel:[1,1,0]
	v_pk_fma_f32 v[8:9], s[24:25], v[18:19], v[8:9] op_sel_hi:[0,1,1]
	v_cvt_scalef32_pk_f32_fp4 v[18:19], v73, 1.0
	v_pk_fma_f32 v[10:11], s[24:25], v[18:19], v[10:11] op_sel_hi:[0,1,1]
	v_cvt_scalef32_pk_f32_fp4 v[18:19], v73, 1.0 op_sel:[1,0,0]
	v_pk_fma_f32 v[12:13], s[24:25], v[18:19], v[12:13] op_sel_hi:[0,1,1]
	v_cvt_scalef32_pk_f32_fp4 v[18:19], v73, 1.0 op_sel:[0,1,0]
	v_pk_fma_f32 v[14:15], s[24:25], v[18:19], v[14:15] op_sel_hi:[0,1,1]
	v_cvt_scalef32_pk_f32_fp4 v[18:19], v73, 1.0 op_sel:[1,1,0]
	v_pk_fma_f32 v[16:17], s[24:25], v[18:19], v[16:17] op_sel_hi:[0,1,1]
	v_readlane_b32 s24, v126, 24
	s_waitcnt vmcnt(14)
	v_cvt_scalef32_pk_f32_fp4 v[18:19], v74, 1.0
	v_pk_fma_f32 v[2:3], v[18:19], s[24:25], v[2:3] op_sel_hi:[1,0,1]
	v_cvt_scalef32_pk_f32_fp4 v[18:19], v74, 1.0 op_sel:[1,0,0]
	v_pk_fma_f32 v[4:5], s[24:25], v[18:19], v[4:5] op_sel_hi:[0,1,1]
	v_cvt_scalef32_pk_f32_fp4 v[18:19], v74, 1.0 op_sel:[0,1,0]
	v_pk_fma_f32 v[6:7], s[24:25], v[18:19], v[6:7] op_sel_hi:[0,1,1]
	v_cvt_scalef32_pk_f32_fp4 v[18:19], v74, 1.0 op_sel:[1,1,0]
	v_pk_fma_f32 v[8:9], s[24:25], v[18:19], v[8:9] op_sel_hi:[0,1,1]
	v_cvt_scalef32_pk_f32_fp4 v[18:19], v75, 1.0
	v_pk_fma_f32 v[10:11], s[24:25], v[18:19], v[10:11] op_sel_hi:[0,1,1]
	v_cvt_scalef32_pk_f32_fp4 v[18:19], v75, 1.0 op_sel:[1,0,0]
	v_pk_fma_f32 v[12:13], s[24:25], v[18:19], v[12:13] op_sel_hi:[0,1,1]
	v_cvt_scalef32_pk_f32_fp4 v[18:19], v75, 1.0 op_sel:[0,1,0]
	v_pk_fma_f32 v[14:15], s[24:25], v[18:19], v[14:15] op_sel_hi:[0,1,1]
	v_cvt_scalef32_pk_f32_fp4 v[18:19], v75, 1.0 op_sel:[1,1,0]
	v_pk_fma_f32 v[16:17], s[24:25], v[18:19], v[16:17] op_sel_hi:[0,1,1]
	v_readlane_b32 s24, v126, 20
	s_waitcnt vmcnt(13)
	v_cvt_scalef32_pk_f32_fp4 v[18:19], v76, 1.0
	v_pk_fma_f32 v[2:3], v[18:19], s[24:25], v[2:3] op_sel_hi:[1,0,1]
	v_cvt_scalef32_pk_f32_fp4 v[18:19], v76, 1.0 op_sel:[1,0,0]
	v_pk_fma_f32 v[4:5], s[24:25], v[18:19], v[4:5] op_sel_hi:[0,1,1]
	v_cvt_scalef32_pk_f32_fp4 v[18:19], v76, 1.0 op_sel:[0,1,0]
	v_pk_fma_f32 v[6:7], s[24:25], v[18:19], v[6:7] op_sel_hi:[0,1,1]
	v_cvt_scalef32_pk_f32_fp4 v[18:19], v76, 1.0 op_sel:[1,1,0]
	v_pk_fma_f32 v[8:9], s[24:25], v[18:19], v[8:9] op_sel_hi:[0,1,1]
	v_cvt_scalef32_pk_f32_fp4 v[18:19], v77, 1.0
	v_pk_fma_f32 v[10:11], s[24:25], v[18:19], v[10:11] op_sel_hi:[0,1,1]
	v_cvt_scalef32_pk_f32_fp4 v[18:19], v77, 1.0 op_sel:[1,0,0]
	v_pk_fma_f32 v[12:13], s[24:25], v[18:19], v[12:13] op_sel_hi:[0,1,1]
	v_cvt_scalef32_pk_f32_fp4 v[18:19], v77, 1.0 op_sel:[0,1,0]
	v_pk_fma_f32 v[14:15], s[24:25], v[18:19], v[14:15] op_sel_hi:[0,1,1]
	v_cvt_scalef32_pk_f32_fp4 v[18:19], v77, 1.0 op_sel:[1,1,0]
	v_pk_fma_f32 v[16:17], s[24:25], v[18:19], v[16:17] op_sel_hi:[0,1,1]
	v_readlane_b32 s24, v126, 28
	s_waitcnt vmcnt(12)
	v_cvt_scalef32_pk_f32_fp4 v[18:19], v78, 1.0
	v_pk_fma_f32 v[2:3], v[18:19], s[24:25], v[2:3] op_sel_hi:[1,0,1]
	v_cvt_scalef32_pk_f32_fp4 v[18:19], v78, 1.0 op_sel:[1,0,0]
	v_pk_fma_f32 v[4:5], s[24:25], v[18:19], v[4:5] op_sel_hi:[0,1,1]
	v_cvt_scalef32_pk_f32_fp4 v[18:19], v78, 1.0 op_sel:[0,1,0]
	v_pk_fma_f32 v[6:7], s[24:25], v[18:19], v[6:7] op_sel_hi:[0,1,1]
	v_cvt_scalef32_pk_f32_fp4 v[18:19], v78, 1.0 op_sel:[1,1,0]
	v_pk_fma_f32 v[8:9], s[24:25], v[18:19], v[8:9] op_sel_hi:[0,1,1]
	v_cvt_scalef32_pk_f32_fp4 v[18:19], v79, 1.0
	v_pk_fma_f32 v[10:11], s[24:25], v[18:19], v[10:11] op_sel_hi:[0,1,1]
	v_cvt_scalef32_pk_f32_fp4 v[18:19], v79, 1.0 op_sel:[1,0,0]
	v_pk_fma_f32 v[12:13], s[24:25], v[18:19], v[12:13] op_sel_hi:[0,1,1]
	v_cvt_scalef32_pk_f32_fp4 v[18:19], v79, 1.0 op_sel:[0,1,0]
	v_pk_fma_f32 v[14:15], s[24:25], v[18:19], v[14:15] op_sel_hi:[0,1,1]
	v_cvt_scalef32_pk_f32_fp4 v[18:19], v79, 1.0 op_sel:[1,1,0]
	v_pk_fma_f32 v[16:17], s[24:25], v[18:19], v[16:17] op_sel_hi:[0,1,1]
	v_readlane_b32 s24, v126, 18
	s_waitcnt vmcnt(11)
	v_cvt_scalef32_pk_f32_fp4 v[18:19], v80, 1.0
	v_pk_fma_f32 v[2:3], v[18:19], s[24:25], v[2:3] op_sel_hi:[1,0,1]
	v_cvt_scalef32_pk_f32_fp4 v[18:19], v80, 1.0 op_sel:[1,0,0]
	v_pk_fma_f32 v[4:5], s[24:25], v[18:19], v[4:5] op_sel_hi:[0,1,1]
	v_cvt_scalef32_pk_f32_fp4 v[18:19], v80, 1.0 op_sel:[0,1,0]
	v_pk_fma_f32 v[6:7], s[24:25], v[18:19], v[6:7] op_sel_hi:[0,1,1]
	v_cvt_scalef32_pk_f32_fp4 v[18:19], v80, 1.0 op_sel:[1,1,0]
	v_pk_fma_f32 v[8:9], s[24:25], v[18:19], v[8:9] op_sel_hi:[0,1,1]
	v_cvt_scalef32_pk_f32_fp4 v[18:19], v81, 1.0
	v_pk_fma_f32 v[10:11], s[24:25], v[18:19], v[10:11] op_sel_hi:[0,1,1]
	v_cvt_scalef32_pk_f32_fp4 v[18:19], v81, 1.0 op_sel:[1,0,0]
	v_pk_fma_f32 v[12:13], s[24:25], v[18:19], v[12:13] op_sel_hi:[0,1,1]
	v_cvt_scalef32_pk_f32_fp4 v[18:19], v81, 1.0 op_sel:[0,1,0]
	v_pk_fma_f32 v[14:15], s[24:25], v[18:19], v[14:15] op_sel_hi:[0,1,1]
	v_cvt_scalef32_pk_f32_fp4 v[18:19], v81, 1.0 op_sel:[1,1,0]
	v_pk_fma_f32 v[16:17], s[24:25], v[18:19], v[16:17] op_sel_hi:[0,1,1]
	v_readlane_b32 s24, v126, 26
	s_waitcnt vmcnt(10)
	v_cvt_scalef32_pk_f32_fp4 v[18:19], v82, 1.0
	v_pk_fma_f32 v[2:3], v[18:19], s[24:25], v[2:3] op_sel_hi:[1,0,1]
	v_cvt_scalef32_pk_f32_fp4 v[18:19], v82, 1.0 op_sel:[1,0,0]
	v_pk_fma_f32 v[4:5], s[24:25], v[18:19], v[4:5] op_sel_hi:[0,1,1]
	v_cvt_scalef32_pk_f32_fp4 v[18:19], v82, 1.0 op_sel:[0,1,0]
	v_pk_fma_f32 v[6:7], s[24:25], v[18:19], v[6:7] op_sel_hi:[0,1,1]
	v_cvt_scalef32_pk_f32_fp4 v[18:19], v82, 1.0 op_sel:[1,1,0]
	v_pk_fma_f32 v[8:9], s[24:25], v[18:19], v[8:9] op_sel_hi:[0,1,1]
	v_cvt_scalef32_pk_f32_fp4 v[18:19], v83, 1.0
	v_pk_fma_f32 v[10:11], s[24:25], v[18:19], v[10:11] op_sel_hi:[0,1,1]
	v_cvt_scalef32_pk_f32_fp4 v[18:19], v83, 1.0 op_sel:[1,0,0]
	v_pk_fma_f32 v[12:13], s[24:25], v[18:19], v[12:13] op_sel_hi:[0,1,1]
	v_cvt_scalef32_pk_f32_fp4 v[18:19], v83, 1.0 op_sel:[0,1,0]
	v_pk_fma_f32 v[14:15], s[24:25], v[18:19], v[14:15] op_sel_hi:[0,1,1]
	v_cvt_scalef32_pk_f32_fp4 v[18:19], v83, 1.0 op_sel:[1,1,0]
	v_pk_fma_f32 v[16:17], s[24:25], v[18:19], v[16:17] op_sel_hi:[0,1,1]
	v_readlane_b32 s24, v126, 22
	s_waitcnt vmcnt(9)
	v_cvt_scalef32_pk_f32_fp4 v[18:19], v84, 1.0
	v_add_u32_e32 v116, 32, v116
	v_pk_fma_f32 v[2:3], v[18:19], s[24:25], v[2:3] op_sel_hi:[1,0,1]
	v_cvt_scalef32_pk_f32_fp4 v[18:19], v84, 1.0 op_sel:[1,0,0]
	v_pk_fma_f32 v[4:5], s[24:25], v[18:19], v[4:5] op_sel_hi:[0,1,1]
	v_cvt_scalef32_pk_f32_fp4 v[18:19], v84, 1.0 op_sel:[0,1,0]
	v_pk_fma_f32 v[6:7], s[24:25], v[18:19], v[6:7] op_sel_hi:[0,1,1]
	v_cvt_scalef32_pk_f32_fp4 v[18:19], v84, 1.0 op_sel:[1,1,0]
	v_pk_fma_f32 v[8:9], s[24:25], v[18:19], v[8:9] op_sel_hi:[0,1,1]
	v_cvt_scalef32_pk_f32_fp4 v[18:19], v85, 1.0
	v_pk_fma_f32 v[10:11], s[24:25], v[18:19], v[10:11] op_sel_hi:[0,1,1]
	v_cvt_scalef32_pk_f32_fp4 v[18:19], v85, 1.0 op_sel:[1,0,0]
	v_pk_fma_f32 v[12:13], s[24:25], v[18:19], v[12:13] op_sel_hi:[0,1,1]
	v_cvt_scalef32_pk_f32_fp4 v[18:19], v85, 1.0 op_sel:[0,1,0]
	v_pk_fma_f32 v[14:15], s[24:25], v[18:19], v[14:15] op_sel_hi:[0,1,1]
	v_cvt_scalef32_pk_f32_fp4 v[18:19], v85, 1.0 op_sel:[1,1,0]
	v_pk_fma_f32 v[16:17], s[24:25], v[18:19], v[16:17] op_sel_hi:[0,1,1]
	v_readlane_b32 s24, v126, 30
	s_waitcnt vmcnt(8)
	v_cvt_scalef32_pk_f32_fp4 v[18:19], v86, 1.0
	v_cmp_ge_u32_e32 vcc, v116, v51
	v_pk_fma_f32 v[2:3], v[18:19], s[24:25], v[2:3] op_sel_hi:[1,0,1]
	v_cvt_scalef32_pk_f32_fp4 v[18:19], v86, 1.0 op_sel:[1,0,0]
	v_pk_fma_f32 v[4:5], s[24:25], v[18:19], v[4:5] op_sel_hi:[0,1,1]
	v_cvt_scalef32_pk_f32_fp4 v[18:19], v86, 1.0 op_sel:[0,1,0]
	v_pk_fma_f32 v[6:7], s[24:25], v[18:19], v[6:7] op_sel_hi:[0,1,1]
	v_cvt_scalef32_pk_f32_fp4 v[18:19], v86, 1.0 op_sel:[1,1,0]
	v_pk_fma_f32 v[8:9], s[24:25], v[18:19], v[8:9] op_sel_hi:[0,1,1]
	v_cvt_scalef32_pk_f32_fp4 v[18:19], v87, 1.0
	v_pk_fma_f32 v[10:11], s[24:25], v[18:19], v[10:11] op_sel_hi:[0,1,1]
	v_cvt_scalef32_pk_f32_fp4 v[18:19], v87, 1.0 op_sel:[1,0,0]
	v_pk_fma_f32 v[12:13], s[24:25], v[18:19], v[12:13] op_sel_hi:[0,1,1]
	v_cvt_scalef32_pk_f32_fp4 v[18:19], v87, 1.0 op_sel:[0,1,0]
	v_pk_fma_f32 v[14:15], s[24:25], v[18:19], v[14:15] op_sel_hi:[0,1,1]
	v_cvt_scalef32_pk_f32_fp4 v[18:19], v87, 1.0 op_sel:[1,1,0]
	v_pk_fma_f32 v[16:17], s[24:25], v[18:19], v[16:17] op_sel_hi:[0,1,1]
	s_waitcnt vmcnt(7)
	v_cvt_scalef32_pk_f32_fp4 v[18:19], v88, 1.0
	s_or_b64 s[12:13], vcc, s[12:13]
	s_nop 0
	v_readlane_b32 s24, v126, 17
	s_nop 1
	v_pk_fma_f32 v[2:3], v[18:19], s[24:25], v[2:3] op_sel_hi:[1,0,1]
	v_cvt_scalef32_pk_f32_fp4 v[18:19], v88, 1.0 op_sel:[1,0,0]
	v_pk_fma_f32 v[4:5], s[24:25], v[18:19], v[4:5] op_sel_hi:[0,1,1]
	v_cvt_scalef32_pk_f32_fp4 v[18:19], v88, 1.0 op_sel:[0,1,0]
	v_pk_fma_f32 v[6:7], s[24:25], v[18:19], v[6:7] op_sel_hi:[0,1,1]
	v_cvt_scalef32_pk_f32_fp4 v[18:19], v88, 1.0 op_sel:[1,1,0]
	v_pk_fma_f32 v[8:9], s[24:25], v[18:19], v[8:9] op_sel_hi:[0,1,1]
	v_cvt_scalef32_pk_f32_fp4 v[18:19], v89, 1.0
	v_pk_fma_f32 v[10:11], s[24:25], v[18:19], v[10:11] op_sel_hi:[0,1,1]
	v_cvt_scalef32_pk_f32_fp4 v[18:19], v89, 1.0 op_sel:[1,0,0]
	v_pk_fma_f32 v[12:13], s[24:25], v[18:19], v[12:13] op_sel_hi:[0,1,1]
	v_cvt_scalef32_pk_f32_fp4 v[18:19], v89, 1.0 op_sel:[0,1,0]
	v_pk_fma_f32 v[14:15], s[24:25], v[18:19], v[14:15] op_sel_hi:[0,1,1]
	v_cvt_scalef32_pk_f32_fp4 v[18:19], v89, 1.0 op_sel:[1,1,0]
	v_pk_fma_f32 v[16:17], s[24:25], v[18:19], v[16:17] op_sel_hi:[0,1,1]
	s_waitcnt vmcnt(6)
	v_cvt_scalef32_pk_f32_fp4 v[18:19], v90, 1.0
	s_nop 1
	v_readlane_b32 s24, v126, 25
	s_nop 1
	v_pk_fma_f32 v[2:3], v[18:19], s[24:25], v[2:3] op_sel_hi:[1,0,1]
	v_cvt_scalef32_pk_f32_fp4 v[18:19], v90, 1.0 op_sel:[1,0,0]
	v_pk_fma_f32 v[4:5], s[24:25], v[18:19], v[4:5] op_sel_hi:[0,1,1]
	v_cvt_scalef32_pk_f32_fp4 v[18:19], v90, 1.0 op_sel:[0,1,0]
	v_pk_fma_f32 v[6:7], s[24:25], v[18:19], v[6:7] op_sel_hi:[0,1,1]
	v_cvt_scalef32_pk_f32_fp4 v[18:19], v90, 1.0 op_sel:[1,1,0]
	v_pk_fma_f32 v[8:9], s[24:25], v[18:19], v[8:9] op_sel_hi:[0,1,1]
	v_cvt_scalef32_pk_f32_fp4 v[18:19], v91, 1.0
	v_pk_fma_f32 v[10:11], s[24:25], v[18:19], v[10:11] op_sel_hi:[0,1,1]
	v_cvt_scalef32_pk_f32_fp4 v[18:19], v91, 1.0 op_sel:[1,0,0]
	v_pk_fma_f32 v[12:13], s[24:25], v[18:19], v[12:13] op_sel_hi:[0,1,1]
	v_cvt_scalef32_pk_f32_fp4 v[18:19], v91, 1.0 op_sel:[0,1,0]
	v_pk_fma_f32 v[14:15], s[24:25], v[18:19], v[14:15] op_sel_hi:[0,1,1]
	v_cvt_scalef32_pk_f32_fp4 v[18:19], v91, 1.0 op_sel:[1,1,0]
	v_pk_fma_f32 v[16:17], s[24:25], v[18:19], v[16:17] op_sel_hi:[0,1,1]
	s_waitcnt vmcnt(5)
	v_cvt_scalef32_pk_f32_fp4 v[18:19], v92, 1.0
	s_nop 1
	v_readlane_b32 s24, v126, 21
	s_nop 1
	v_pk_fma_f32 v[2:3], v[18:19], s[24:25], v[2:3] op_sel_hi:[1,0,1]
	v_cvt_scalef32_pk_f32_fp4 v[18:19], v92, 1.0 op_sel:[1,0,0]
	v_pk_fma_f32 v[4:5], s[24:25], v[18:19], v[4:5] op_sel_hi:[0,1,1]
	v_cvt_scalef32_pk_f32_fp4 v[18:19], v92, 1.0 op_sel:[0,1,0]
	v_pk_fma_f32 v[6:7], s[24:25], v[18:19], v[6:7] op_sel_hi:[0,1,1]
	v_cvt_scalef32_pk_f32_fp4 v[18:19], v92, 1.0 op_sel:[1,1,0]
	v_pk_fma_f32 v[8:9], s[24:25], v[18:19], v[8:9] op_sel_hi:[0,1,1]
	v_cvt_scalef32_pk_f32_fp4 v[18:19], v93, 1.0
	v_pk_fma_f32 v[10:11], s[24:25], v[18:19], v[10:11] op_sel_hi:[0,1,1]
	v_cvt_scalef32_pk_f32_fp4 v[18:19], v93, 1.0 op_sel:[1,0,0]
	v_pk_fma_f32 v[12:13], s[24:25], v[18:19], v[12:13] op_sel_hi:[0,1,1]
	v_cvt_scalef32_pk_f32_fp4 v[18:19], v93, 1.0 op_sel:[0,1,0]
	v_pk_fma_f32 v[14:15], s[24:25], v[18:19], v[14:15] op_sel_hi:[0,1,1]
	v_cvt_scalef32_pk_f32_fp4 v[18:19], v93, 1.0 op_sel:[1,1,0]
	v_pk_fma_f32 v[16:17], s[24:25], v[18:19], v[16:17] op_sel_hi:[0,1,1]
	s_waitcnt vmcnt(4)
	v_cvt_scalef32_pk_f32_fp4 v[18:19], v94, 1.0
	s_nop 1
	v_readlane_b32 s24, v126, 29
	s_nop 1
	v_pk_fma_f32 v[2:3], v[18:19], s[24:25], v[2:3] op_sel_hi:[1,0,1]
	v_cvt_scalef32_pk_f32_fp4 v[18:19], v94, 1.0 op_sel:[1,0,0]
	v_pk_fma_f32 v[4:5], s[24:25], v[18:19], v[4:5] op_sel_hi:[0,1,1]
	v_cvt_scalef32_pk_f32_fp4 v[18:19], v94, 1.0 op_sel:[0,1,0]
	v_pk_fma_f32 v[6:7], s[24:25], v[18:19], v[6:7] op_sel_hi:[0,1,1]
	v_cvt_scalef32_pk_f32_fp4 v[18:19], v94, 1.0 op_sel:[1,1,0]
	v_pk_fma_f32 v[8:9], s[24:25], v[18:19], v[8:9] op_sel_hi:[0,1,1]
	v_cvt_scalef32_pk_f32_fp4 v[18:19], v95, 1.0
	v_pk_fma_f32 v[10:11], s[24:25], v[18:19], v[10:11] op_sel_hi:[0,1,1]
	v_cvt_scalef32_pk_f32_fp4 v[18:19], v95, 1.0 op_sel:[1,0,0]
	v_pk_fma_f32 v[12:13], s[24:25], v[18:19], v[12:13] op_sel_hi:[0,1,1]
	v_cvt_scalef32_pk_f32_fp4 v[18:19], v95, 1.0 op_sel:[0,1,0]
	v_pk_fma_f32 v[14:15], s[24:25], v[18:19], v[14:15] op_sel_hi:[0,1,1]
	v_cvt_scalef32_pk_f32_fp4 v[18:19], v95, 1.0 op_sel:[1,1,0]
	v_pk_fma_f32 v[16:17], s[24:25], v[18:19], v[16:17] op_sel_hi:[0,1,1]
	s_waitcnt vmcnt(3)
	v_cvt_scalef32_pk_f32_fp4 v[18:19], v96, 1.0
	s_nop 1
	v_readlane_b32 s24, v126, 19
	s_nop 1
	v_pk_fma_f32 v[2:3], v[18:19], s[24:25], v[2:3] op_sel_hi:[1,0,1]
	v_cvt_scalef32_pk_f32_fp4 v[18:19], v96, 1.0 op_sel:[1,0,0]
	v_pk_fma_f32 v[4:5], s[24:25], v[18:19], v[4:5] op_sel_hi:[0,1,1]
	v_cvt_scalef32_pk_f32_fp4 v[18:19], v96, 1.0 op_sel:[0,1,0]
	v_pk_fma_f32 v[6:7], s[24:25], v[18:19], v[6:7] op_sel_hi:[0,1,1]
	v_cvt_scalef32_pk_f32_fp4 v[18:19], v96, 1.0 op_sel:[1,1,0]
	v_pk_fma_f32 v[8:9], s[24:25], v[18:19], v[8:9] op_sel_hi:[0,1,1]
	v_cvt_scalef32_pk_f32_fp4 v[18:19], v97, 1.0
	v_pk_fma_f32 v[10:11], s[24:25], v[18:19], v[10:11] op_sel_hi:[0,1,1]
	v_cvt_scalef32_pk_f32_fp4 v[18:19], v97, 1.0 op_sel:[1,0,0]
	v_pk_fma_f32 v[12:13], s[24:25], v[18:19], v[12:13] op_sel_hi:[0,1,1]
	v_cvt_scalef32_pk_f32_fp4 v[18:19], v97, 1.0 op_sel:[0,1,0]
	v_pk_fma_f32 v[14:15], s[24:25], v[18:19], v[14:15] op_sel_hi:[0,1,1]
	v_cvt_scalef32_pk_f32_fp4 v[18:19], v97, 1.0 op_sel:[1,1,0]
	v_pk_fma_f32 v[16:17], s[24:25], v[18:19], v[16:17] op_sel_hi:[0,1,1]
	s_waitcnt vmcnt(2)
	v_cvt_scalef32_pk_f32_fp4 v[18:19], v98, 1.0
	s_nop 1
	v_readlane_b32 s24, v126, 27
	s_nop 1
	v_pk_fma_f32 v[2:3], v[18:19], s[24:25], v[2:3] op_sel_hi:[1,0,1]
	v_cvt_scalef32_pk_f32_fp4 v[18:19], v98, 1.0 op_sel:[1,0,0]
	v_pk_fma_f32 v[4:5], s[24:25], v[18:19], v[4:5] op_sel_hi:[0,1,1]
	v_cvt_scalef32_pk_f32_fp4 v[18:19], v98, 1.0 op_sel:[0,1,0]
	v_pk_fma_f32 v[6:7], s[24:25], v[18:19], v[6:7] op_sel_hi:[0,1,1]
	v_cvt_scalef32_pk_f32_fp4 v[18:19], v98, 1.0 op_sel:[1,1,0]
	v_pk_fma_f32 v[8:9], s[24:25], v[18:19], v[8:9] op_sel_hi:[0,1,1]
	v_cvt_scalef32_pk_f32_fp4 v[18:19], v99, 1.0
	v_pk_fma_f32 v[10:11], s[24:25], v[18:19], v[10:11] op_sel_hi:[0,1,1]
	v_cvt_scalef32_pk_f32_fp4 v[18:19], v99, 1.0 op_sel:[1,0,0]
	v_pk_fma_f32 v[12:13], s[24:25], v[18:19], v[12:13] op_sel_hi:[0,1,1]
	v_cvt_scalef32_pk_f32_fp4 v[18:19], v99, 1.0 op_sel:[0,1,0]
	v_pk_fma_f32 v[14:15], s[24:25], v[18:19], v[14:15] op_sel_hi:[0,1,1]
	v_cvt_scalef32_pk_f32_fp4 v[18:19], v99, 1.0 op_sel:[1,1,0]
	v_pk_fma_f32 v[16:17], s[24:25], v[18:19], v[16:17] op_sel_hi:[0,1,1]
	s_waitcnt vmcnt(1)
	v_cvt_scalef32_pk_f32_fp4 v[18:19], v100, 1.0
	s_nop 1
	v_readlane_b32 s24, v126, 23
	s_nop 1
	v_pk_fma_f32 v[2:3], v[18:19], s[24:25], v[2:3] op_sel_hi:[1,0,1]
	v_cvt_scalef32_pk_f32_fp4 v[18:19], v100, 1.0 op_sel:[1,0,0]
	v_pk_fma_f32 v[4:5], s[24:25], v[18:19], v[4:5] op_sel_hi:[0,1,1]
	v_cvt_scalef32_pk_f32_fp4 v[18:19], v100, 1.0 op_sel:[0,1,0]
	v_pk_fma_f32 v[6:7], s[24:25], v[18:19], v[6:7] op_sel_hi:[0,1,1]
	v_cvt_scalef32_pk_f32_fp4 v[18:19], v100, 1.0 op_sel:[1,1,0]
	v_pk_fma_f32 v[8:9], s[24:25], v[18:19], v[8:9] op_sel_hi:[0,1,1]
	v_cvt_scalef32_pk_f32_fp4 v[18:19], v101, 1.0
	v_pk_fma_f32 v[10:11], s[24:25], v[18:19], v[10:11] op_sel_hi:[0,1,1]
	v_cvt_scalef32_pk_f32_fp4 v[18:19], v101, 1.0 op_sel:[1,0,0]
	v_pk_fma_f32 v[12:13], s[24:25], v[18:19], v[12:13] op_sel_hi:[0,1,1]
	v_cvt_scalef32_pk_f32_fp4 v[18:19], v101, 1.0 op_sel:[0,1,0]
	v_pk_fma_f32 v[14:15], s[24:25], v[18:19], v[14:15] op_sel_hi:[0,1,1]
	v_cvt_scalef32_pk_f32_fp4 v[18:19], v101, 1.0 op_sel:[1,1,0]
	v_pk_fma_f32 v[16:17], s[24:25], v[18:19], v[16:17] op_sel_hi:[0,1,1]
	s_waitcnt vmcnt(0)
	v_cvt_scalef32_pk_f32_fp4 v[18:19], v102, 1.0
	s_nop 1
	v_readlane_b32 s24, v126, 31
	s_nop 1
	v_pk_fma_f32 v[2:3], v[18:19], s[24:25], v[2:3] op_sel_hi:[1,0,1]
	v_cvt_scalef32_pk_f32_fp4 v[18:19], v102, 1.0 op_sel:[1,0,0]
	v_pk_fma_f32 v[4:5], s[24:25], v[18:19], v[4:5] op_sel_hi:[0,1,1]
	v_cvt_scalef32_pk_f32_fp4 v[18:19], v102, 1.0 op_sel:[0,1,0]
	v_pk_fma_f32 v[6:7], s[24:25], v[18:19], v[6:7] op_sel_hi:[0,1,1]
	v_cvt_scalef32_pk_f32_fp4 v[18:19], v102, 1.0 op_sel:[1,1,0]
	v_pk_fma_f32 v[8:9], s[24:25], v[18:19], v[8:9] op_sel_hi:[0,1,1]
	v_cvt_scalef32_pk_f32_fp4 v[18:19], v103, 1.0
	v_pk_fma_f32 v[10:11], s[24:25], v[18:19], v[10:11] op_sel_hi:[0,1,1]
	v_cvt_scalef32_pk_f32_fp4 v[18:19], v103, 1.0 op_sel:[1,0,0]
	v_pk_fma_f32 v[12:13], s[24:25], v[18:19], v[12:13] op_sel_hi:[0,1,1]
	v_cvt_scalef32_pk_f32_fp4 v[18:19], v103, 1.0 op_sel:[0,1,0]
	v_pk_fma_f32 v[14:15], s[24:25], v[18:19], v[14:15] op_sel_hi:[0,1,1]
	v_cvt_scalef32_pk_f32_fp4 v[18:19], v103, 1.0 op_sel:[1,1,0]
	v_pk_fma_f32 v[16:17], s[24:25], v[18:19], v[16:17] op_sel_hi:[0,1,1]
	s_branch .Lh3_v19_join
.Lh3_v19_hi:
	v_readlane_b32 s84, v102, 32
	v_readlane_b32 s86, v102, 33
	v_readlane_b32 s88, v102, 34
	v_readlane_b32 s90, v102, 35
	s_ashr_i32 s85, s84, 31
	s_ashr_i32 s87, s86, 31
	s_ashr_i32 s89, s88, 31
	s_ashr_i32 s91, s90, 31
	s_lshl_b64 s[84:85], s[84:85], 9
	s_lshl_b64 s[86:87], s[86:87], 9
	s_lshl_b64 s[88:89], s[88:89], 9
	s_lshl_b64 s[90:91], s[90:91], 9
	v_lshl_add_u64 v[18:19], v[38:39], 0, s[84:85]
	v_lshl_add_u64 v[20:21], v[38:39], 0, s[86:87]
	v_lshl_add_u64 v[22:23], v[38:39], 0, s[88:89]
	v_lshl_add_u64 v[24:25], v[38:39], 0, s[90:91]
	global_load_dwordx2 v[18:19], v[18:19], off
	global_load_dwordx2 v[20:21], v[20:21], off
	global_load_dwordx2 v[22:23], v[22:23], off
	global_load_dwordx2 v[24:25], v[24:25], off
	v_readlane_b32 s84, v102, 36
	v_readlane_b32 s86, v102, 37
	v_readlane_b32 s88, v102, 38
	v_readlane_b32 s90, v102, 39
	s_ashr_i32 s85, s84, 31
	s_ashr_i32 s87, s86, 31
	s_ashr_i32 s89, s88, 31
	s_ashr_i32 s91, s90, 31
	s_lshl_b64 s[84:85], s[84:85], 9
	s_lshl_b64 s[86:87], s[86:87], 9
	s_lshl_b64 s[88:89], s[88:89], 9
	s_lshl_b64 s[90:91], s[90:91], 9
	v_lshl_add_u64 v[26:27], v[38:39], 0, s[84:85]
	v_lshl_add_u64 v[28:29], v[38:39], 0, s[86:87]
	v_lshl_add_u64 v[30:31], v[38:39], 0, s[88:89]
	v_lshl_add_u64 v[32:33], v[38:39], 0, s[90:91]
	global_load_dwordx2 v[26:27], v[26:27], off
	global_load_dwordx2 v[28:29], v[28:29], off
	global_load_dwordx2 v[30:31], v[30:31], off
	global_load_dwordx2 v[32:33], v[32:33], off
	v_readlane_b32 s84, v102, 40
	v_readlane_b32 s86, v102, 41
	v_readlane_b32 s88, v102, 42
	v_readlane_b32 s90, v102, 43
	s_ashr_i32 s85, s84, 31
	s_ashr_i32 s87, s86, 31
	s_ashr_i32 s89, s88, 31
	s_ashr_i32 s91, s90, 31
	s_lshl_b64 s[84:85], s[84:85], 9
	s_lshl_b64 s[86:87], s[86:87], 9
	s_lshl_b64 s[88:89], s[88:89], 9
	s_lshl_b64 s[90:91], s[90:91], 9
	v_lshl_add_u64 v[56:57], v[38:39], 0, s[84:85]
	v_lshl_add_u64 v[58:59], v[38:39], 0, s[86:87]
	v_lshl_add_u64 v[60:61], v[38:39], 0, s[88:89]
	v_lshl_add_u64 v[62:63], v[38:39], 0, s[90:91]
	global_load_dwordx2 v[56:57], v[56:57], off
	global_load_dwordx2 v[58:59], v[58:59], off
	global_load_dwordx2 v[60:61], v[60:61], off
	global_load_dwordx2 v[62:63], v[62:63], off
	v_readlane_b32 s84, v102, 44
	v_readlane_b32 s86, v102, 45
	v_readlane_b32 s88, v102, 46
	v_readlane_b32 s90, v102, 47
	s_ashr_i32 s85, s84, 31
	s_ashr_i32 s87, s86, 31
	s_ashr_i32 s89, s88, 31
	s_ashr_i32 s91, s90, 31
	s_lshl_b64 s[84:85], s[84:85], 9
	s_lshl_b64 s[86:87], s[86:87], 9
	s_lshl_b64 s[88:89], s[88:89], 9
	s_lshl_b64 s[90:91], s[90:91], 9
	v_lshl_add_u64 v[64:65], v[38:39], 0, s[84:85]
	v_lshl_add_u64 v[66:67], v[38:39], 0, s[86:87]
	v_lshl_add_u64 v[68:69], v[38:39], 0, s[88:89]
	v_lshl_add_u64 v[70:71], v[38:39], 0, s[90:91]
	global_load_dwordx2 v[64:65], v[64:65], off
	global_load_dwordx2 v[66:67], v[66:67], off
	global_load_dwordx2 v[68:69], v[68:69], off
	global_load_dwordx2 v[70:71], v[70:71], off
	v_readlane_b32 s84, v102, 48
	v_readlane_b32 s86, v102, 49
	v_readlane_b32 s88, v102, 50
	v_readlane_b32 s90, v102, 51
	s_ashr_i32 s85, s84, 31
	s_ashr_i32 s87, s86, 31
	s_ashr_i32 s89, s88, 31
	s_ashr_i32 s91, s90, 31
	s_lshl_b64 s[84:85], s[84:85], 9
	s_lshl_b64 s[86:87], s[86:87], 9
	s_lshl_b64 s[88:89], s[88:89], 9
	s_lshl_b64 s[90:91], s[90:91], 9
	v_lshl_add_u64 v[72:73], v[38:39], 0, s[84:85]
	v_lshl_add_u64 v[74:75], v[38:39], 0, s[86:87]
	v_lshl_add_u64 v[76:77], v[38:39], 0, s[88:89]
	v_lshl_add_u64 v[78:79], v[38:39], 0, s[90:91]
	global_load_dwordx2 v[72:73], v[72:73], off
	global_load_dwordx2 v[74:75], v[74:75], off
	global_load_dwordx2 v[76:77], v[76:77], off
	global_load_dwordx2 v[78:79], v[78:79], off
	v_readlane_b32 s84, v102, 52
	v_readlane_b32 s86, v102, 53
	v_readlane_b32 s88, v102, 54
	v_readlane_b32 s90, v102, 55
	s_ashr_i32 s85, s84, 31
	s_ashr_i32 s87, s86, 31
	s_ashr_i32 s89, s88, 31
	s_ashr_i32 s91, s90, 31
	s_lshl_b64 s[84:85], s[84:85], 9
	s_lshl_b64 s[86:87], s[86:87], 9
	s_lshl_b64 s[88:89], s[88:89], 9
	s_lshl_b64 s[90:91], s[90:91], 9
	v_lshl_add_u64 v[80:81], v[38:39], 0, s[84:85]
	v_lshl_add_u64 v[82:83], v[38:39], 0, s[86:87]
	v_lshl_add_u64 v[84:85], v[38:39], 0, s[88:89]
	v_lshl_add_u64 v[86:87], v[38:39], 0, s[90:91]
	global_load_dwordx2 v[80:81], v[80:81], off
	global_load_dwordx2 v[82:83], v[82:83], off
	global_load_dwordx2 v[84:85], v[84:85], off
	global_load_dwordx2 v[86:87], v[86:87], off
	v_readlane_b32 s84, v102, 56
	v_readlane_b32 s86, v102, 57
	v_readlane_b32 s88, v102, 58
	v_readlane_b32 s90, v102, 59
	s_ashr_i32 s85, s84, 31
	s_ashr_i32 s87, s86, 31
	s_ashr_i32 s89, s88, 31
	s_ashr_i32 s91, s90, 31
	s_lshl_b64 s[84:85], s[84:85], 9
	s_lshl_b64 s[86:87], s[86:87], 9
	s_lshl_b64 s[88:89], s[88:89], 9
	s_lshl_b64 s[90:91], s[90:91], 9
	v_lshl_add_u64 v[88:89], v[38:39], 0, s[84:85]
	v_lshl_add_u64 v[90:91], v[38:39], 0, s[86:87]
	v_lshl_add_u64 v[92:93], v[38:39], 0, s[88:89]
	v_lshl_add_u64 v[94:95], v[38:39], 0, s[90:91]
	global_load_dwordx2 v[88:89], v[88:89], off
	global_load_dwordx2 v[90:91], v[90:91], off
	global_load_dwordx2 v[92:93], v[92:93], off
	global_load_dwordx2 v[94:95], v[94:95], off
	v_readlane_b32 s84, v102, 60
	v_readlane_b32 s86, v102, 61
	v_readlane_b32 s88, v102, 62
	v_readlane_b32 s90, v102, 63
	s_ashr_i32 s85, s84, 31
	s_ashr_i32 s87, s86, 31
	s_ashr_i32 s89, s88, 31
	s_ashr_i32 s91, s90, 31
	s_lshl_b64 s[84:85], s[84:85], 9
	s_lshl_b64 s[86:87], s[86:87], 9
	s_lshl_b64 s[88:89], s[88:89], 9
	s_lshl_b64 s[90:91], s[90:91], 9
	v_lshl_add_u64 v[96:97], v[38:39], 0, s[84:85]
	v_lshl_add_u64 v[98:99], v[38:39], 0, s[86:87]
	v_lshl_add_u64 v[100:101], v[38:39], 0, s[88:89]
	v_lshl_add_u64 v[102:103], v[38:39], 0, s[90:91]
	global_load_dwordx2 v[96:97], v[96:97], off
	global_load_dwordx2 v[98:99], v[98:99], off
	global_load_dwordx2 v[100:101], v[100:101], off
	global_load_dwordx2 v[102:103], v[102:103], off
	v_cndmask_b32_e32 v126, v1, v118, vcc
	s_nop 0
	v_readlane_b32 s48, v126, 32
	s_waitcnt vmcnt(31)
	v_cvt_scalef32_pk_f32_fp4 v[128:129], v18, 1.0
	v_pk_fma_f32 v[2:3], v[128:129], s[48:49], v[2:3] op_sel_hi:[1,0,1]
	v_cvt_scalef32_pk_f32_fp4 v[128:129], v18, 1.0 op_sel:[1,0,0]
	v_pk_fma_f32 v[4:5], s[48:49], v[128:129], v[4:5] op_sel_hi:[0,1,1]
	v_cvt_scalef32_pk_f32_fp4 v[128:129], v18, 1.0 op_sel:[0,1,0]
	v_pk_fma_f32 v[6:7], s[48:49], v[128:129], v[6:7] op_sel_hi:[0,1,1]
	v_cvt_scalef32_pk_f32_fp4 v[128:129], v18, 1.0 op_sel:[1,1,0]
	v_pk_fma_f32 v[8:9], s[48:49], v[128:129], v[8:9] op_sel_hi:[0,1,1]
	v_cvt_scalef32_pk_f32_fp4 v[128:129], v19, 1.0
	v_pk_fma_f32 v[10:11], s[48:49], v[128:129], v[10:11] op_sel_hi:[0,1,1]
	v_cvt_scalef32_pk_f32_fp4 v[128:129], v19, 1.0 op_sel:[1,0,0]
	v_pk_fma_f32 v[12:13], s[48:49], v[128:129], v[12:13] op_sel_hi:[0,1,1]
	v_cvt_scalef32_pk_f32_fp4 v[128:129], v19, 1.0 op_sel:[0,1,0]
	v_cvt_scalef32_pk_f32_fp4 v[18:19], v19, 1.0 op_sel:[1,1,0]
	v_pk_fma_f32 v[14:15], s[48:49], v[128:129], v[14:15] op_sel_hi:[0,1,1]
	v_pk_fma_f32 v[16:17], s[48:49], v[18:19], v[16:17] op_sel_hi:[0,1,1]
	v_readlane_b32 s48, v126, 40
	s_waitcnt vmcnt(30)
	v_cvt_scalef32_pk_f32_fp4 v[18:19], v20, 1.0
	v_pk_fma_f32 v[2:3], v[18:19], s[48:49], v[2:3] op_sel_hi:[1,0,1]
	v_cvt_scalef32_pk_f32_fp4 v[18:19], v20, 1.0 op_sel:[1,0,0]
	v_pk_fma_f32 v[4:5], s[48:49], v[18:19], v[4:5] op_sel_hi:[0,1,1]
	v_cvt_scalef32_pk_f32_fp4 v[18:19], v20, 1.0 op_sel:[0,1,0]
	v_pk_fma_f32 v[6:7], s[48:49], v[18:19], v[6:7] op_sel_hi:[0,1,1]
	v_cvt_scalef32_pk_f32_fp4 v[18:19], v20, 1.0 op_sel:[1,1,0]
	v_pk_fma_f32 v[8:9], s[48:49], v[18:19], v[8:9] op_sel_hi:[0,1,1]
	v_cvt_scalef32_pk_f32_fp4 v[18:19], v21, 1.0
	v_pk_fma_f32 v[10:11], s[48:49], v[18:19], v[10:11] op_sel_hi:[0,1,1]
	v_cvt_scalef32_pk_f32_fp4 v[18:19], v21, 1.0 op_sel:[1,0,0]
	v_pk_fma_f32 v[12:13], s[48:49], v[18:19], v[12:13] op_sel_hi:[0,1,1]
	v_cvt_scalef32_pk_f32_fp4 v[18:19], v21, 1.0 op_sel:[0,1,0]
	v_pk_fma_f32 v[14:15], s[48:49], v[18:19], v[14:15] op_sel_hi:[0,1,1]
	v_cvt_scalef32_pk_f32_fp4 v[18:19], v21, 1.0 op_sel:[1,1,0]
	v_pk_fma_f32 v[16:17], s[48:49], v[18:19], v[16:17] op_sel_hi:[0,1,1]
	v_readlane_b32 s48, v126, 36
	s_waitcnt vmcnt(29)
	v_cvt_scalef32_pk_f32_fp4 v[18:19], v22, 1.0
	v_pk_fma_f32 v[2:3], v[18:19], s[48:49], v[2:3] op_sel_hi:[1,0,1]
	v_cvt_scalef32_pk_f32_fp4 v[18:19], v22, 1.0 op_sel:[1,0,0]
	v_pk_fma_f32 v[4:5], s[48:49], v[18:19], v[4:5] op_sel_hi:[0,1,1]
	v_cvt_scalef32_pk_f32_fp4 v[18:19], v22, 1.0 op_sel:[0,1,0]
	v_pk_fma_f32 v[6:7], s[48:49], v[18:19], v[6:7] op_sel_hi:[0,1,1]
	v_cvt_scalef32_pk_f32_fp4 v[18:19], v22, 1.0 op_sel:[1,1,0]
	v_pk_fma_f32 v[8:9], s[48:49], v[18:19], v[8:9] op_sel_hi:[0,1,1]
	v_cvt_scalef32_pk_f32_fp4 v[18:19], v23, 1.0
	v_pk_fma_f32 v[10:11], s[48:49], v[18:19], v[10:11] op_sel_hi:[0,1,1]
	v_cvt_scalef32_pk_f32_fp4 v[18:19], v23, 1.0 op_sel:[1,0,0]
	v_pk_fma_f32 v[12:13], s[48:49], v[18:19], v[12:13] op_sel_hi:[0,1,1]
	v_cvt_scalef32_pk_f32_fp4 v[18:19], v23, 1.0 op_sel:[0,1,0]
	v_pk_fma_f32 v[14:15], s[48:49], v[18:19], v[14:15] op_sel_hi:[0,1,1]
	v_cvt_scalef32_pk_f32_fp4 v[18:19], v23, 1.0 op_sel:[1,1,0]
	v_pk_fma_f32 v[16:17], s[48:49], v[18:19], v[16:17] op_sel_hi:[0,1,1]
	v_readlane_b32 s48, v126, 44
	s_waitcnt vmcnt(28)
	v_cvt_scalef32_pk_f32_fp4 v[18:19], v24, 1.0
	v_pk_fma_f32 v[2:3], v[18:19], s[48:49], v[2:3] op_sel_hi:[1,0,1]
	v_cvt_scalef32_pk_f32_fp4 v[18:19], v24, 1.0 op_sel:[1,0,0]
	v_pk_fma_f32 v[4:5], s[48:49], v[18:19], v[4:5] op_sel_hi:[0,1,1]
	v_cvt_scalef32_pk_f32_fp4 v[18:19], v24, 1.0 op_sel:[0,1,0]
	v_pk_fma_f32 v[6:7], s[48:49], v[18:19], v[6:7] op_sel_hi:[0,1,1]
	v_cvt_scalef32_pk_f32_fp4 v[18:19], v24, 1.0 op_sel:[1,1,0]
	v_pk_fma_f32 v[8:9], s[48:49], v[18:19], v[8:9] op_sel_hi:[0,1,1]
	v_cvt_scalef32_pk_f32_fp4 v[18:19], v25, 1.0
	v_pk_fma_f32 v[10:11], s[48:49], v[18:19], v[10:11] op_sel_hi:[0,1,1]
	v_cvt_scalef32_pk_f32_fp4 v[18:19], v25, 1.0 op_sel:[1,0,0]
	v_pk_fma_f32 v[12:13], s[48:49], v[18:19], v[12:13] op_sel_hi:[0,1,1]
	v_cvt_scalef32_pk_f32_fp4 v[18:19], v25, 1.0 op_sel:[0,1,0]
	v_pk_fma_f32 v[14:15], s[48:49], v[18:19], v[14:15] op_sel_hi:[0,1,1]
	v_cvt_scalef32_pk_f32_fp4 v[18:19], v25, 1.0 op_sel:[1,1,0]
	v_pk_fma_f32 v[16:17], s[48:49], v[18:19], v[16:17] op_sel_hi:[0,1,1]
	v_readlane_b32 s48, v126, 34
	s_waitcnt vmcnt(27)
	v_cvt_scalef32_pk_f32_fp4 v[18:19], v26, 1.0
	v_pk_fma_f32 v[2:3], v[18:19], s[48:49], v[2:3] op_sel_hi:[1,0,1]
	v_cvt_scalef32_pk_f32_fp4 v[18:19], v26, 1.0 op_sel:[1,0,0]
	v_pk_fma_f32 v[4:5], s[48:49], v[18:19], v[4:5] op_sel_hi:[0,1,1]
	v_cvt_scalef32_pk_f32_fp4 v[18:19], v26, 1.0 op_sel:[0,1,0]
	v_pk_fma_f32 v[6:7], s[48:49], v[18:19], v[6:7] op_sel_hi:[0,1,1]
	v_cvt_scalef32_pk_f32_fp4 v[18:19], v26, 1.0 op_sel:[1,1,0]
	v_pk_fma_f32 v[8:9], s[48:49], v[18:19], v[8:9] op_sel_hi:[0,1,1]
	v_cvt_scalef32_pk_f32_fp4 v[18:19], v27, 1.0
	v_pk_fma_f32 v[10:11], s[48:49], v[18:19], v[10:11] op_sel_hi:[0,1,1]
	v_cvt_scalef32_pk_f32_fp4 v[18:19], v27, 1.0 op_sel:[1,0,0]
	v_pk_fma_f32 v[12:13], s[48:49], v[18:19], v[12:13] op_sel_hi:[0,1,1]
	v_cvt_scalef32_pk_f32_fp4 v[18:19], v27, 1.0 op_sel:[0,1,0]
	v_pk_fma_f32 v[14:15], s[48:49], v[18:19], v[14:15] op_sel_hi:[0,1,1]
	v_cvt_scalef32_pk_f32_fp4 v[18:19], v27, 1.0 op_sel:[1,1,0]
	v_pk_fma_f32 v[16:17], s[48:49], v[18:19], v[16:17] op_sel_hi:[0,1,1]
	v_readlane_b32 s48, v126, 42
	s_waitcnt vmcnt(26)
	v_cvt_scalef32_pk_f32_fp4 v[18:19], v28, 1.0
	v_pk_fma_f32 v[2:3], v[18:19], s[48:49], v[2:3] op_sel_hi:[1,0,1]
	v_cvt_scalef32_pk_f32_fp4 v[18:19], v28, 1.0 op_sel:[1,0,0]
	v_pk_fma_f32 v[4:5], s[48:49], v[18:19], v[4:5] op_sel_hi:[0,1,1]
	v_cvt_scalef32_pk_f32_fp4 v[18:19], v28, 1.0 op_sel:[0,1,0]
	v_pk_fma_f32 v[6:7], s[48:49], v[18:19], v[6:7] op_sel_hi:[0,1,1]
	v_cvt_scalef32_pk_f32_fp4 v[18:19], v28, 1.0 op_sel:[1,1,0]
	v_pk_fma_f32 v[8:9], s[48:49], v[18:19], v[8:9] op_sel_hi:[0,1,1]
	v_cvt_scalef32_pk_f32_fp4 v[18:19], v29, 1.0
	v_pk_fma_f32 v[10:11], s[48:49], v[18:19], v[10:11] op_sel_hi:[0,1,1]
	v_cvt_scalef32_pk_f32_fp4 v[18:19], v29, 1.0 op_sel:[1,0,0]
	v_pk_fma_f32 v[12:13], s[48:49], v[18:19], v[12:13] op_sel_hi:[0,1,1]
	v_cvt_scalef32_pk_f32_fp4 v[18:19], v29, 1.0 op_sel:[0,1,0]
	v_pk_fma_f32 v[14:15], s[48:49], v[18:19], v[14:15] op_sel_hi:[0,1,1]
	v_cvt_scalef32_pk_f32_fp4 v[18:19], v29, 1.0 op_sel:[1,1,0]
	v_pk_fma_f32 v[16:17], s[48:49], v[18:19], v[16:17] op_sel_hi:[0,1,1]
	v_readlane_b32 s48, v126, 38
	s_waitcnt vmcnt(25)
	v_cvt_scalef32_pk_f32_fp4 v[18:19], v30, 1.0
	v_pk_fma_f32 v[2:3], v[18:19], s[48:49], v[2:3] op_sel_hi:[1,0,1]
	v_cvt_scalef32_pk_f32_fp4 v[18:19], v30, 1.0 op_sel:[1,0,0]
	v_pk_fma_f32 v[4:5], s[48:49], v[18:19], v[4:5] op_sel_hi:[0,1,1]
	v_cvt_scalef32_pk_f32_fp4 v[18:19], v30, 1.0 op_sel:[0,1,0]
	v_pk_fma_f32 v[6:7], s[48:49], v[18:19], v[6:7] op_sel_hi:[0,1,1]
	v_cvt_scalef32_pk_f32_fp4 v[18:19], v30, 1.0 op_sel:[1,1,0]
	v_pk_fma_f32 v[8:9], s[48:49], v[18:19], v[8:9] op_sel_hi:[0,1,1]
	v_cvt_scalef32_pk_f32_fp4 v[18:19], v31, 1.0
	v_pk_fma_f32 v[10:11], s[48:49], v[18:19], v[10:11] op_sel_hi:[0,1,1]
	v_cvt_scalef32_pk_f32_fp4 v[18:19], v31, 1.0 op_sel:[1,0,0]
	v_pk_fma_f32 v[12:13], s[48:49], v[18:19], v[12:13] op_sel_hi:[0,1,1]
	v_cvt_scalef32_pk_f32_fp4 v[18:19], v31, 1.0 op_sel:[0,1,0]
	v_pk_fma_f32 v[14:15], s[48:49], v[18:19], v[14:15] op_sel_hi:[0,1,1]
	v_cvt_scalef32_pk_f32_fp4 v[18:19], v31, 1.0 op_sel:[1,1,0]
	v_pk_fma_f32 v[16:17], s[48:49], v[18:19], v[16:17] op_sel_hi:[0,1,1]
	v_readlane_b32 s48, v126, 46
	s_waitcnt vmcnt(24)
	v_cvt_scalef32_pk_f32_fp4 v[18:19], v32, 1.0
	v_pk_fma_f32 v[2:3], v[18:19], s[48:49], v[2:3] op_sel_hi:[1,0,1]
	v_cvt_scalef32_pk_f32_fp4 v[18:19], v32, 1.0 op_sel:[1,0,0]
	v_pk_fma_f32 v[4:5], s[48:49], v[18:19], v[4:5] op_sel_hi:[0,1,1]
	v_cvt_scalef32_pk_f32_fp4 v[18:19], v32, 1.0 op_sel:[0,1,0]
	v_pk_fma_f32 v[6:7], s[48:49], v[18:19], v[6:7] op_sel_hi:[0,1,1]
	v_cvt_scalef32_pk_f32_fp4 v[18:19], v32, 1.0 op_sel:[1,1,0]
	v_pk_fma_f32 v[8:9], s[48:49], v[18:19], v[8:9] op_sel_hi:[0,1,1]
	v_cvt_scalef32_pk_f32_fp4 v[18:19], v33, 1.0
	v_pk_fma_f32 v[10:11], s[48:49], v[18:19], v[10:11] op_sel_hi:[0,1,1]
	v_cvt_scalef32_pk_f32_fp4 v[18:19], v33, 1.0 op_sel:[1,0,0]
	v_pk_fma_f32 v[12:13], s[48:49], v[18:19], v[12:13] op_sel_hi:[0,1,1]
	v_cvt_scalef32_pk_f32_fp4 v[18:19], v33, 1.0 op_sel:[0,1,0]
	v_pk_fma_f32 v[14:15], s[48:49], v[18:19], v[14:15] op_sel_hi:[0,1,1]
	v_cvt_scalef32_pk_f32_fp4 v[18:19], v33, 1.0 op_sel:[1,1,0]
	v_pk_fma_f32 v[16:17], s[48:49], v[18:19], v[16:17] op_sel_hi:[0,1,1]
	v_readlane_b32 s48, v126, 33
	s_waitcnt vmcnt(23)
	v_cvt_scalef32_pk_f32_fp4 v[18:19], v56, 1.0
	v_pk_fma_f32 v[2:3], v[18:19], s[48:49], v[2:3] op_sel_hi:[1,0,1]
	v_cvt_scalef32_pk_f32_fp4 v[18:19], v56, 1.0 op_sel:[1,0,0]
	v_pk_fma_f32 v[4:5], s[48:49], v[18:19], v[4:5] op_sel_hi:[0,1,1]
	v_cvt_scalef32_pk_f32_fp4 v[18:19], v56, 1.0 op_sel:[0,1,0]
	v_pk_fma_f32 v[6:7], s[48:49], v[18:19], v[6:7] op_sel_hi:[0,1,1]
	v_cvt_scalef32_pk_f32_fp4 v[18:19], v56, 1.0 op_sel:[1,1,0]
	v_pk_fma_f32 v[8:9], s[48:49], v[18:19], v[8:9] op_sel_hi:[0,1,1]
	v_cvt_scalef32_pk_f32_fp4 v[18:19], v57, 1.0
	v_pk_fma_f32 v[10:11], s[48:49], v[18:19], v[10:11] op_sel_hi:[0,1,1]
	v_cvt_scalef32_pk_f32_fp4 v[18:19], v57, 1.0 op_sel:[1,0,0]
	v_pk_fma_f32 v[12:13], s[48:49], v[18:19], v[12:13] op_sel_hi:[0,1,1]
	v_cvt_scalef32_pk_f32_fp4 v[18:19], v57, 1.0 op_sel:[0,1,0]
	v_pk_fma_f32 v[14:15], s[48:49], v[18:19], v[14:15] op_sel_hi:[0,1,1]
	v_cvt_scalef32_pk_f32_fp4 v[18:19], v57, 1.0 op_sel:[1,1,0]
	v_pk_fma_f32 v[16:17], s[48:49], v[18:19], v[16:17] op_sel_hi:[0,1,1]
	v_readlane_b32 s48, v126, 41
	s_waitcnt vmcnt(22)
	v_cvt_scalef32_pk_f32_fp4 v[18:19], v58, 1.0
	v_pk_fma_f32 v[2:3], v[18:19], s[48:49], v[2:3] op_sel_hi:[1,0,1]
	v_cvt_scalef32_pk_f32_fp4 v[18:19], v58, 1.0 op_sel:[1,0,0]
	v_pk_fma_f32 v[4:5], s[48:49], v[18:19], v[4:5] op_sel_hi:[0,1,1]
	v_cvt_scalef32_pk_f32_fp4 v[18:19], v58, 1.0 op_sel:[0,1,0]
	v_pk_fma_f32 v[6:7], s[48:49], v[18:19], v[6:7] op_sel_hi:[0,1,1]
	v_cvt_scalef32_pk_f32_fp4 v[18:19], v58, 1.0 op_sel:[1,1,0]
	v_pk_fma_f32 v[8:9], s[48:49], v[18:19], v[8:9] op_sel_hi:[0,1,1]
	v_cvt_scalef32_pk_f32_fp4 v[18:19], v59, 1.0
	v_pk_fma_f32 v[10:11], s[48:49], v[18:19], v[10:11] op_sel_hi:[0,1,1]
	v_cvt_scalef32_pk_f32_fp4 v[18:19], v59, 1.0 op_sel:[1,0,0]
	v_pk_fma_f32 v[12:13], s[48:49], v[18:19], v[12:13] op_sel_hi:[0,1,1]
	v_cvt_scalef32_pk_f32_fp4 v[18:19], v59, 1.0 op_sel:[0,1,0]
	v_pk_fma_f32 v[14:15], s[48:49], v[18:19], v[14:15] op_sel_hi:[0,1,1]
	v_cvt_scalef32_pk_f32_fp4 v[18:19], v59, 1.0 op_sel:[1,1,0]
	v_pk_fma_f32 v[16:17], s[48:49], v[18:19], v[16:17] op_sel_hi:[0,1,1]
	v_readlane_b32 s48, v126, 37
	s_waitcnt vmcnt(21)
	v_cvt_scalef32_pk_f32_fp4 v[18:19], v60, 1.0
	v_pk_fma_f32 v[2:3], v[18:19], s[48:49], v[2:3] op_sel_hi:[1,0,1]
	v_cvt_scalef32_pk_f32_fp4 v[18:19], v60, 1.0 op_sel:[1,0,0]
	v_pk_fma_f32 v[4:5], s[48:49], v[18:19], v[4:5] op_sel_hi:[0,1,1]
	v_cvt_scalef32_pk_f32_fp4 v[18:19], v60, 1.0 op_sel:[0,1,0]
	v_pk_fma_f32 v[6:7], s[48:49], v[18:19], v[6:7] op_sel_hi:[0,1,1]
	v_cvt_scalef32_pk_f32_fp4 v[18:19], v60, 1.0 op_sel:[1,1,0]
	v_pk_fma_f32 v[8:9], s[48:49], v[18:19], v[8:9] op_sel_hi:[0,1,1]
	v_cvt_scalef32_pk_f32_fp4 v[18:19], v61, 1.0
	v_pk_fma_f32 v[10:11], s[48:49], v[18:19], v[10:11] op_sel_hi:[0,1,1]
	v_cvt_scalef32_pk_f32_fp4 v[18:19], v61, 1.0 op_sel:[1,0,0]
	v_pk_fma_f32 v[12:13], s[48:49], v[18:19], v[12:13] op_sel_hi:[0,1,1]
	v_cvt_scalef32_pk_f32_fp4 v[18:19], v61, 1.0 op_sel:[0,1,0]
	v_pk_fma_f32 v[14:15], s[48:49], v[18:19], v[14:15] op_sel_hi:[0,1,1]
	v_cvt_scalef32_pk_f32_fp4 v[18:19], v61, 1.0 op_sel:[1,1,0]
	v_pk_fma_f32 v[16:17], s[48:49], v[18:19], v[16:17] op_sel_hi:[0,1,1]
	v_readlane_b32 s48, v126, 45
	s_waitcnt vmcnt(20)
	v_cvt_scalef32_pk_f32_fp4 v[18:19], v62, 1.0
	v_pk_fma_f32 v[2:3], v[18:19], s[48:49], v[2:3] op_sel_hi:[1,0,1]
	v_cvt_scalef32_pk_f32_fp4 v[18:19], v62, 1.0 op_sel:[1,0,0]
	v_pk_fma_f32 v[4:5], s[48:49], v[18:19], v[4:5] op_sel_hi:[0,1,1]
	v_cvt_scalef32_pk_f32_fp4 v[18:19], v62, 1.0 op_sel:[0,1,0]
	v_pk_fma_f32 v[6:7], s[48:49], v[18:19], v[6:7] op_sel_hi:[0,1,1]
	v_cvt_scalef32_pk_f32_fp4 v[18:19], v62, 1.0 op_sel:[1,1,0]
	v_pk_fma_f32 v[8:9], s[48:49], v[18:19], v[8:9] op_sel_hi:[0,1,1]
	v_cvt_scalef32_pk_f32_fp4 v[18:19], v63, 1.0
	v_pk_fma_f32 v[10:11], s[48:49], v[18:19], v[10:11] op_sel_hi:[0,1,1]
	v_cvt_scalef32_pk_f32_fp4 v[18:19], v63, 1.0 op_sel:[1,0,0]
	v_pk_fma_f32 v[12:13], s[48:49], v[18:19], v[12:13] op_sel_hi:[0,1,1]
	v_cvt_scalef32_pk_f32_fp4 v[18:19], v63, 1.0 op_sel:[0,1,0]
	v_pk_fma_f32 v[14:15], s[48:49], v[18:19], v[14:15] op_sel_hi:[0,1,1]
	v_cvt_scalef32_pk_f32_fp4 v[18:19], v63, 1.0 op_sel:[1,1,0]
	v_pk_fma_f32 v[16:17], s[48:49], v[18:19], v[16:17] op_sel_hi:[0,1,1]
	v_readlane_b32 s24, v126, 35
	s_waitcnt vmcnt(19)
	v_cvt_scalef32_pk_f32_fp4 v[18:19], v64, 1.0
	v_pk_fma_f32 v[2:3], v[18:19], s[24:25], v[2:3] op_sel_hi:[1,0,1]
	v_cvt_scalef32_pk_f32_fp4 v[18:19], v64, 1.0 op_sel:[1,0,0]
	v_pk_fma_f32 v[4:5], s[24:25], v[18:19], v[4:5] op_sel_hi:[0,1,1]
	v_cvt_scalef32_pk_f32_fp4 v[18:19], v64, 1.0 op_sel:[0,1,0]
	v_pk_fma_f32 v[6:7], s[24:25], v[18:19], v[6:7] op_sel_hi:[0,1,1]
	v_cvt_scalef32_pk_f32_fp4 v[18:19], v64, 1.0 op_sel:[1,1,0]
	v_pk_fma_f32 v[8:9], s[24:25], v[18:19], v[8:9] op_sel_hi:[0,1,1]
	v_cvt_scalef32_pk_f32_fp4 v[18:19], v65, 1.0
	v_pk_fma_f32 v[10:11], s[24:25], v[18:19], v[10:11] op_sel_hi:[0,1,1]
	v_cvt_scalef32_pk_f32_fp4 v[18:19], v65, 1.0 op_sel:[1,0,0]
	v_pk_fma_f32 v[12:13], s[24:25], v[18:19], v[12:13] op_sel_hi:[0,1,1]
	v_cvt_scalef32_pk_f32_fp4 v[18:19], v65, 1.0 op_sel:[0,1,0]
	v_pk_fma_f32 v[14:15], s[24:25], v[18:19], v[14:15] op_sel_hi:[0,1,1]
	v_cvt_scalef32_pk_f32_fp4 v[18:19], v65, 1.0 op_sel:[1,1,0]
	v_pk_fma_f32 v[16:17], s[24:25], v[18:19], v[16:17] op_sel_hi:[0,1,1]
	v_readlane_b32 s24, v126, 43
	s_waitcnt vmcnt(18)
	v_cvt_scalef32_pk_f32_fp4 v[18:19], v66, 1.0
	v_pk_fma_f32 v[2:3], v[18:19], s[24:25], v[2:3] op_sel_hi:[1,0,1]
	v_cvt_scalef32_pk_f32_fp4 v[18:19], v66, 1.0 op_sel:[1,0,0]
	v_pk_fma_f32 v[4:5], s[24:25], v[18:19], v[4:5] op_sel_hi:[0,1,1]
	v_cvt_scalef32_pk_f32_fp4 v[18:19], v66, 1.0 op_sel:[0,1,0]
	v_pk_fma_f32 v[6:7], s[24:25], v[18:19], v[6:7] op_sel_hi:[0,1,1]
	v_cvt_scalef32_pk_f32_fp4 v[18:19], v66, 1.0 op_sel:[1,1,0]
	v_pk_fma_f32 v[8:9], s[24:25], v[18:19], v[8:9] op_sel_hi:[0,1,1]
	v_cvt_scalef32_pk_f32_fp4 v[18:19], v67, 1.0
	v_pk_fma_f32 v[10:11], s[24:25], v[18:19], v[10:11] op_sel_hi:[0,1,1]
	v_cvt_scalef32_pk_f32_fp4 v[18:19], v67, 1.0 op_sel:[1,0,0]
	v_pk_fma_f32 v[12:13], s[24:25], v[18:19], v[12:13] op_sel_hi:[0,1,1]
	v_cvt_scalef32_pk_f32_fp4 v[18:19], v67, 1.0 op_sel:[0,1,0]
	v_pk_fma_f32 v[14:15], s[24:25], v[18:19], v[14:15] op_sel_hi:[0,1,1]
	v_cvt_scalef32_pk_f32_fp4 v[18:19], v67, 1.0 op_sel:[1,1,0]
	v_pk_fma_f32 v[16:17], s[24:25], v[18:19], v[16:17] op_sel_hi:[0,1,1]
	v_readlane_b32 s24, v126, 39
	s_waitcnt vmcnt(17)
	v_cvt_scalef32_pk_f32_fp4 v[18:19], v68, 1.0
	v_pk_fma_f32 v[2:3], v[18:19], s[24:25], v[2:3] op_sel_hi:[1,0,1]
	v_cvt_scalef32_pk_f32_fp4 v[18:19], v68, 1.0 op_sel:[1,0,0]
	v_pk_fma_f32 v[4:5], s[24:25], v[18:19], v[4:5] op_sel_hi:[0,1,1]
	v_cvt_scalef32_pk_f32_fp4 v[18:19], v68, 1.0 op_sel:[0,1,0]
	v_pk_fma_f32 v[6:7], s[24:25], v[18:19], v[6:7] op_sel_hi:[0,1,1]
	v_cvt_scalef32_pk_f32_fp4 v[18:19], v68, 1.0 op_sel:[1,1,0]
	v_pk_fma_f32 v[8:9], s[24:25], v[18:19], v[8:9] op_sel_hi:[0,1,1]
	v_cvt_scalef32_pk_f32_fp4 v[18:19], v69, 1.0
	v_pk_fma_f32 v[10:11], s[24:25], v[18:19], v[10:11] op_sel_hi:[0,1,1]
	v_cvt_scalef32_pk_f32_fp4 v[18:19], v69, 1.0 op_sel:[1,0,0]
	v_pk_fma_f32 v[12:13], s[24:25], v[18:19], v[12:13] op_sel_hi:[0,1,1]
	v_cvt_scalef32_pk_f32_fp4 v[18:19], v69, 1.0 op_sel:[0,1,0]
	v_pk_fma_f32 v[14:15], s[24:25], v[18:19], v[14:15] op_sel_hi:[0,1,1]
	v_cvt_scalef32_pk_f32_fp4 v[18:19], v69, 1.0 op_sel:[1,1,0]
	v_pk_fma_f32 v[16:17], s[24:25], v[18:19], v[16:17] op_sel_hi:[0,1,1]
	v_readlane_b32 s24, v126, 47
	s_waitcnt vmcnt(16)
	v_cvt_scalef32_pk_f32_fp4 v[18:19], v70, 1.0
	v_pk_fma_f32 v[2:3], v[18:19], s[24:25], v[2:3] op_sel_hi:[1,0,1]
	v_cvt_scalef32_pk_f32_fp4 v[18:19], v70, 1.0 op_sel:[1,0,0]
	v_pk_fma_f32 v[4:5], s[24:25], v[18:19], v[4:5] op_sel_hi:[0,1,1]
	v_cvt_scalef32_pk_f32_fp4 v[18:19], v70, 1.0 op_sel:[0,1,0]
	v_pk_fma_f32 v[6:7], s[24:25], v[18:19], v[6:7] op_sel_hi:[0,1,1]
	v_cvt_scalef32_pk_f32_fp4 v[18:19], v70, 1.0 op_sel:[1,1,0]
	v_pk_fma_f32 v[8:9], s[24:25], v[18:19], v[8:9] op_sel_hi:[0,1,1]
	v_cvt_scalef32_pk_f32_fp4 v[18:19], v71, 1.0
	v_pk_fma_f32 v[10:11], s[24:25], v[18:19], v[10:11] op_sel_hi:[0,1,1]
	v_cvt_scalef32_pk_f32_fp4 v[18:19], v71, 1.0 op_sel:[1,0,0]
	v_pk_fma_f32 v[12:13], s[24:25], v[18:19], v[12:13] op_sel_hi:[0,1,1]
	v_cvt_scalef32_pk_f32_fp4 v[18:19], v71, 1.0 op_sel:[0,1,0]
	v_pk_fma_f32 v[14:15], s[24:25], v[18:19], v[14:15] op_sel_hi:[0,1,1]
	v_cvt_scalef32_pk_f32_fp4 v[18:19], v71, 1.0 op_sel:[1,1,0]
	v_pk_fma_f32 v[16:17], s[24:25], v[18:19], v[16:17] op_sel_hi:[0,1,1]
	v_readlane_b32 s24, v126, 48
	s_waitcnt vmcnt(15)
	v_cvt_scalef32_pk_f32_fp4 v[18:19], v72, 1.0
	v_pk_fma_f32 v[2:3], v[18:19], s[24:25], v[2:3] op_sel_hi:[1,0,1]
	v_cvt_scalef32_pk_f32_fp4 v[18:19], v72, 1.0 op_sel:[1,0,0]
	v_pk_fma_f32 v[4:5], s[24:25], v[18:19], v[4:5] op_sel_hi:[0,1,1]
	v_cvt_scalef32_pk_f32_fp4 v[18:19], v72, 1.0 op_sel:[0,1,0]
	v_pk_fma_f32 v[6:7], s[24:25], v[18:19], v[6:7] op_sel_hi:[0,1,1]
	v_cvt_scalef32_pk_f32_fp4 v[18:19], v72, 1.0 op_sel:[1,1,0]
	v_pk_fma_f32 v[8:9], s[24:25], v[18:19], v[8:9] op_sel_hi:[0,1,1]
	v_cvt_scalef32_pk_f32_fp4 v[18:19], v73, 1.0
	v_pk_fma_f32 v[10:11], s[24:25], v[18:19], v[10:11] op_sel_hi:[0,1,1]
	v_cvt_scalef32_pk_f32_fp4 v[18:19], v73, 1.0 op_sel:[1,0,0]
	v_pk_fma_f32 v[12:13], s[24:25], v[18:19], v[12:13] op_sel_hi:[0,1,1]
	v_cvt_scalef32_pk_f32_fp4 v[18:19], v73, 1.0 op_sel:[0,1,0]
	v_pk_fma_f32 v[14:15], s[24:25], v[18:19], v[14:15] op_sel_hi:[0,1,1]
	v_cvt_scalef32_pk_f32_fp4 v[18:19], v73, 1.0 op_sel:[1,1,0]
	v_pk_fma_f32 v[16:17], s[24:25], v[18:19], v[16:17] op_sel_hi:[0,1,1]
	v_readlane_b32 s24, v126, 56
	s_waitcnt vmcnt(14)
	v_cvt_scalef32_pk_f32_fp4 v[18:19], v74, 1.0
	v_pk_fma_f32 v[2:3], v[18:19], s[24:25], v[2:3] op_sel_hi:[1,0,1]
	v_cvt_scalef32_pk_f32_fp4 v[18:19], v74, 1.0 op_sel:[1,0,0]
	v_pk_fma_f32 v[4:5], s[24:25], v[18:19], v[4:5] op_sel_hi:[0,1,1]
	v_cvt_scalef32_pk_f32_fp4 v[18:19], v74, 1.0 op_sel:[0,1,0]
	v_pk_fma_f32 v[6:7], s[24:25], v[18:19], v[6:7] op_sel_hi:[0,1,1]
	v_cvt_scalef32_pk_f32_fp4 v[18:19], v74, 1.0 op_sel:[1,1,0]
	v_pk_fma_f32 v[8:9], s[24:25], v[18:19], v[8:9] op_sel_hi:[0,1,1]
	v_cvt_scalef32_pk_f32_fp4 v[18:19], v75, 1.0
	v_pk_fma_f32 v[10:11], s[24:25], v[18:19], v[10:11] op_sel_hi:[0,1,1]
	v_cvt_scalef32_pk_f32_fp4 v[18:19], v75, 1.0 op_sel:[1,0,0]
	v_pk_fma_f32 v[12:13], s[24:25], v[18:19], v[12:13] op_sel_hi:[0,1,1]
	v_cvt_scalef32_pk_f32_fp4 v[18:19], v75, 1.0 op_sel:[0,1,0]
	v_pk_fma_f32 v[14:15], s[24:25], v[18:19], v[14:15] op_sel_hi:[0,1,1]
	v_cvt_scalef32_pk_f32_fp4 v[18:19], v75, 1.0 op_sel:[1,1,0]
	v_pk_fma_f32 v[16:17], s[24:25], v[18:19], v[16:17] op_sel_hi:[0,1,1]
	v_readlane_b32 s24, v126, 52
	s_waitcnt vmcnt(13)
	v_cvt_scalef32_pk_f32_fp4 v[18:19], v76, 1.0
	v_pk_fma_f32 v[2:3], v[18:19], s[24:25], v[2:3] op_sel_hi:[1,0,1]
	v_cvt_scalef32_pk_f32_fp4 v[18:19], v76, 1.0 op_sel:[1,0,0]
	v_pk_fma_f32 v[4:5], s[24:25], v[18:19], v[4:5] op_sel_hi:[0,1,1]
	v_cvt_scalef32_pk_f32_fp4 v[18:19], v76, 1.0 op_sel:[0,1,0]
	v_pk_fma_f32 v[6:7], s[24:25], v[18:19], v[6:7] op_sel_hi:[0,1,1]
	v_cvt_scalef32_pk_f32_fp4 v[18:19], v76, 1.0 op_sel:[1,1,0]
	v_pk_fma_f32 v[8:9], s[24:25], v[18:19], v[8:9] op_sel_hi:[0,1,1]
	v_cvt_scalef32_pk_f32_fp4 v[18:19], v77, 1.0
	v_pk_fma_f32 v[10:11], s[24:25], v[18:19], v[10:11] op_sel_hi:[0,1,1]
	v_cvt_scalef32_pk_f32_fp4 v[18:19], v77, 1.0 op_sel:[1,0,0]
	v_pk_fma_f32 v[12:13], s[24:25], v[18:19], v[12:13] op_sel_hi:[0,1,1]
	v_cvt_scalef32_pk_f32_fp4 v[18:19], v77, 1.0 op_sel:[0,1,0]
	v_pk_fma_f32 v[14:15], s[24:25], v[18:19], v[14:15] op_sel_hi:[0,1,1]
	v_cvt_scalef32_pk_f32_fp4 v[18:19], v77, 1.0 op_sel:[1,1,0]
	v_pk_fma_f32 v[16:17], s[24:25], v[18:19], v[16:17] op_sel_hi:[0,1,1]
	v_readlane_b32 s24, v126, 60
	s_waitcnt vmcnt(12)
	v_cvt_scalef32_pk_f32_fp4 v[18:19], v78, 1.0
	v_pk_fma_f32 v[2:3], v[18:19], s[24:25], v[2:3] op_sel_hi:[1,0,1]
	v_cvt_scalef32_pk_f32_fp4 v[18:19], v78, 1.0 op_sel:[1,0,0]
	v_pk_fma_f32 v[4:5], s[24:25], v[18:19], v[4:5] op_sel_hi:[0,1,1]
	v_cvt_scalef32_pk_f32_fp4 v[18:19], v78, 1.0 op_sel:[0,1,0]
	v_pk_fma_f32 v[6:7], s[24:25], v[18:19], v[6:7] op_sel_hi:[0,1,1]
	v_cvt_scalef32_pk_f32_fp4 v[18:19], v78, 1.0 op_sel:[1,1,0]
	v_pk_fma_f32 v[8:9], s[24:25], v[18:19], v[8:9] op_sel_hi:[0,1,1]
	v_cvt_scalef32_pk_f32_fp4 v[18:19], v79, 1.0
	v_pk_fma_f32 v[10:11], s[24:25], v[18:19], v[10:11] op_sel_hi:[0,1,1]
	v_cvt_scalef32_pk_f32_fp4 v[18:19], v79, 1.0 op_sel:[1,0,0]
	v_pk_fma_f32 v[12:13], s[24:25], v[18:19], v[12:13] op_sel_hi:[0,1,1]
	v_cvt_scalef32_pk_f32_fp4 v[18:19], v79, 1.0 op_sel:[0,1,0]
	v_pk_fma_f32 v[14:15], s[24:25], v[18:19], v[14:15] op_sel_hi:[0,1,1]
	v_cvt_scalef32_pk_f32_fp4 v[18:19], v79, 1.0 op_sel:[1,1,0]
	v_pk_fma_f32 v[16:17], s[24:25], v[18:19], v[16:17] op_sel_hi:[0,1,1]
	v_readlane_b32 s24, v126, 50
	s_waitcnt vmcnt(11)
	v_cvt_scalef32_pk_f32_fp4 v[18:19], v80, 1.0
	v_pk_fma_f32 v[2:3], v[18:19], s[24:25], v[2:3] op_sel_hi:[1,0,1]
	v_cvt_scalef32_pk_f32_fp4 v[18:19], v80, 1.0 op_sel:[1,0,0]
	v_pk_fma_f32 v[4:5], s[24:25], v[18:19], v[4:5] op_sel_hi:[0,1,1]
	v_cvt_scalef32_pk_f32_fp4 v[18:19], v80, 1.0 op_sel:[0,1,0]
	v_pk_fma_f32 v[6:7], s[24:25], v[18:19], v[6:7] op_sel_hi:[0,1,1]
	v_cvt_scalef32_pk_f32_fp4 v[18:19], v80, 1.0 op_sel:[1,1,0]
	v_pk_fma_f32 v[8:9], s[24:25], v[18:19], v[8:9] op_sel_hi:[0,1,1]
	v_cvt_scalef32_pk_f32_fp4 v[18:19], v81, 1.0
	v_pk_fma_f32 v[10:11], s[24:25], v[18:19], v[10:11] op_sel_hi:[0,1,1]
	v_cvt_scalef32_pk_f32_fp4 v[18:19], v81, 1.0 op_sel:[1,0,0]
	v_pk_fma_f32 v[12:13], s[24:25], v[18:19], v[12:13] op_sel_hi:[0,1,1]
	v_cvt_scalef32_pk_f32_fp4 v[18:19], v81, 1.0 op_sel:[0,1,0]
	v_pk_fma_f32 v[14:15], s[24:25], v[18:19], v[14:15] op_sel_hi:[0,1,1]
	v_cvt_scalef32_pk_f32_fp4 v[18:19], v81, 1.0 op_sel:[1,1,0]
	v_pk_fma_f32 v[16:17], s[24:25], v[18:19], v[16:17] op_sel_hi:[0,1,1]
	v_readlane_b32 s24, v126, 58
	s_waitcnt vmcnt(10)
	v_cvt_scalef32_pk_f32_fp4 v[18:19], v82, 1.0
	v_pk_fma_f32 v[2:3], v[18:19], s[24:25], v[2:3] op_sel_hi:[1,0,1]
	v_cvt_scalef32_pk_f32_fp4 v[18:19], v82, 1.0 op_sel:[1,0,0]
	v_pk_fma_f32 v[4:5], s[24:25], v[18:19], v[4:5] op_sel_hi:[0,1,1]
	v_cvt_scalef32_pk_f32_fp4 v[18:19], v82, 1.0 op_sel:[0,1,0]
	v_pk_fma_f32 v[6:7], s[24:25], v[18:19], v[6:7] op_sel_hi:[0,1,1]
	v_cvt_scalef32_pk_f32_fp4 v[18:19], v82, 1.0 op_sel:[1,1,0]
	v_pk_fma_f32 v[8:9], s[24:25], v[18:19], v[8:9] op_sel_hi:[0,1,1]
	v_cvt_scalef32_pk_f32_fp4 v[18:19], v83, 1.0
	v_pk_fma_f32 v[10:11], s[24:25], v[18:19], v[10:11] op_sel_hi:[0,1,1]
	v_cvt_scalef32_pk_f32_fp4 v[18:19], v83, 1.0 op_sel:[1,0,0]
	v_pk_fma_f32 v[12:13], s[24:25], v[18:19], v[12:13] op_sel_hi:[0,1,1]
	v_cvt_scalef32_pk_f32_fp4 v[18:19], v83, 1.0 op_sel:[0,1,0]
	v_pk_fma_f32 v[14:15], s[24:25], v[18:19], v[14:15] op_sel_hi:[0,1,1]
	v_cvt_scalef32_pk_f32_fp4 v[18:19], v83, 1.0 op_sel:[1,1,0]
	v_pk_fma_f32 v[16:17], s[24:25], v[18:19], v[16:17] op_sel_hi:[0,1,1]
	v_readlane_b32 s24, v126, 54
	s_waitcnt vmcnt(9)
	v_cvt_scalef32_pk_f32_fp4 v[18:19], v84, 1.0
	v_add_u32_e32 v116, 32, v116
	v_pk_fma_f32 v[2:3], v[18:19], s[24:25], v[2:3] op_sel_hi:[1,0,1]
	v_cvt_scalef32_pk_f32_fp4 v[18:19], v84, 1.0 op_sel:[1,0,0]
	v_pk_fma_f32 v[4:5], s[24:25], v[18:19], v[4:5] op_sel_hi:[0,1,1]
	v_cvt_scalef32_pk_f32_fp4 v[18:19], v84, 1.0 op_sel:[0,1,0]
	v_pk_fma_f32 v[6:7], s[24:25], v[18:19], v[6:7] op_sel_hi:[0,1,1]
	v_cvt_scalef32_pk_f32_fp4 v[18:19], v84, 1.0 op_sel:[1,1,0]
	v_pk_fma_f32 v[8:9], s[24:25], v[18:19], v[8:9] op_sel_hi:[0,1,1]
	v_cvt_scalef32_pk_f32_fp4 v[18:19], v85, 1.0
	v_pk_fma_f32 v[10:11], s[24:25], v[18:19], v[10:11] op_sel_hi:[0,1,1]
	v_cvt_scalef32_pk_f32_fp4 v[18:19], v85, 1.0 op_sel:[1,0,0]
	v_pk_fma_f32 v[12:13], s[24:25], v[18:19], v[12:13] op_sel_hi:[0,1,1]
	v_cvt_scalef32_pk_f32_fp4 v[18:19], v85, 1.0 op_sel:[0,1,0]
	v_pk_fma_f32 v[14:15], s[24:25], v[18:19], v[14:15] op_sel_hi:[0,1,1]
	v_cvt_scalef32_pk_f32_fp4 v[18:19], v85, 1.0 op_sel:[1,1,0]
	v_pk_fma_f32 v[16:17], s[24:25], v[18:19], v[16:17] op_sel_hi:[0,1,1]
	v_readlane_b32 s24, v126, 62
	s_waitcnt vmcnt(8)
	v_cvt_scalef32_pk_f32_fp4 v[18:19], v86, 1.0
	v_cmp_ge_u32_e32 vcc, v116, v51
	v_pk_fma_f32 v[2:3], v[18:19], s[24:25], v[2:3] op_sel_hi:[1,0,1]
	v_cvt_scalef32_pk_f32_fp4 v[18:19], v86, 1.0 op_sel:[1,0,0]
	v_pk_fma_f32 v[4:5], s[24:25], v[18:19], v[4:5] op_sel_hi:[0,1,1]
	v_cvt_scalef32_pk_f32_fp4 v[18:19], v86, 1.0 op_sel:[0,1,0]
	v_pk_fma_f32 v[6:7], s[24:25], v[18:19], v[6:7] op_sel_hi:[0,1,1]
	v_cvt_scalef32_pk_f32_fp4 v[18:19], v86, 1.0 op_sel:[1,1,0]
	v_pk_fma_f32 v[8:9], s[24:25], v[18:19], v[8:9] op_sel_hi:[0,1,1]
	v_cvt_scalef32_pk_f32_fp4 v[18:19], v87, 1.0
	v_pk_fma_f32 v[10:11], s[24:25], v[18:19], v[10:11] op_sel_hi:[0,1,1]
	v_cvt_scalef32_pk_f32_fp4 v[18:19], v87, 1.0 op_sel:[1,0,0]
	v_pk_fma_f32 v[12:13], s[24:25], v[18:19], v[12:13] op_sel_hi:[0,1,1]
	v_cvt_scalef32_pk_f32_fp4 v[18:19], v87, 1.0 op_sel:[0,1,0]
	v_pk_fma_f32 v[14:15], s[24:25], v[18:19], v[14:15] op_sel_hi:[0,1,1]
	v_cvt_scalef32_pk_f32_fp4 v[18:19], v87, 1.0 op_sel:[1,1,0]
	v_pk_fma_f32 v[16:17], s[24:25], v[18:19], v[16:17] op_sel_hi:[0,1,1]
	s_waitcnt vmcnt(7)
	v_cvt_scalef32_pk_f32_fp4 v[18:19], v88, 1.0
	s_or_b64 s[12:13], vcc, s[12:13]
	s_nop 0
	v_readlane_b32 s24, v126, 49
	s_nop 1
	v_pk_fma_f32 v[2:3], v[18:19], s[24:25], v[2:3] op_sel_hi:[1,0,1]
	v_cvt_scalef32_pk_f32_fp4 v[18:19], v88, 1.0 op_sel:[1,0,0]
	v_pk_fma_f32 v[4:5], s[24:25], v[18:19], v[4:5] op_sel_hi:[0,1,1]
	v_cvt_scalef32_pk_f32_fp4 v[18:19], v88, 1.0 op_sel:[0,1,0]
	v_pk_fma_f32 v[6:7], s[24:25], v[18:19], v[6:7] op_sel_hi:[0,1,1]
	v_cvt_scalef32_pk_f32_fp4 v[18:19], v88, 1.0 op_sel:[1,1,0]
	v_pk_fma_f32 v[8:9], s[24:25], v[18:19], v[8:9] op_sel_hi:[0,1,1]
	v_cvt_scalef32_pk_f32_fp4 v[18:19], v89, 1.0
	v_pk_fma_f32 v[10:11], s[24:25], v[18:19], v[10:11] op_sel_hi:[0,1,1]
	v_cvt_scalef32_pk_f32_fp4 v[18:19], v89, 1.0 op_sel:[1,0,0]
	v_pk_fma_f32 v[12:13], s[24:25], v[18:19], v[12:13] op_sel_hi:[0,1,1]
	v_cvt_scalef32_pk_f32_fp4 v[18:19], v89, 1.0 op_sel:[0,1,0]
	v_pk_fma_f32 v[14:15], s[24:25], v[18:19], v[14:15] op_sel_hi:[0,1,1]
	v_cvt_scalef32_pk_f32_fp4 v[18:19], v89, 1.0 op_sel:[1,1,0]
	v_pk_fma_f32 v[16:17], s[24:25], v[18:19], v[16:17] op_sel_hi:[0,1,1]
	s_waitcnt vmcnt(6)
	v_cvt_scalef32_pk_f32_fp4 v[18:19], v90, 1.0
	s_nop 1
	v_readlane_b32 s24, v126, 57
	s_nop 1
	v_pk_fma_f32 v[2:3], v[18:19], s[24:25], v[2:3] op_sel_hi:[1,0,1]
	v_cvt_scalef32_pk_f32_fp4 v[18:19], v90, 1.0 op_sel:[1,0,0]
	v_pk_fma_f32 v[4:5], s[24:25], v[18:19], v[4:5] op_sel_hi:[0,1,1]
	v_cvt_scalef32_pk_f32_fp4 v[18:19], v90, 1.0 op_sel:[0,1,0]
	v_pk_fma_f32 v[6:7], s[24:25], v[18:19], v[6:7] op_sel_hi:[0,1,1]
	v_cvt_scalef32_pk_f32_fp4 v[18:19], v90, 1.0 op_sel:[1,1,0]
	v_pk_fma_f32 v[8:9], s[24:25], v[18:19], v[8:9] op_sel_hi:[0,1,1]
	v_cvt_scalef32_pk_f32_fp4 v[18:19], v91, 1.0
	v_pk_fma_f32 v[10:11], s[24:25], v[18:19], v[10:11] op_sel_hi:[0,1,1]
	v_cvt_scalef32_pk_f32_fp4 v[18:19], v91, 1.0 op_sel:[1,0,0]
	v_pk_fma_f32 v[12:13], s[24:25], v[18:19], v[12:13] op_sel_hi:[0,1,1]
	v_cvt_scalef32_pk_f32_fp4 v[18:19], v91, 1.0 op_sel:[0,1,0]
	v_pk_fma_f32 v[14:15], s[24:25], v[18:19], v[14:15] op_sel_hi:[0,1,1]
	v_cvt_scalef32_pk_f32_fp4 v[18:19], v91, 1.0 op_sel:[1,1,0]
	v_pk_fma_f32 v[16:17], s[24:25], v[18:19], v[16:17] op_sel_hi:[0,1,1]
	s_waitcnt vmcnt(5)
	v_cvt_scalef32_pk_f32_fp4 v[18:19], v92, 1.0
	s_nop 1
	v_readlane_b32 s24, v126, 53
	s_nop 1
	v_pk_fma_f32 v[2:3], v[18:19], s[24:25], v[2:3] op_sel_hi:[1,0,1]
	v_cvt_scalef32_pk_f32_fp4 v[18:19], v92, 1.0 op_sel:[1,0,0]
	v_pk_fma_f32 v[4:5], s[24:25], v[18:19], v[4:5] op_sel_hi:[0,1,1]
	v_cvt_scalef32_pk_f32_fp4 v[18:19], v92, 1.0 op_sel:[0,1,0]
	v_pk_fma_f32 v[6:7], s[24:25], v[18:19], v[6:7] op_sel_hi:[0,1,1]
	v_cvt_scalef32_pk_f32_fp4 v[18:19], v92, 1.0 op_sel:[1,1,0]
	v_pk_fma_f32 v[8:9], s[24:25], v[18:19], v[8:9] op_sel_hi:[0,1,1]
	v_cvt_scalef32_pk_f32_fp4 v[18:19], v93, 1.0
	v_pk_fma_f32 v[10:11], s[24:25], v[18:19], v[10:11] op_sel_hi:[0,1,1]
	v_cvt_scalef32_pk_f32_fp4 v[18:19], v93, 1.0 op_sel:[1,0,0]
	v_pk_fma_f32 v[12:13], s[24:25], v[18:19], v[12:13] op_sel_hi:[0,1,1]
	v_cvt_scalef32_pk_f32_fp4 v[18:19], v93, 1.0 op_sel:[0,1,0]
	v_pk_fma_f32 v[14:15], s[24:25], v[18:19], v[14:15] op_sel_hi:[0,1,1]
	v_cvt_scalef32_pk_f32_fp4 v[18:19], v93, 1.0 op_sel:[1,1,0]
	v_pk_fma_f32 v[16:17], s[24:25], v[18:19], v[16:17] op_sel_hi:[0,1,1]
	s_waitcnt vmcnt(4)
	v_cvt_scalef32_pk_f32_fp4 v[18:19], v94, 1.0
	s_nop 1
	v_readlane_b32 s24, v126, 61
	s_nop 1
	v_pk_fma_f32 v[2:3], v[18:19], s[24:25], v[2:3] op_sel_hi:[1,0,1]
	v_cvt_scalef32_pk_f32_fp4 v[18:19], v94, 1.0 op_sel:[1,0,0]
	v_pk_fma_f32 v[4:5], s[24:25], v[18:19], v[4:5] op_sel_hi:[0,1,1]
	v_cvt_scalef32_pk_f32_fp4 v[18:19], v94, 1.0 op_sel:[0,1,0]
	v_pk_fma_f32 v[6:7], s[24:25], v[18:19], v[6:7] op_sel_hi:[0,1,1]
	v_cvt_scalef32_pk_f32_fp4 v[18:19], v94, 1.0 op_sel:[1,1,0]
	v_pk_fma_f32 v[8:9], s[24:25], v[18:19], v[8:9] op_sel_hi:[0,1,1]
	v_cvt_scalef32_pk_f32_fp4 v[18:19], v95, 1.0
	v_pk_fma_f32 v[10:11], s[24:25], v[18:19], v[10:11] op_sel_hi:[0,1,1]
	v_cvt_scalef32_pk_f32_fp4 v[18:19], v95, 1.0 op_sel:[1,0,0]
	v_pk_fma_f32 v[12:13], s[24:25], v[18:19], v[12:13] op_sel_hi:[0,1,1]
	v_cvt_scalef32_pk_f32_fp4 v[18:19], v95, 1.0 op_sel:[0,1,0]
	v_pk_fma_f32 v[14:15], s[24:25], v[18:19], v[14:15] op_sel_hi:[0,1,1]
	v_cvt_scalef32_pk_f32_fp4 v[18:19], v95, 1.0 op_sel:[1,1,0]
	v_pk_fma_f32 v[16:17], s[24:25], v[18:19], v[16:17] op_sel_hi:[0,1,1]
	s_waitcnt vmcnt(3)
	v_cvt_scalef32_pk_f32_fp4 v[18:19], v96, 1.0
	s_nop 1
	v_readlane_b32 s24, v126, 51
	s_nop 1
	v_pk_fma_f32 v[2:3], v[18:19], s[24:25], v[2:3] op_sel_hi:[1,0,1]
	v_cvt_scalef32_pk_f32_fp4 v[18:19], v96, 1.0 op_sel:[1,0,0]
	v_pk_fma_f32 v[4:5], s[24:25], v[18:19], v[4:5] op_sel_hi:[0,1,1]
	v_cvt_scalef32_pk_f32_fp4 v[18:19], v96, 1.0 op_sel:[0,1,0]
	v_pk_fma_f32 v[6:7], s[24:25], v[18:19], v[6:7] op_sel_hi:[0,1,1]
	v_cvt_scalef32_pk_f32_fp4 v[18:19], v96, 1.0 op_sel:[1,1,0]
	v_pk_fma_f32 v[8:9], s[24:25], v[18:19], v[8:9] op_sel_hi:[0,1,1]
	v_cvt_scalef32_pk_f32_fp4 v[18:19], v97, 1.0
	v_pk_fma_f32 v[10:11], s[24:25], v[18:19], v[10:11] op_sel_hi:[0,1,1]
	v_cvt_scalef32_pk_f32_fp4 v[18:19], v97, 1.0 op_sel:[1,0,0]
	v_pk_fma_f32 v[12:13], s[24:25], v[18:19], v[12:13] op_sel_hi:[0,1,1]
	v_cvt_scalef32_pk_f32_fp4 v[18:19], v97, 1.0 op_sel:[0,1,0]
	v_pk_fma_f32 v[14:15], s[24:25], v[18:19], v[14:15] op_sel_hi:[0,1,1]
	v_cvt_scalef32_pk_f32_fp4 v[18:19], v97, 1.0 op_sel:[1,1,0]
	v_pk_fma_f32 v[16:17], s[24:25], v[18:19], v[16:17] op_sel_hi:[0,1,1]
	s_waitcnt vmcnt(2)
	v_cvt_scalef32_pk_f32_fp4 v[18:19], v98, 1.0
	s_nop 1
	v_readlane_b32 s24, v126, 59
	s_nop 1
	v_pk_fma_f32 v[2:3], v[18:19], s[24:25], v[2:3] op_sel_hi:[1,0,1]
	v_cvt_scalef32_pk_f32_fp4 v[18:19], v98, 1.0 op_sel:[1,0,0]
	v_pk_fma_f32 v[4:5], s[24:25], v[18:19], v[4:5] op_sel_hi:[0,1,1]
	v_cvt_scalef32_pk_f32_fp4 v[18:19], v98, 1.0 op_sel:[0,1,0]
	v_pk_fma_f32 v[6:7], s[24:25], v[18:19], v[6:7] op_sel_hi:[0,1,1]
	v_cvt_scalef32_pk_f32_fp4 v[18:19], v98, 1.0 op_sel:[1,1,0]
	v_pk_fma_f32 v[8:9], s[24:25], v[18:19], v[8:9] op_sel_hi:[0,1,1]
	v_cvt_scalef32_pk_f32_fp4 v[18:19], v99, 1.0
	v_pk_fma_f32 v[10:11], s[24:25], v[18:19], v[10:11] op_sel_hi:[0,1,1]
	v_cvt_scalef32_pk_f32_fp4 v[18:19], v99, 1.0 op_sel:[1,0,0]
	v_pk_fma_f32 v[12:13], s[24:25], v[18:19], v[12:13] op_sel_hi:[0,1,1]
	v_cvt_scalef32_pk_f32_fp4 v[18:19], v99, 1.0 op_sel:[0,1,0]
	v_pk_fma_f32 v[14:15], s[24:25], v[18:19], v[14:15] op_sel_hi:[0,1,1]
	v_cvt_scalef32_pk_f32_fp4 v[18:19], v99, 1.0 op_sel:[1,1,0]
	v_pk_fma_f32 v[16:17], s[24:25], v[18:19], v[16:17] op_sel_hi:[0,1,1]
	s_waitcnt vmcnt(1)
	v_cvt_scalef32_pk_f32_fp4 v[18:19], v100, 1.0
	s_nop 1
	v_readlane_b32 s24, v126, 55
	s_nop 1
	v_pk_fma_f32 v[2:3], v[18:19], s[24:25], v[2:3] op_sel_hi:[1,0,1]
	v_cvt_scalef32_pk_f32_fp4 v[18:19], v100, 1.0 op_sel:[1,0,0]
	v_pk_fma_f32 v[4:5], s[24:25], v[18:19], v[4:5] op_sel_hi:[0,1,1]
	v_cvt_scalef32_pk_f32_fp4 v[18:19], v100, 1.0 op_sel:[0,1,0]
	v_pk_fma_f32 v[6:7], s[24:25], v[18:19], v[6:7] op_sel_hi:[0,1,1]
	v_cvt_scalef32_pk_f32_fp4 v[18:19], v100, 1.0 op_sel:[1,1,0]
	v_pk_fma_f32 v[8:9], s[24:25], v[18:19], v[8:9] op_sel_hi:[0,1,1]
	v_cvt_scalef32_pk_f32_fp4 v[18:19], v101, 1.0
	v_pk_fma_f32 v[10:11], s[24:25], v[18:19], v[10:11] op_sel_hi:[0,1,1]
	v_cvt_scalef32_pk_f32_fp4 v[18:19], v101, 1.0 op_sel:[1,0,0]
	v_pk_fma_f32 v[12:13], s[24:25], v[18:19], v[12:13] op_sel_hi:[0,1,1]
	v_cvt_scalef32_pk_f32_fp4 v[18:19], v101, 1.0 op_sel:[0,1,0]
	v_pk_fma_f32 v[14:15], s[24:25], v[18:19], v[14:15] op_sel_hi:[0,1,1]
	v_cvt_scalef32_pk_f32_fp4 v[18:19], v101, 1.0 op_sel:[1,1,0]
	v_pk_fma_f32 v[16:17], s[24:25], v[18:19], v[16:17] op_sel_hi:[0,1,1]
	s_waitcnt vmcnt(0)
	v_cvt_scalef32_pk_f32_fp4 v[18:19], v102, 1.0
	s_nop 1
	v_readlane_b32 s24, v126, 63
	s_nop 1
	v_pk_fma_f32 v[2:3], v[18:19], s[24:25], v[2:3] op_sel_hi:[1,0,1]
	v_cvt_scalef32_pk_f32_fp4 v[18:19], v102, 1.0 op_sel:[1,0,0]
	v_pk_fma_f32 v[4:5], s[24:25], v[18:19], v[4:5] op_sel_hi:[0,1,1]
	v_cvt_scalef32_pk_f32_fp4 v[18:19], v102, 1.0 op_sel:[0,1,0]
	v_pk_fma_f32 v[6:7], s[24:25], v[18:19], v[6:7] op_sel_hi:[0,1,1]
	v_cvt_scalef32_pk_f32_fp4 v[18:19], v102, 1.0 op_sel:[1,1,0]
	v_pk_fma_f32 v[8:9], s[24:25], v[18:19], v[8:9] op_sel_hi:[0,1,1]
	v_cvt_scalef32_pk_f32_fp4 v[18:19], v103, 1.0
	v_pk_fma_f32 v[10:11], s[24:25], v[18:19], v[10:11] op_sel_hi:[0,1,1]
	v_cvt_scalef32_pk_f32_fp4 v[18:19], v103, 1.0 op_sel:[1,0,0]
	v_pk_fma_f32 v[12:13], s[24:25], v[18:19], v[12:13] op_sel_hi:[0,1,1]
	v_cvt_scalef32_pk_f32_fp4 v[18:19], v103, 1.0 op_sel:[0,1,0]
	v_pk_fma_f32 v[14:15], s[24:25], v[18:19], v[14:15] op_sel_hi:[0,1,1]
	v_cvt_scalef32_pk_f32_fp4 v[18:19], v103, 1.0 op_sel:[1,1,0]
	v_pk_fma_f32 v[16:17], s[24:25], v[18:19], v[16:17] op_sel_hi:[0,1,1]
.Lh3_v19_join:
	s_andn2_b64 exec, exec, s[12:13]
	s_cbranch_execnz .LBB0_3313
	s_or_b64 exec, exec, s[12:13]
	v_mov_b64_e32 v[32:33], v[16:17]
	v_mov_b64_e32 v[30:31], v[14:15]
	v_mov_b64_e32 v[28:29], v[12:13]
	v_mov_b64_e32 v[26:27], v[10:11]
	v_mov_b64_e32 v[24:25], v[8:9]
	v_mov_b64_e32 v[22:23], v[6:7]
	v_mov_b64_e32 v[20:21], v[4:5]
	v_mov_b64_e32 v[18:19], v[2:3]
	s_or_b64 exec, exec, s[10:11]
	s_mov_b64 s[12:13], -1
	s_and_b64 vcc, exec, s[22:23]
	s_cbranch_vccnz .LBB0_3317
